# GEMM K-loops: LDS-DMA loads use SGPR base + 32-bit VGPR offset (bases advanced by SALU instead of 8 v_lshl_add_u64 per K-step); pipelined final K-step for FFN-up tiles
# speedup vs baseline: 1.0068x; 1.0054x over previous
.LBB0_149:
	s_or_b64 exec, exec, s[4:5]
	s_and_b64 s[4:5], exec, s[28:29]
	s_cselect_b32 s4, 0x8000, 0
	s_add_i32 s4, s66, s4
	v_mov_b32_e32 v10, v132
	s_ashr_i32 s5, s4, 31
	s_lshl_b64 s[4:5], s[4:5], 11
	v_lshlrev_b32_e32 v1, 4, v10
	v_and_b32_e32 v0, 32, v10
	v_lshrrev_b32_e32 v2, 1, v10
	v_bitop3_b32 v0, v1, v0, 48 bitop3:0x6c
	s_add_u32 s42, s6, s4
	v_bfe_u32 v11, v10, 2, 4
	v_and_b32_e32 v12, 32, v2
	v_lshrrev_b32_e32 v13, 1, v0
	v_ashrrev_i32_e32 v14, 3, v10
	s_addc_u32 s43, s36, s5
	v_or_b32_e32 v4, v13, v12
	v_and_or_b32 v0, v14, s48, v11
	s_add_u32 s38, s42, 0x2400000
	v_and_b32_e32 v3, 0xfffffc00, v1
	v_lshl_or_b32 v134, v0, 10, v4
	v_add_u32_e32 v0, 0x2000, v1
	v_add_u32_e32 v2, 0x4000, v1
	v_add_u32_e32 v1, 0x6000, v1
	s_addc_u32 s39, s43, 0
	s_ashr_i32 s27, s26, 31
	v_ashrrev_i32_e32 v15, 7, v0
	v_ashrrev_i32_e32 v16, 7, v2
	v_ashrrev_i32_e32 v17, 7, v1
	s_lshl_b64 s[4:5], s[26:27], 19
	v_and_or_b32 v0, v15, s48, v11
	v_and_or_b32 v2, v16, s48, v11
	v_and_or_b32 v1, v17, s48, v11
	v_add_u32_e32 v148, 0, v3
	s_add_u32 s4, s6, s4
	v_lshl_or_b32 v0, v0, 10, v4
	v_lshl_or_b32 v2, v2, 10, v4
	v_lshl_or_b32 v4, v1, 10, v4
	v_add_u32_e32 v1, 0x8000, v148
	v_lshlrev_b64 v[6:7], 1, v[134:135]
	v_readfirstlane_b32 s27, v148
	s_addc_u32 s5, s36, s5
	v_lshl_add_u64 v[8:9], s[38:39], 0, v[6:7]
	s_mov_b32 m0, s27
	v_readfirstlane_b32 s27, v1
	v_mov_b32_e32 v1, v135
	v_add_u32_e32 v3, 0x2000, v148
	global_load_lds_dwordx4 v[8:9], off
	v_lshl_add_u64 v[6:7], s[4:5], 0, v[6:7]
	s_mov_b32 m0, s27
	v_lshlrev_b64 v[0:1], 1, v[0:1]
	v_readfirstlane_b32 s27, v3
	v_add_u32_e32 v3, 0xa000, v148
	global_load_lds_dwordx4 v[6:7], off
	v_lshl_add_u64 v[6:7], s[38:39], 0, v[0:1]
	s_mov_b32 m0, s27
	v_readfirstlane_b32 s27, v3
	global_load_lds_dwordx4 v[6:7], off
	v_lshl_add_u64 v[0:1], s[4:5], 0, v[0:1]
	s_mov_b32 m0, s27
	v_mov_b32_e32 v3, v135
	v_add_u32_e32 v5, 0x4000, v148
	global_load_lds_dwordx4 v[0:1], off
	v_lshlrev_b64 v[0:1], 1, v[2:3]
	v_readfirstlane_b32 s27, v5
	v_lshl_add_u64 v[2:3], s[38:39], 0, v[0:1]
	s_mov_b32 m0, s27
	v_lshl_add_u64 v[0:1], s[4:5], 0, v[0:1]
	global_load_lds_dwordx4 v[2:3], off
	v_add_u32_e32 v2, 0xc000, v148
	v_mov_b32_e32 v5, v135
	v_readfirstlane_b32 s27, v2
	s_mov_b32 m0, s27
	v_lshlrev_b32_e32 v6, 10, v11
	global_load_lds_dwordx4 v[0:1], off
	v_lshlrev_b64 v[0:1], 1, v[4:5]
	v_add_u32_e32 v4, 0x6000, v148
	v_lshl_add_u64 v[2:3], s[38:39], 0, v[0:1]
	v_readfirstlane_b32 s27, v4
	s_mov_b32 m0, s27
	v_lshl_add_u64 v[0:1], s[4:5], 0, v[0:1]
	global_load_lds_dwordx4 v[2:3], off
	v_add_u32_e32 v2, 0xe000, v148
	v_lshlrev_b32_e32 v4, 10, v15
	v_readfirstlane_b32 s27, v2
	s_mov_b32 m0, s27
	v_lshlrev_b32_e32 v2, 2, v10
	global_load_lds_dwordx4 v[0:1], off
	v_and_b32_e32 v0, 15, v10
	v_and_b32_e32 v1, 48, v10
	v_lshlrev_b32_e32 v0, 6, v0
	v_and_b32_e32 v2, 32, v2
	v_bitop3_b32 v149, v0, v2, v1 bitop3:0x36
	v_lshlrev_b32_e32 v0, 7, v10
	v_and_b32_e32 v150, 0x6000, v0
	v_lshlrev_b32_e32 v0, 6, v10
	v_and_b32_e32 v151, 0xffffc000, v0
	v_and_b32_e32 v0, 0x3c0, v0
	v_bitop3_b32 v153, v0, v2, v1 bitop3:0x36
	v_lshlrev_b32_e32 v0, 10, v17
	v_and_or_b32 v0, v0, s49, v13
	v_lshlrev_b32_e32 v2, 10, v16
	v_or3_b32 v134, v0, v6, v12
	v_and_or_b32 v2, v2, s49, v13
	v_lshlrev_b64 v[0:1], 1, v[134:135]
	v_or3_b32 v134, v2, v6, v12
	v_and_or_b32 v4, v4, s49, v13
	v_lshlrev_b32_e32 v7, 10, v14
	v_lshlrev_b64 v[2:3], 1, v[134:135]
	v_or3_b32 v134, v4, v6, v12
	v_and_or_b32 v7, v7, s49, v13
	s_add_u32 s4, s4, 0x80
	v_lshlrev_b64 v[4:5], 1, v[134:135]
	v_or3_b32 v134, v7, v6, v12
	s_addc_u32 s5, s5, 0
	v_lshlrev_b64 v[6:7], 1, v[134:135]
	s_waitcnt vmcnt(0)
	v_lshl_add_u64 v[128:129], s[4:5], 0, v[0:1]
	v_lshl_add_u64 v[130:131], s[4:5], 0, v[2:3]
	v_lshl_add_u64 v[136:137], s[4:5], 0, v[4:5]
	v_lshl_add_u64 v[138:139], s[4:5], 0, v[6:7]
	s_add_u32 s4, s42, 0x2400080
	s_addc_u32 s5, s43, 0
	v_mov_b32_e32 v8, 0
	s_mov_b32 s37, 0
	v_or_b32_e32 v152, 0x800, v151
	v_or_b32_e32 v154, 0x1000, v151
	v_or_b32_e32 v155, 0x1800, v151
	v_or_b32_e32 v156, 0x2000, v151
	v_or_b32_e32 v157, 0x2800, v151
	v_or_b32_e32 v158, 0x3000, v151
	v_or_b32_e32 v159, 0x3800, v151
	v_lshl_add_u64 v[140:141], s[4:5], 0, v[0:1]
	v_lshl_add_u64 v[142:143], s[4:5], 0, v[2:3]
	v_lshl_add_u64 v[144:145], s[4:5], 0, v[4:5]
	v_lshl_add_u64 v[146:147], s[4:5], 0, v[6:7]
	s_mov_b64 s[4:5], 0
	v_mov_b32_e32 v9, v8
	v_mov_b32_e32 v10, v8
	v_mov_b32_e32 v11, v8
	v_mov_b32_e32 v20, v8
	v_mov_b32_e32 v21, v8
	v_mov_b32_e32 v22, v8
	v_mov_b32_e32 v23, v8
	v_mov_b32_e32 v28, v8
	v_mov_b32_e32 v29, v8
	v_mov_b32_e32 v30, v8
	v_mov_b32_e32 v31, v8
	v_mov_b32_e32 v36, v8
	v_mov_b32_e32 v37, v8
	v_mov_b32_e32 v38, v8
	v_mov_b32_e32 v39, v8
	v_mov_b32_e32 v0, v8
	v_mov_b32_e32 v1, v8
	v_mov_b32_e32 v2, v8
	v_mov_b32_e32 v3, v8
	v_mov_b32_e32 v4, v8
	v_mov_b32_e32 v5, v8
	v_mov_b32_e32 v6, v8
	v_mov_b32_e32 v7, v8
	v_mov_b32_e32 v12, v8
	v_mov_b32_e32 v13, v8
	v_mov_b32_e32 v14, v8
	v_mov_b32_e32 v15, v8
	v_mov_b32_e32 v16, v8
	v_mov_b32_e32 v17, v8
	v_mov_b32_e32 v18, v8
	v_mov_b32_e32 v19, v8
	v_mov_b32_e32 v24, v8
	v_mov_b32_e32 v25, v8
	v_mov_b32_e32 v26, v8
	v_mov_b32_e32 v27, v8
	v_mov_b32_e32 v32, v8
	v_mov_b32_e32 v33, v8
	v_mov_b32_e32 v34, v8
	v_mov_b32_e32 v35, v8
	v_mov_b32_e32 v40, v8
	v_mov_b32_e32 v41, v8
	v_mov_b32_e32 v42, v8
	v_mov_b32_e32 v43, v8
	v_mov_b32_e32 v44, v8
	v_mov_b32_e32 v45, v8
	v_mov_b32_e32 v46, v8
	v_mov_b32_e32 v47, v8
	v_mov_b32_e32 v48, v8
	v_mov_b32_e32 v49, v8
	v_mov_b32_e32 v50, v8
	v_mov_b32_e32 v51, v8
	v_mov_b32_e32 v52, v8
	v_mov_b32_e32 v53, v8
	v_mov_b32_e32 v54, v8
	v_mov_b32_e32 v55, v8
	v_mov_b32_e32 v56, v8
	v_mov_b32_e32 v57, v8
	v_mov_b32_e32 v58, v8
	v_mov_b32_e32 v59, v8
	v_mov_b32_e32 v60, v8
	v_mov_b32_e32 v61, v8
	v_mov_b32_e32 v62, v8
	v_mov_b32_e32 v63, v8
	v_mov_b32_e32 v64, v8
	v_mov_b32_e32 v65, v8
	v_mov_b32_e32 v66, v8
	v_mov_b32_e32 v67, v8
	v_mov_b32_e32 v68, v8
	v_mov_b32_e32 v69, v8
	v_mov_b32_e32 v70, v8
	v_mov_b32_e32 v71, v8
	v_mov_b32_e32 v72, v8
	v_mov_b32_e32 v73, v8
	v_mov_b32_e32 v74, v8
	v_mov_b32_e32 v75, v8
	v_mov_b32_e32 v76, v8
	v_mov_b32_e32 v77, v8
	v_mov_b32_e32 v78, v8
	v_mov_b32_e32 v79, v8
	v_mov_b32_e32 v80, v8
	v_mov_b32_e32 v81, v8
	v_mov_b32_e32 v82, v8
	v_mov_b32_e32 v83, v8
	v_mov_b32_e32 v84, v8
	v_mov_b32_e32 v85, v8
	v_mov_b32_e32 v86, v8
	v_mov_b32_e32 v87, v8
	v_mov_b32_e32 v88, v8
	v_mov_b32_e32 v89, v8
	v_mov_b32_e32 v90, v8
	v_mov_b32_e32 v91, v8
	v_mov_b32_e32 v92, v8
	v_mov_b32_e32 v93, v8
	v_mov_b32_e32 v94, v8
	v_mov_b32_e32 v95, v8
	v_mov_b32_e32 v96, v8
	v_mov_b32_e32 v97, v8
	v_mov_b32_e32 v98, v8
	v_mov_b32_e32 v99, v8
	v_mov_b32_e32 v100, v8
	v_mov_b32_e32 v101, v8
	v_mov_b32_e32 v102, v8
	v_mov_b32_e32 v103, v8
	v_mov_b32_e32 v104, v8
	v_mov_b32_e32 v105, v8
	v_mov_b32_e32 v106, v8
	v_mov_b32_e32 v107, v8
	v_mov_b32_e32 v108, v8
	v_mov_b32_e32 v109, v8
	v_mov_b32_e32 v110, v8
	v_mov_b32_e32 v111, v8
	v_mov_b32_e32 v112, v8
	v_mov_b32_e32 v113, v8
	v_mov_b32_e32 v114, v8
	v_mov_b32_e32 v115, v8
	v_mov_b32_e32 v116, v8
	v_mov_b32_e32 v117, v8
	v_mov_b32_e32 v118, v8
	v_mov_b32_e32 v119, v8
	v_mov_b32_e32 v120, v8
	v_mov_b32_e32 v121, v8
	v_mov_b32_e32 v122, v8
	v_mov_b32_e32 v123, v8
	v_mov_b32_e32 v124, v8
	v_mov_b32_e32 v125, v8
	v_mov_b32_e32 v126, v8
	v_mov_b32_e32 v127, v8
	s_waitcnt vmcnt(0) lgkmcnt(0)
	s_barrier
	v_readfirstlane_b32 s100, v148
	s_and_b32 s27, s37, 0x10000
	s_xor_b32 s38, s27, 0x10000
	s_add_i32 s27, s27, 0
	v_add3_u32 v134, s27, v149, v150
	v_add3_u32 v196, s27, v149, v151
	v_add3_u32 v197, s27, v153, v152
	v_add3_u32 v198, s27, v153, v154
	v_add3_u32 v199, s27, v153, v155
	v_add3_u32 v200, s27, v153, v156
	v_add3_u32 v201, s27, v153, v157
	v_add3_u32 v202, s27, v153, v158
	v_add3_u32 v203, s27, v153, v159
	ds_read_b128 v[180:183], v134 offset:32768
	ds_read_b128 v[160:163], v196
	ds_read_b128 v[168:171], v197
	ds_read_b128 v[172:175], v198
	ds_read_b128 v[176:179], v199
	ds_read_b128 v[184:187], v134 offset:34816
	ds_read_b128 v[188:191], v134 offset:36864
	ds_read_b128 v[192:195], v134 offset:38912
	s_add_i32 s101, s100, s38
	v_readfirstlane_b32 s98, v146
	v_readfirstlane_b32 s99, v147
	v_readfirstlane_b32 vcc_lo, v138
	v_readfirstlane_b32 vcc_hi, v139
	s_sub_u32 s98, s98, 0x1000000
	s_subb_u32 s99, s99, 0
	s_sub_u32 vcc_lo, vcc_lo, 0x1000000
	s_subb_u32 vcc_hi, vcc_hi, 0
	v_subrev_u32_e32 v146, s98, v146
	v_subrev_u32_e32 v138, vcc_lo, v138
	v_subrev_u32_e32 v144, s98, v144
	v_subrev_u32_e32 v136, vcc_lo, v136
	v_subrev_u32_e32 v142, s98, v142
	v_subrev_u32_e32 v130, vcc_lo, v130
	v_subrev_u32_e32 v140, s98, v140
	v_subrev_u32_e32 v128, vcc_lo, v128
	s_mov_b32 m0, s101
	s_nop 0
	global_load_lds_dwordx4 v146, s[98:99]
	s_add_i32 m0, s101, 0x8000
	s_nop 0
	global_load_lds_dwordx4 v138, vcc
	s_add_i32 m0, s101, 0x2000
	s_nop 0
	global_load_lds_dwordx4 v144, s[98:99]
	s_add_i32 m0, s101, 0xa000
	s_nop 0
	global_load_lds_dwordx4 v136, vcc
	s_add_i32 m0, s101, 0x4000
	s_nop 0
	global_load_lds_dwordx4 v142, s[98:99]
	s_add_i32 m0, s101, 0xc000
	s_nop 0
	global_load_lds_dwordx4 v130, vcc
	s_add_i32 m0, s101, 0x6000
	s_nop 0
	global_load_lds_dwordx4 v140, s[98:99]
	s_add_i32 m0, s101, 0xe000
	s_nop 0
	global_load_lds_dwordx4 v128, vcc
.LBB0_150:
	s_and_b32 s27, s37, 0x10000
	s_xor_b32 s38, s27, 0x10000
	s_add_i32 s27, s27, 0
	s_add_i32 s101, s100, s38
	s_cmpk_eq_i32 s4, 0
	s_cbranch_scc1 .Lg1n_150
	s_waitcnt lgkmcnt(3)
	v_mfma_f32_16x16x32_bf16 v[124:127], v[160:163], v[180:183], v[124:127]
	v_mfma_f32_16x16x32_bf16 v[108:111], v[168:171], v[180:183], v[108:111]
	v_mfma_f32_16x16x32_bf16 v[92:95], v[172:175], v[180:183], v[92:95]
	v_mfma_f32_16x16x32_bf16 v[76:79], v[176:179], v[180:183], v[76:79]
	ds_read_b128 v[240:243], v200
	ds_read_b128 v[244:247], v201
	s_add_i32 m0, s101, 0x4000
	s_nop 0
	global_load_lds_dwordx4 v142, s[98:99]
	s_waitcnt lgkmcnt(4)
	v_mfma_f32_16x16x32_bf16 v[120:123], v[160:163], v[184:187], v[120:123]
	v_mfma_f32_16x16x32_bf16 v[104:107], v[168:171], v[184:187], v[104:107]
	v_mfma_f32_16x16x32_bf16 v[88:91], v[172:175], v[184:187], v[88:91]
	v_mfma_f32_16x16x32_bf16 v[72:75], v[176:179], v[184:187], v[72:75]
	ds_read_b128 v[248:251], v202
	ds_read_b128 v[252:255], v203
	s_add_i32 m0, s101, 0xc000
	s_nop 0
	global_load_lds_dwordx4 v130, vcc
	s_waitcnt lgkmcnt(5)
	v_mfma_f32_16x16x32_bf16 v[116:119], v[160:163], v[188:191], v[116:119]
	v_mfma_f32_16x16x32_bf16 v[100:103], v[168:171], v[188:191], v[100:103]
	v_mfma_f32_16x16x32_bf16 v[84:87], v[172:175], v[188:191], v[84:87]
	v_mfma_f32_16x16x32_bf16 v[68:71], v[176:179], v[188:191], v[68:71]
	s_add_i32 m0, s101, 0x6000
	s_nop 0
	global_load_lds_dwordx4 v140, s[98:99]
	s_waitcnt lgkmcnt(4)
	v_mfma_f32_16x16x32_bf16 v[112:115], v[160:163], v[192:195], v[112:115]
	v_mfma_f32_16x16x32_bf16 v[96:99], v[168:171], v[192:195], v[96:99]
	v_mfma_f32_16x16x32_bf16 v[80:83], v[172:175], v[192:195], v[80:83]
	v_mfma_f32_16x16x32_bf16 v[64:67], v[176:179], v[192:195], v[64:67]
	s_add_i32 m0, s101, 0xe000
	s_nop 0
	global_load_lds_dwordx4 v128, vcc
.Lg2_150:
	ds_read_b128 v[160:163], v196 offset:1024
	ds_read_b128 v[168:171], v197 offset:1024
	ds_read_b128 v[172:175], v198 offset:1024
	ds_read_b128 v[176:179], v199 offset:1024
	s_waitcnt lgkmcnt(4)
	v_mfma_f32_16x16x32_bf16 v[60:63], v[240:243], v[180:183], v[60:63]
	v_mfma_f32_16x16x32_bf16 v[44:47], v[244:247], v[180:183], v[44:47]
	v_mfma_f32_16x16x32_bf16 v[16:19], v[248:251], v[180:183], v[16:19]
	v_mfma_f32_16x16x32_bf16 v[36:39], v[252:255], v[180:183], v[36:39]
	ds_read_b128 v[180:183], v134 offset:33792
	v_mfma_f32_16x16x32_bf16 v[56:59], v[240:243], v[184:187], v[56:59]
	v_mfma_f32_16x16x32_bf16 v[40:43], v[244:247], v[184:187], v[40:43]
	v_mfma_f32_16x16x32_bf16 v[12:15], v[248:251], v[184:187], v[12:15]
	v_mfma_f32_16x16x32_bf16 v[28:31], v[252:255], v[184:187], v[28:31]
	ds_read_b128 v[184:187], v134 offset:35840
	v_mfma_f32_16x16x32_bf16 v[52:55], v[240:243], v[188:191], v[52:55]
	v_mfma_f32_16x16x32_bf16 v[32:35], v[244:247], v[188:191], v[32:35]
	v_mfma_f32_16x16x32_bf16 v[4:7], v[248:251], v[188:191], v[4:7]
	v_mfma_f32_16x16x32_bf16 v[20:23], v[252:255], v[188:191], v[20:23]
	ds_read_b128 v[188:191], v134 offset:37888
	v_mfma_f32_16x16x32_bf16 v[48:51], v[240:243], v[192:195], v[48:51]
	v_mfma_f32_16x16x32_bf16 v[24:27], v[244:247], v[192:195], v[24:27]
	v_mfma_f32_16x16x32_bf16 v[0:3], v[248:251], v[192:195], v[0:3]
	v_mfma_f32_16x16x32_bf16 v[8:11], v[252:255], v[192:195], v[8:11]
	ds_read_b128 v[192:195], v134 offset:39936
	s_waitcnt lgkmcnt(3)
	v_mfma_f32_16x16x32_bf16 v[124:127], v[160:163], v[180:183], v[124:127]
	v_mfma_f32_16x16x32_bf16 v[108:111], v[168:171], v[180:183], v[108:111]
	v_mfma_f32_16x16x32_bf16 v[92:95], v[172:175], v[180:183], v[92:95]
	v_mfma_f32_16x16x32_bf16 v[76:79], v[176:179], v[180:183], v[76:79]
	ds_read_b128 v[240:243], v200 offset:1024
	ds_read_b128 v[244:247], v201 offset:1024
	s_waitcnt lgkmcnt(4)
	v_mfma_f32_16x16x32_bf16 v[120:123], v[160:163], v[184:187], v[120:123]
	v_mfma_f32_16x16x32_bf16 v[104:107], v[168:171], v[184:187], v[104:107]
	v_mfma_f32_16x16x32_bf16 v[88:91], v[172:175], v[184:187], v[88:91]
	v_mfma_f32_16x16x32_bf16 v[72:75], v[176:179], v[184:187], v[72:75]
	ds_read_b128 v[248:251], v202 offset:1024
	ds_read_b128 v[252:255], v203 offset:1024
	s_waitcnt lgkmcnt(5)
	v_mfma_f32_16x16x32_bf16 v[116:119], v[160:163], v[188:191], v[116:119]
	v_mfma_f32_16x16x32_bf16 v[100:103], v[168:171], v[188:191], v[100:103]
	v_mfma_f32_16x16x32_bf16 v[84:87], v[172:175], v[188:191], v[84:87]
	v_mfma_f32_16x16x32_bf16 v[68:71], v[176:179], v[188:191], v[68:71]
	s_waitcnt lgkmcnt(4)
	v_mfma_f32_16x16x32_bf16 v[112:115], v[160:163], v[192:195], v[112:115]
	v_mfma_f32_16x16x32_bf16 v[96:99], v[168:171], v[192:195], v[96:99]
	v_mfma_f32_16x16x32_bf16 v[80:83], v[172:175], v[192:195], v[80:83]
	v_mfma_f32_16x16x32_bf16 v[64:67], v[176:179], v[192:195], v[64:67]
	s_waitcnt vmcnt(0) lgkmcnt(0)
	s_barrier
	s_add_i32 s101, s100, s27
	s_cmpk_eq_i32 s4, 0x700
	s_cbranch_scc1 .Lg4n_150
	s_add_u32 s98, s98, 0x80
	s_addc_u32 s99, s99, 0
	s_add_u32 vcc_lo, vcc_lo, 0x80
	s_addc_u32 vcc_hi, vcc_hi, 0
	v_mfma_f32_16x16x32_bf16 v[60:63], v[240:243], v[180:183], v[60:63]
	v_mfma_f32_16x16x32_bf16 v[44:47], v[244:247], v[180:183], v[44:47]
	v_mfma_f32_16x16x32_bf16 v[16:19], v[248:251], v[180:183], v[16:19]
	v_mfma_f32_16x16x32_bf16 v[36:39], v[252:255], v[180:183], v[36:39]
	v_add3_u32 v134, s38, v149, v150
	ds_read_b128 v[180:183], v134 offset:32768
	v_add3_u32 v196, s38, v149, v151
	v_add3_u32 v197, s38, v153, v152
	v_add3_u32 v198, s38, v153, v154
	v_add3_u32 v199, s38, v153, v155
	ds_read_b128 v[160:163], v196
	ds_read_b128 v[168:171], v197
	ds_read_b128 v[172:175], v198
	ds_read_b128 v[176:179], v199
	s_mov_b32 m0, s101
	s_nop 0
	global_load_lds_dwordx4 v146, s[98:99]
	v_mfma_f32_16x16x32_bf16 v[56:59], v[240:243], v[184:187], v[56:59]
	v_mfma_f32_16x16x32_bf16 v[40:43], v[244:247], v[184:187], v[40:43]
	v_mfma_f32_16x16x32_bf16 v[12:15], v[248:251], v[184:187], v[12:15]
	v_mfma_f32_16x16x32_bf16 v[28:31], v[252:255], v[184:187], v[28:31]
	ds_read_b128 v[184:187], v134 offset:34816
	v_add3_u32 v200, s38, v153, v156
	v_add3_u32 v201, s38, v153, v157
	v_add3_u32 v202, s38, v153, v158
	v_add3_u32 v203, s38, v153, v159
	s_add_i32 m0, s101, 0x8000
	s_nop 0
	global_load_lds_dwordx4 v138, vcc
	v_mfma_f32_16x16x32_bf16 v[52:55], v[240:243], v[188:191], v[52:55]
	v_mfma_f32_16x16x32_bf16 v[32:35], v[244:247], v[188:191], v[32:35]
	v_mfma_f32_16x16x32_bf16 v[4:7], v[248:251], v[188:191], v[4:7]
	v_mfma_f32_16x16x32_bf16 v[20:23], v[252:255], v[188:191], v[20:23]
	ds_read_b128 v[188:191], v134 offset:36864
	s_add_i32 m0, s101, 0x2000
	s_nop 0
	global_load_lds_dwordx4 v144, s[98:99]
	v_mfma_f32_16x16x32_bf16 v[48:51], v[240:243], v[192:195], v[48:51]
	v_mfma_f32_16x16x32_bf16 v[24:27], v[244:247], v[192:195], v[24:27]
	v_mfma_f32_16x16x32_bf16 v[0:3], v[248:251], v[192:195], v[0:3]
	v_mfma_f32_16x16x32_bf16 v[8:11], v[252:255], v[192:195], v[8:11]
	ds_read_b128 v[192:195], v134 offset:38912
	s_add_i32 m0, s101, 0xa000
	s_nop 0
	global_load_lds_dwordx4 v136, vcc

.LBB0_163:
	s_cmp_lg_u32 s67, 5
	s_cselect_b64 s[4:5], -1, 0
	s_and_b32 s6, s26, -10
	s_cmp_lg_u32 s6, 4
	s_cselect_b64 s[30:31], -1, 0
	v_mov_b32_e32 v0, s19
	s_and_b64 s[34:35], s[30:31], s[4:5]
	ds_read_b64 v[0:1], v0
	s_and_b64 s[4:5], exec, s[28:29]
	s_cselect_b32 s4, 0x8000, 0
	s_add_i32 s4, s66, s4
	s_ashr_i32 s5, s4, 31
	s_lshl_b64 s[4:5], s[4:5], 11
	s_waitcnt lgkmcnt(0)
	v_readfirstlane_b32 s38, v0
	v_readfirstlane_b32 s39, v1
	v_lshl_add_u64 v[0:1], v[0:1], 0, s[4:5]
	v_lshl_add_u64 v[128:129], v[0:1], 0, s[8:9]
	s_mov_b64 s[30:31], -1
	s_and_b64 vcc, exec, s[34:35]
	s_cbranch_vccz .LBB0_175
	v_mov_b32_e32 v10, v132
	s_ashr_i32 s27, s26, 31
	v_lshlrev_b32_e32 v1, 4, v10
	v_and_b32_e32 v0, 32, v10
	v_lshrrev_b32_e32 v2, 1, v10
	v_bitop3_b32 v0, v1, v0, 48 bitop3:0x6c
	v_bfe_u32 v11, v10, 2, 4
	v_and_b32_e32 v12, 32, v2
	v_lshrrev_b32_e32 v13, 1, v0
	v_ashrrev_i32_e32 v14, 3, v10
	v_or_b32_e32 v4, v13, v12
	v_and_or_b32 v0, v14, s48, v11
	v_and_b32_e32 v3, 0xfffffc00, v1
	v_lshl_or_b32 v134, v0, 10, v4
	v_add_u32_e32 v0, 0x2000, v1
	v_add_u32_e32 v2, 0x4000, v1
	v_add_u32_e32 v1, 0x6000, v1
	v_ashrrev_i32_e32 v15, 7, v0
	v_ashrrev_i32_e32 v16, 7, v2
	v_ashrrev_i32_e32 v17, 7, v1
	s_lshl_b64 s[30:31], s[26:27], 19
	v_and_or_b32 v0, v15, s48, v11
	v_and_or_b32 v2, v16, s48, v11
	v_and_or_b32 v1, v17, s48, v11
	v_add_u32_e32 v150, 0, v3
	s_add_u32 s30, s38, s30
	v_lshl_or_b32 v0, v0, 10, v4
	v_lshl_or_b32 v2, v2, 10, v4
	v_lshl_or_b32 v4, v1, 10, v4
	v_add_u32_e32 v1, 0x8000, v150
	v_lshlrev_b64 v[6:7], 1, v[134:135]
	v_readfirstlane_b32 s6, v150
	s_addc_u32 s31, s39, s31
	v_lshl_add_u64 v[8:9], v[128:129], 0, v[6:7]
	s_mov_b32 m0, s6
	v_readfirstlane_b32 s6, v1
	v_mov_b32_e32 v1, v135
	v_add_u32_e32 v3, 0x2000, v150
	global_load_lds_dwordx4 v[8:9], off
	v_lshl_add_u64 v[6:7], s[30:31], 0, v[6:7]
	s_mov_b32 m0, s6
	v_lshlrev_b64 v[0:1], 1, v[0:1]
	v_readfirstlane_b32 s6, v3
	v_add_u32_e32 v3, 0xa000, v150
	global_load_lds_dwordx4 v[6:7], off
	v_lshl_add_u64 v[6:7], v[128:129], 0, v[0:1]
	s_mov_b32 m0, s6
	v_readfirstlane_b32 s6, v3
	global_load_lds_dwordx4 v[6:7], off
	v_lshl_add_u64 v[0:1], s[30:31], 0, v[0:1]
	s_mov_b32 m0, s6
	v_mov_b32_e32 v3, v135
	v_add_u32_e32 v5, 0x4000, v150
	global_load_lds_dwordx4 v[0:1], off
	v_lshlrev_b64 v[0:1], 1, v[2:3]
	v_readfirstlane_b32 s6, v5
	v_lshl_add_u64 v[2:3], v[128:129], 0, v[0:1]
	s_mov_b32 m0, s6
	v_lshl_add_u64 v[0:1], s[30:31], 0, v[0:1]
	global_load_lds_dwordx4 v[2:3], off
	v_add_u32_e32 v2, 0xc000, v150
	v_mov_b32_e32 v5, v135
	v_readfirstlane_b32 s6, v2
	s_mov_b32 m0, s6
	v_and_b32_e32 v18, 15, v10
	global_load_lds_dwordx4 v[0:1], off
	v_lshlrev_b64 v[0:1], 1, v[4:5]
	v_add_u32_e32 v4, 0x6000, v150
	v_lshl_add_u64 v[2:3], v[128:129], 0, v[0:1]
	v_readfirstlane_b32 s6, v4
	s_mov_b32 m0, s6
	v_lshl_add_u64 v[0:1], s[30:31], 0, v[0:1]
	global_load_lds_dwordx4 v[2:3], off
	v_add_u32_e32 v2, 0xe000, v150
	v_lshlrev_b32_e32 v6, 10, v11
	v_readfirstlane_b32 s6, v2
	s_mov_b32 m0, s6
	v_lshlrev_b32_e32 v2, 2, v10
	global_load_lds_dwordx4 v[0:1], off
	v_and_b32_e32 v0, 48, v10
	v_lshlrev_b32_e32 v1, 6, v18
	v_and_b32_e32 v2, 32, v2
	v_bitop3_b32 v151, v1, v2, v0 bitop3:0x36
	v_lshlrev_b32_e32 v1, 7, v10
	v_and_b32_e32 v152, 0x6000, v1
	v_lshlrev_b32_e32 v1, 6, v10
	v_and_b32_e32 v153, 0xffffc000, v1
	v_and_b32_e32 v1, 0x3c0, v1
	v_bitop3_b32 v155, v1, v2, v0 bitop3:0x36
	v_lshlrev_b32_e32 v0, 10, v17
	v_and_or_b32 v0, v0, s49, v13
	v_lshlrev_b32_e32 v2, 10, v16
	v_or3_b32 v134, v0, v6, v12
	v_and_or_b32 v2, v2, s49, v13
	v_lshlrev_b32_e32 v4, 10, v15
	v_lshlrev_b64 v[0:1], 1, v[134:135]
	s_add_u32 s30, s30, 0x80
	v_or3_b32 v134, v2, v6, v12
	v_and_or_b32 v4, v4, s49, v13
	v_lshlrev_b32_e32 v7, 10, v14
	s_addc_u32 s31, s31, 0
	v_lshlrev_b64 v[2:3], 1, v[134:135]
	v_or3_b32 v134, v4, v6, v12
	v_and_or_b32 v7, v7, s49, v13
	v_lshlrev_b64 v[4:5], 1, v[134:135]
	v_or3_b32 v134, v7, v6, v12
	s_add_u32 s6, s38, s4
	v_lshlrev_b64 v[6:7], 1, v[134:135]
	s_addc_u32 s27, s39, s5
	v_lshl_add_u64 v[130:131], s[30:31], 0, v[0:1]
	v_lshl_add_u64 v[136:137], s[30:31], 0, v[2:3]
	v_lshl_add_u64 v[138:139], s[30:31], 0, v[4:5]
	v_lshl_add_u64 v[140:141], s[30:31], 0, v[6:7]
	s_add_u32 s30, s6, 0x2400080
	s_waitcnt vmcnt(0)
	s_addc_u32 s31, s27, 0
	v_lshl_add_u64 v[142:143], s[30:31], 0, v[0:1]
	v_mov_b32_e32 v0, 0
	v_or_b32_e32 v154, 0x800, v153
	v_or_b32_e32 v156, 0x1000, v153
	v_or_b32_e32 v157, 0x1800, v153
	v_or_b32_e32 v158, 0x2000, v153
	v_or_b32_e32 v159, 0x2800, v153
	v_or_b32_e32 v160, 0x3000, v153
	v_or_b32_e32 v161, 0x3800, v153
	v_lshl_add_u64 v[144:145], s[30:31], 0, v[2:3]
	v_lshl_add_u64 v[146:147], s[30:31], 0, v[4:5]
	v_lshl_add_u64 v[148:149], s[30:31], 0, v[6:7]
	s_mov_b32 s6, 0
	s_mov_b64 s[30:31], 0
	v_mov_b32_e32 v1, v0
	v_mov_b32_e32 v2, v0
	v_mov_b32_e32 v3, v0
	v_mov_b32_e32 v4, v0
	v_mov_b32_e32 v5, v0
	v_mov_b32_e32 v6, v0
	v_mov_b32_e32 v7, v0
	v_mov_b32_e32 v8, v0
	v_mov_b32_e32 v9, v0
	v_mov_b32_e32 v10, v0
	v_mov_b32_e32 v11, v0
	v_mov_b32_e32 v12, v0
	v_mov_b32_e32 v13, v0
	v_mov_b32_e32 v14, v0
	v_mov_b32_e32 v15, v0
	v_mov_b32_e32 v16, v0
	v_mov_b32_e32 v17, v0
	v_mov_b32_e32 v18, v0
	v_mov_b32_e32 v19, v0
	v_mov_b32_e32 v20, v0
	v_mov_b32_e32 v21, v0
	v_mov_b32_e32 v22, v0
	v_mov_b32_e32 v23, v0
	v_mov_b32_e32 v24, v0
	v_mov_b32_e32 v25, v0
	v_mov_b32_e32 v26, v0
	v_mov_b32_e32 v27, v0
	v_mov_b32_e32 v28, v0
	v_mov_b32_e32 v29, v0
	v_mov_b32_e32 v30, v0
	v_mov_b32_e32 v31, v0
	v_mov_b32_e32 v32, v0
	v_mov_b32_e32 v33, v0
	v_mov_b32_e32 v34, v0
	v_mov_b32_e32 v35, v0
	v_mov_b32_e32 v36, v0
	v_mov_b32_e32 v37, v0
	v_mov_b32_e32 v38, v0
	v_mov_b32_e32 v39, v0
	v_mov_b32_e32 v40, v0
	v_mov_b32_e32 v41, v0
	v_mov_b32_e32 v42, v0
	v_mov_b32_e32 v43, v0
	v_mov_b32_e32 v44, v0
	v_mov_b32_e32 v45, v0
	v_mov_b32_e32 v46, v0
	v_mov_b32_e32 v47, v0
	v_mov_b32_e32 v48, v0
	v_mov_b32_e32 v49, v0
	v_mov_b32_e32 v50, v0
	v_mov_b32_e32 v51, v0
	v_mov_b32_e32 v52, v0
	v_mov_b32_e32 v53, v0
	v_mov_b32_e32 v54, v0
	v_mov_b32_e32 v55, v0
	v_mov_b32_e32 v56, v0
	v_mov_b32_e32 v57, v0
	v_mov_b32_e32 v58, v0
	v_mov_b32_e32 v59, v0
	v_mov_b32_e32 v60, v0
	v_mov_b32_e32 v61, v0
	v_mov_b32_e32 v62, v0
	v_mov_b32_e32 v63, v0
	v_mov_b32_e32 v64, v0
	v_mov_b32_e32 v65, v0
	v_mov_b32_e32 v66, v0
	v_mov_b32_e32 v67, v0
	v_mov_b32_e32 v68, v0
	v_mov_b32_e32 v69, v0
	v_mov_b32_e32 v70, v0
	v_mov_b32_e32 v71, v0
	v_mov_b32_e32 v72, v0
	v_mov_b32_e32 v73, v0
	v_mov_b32_e32 v74, v0
	v_mov_b32_e32 v75, v0
	v_mov_b32_e32 v76, v0
	v_mov_b32_e32 v77, v0
	v_mov_b32_e32 v78, v0
	v_mov_b32_e32 v79, v0
	v_mov_b32_e32 v80, v0
	v_mov_b32_e32 v81, v0
	v_mov_b32_e32 v82, v0
	v_mov_b32_e32 v83, v0
	v_mov_b32_e32 v84, v0
	v_mov_b32_e32 v85, v0
	v_mov_b32_e32 v86, v0
	v_mov_b32_e32 v87, v0
	v_mov_b32_e32 v88, v0
	v_mov_b32_e32 v89, v0
	v_mov_b32_e32 v90, v0
	v_mov_b32_e32 v91, v0
	v_mov_b32_e32 v92, v0
	v_mov_b32_e32 v93, v0
	v_mov_b32_e32 v94, v0
	v_mov_b32_e32 v95, v0
	v_mov_b32_e32 v96, v0
	v_mov_b32_e32 v97, v0
	v_mov_b32_e32 v98, v0
	v_mov_b32_e32 v99, v0
	v_mov_b32_e32 v100, v0
	v_mov_b32_e32 v101, v0
	v_mov_b32_e32 v102, v0
	v_mov_b32_e32 v103, v0
	v_mov_b32_e32 v104, v0
	v_mov_b32_e32 v105, v0
	v_mov_b32_e32 v106, v0
	v_mov_b32_e32 v107, v0
	v_mov_b32_e32 v108, v0
	v_mov_b32_e32 v109, v0
	v_mov_b32_e32 v110, v0
	v_mov_b32_e32 v111, v0
	v_mov_b32_e32 v112, v0
	v_mov_b32_e32 v113, v0
	v_mov_b32_e32 v114, v0
	v_mov_b32_e32 v115, v0
	v_mov_b32_e32 v116, v0
	v_mov_b32_e32 v117, v0
	v_mov_b32_e32 v118, v0
	v_mov_b32_e32 v119, v0
	v_mov_b32_e32 v120, v0
	v_mov_b32_e32 v121, v0
	v_mov_b32_e32 v122, v0
	v_mov_b32_e32 v123, v0
	v_mov_b32_e32 v124, v0
	v_mov_b32_e32 v125, v0
	v_mov_b32_e32 v126, v0
	v_mov_b32_e32 v127, v0
	s_waitcnt vmcnt(0) lgkmcnt(0)
	s_barrier
	v_readfirstlane_b32 s100, v150
	s_and_b32 s27, s6, 0x10000
	s_xor_b32 s34, s27, 0x10000
	s_add_i32 s27, s27, 0
	v_add3_u32 v134, s27, v151, v152
	v_add3_u32 v162, s27, v151, v153
	v_add3_u32 v163, s27, v155, v154
	v_add3_u32 v200, s27, v155, v156
	v_add3_u32 v201, s27, v155, v157
	v_add3_u32 v202, s27, v155, v158
	v_add3_u32 v203, s27, v155, v159
	v_add3_u32 v204, s27, v155, v160
	v_add3_u32 v205, s27, v155, v161
	ds_read_b128 v[184:187], v134 offset:32768
	ds_read_b128 v[168:171], v162
	ds_read_b128 v[172:175], v163
	ds_read_b128 v[176:179], v200
	ds_read_b128 v[180:183], v201
	ds_read_b128 v[188:191], v134 offset:34816
	ds_read_b128 v[192:195], v134 offset:36864
	ds_read_b128 v[196:199], v134 offset:38912
	s_add_i32 s101, s100, s34
	v_readfirstlane_b32 s98, v148
	v_readfirstlane_b32 s99, v149
	v_readfirstlane_b32 vcc_lo, v140
	v_readfirstlane_b32 vcc_hi, v141
	s_sub_u32 s98, s98, 0x1000000
	s_subb_u32 s99, s99, 0
	s_sub_u32 vcc_lo, vcc_lo, 0x1000000
	s_subb_u32 vcc_hi, vcc_hi, 0
	v_subrev_u32_e32 v148, s98, v148
	v_subrev_u32_e32 v140, vcc_lo, v140
	v_subrev_u32_e32 v146, s98, v146
	v_subrev_u32_e32 v138, vcc_lo, v138
	v_subrev_u32_e32 v144, s98, v144
	v_subrev_u32_e32 v136, vcc_lo, v136
	v_subrev_u32_e32 v142, s98, v142
	v_subrev_u32_e32 v130, vcc_lo, v130
	s_mov_b32 m0, s101
	s_nop 0
	global_load_lds_dwordx4 v148, s[98:99]
	s_add_i32 m0, s101, 0x8000
	s_nop 0
	global_load_lds_dwordx4 v140, vcc
	s_add_i32 m0, s101, 0x2000
	s_nop 0
	global_load_lds_dwordx4 v146, s[98:99]
	s_add_i32 m0, s101, 0xa000
	s_nop 0
	global_load_lds_dwordx4 v138, vcc
	s_add_i32 m0, s101, 0x4000
	s_nop 0
	global_load_lds_dwordx4 v144, s[98:99]
	s_add_i32 m0, s101, 0xc000
	s_nop 0
	global_load_lds_dwordx4 v136, vcc
	s_add_i32 m0, s101, 0x6000
	s_nop 0
	global_load_lds_dwordx4 v142, s[98:99]
	s_add_i32 m0, s101, 0xe000
	s_nop 0
	global_load_lds_dwordx4 v130, vcc
.LBB0_165:
	s_and_b32 s27, s6, 0x10000
	s_xor_b32 s34, s27, 0x10000
	s_add_i32 s27, s27, 0
	s_add_i32 s101, s100, s34
	s_cmpk_eq_i32 s30, 0
	s_cbranch_scc1 .Lg1n_165
	s_waitcnt lgkmcnt(3)
	v_mfma_f32_16x16x32_bf16 v[108:111], v[184:187], v[168:171], v[108:111]
	v_mfma_f32_16x16x32_bf16 v[92:95], v[184:187], v[172:175], v[92:95]
	v_mfma_f32_16x16x32_bf16 v[76:79], v[184:187], v[176:179], v[76:79]
	v_mfma_f32_16x16x32_bf16 v[60:63], v[184:187], v[180:183], v[60:63]
	ds_read_b128 v[240:243], v202
	ds_read_b128 v[244:247], v203
	s_add_i32 m0, s101, 0x4000
	s_nop 0
	global_load_lds_dwordx4 v144, s[98:99]
	s_waitcnt lgkmcnt(4)
	v_mfma_f32_16x16x32_bf16 v[104:107], v[188:191], v[168:171], v[104:107]
	v_mfma_f32_16x16x32_bf16 v[88:91], v[188:191], v[172:175], v[88:91]
	v_mfma_f32_16x16x32_bf16 v[72:75], v[188:191], v[176:179], v[72:75]
	v_mfma_f32_16x16x32_bf16 v[56:59], v[188:191], v[180:183], v[56:59]
	ds_read_b128 v[248:251], v204
	ds_read_b128 v[252:255], v205
	s_add_i32 m0, s101, 0xc000
	s_nop 0
	global_load_lds_dwordx4 v136, vcc
	s_waitcnt lgkmcnt(5)
	v_mfma_f32_16x16x32_bf16 v[100:103], v[192:195], v[168:171], v[100:103]
	v_mfma_f32_16x16x32_bf16 v[84:87], v[192:195], v[172:175], v[84:87]
	v_mfma_f32_16x16x32_bf16 v[68:71], v[192:195], v[176:179], v[68:71]
	v_mfma_f32_16x16x32_bf16 v[52:55], v[192:195], v[180:183], v[52:55]
	s_add_i32 m0, s101, 0x6000
	s_nop 0
	global_load_lds_dwordx4 v142, s[98:99]
	s_waitcnt lgkmcnt(4)
	v_mfma_f32_16x16x32_bf16 v[96:99], v[196:199], v[168:171], v[96:99]
	v_mfma_f32_16x16x32_bf16 v[80:83], v[196:199], v[172:175], v[80:83]
	v_mfma_f32_16x16x32_bf16 v[64:67], v[196:199], v[176:179], v[64:67]
	v_mfma_f32_16x16x32_bf16 v[48:51], v[196:199], v[180:183], v[48:51]
	s_add_i32 m0, s101, 0xe000
	s_nop 0
	global_load_lds_dwordx4 v130, vcc
.Lg2_165:
	ds_read_b128 v[168:171], v162 offset:1024
	ds_read_b128 v[172:175], v163 offset:1024
	ds_read_b128 v[176:179], v200 offset:1024
	ds_read_b128 v[180:183], v201 offset:1024
	s_waitcnt lgkmcnt(4)
	v_mfma_f32_16x16x32_bf16 v[44:47], v[184:187], v[240:243], v[44:47]
	v_mfma_f32_16x16x32_bf16 v[28:31], v[184:187], v[244:247], v[28:31]
	v_mfma_f32_16x16x32_bf16 v[12:15], v[184:187], v[248:251], v[12:15]
	v_mfma_f32_16x16x32_bf16 v[112:115], v[184:187], v[252:255], v[112:115]
	ds_read_b128 v[184:187], v134 offset:33792
	v_mfma_f32_16x16x32_bf16 v[40:43], v[188:191], v[240:243], v[40:43]
	v_mfma_f32_16x16x32_bf16 v[24:27], v[188:191], v[244:247], v[24:27]
	v_mfma_f32_16x16x32_bf16 v[8:11], v[188:191], v[248:251], v[8:11]
	v_mfma_f32_16x16x32_bf16 v[116:119], v[188:191], v[252:255], v[116:119]
	ds_read_b128 v[188:191], v134 offset:35840
	v_mfma_f32_16x16x32_bf16 v[36:39], v[192:195], v[240:243], v[36:39]
	v_mfma_f32_16x16x32_bf16 v[20:23], v[192:195], v[244:247], v[20:23]
	v_mfma_f32_16x16x32_bf16 v[4:7], v[192:195], v[248:251], v[4:7]
	v_mfma_f32_16x16x32_bf16 v[120:123], v[192:195], v[252:255], v[120:123]
	ds_read_b128 v[192:195], v134 offset:37888
	v_mfma_f32_16x16x32_bf16 v[32:35], v[196:199], v[240:243], v[32:35]
	v_mfma_f32_16x16x32_bf16 v[16:19], v[196:199], v[244:247], v[16:19]
	v_mfma_f32_16x16x32_bf16 v[0:3], v[196:199], v[248:251], v[0:3]
	v_mfma_f32_16x16x32_bf16 v[124:127], v[196:199], v[252:255], v[124:127]
	ds_read_b128 v[196:199], v134 offset:39936
	s_waitcnt lgkmcnt(3)
	v_mfma_f32_16x16x32_bf16 v[108:111], v[184:187], v[168:171], v[108:111]
	v_mfma_f32_16x16x32_bf16 v[92:95], v[184:187], v[172:175], v[92:95]
	v_mfma_f32_16x16x32_bf16 v[76:79], v[184:187], v[176:179], v[76:79]
	v_mfma_f32_16x16x32_bf16 v[60:63], v[184:187], v[180:183], v[60:63]
	ds_read_b128 v[240:243], v202 offset:1024
	ds_read_b128 v[244:247], v203 offset:1024
	s_waitcnt lgkmcnt(4)
	v_mfma_f32_16x16x32_bf16 v[104:107], v[188:191], v[168:171], v[104:107]
	v_mfma_f32_16x16x32_bf16 v[88:91], v[188:191], v[172:175], v[88:91]
	v_mfma_f32_16x16x32_bf16 v[72:75], v[188:191], v[176:179], v[72:75]
	v_mfma_f32_16x16x32_bf16 v[56:59], v[188:191], v[180:183], v[56:59]
	ds_read_b128 v[248:251], v204 offset:1024
	ds_read_b128 v[252:255], v205 offset:1024
	s_waitcnt lgkmcnt(5)
	v_mfma_f32_16x16x32_bf16 v[100:103], v[192:195], v[168:171], v[100:103]
	v_mfma_f32_16x16x32_bf16 v[84:87], v[192:195], v[172:175], v[84:87]
	v_mfma_f32_16x16x32_bf16 v[68:71], v[192:195], v[176:179], v[68:71]
	v_mfma_f32_16x16x32_bf16 v[52:55], v[192:195], v[180:183], v[52:55]
	s_waitcnt lgkmcnt(4)
	v_mfma_f32_16x16x32_bf16 v[96:99], v[196:199], v[168:171], v[96:99]
	v_mfma_f32_16x16x32_bf16 v[80:83], v[196:199], v[172:175], v[80:83]
	v_mfma_f32_16x16x32_bf16 v[64:67], v[196:199], v[176:179], v[64:67]
	v_mfma_f32_16x16x32_bf16 v[48:51], v[196:199], v[180:183], v[48:51]
	s_waitcnt vmcnt(0) lgkmcnt(0)
	s_barrier
	s_add_i32 s101, s100, s27
	s_cmpk_eq_i32 s30, 0x700
	s_cbranch_scc1 .Lg4n_165
	s_add_u32 s98, s98, 0x80
	s_addc_u32 s99, s99, 0
	s_add_u32 vcc_lo, vcc_lo, 0x80
	s_addc_u32 vcc_hi, vcc_hi, 0
	v_mfma_f32_16x16x32_bf16 v[44:47], v[184:187], v[240:243], v[44:47]
	v_mfma_f32_16x16x32_bf16 v[28:31], v[184:187], v[244:247], v[28:31]
	v_mfma_f32_16x16x32_bf16 v[12:15], v[184:187], v[248:251], v[12:15]
	v_mfma_f32_16x16x32_bf16 v[112:115], v[184:187], v[252:255], v[112:115]
	v_add3_u32 v134, s34, v151, v152
	ds_read_b128 v[184:187], v134 offset:32768
	v_add3_u32 v162, s34, v151, v153
	v_add3_u32 v163, s34, v155, v154
	v_add3_u32 v200, s34, v155, v156
	v_add3_u32 v201, s34, v155, v157
	ds_read_b128 v[168:171], v162
	ds_read_b128 v[172:175], v163
	ds_read_b128 v[176:179], v200
	ds_read_b128 v[180:183], v201
	s_mov_b32 m0, s101
	s_nop 0
	global_load_lds_dwordx4 v148, s[98:99]
	v_mfma_f32_16x16x32_bf16 v[40:43], v[188:191], v[240:243], v[40:43]
	v_mfma_f32_16x16x32_bf16 v[24:27], v[188:191], v[244:247], v[24:27]
	v_mfma_f32_16x16x32_bf16 v[8:11], v[188:191], v[248:251], v[8:11]
	v_mfma_f32_16x16x32_bf16 v[116:119], v[188:191], v[252:255], v[116:119]
	ds_read_b128 v[188:191], v134 offset:34816
	v_add3_u32 v202, s34, v155, v158
	v_add3_u32 v203, s34, v155, v159
	v_add3_u32 v204, s34, v155, v160
	v_add3_u32 v205, s34, v155, v161
	s_add_i32 m0, s101, 0x8000
	s_nop 0
	global_load_lds_dwordx4 v140, vcc
	v_mfma_f32_16x16x32_bf16 v[36:39], v[192:195], v[240:243], v[36:39]
	v_mfma_f32_16x16x32_bf16 v[20:23], v[192:195], v[244:247], v[20:23]
	v_mfma_f32_16x16x32_bf16 v[4:7], v[192:195], v[248:251], v[4:7]
	v_mfma_f32_16x16x32_bf16 v[120:123], v[192:195], v[252:255], v[120:123]
	ds_read_b128 v[192:195], v134 offset:36864
	s_add_i32 m0, s101, 0x2000
	s_nop 0
	global_load_lds_dwordx4 v146, s[98:99]
	v_mfma_f32_16x16x32_bf16 v[32:35], v[196:199], v[240:243], v[32:35]
	v_mfma_f32_16x16x32_bf16 v[16:19], v[196:199], v[244:247], v[16:19]
	v_mfma_f32_16x16x32_bf16 v[0:3], v[196:199], v[248:251], v[0:3]
	v_mfma_f32_16x16x32_bf16 v[124:127], v[196:199], v[252:255], v[124:127]
	ds_read_b128 v[196:199], v134 offset:38912
	s_add_i32 m0, s101, 0xa000
	s_nop 0
	global_load_lds_dwordx4 v138, vcc

.LBB0_175:
	s_and_b64 vcc, exec, s[30:31]
	s_cbranch_vccz .LBB0_179
	v_mov_b32_e32 v10, v132
	s_lshl_b32 s6, s26, 19
	v_lshlrev_b32_e32 v1, 4, v10
	v_and_b32_e32 v0, 32, v10
	v_lshrrev_b32_e32 v2, 1, v10
	v_bitop3_b32 v0, v1, v0, 48 bitop3:0x6c
	v_bfe_u32 v11, v10, 2, 4
	v_and_b32_e32 v12, 32, v2
	v_lshrrev_b32_e32 v13, 1, v0
	v_ashrrev_i32_e32 v14, 3, v10
	v_or_b32_e32 v4, v13, v12
	v_and_or_b32 v0, v14, s48, v11
	v_and_b32_e32 v3, 0xfffffc00, v1
	v_lshl_or_b32 v134, v0, 10, v4
	v_add_u32_e32 v0, 0x2000, v1
	v_add_u32_e32 v2, 0x4000, v1
	v_add_u32_e32 v1, 0x6000, v1
	v_ashrrev_i32_e32 v15, 7, v0
	v_ashrrev_i32_e32 v16, 7, v2
	v_ashrrev_i32_e32 v17, 7, v1
	v_and_or_b32 v0, v15, s48, v11
	v_and_or_b32 v2, v16, s48, v11
	v_and_or_b32 v1, v17, s48, v11
	v_add_u32_e32 v148, 0, v3
	s_add_u32 s30, s38, s6
	v_lshl_or_b32 v0, v0, 10, v4
	v_lshl_or_b32 v2, v2, 10, v4
	v_lshl_or_b32 v4, v1, 10, v4
	v_add_u32_e32 v1, 0x8000, v148
	v_lshlrev_b64 v[6:7], 1, v[134:135]
	v_readfirstlane_b32 s6, v148
	s_addc_u32 s31, s39, 0
	v_lshl_add_u64 v[8:9], v[128:129], 0, v[6:7]
	s_mov_b32 m0, s6
	v_readfirstlane_b32 s6, v1
	v_mov_b32_e32 v1, v135
	v_add_u32_e32 v3, 0x2000, v148
	global_load_lds_dwordx4 v[8:9], off
	v_lshl_add_u64 v[6:7], s[30:31], 0, v[6:7]
	s_mov_b32 m0, s6
	v_lshlrev_b64 v[0:1], 1, v[0:1]
	v_readfirstlane_b32 s6, v3
	v_add_u32_e32 v3, 0xa000, v148
	global_load_lds_dwordx4 v[6:7], off
	v_lshl_add_u64 v[6:7], v[128:129], 0, v[0:1]
	s_mov_b32 m0, s6
	v_readfirstlane_b32 s6, v3
	global_load_lds_dwordx4 v[6:7], off
	v_lshl_add_u64 v[0:1], s[30:31], 0, v[0:1]
	s_mov_b32 m0, s6
	v_mov_b32_e32 v3, v135
	v_add_u32_e32 v5, 0x4000, v148
	global_load_lds_dwordx4 v[0:1], off
	v_lshlrev_b64 v[0:1], 1, v[2:3]
	v_readfirstlane_b32 s6, v5
	v_lshl_add_u64 v[2:3], v[128:129], 0, v[0:1]
	s_mov_b32 m0, s6
	v_lshl_add_u64 v[0:1], s[30:31], 0, v[0:1]
	global_load_lds_dwordx4 v[2:3], off
	v_add_u32_e32 v2, 0xc000, v148
	v_mov_b32_e32 v5, v135
	v_readfirstlane_b32 s6, v2
	s_mov_b32 m0, s6
	v_lshlrev_b32_e32 v6, 10, v11
	global_load_lds_dwordx4 v[0:1], off
	v_lshlrev_b64 v[0:1], 1, v[4:5]
	v_add_u32_e32 v4, 0x6000, v148
	v_lshl_add_u64 v[2:3], v[128:129], 0, v[0:1]
	v_readfirstlane_b32 s6, v4
	s_mov_b32 m0, s6
	v_lshl_add_u64 v[0:1], s[30:31], 0, v[0:1]
	global_load_lds_dwordx4 v[2:3], off
	v_add_u32_e32 v2, 0xe000, v148
	s_add_u32 s30, s30, 0x80
	v_readfirstlane_b32 s6, v2
	s_mov_b32 m0, s6
	v_lshlrev_b32_e32 v2, 2, v10
	global_load_lds_dwordx4 v[0:1], off
	v_and_b32_e32 v0, 15, v10
	v_and_b32_e32 v1, 48, v10
	v_lshlrev_b32_e32 v0, 6, v0
	v_and_b32_e32 v2, 32, v2
	v_bitop3_b32 v149, v0, v2, v1 bitop3:0x36
	v_lshlrev_b32_e32 v0, 7, v10
	v_and_b32_e32 v150, 0x6000, v0
	v_lshlrev_b32_e32 v0, 6, v10
	v_and_b32_e32 v151, 0xffffc000, v0
	v_and_b32_e32 v0, 0x3c0, v0
	v_bitop3_b32 v153, v0, v2, v1 bitop3:0x36
	v_lshlrev_b32_e32 v0, 10, v17
	v_and_or_b32 v0, v0, s49, v13
	s_addc_u32 s31, s31, 0
	v_lshlrev_b32_e32 v2, 10, v16
	v_or3_b32 v134, v0, v6, v12
	v_and_or_b32 v2, v2, s49, v13
	v_lshlrev_b32_e32 v4, 10, v15
	s_add_u32 s4, s38, s4
	v_lshlrev_b64 v[0:1], 1, v[134:135]
	v_or3_b32 v134, v2, v6, v12
	v_and_or_b32 v4, v4, s49, v13
	v_lshlrev_b32_e32 v7, 10, v14
	s_addc_u32 s5, s39, s5
	v_lshlrev_b64 v[2:3], 1, v[134:135]
	v_or3_b32 v134, v4, v6, v12
	v_and_or_b32 v7, v7, s49, v13
	s_add_u32 s4, s4, 0x2400080
	s_waitcnt vmcnt(0)
	v_lshlrev_b64 v[4:5], 1, v[134:135]
	v_or3_b32 v134, v7, v6, v12
	s_addc_u32 s5, s5, 0
	v_lshl_add_u64 v[128:129], s[30:31], 0, v[0:1]
	v_lshlrev_b64 v[6:7], 1, v[134:135]
	v_lshl_add_u64 v[140:141], s[4:5], 0, v[0:1]
	v_mov_b32_e32 v0, 0
	v_or_b32_e32 v152, 0x800, v151
	v_or_b32_e32 v154, 0x1000, v151
	v_or_b32_e32 v155, 0x1800, v151
	v_or_b32_e32 v156, 0x2000, v151
	v_or_b32_e32 v157, 0x2800, v151
	v_or_b32_e32 v158, 0x3000, v151
	v_or_b32_e32 v159, 0x3800, v151
	v_lshl_add_u64 v[130:131], s[30:31], 0, v[2:3]
	v_lshl_add_u64 v[136:137], s[30:31], 0, v[4:5]
	v_lshl_add_u64 v[138:139], s[30:31], 0, v[6:7]
	v_lshl_add_u64 v[142:143], s[4:5], 0, v[2:3]
	v_lshl_add_u64 v[144:145], s[4:5], 0, v[4:5]
	v_lshl_add_u64 v[146:147], s[4:5], 0, v[6:7]
	s_mov_b32 s6, 0
	s_mov_b64 s[4:5], 0
	v_mov_b32_e32 v1, v0
	v_mov_b32_e32 v2, v0
	v_mov_b32_e32 v3, v0
	v_mov_b32_e32 v4, v0
	v_mov_b32_e32 v5, v0
	v_mov_b32_e32 v6, v0
	v_mov_b32_e32 v7, v0
	v_mov_b32_e32 v8, v0
	v_mov_b32_e32 v9, v0
	v_mov_b32_e32 v10, v0
	v_mov_b32_e32 v11, v0
	v_mov_b32_e32 v12, v0
	v_mov_b32_e32 v13, v0
	v_mov_b32_e32 v14, v0
	v_mov_b32_e32 v15, v0
	v_mov_b32_e32 v16, v0
	v_mov_b32_e32 v17, v0
	v_mov_b32_e32 v18, v0
	v_mov_b32_e32 v19, v0
	v_mov_b32_e32 v20, v0
	v_mov_b32_e32 v21, v0
	v_mov_b32_e32 v22, v0
	v_mov_b32_e32 v23, v0
	v_mov_b32_e32 v24, v0
	v_mov_b32_e32 v25, v0
	v_mov_b32_e32 v26, v0
	v_mov_b32_e32 v27, v0
	v_mov_b32_e32 v28, v0
	v_mov_b32_e32 v29, v0
	v_mov_b32_e32 v30, v0
	v_mov_b32_e32 v31, v0
	v_mov_b32_e32 v32, v0
	v_mov_b32_e32 v33, v0
	v_mov_b32_e32 v34, v0
	v_mov_b32_e32 v35, v0
	v_mov_b32_e32 v36, v0
	v_mov_b32_e32 v37, v0
	v_mov_b32_e32 v38, v0
	v_mov_b32_e32 v39, v0
	v_mov_b32_e32 v40, v0
	v_mov_b32_e32 v41, v0
	v_mov_b32_e32 v42, v0
	v_mov_b32_e32 v43, v0
	v_mov_b32_e32 v44, v0
	v_mov_b32_e32 v45, v0
	v_mov_b32_e32 v46, v0
	v_mov_b32_e32 v47, v0
	v_mov_b32_e32 v48, v0
	v_mov_b32_e32 v49, v0
	v_mov_b32_e32 v50, v0
	v_mov_b32_e32 v51, v0
	v_mov_b32_e32 v52, v0
	v_mov_b32_e32 v53, v0
	v_mov_b32_e32 v54, v0
	v_mov_b32_e32 v55, v0
	v_mov_b32_e32 v56, v0
	v_mov_b32_e32 v57, v0
	v_mov_b32_e32 v58, v0
	v_mov_b32_e32 v59, v0
	v_mov_b32_e32 v60, v0
	v_mov_b32_e32 v61, v0
	v_mov_b32_e32 v62, v0
	v_mov_b32_e32 v63, v0
	v_mov_b32_e32 v64, v0
	v_mov_b32_e32 v65, v0
	v_mov_b32_e32 v66, v0
	v_mov_b32_e32 v67, v0
	v_mov_b32_e32 v68, v0
	v_mov_b32_e32 v69, v0
	v_mov_b32_e32 v70, v0
	v_mov_b32_e32 v71, v0
	v_mov_b32_e32 v72, v0
	v_mov_b32_e32 v73, v0
	v_mov_b32_e32 v74, v0
	v_mov_b32_e32 v75, v0
	v_mov_b32_e32 v76, v0
	v_mov_b32_e32 v77, v0
	v_mov_b32_e32 v78, v0
	v_mov_b32_e32 v79, v0
	v_mov_b32_e32 v80, v0
	v_mov_b32_e32 v81, v0
	v_mov_b32_e32 v82, v0
	v_mov_b32_e32 v83, v0
	v_mov_b32_e32 v84, v0
	v_mov_b32_e32 v85, v0
	v_mov_b32_e32 v86, v0
	v_mov_b32_e32 v87, v0
	v_mov_b32_e32 v88, v0
	v_mov_b32_e32 v89, v0
	v_mov_b32_e32 v90, v0
	v_mov_b32_e32 v91, v0
	v_mov_b32_e32 v92, v0
	v_mov_b32_e32 v93, v0
	v_mov_b32_e32 v94, v0
	v_mov_b32_e32 v95, v0
	v_mov_b32_e32 v96, v0
	v_mov_b32_e32 v97, v0
	v_mov_b32_e32 v98, v0
	v_mov_b32_e32 v99, v0
	v_mov_b32_e32 v100, v0
	v_mov_b32_e32 v101, v0
	v_mov_b32_e32 v102, v0
	v_mov_b32_e32 v103, v0
	v_mov_b32_e32 v104, v0
	v_mov_b32_e32 v105, v0
	v_mov_b32_e32 v106, v0
	v_mov_b32_e32 v107, v0
	v_mov_b32_e32 v108, v0
	v_mov_b32_e32 v109, v0
	v_mov_b32_e32 v110, v0
	v_mov_b32_e32 v111, v0
	v_mov_b32_e32 v112, v0
	v_mov_b32_e32 v113, v0
	v_mov_b32_e32 v114, v0
	v_mov_b32_e32 v115, v0
	v_mov_b32_e32 v116, v0
	v_mov_b32_e32 v117, v0
	v_mov_b32_e32 v118, v0
	v_mov_b32_e32 v119, v0
	v_mov_b32_e32 v120, v0
	v_mov_b32_e32 v121, v0
	v_mov_b32_e32 v122, v0
	v_mov_b32_e32 v123, v0
	v_mov_b32_e32 v124, v0
	v_mov_b32_e32 v125, v0
	v_mov_b32_e32 v126, v0
	v_mov_b32_e32 v127, v0
	s_waitcnt vmcnt(0) lgkmcnt(0)
	s_barrier
	v_readfirstlane_b32 s100, v148
	s_and_b32 s27, s6, 0x10000
	s_xor_b32 s30, s27, 0x10000
	s_add_i32 s27, s27, 0
	v_add3_u32 v134, s27, v149, v150
	v_add3_u32 v196, s27, v149, v151
	v_add3_u32 v197, s27, v153, v152
	v_add3_u32 v198, s27, v153, v154
	v_add3_u32 v199, s27, v153, v155
	v_add3_u32 v200, s27, v153, v156
	v_add3_u32 v201, s27, v153, v157
	v_add3_u32 v202, s27, v153, v158
	v_add3_u32 v203, s27, v153, v159
	ds_read_b128 v[180:183], v134 offset:32768
	ds_read_b128 v[160:163], v196
	ds_read_b128 v[168:171], v197
	ds_read_b128 v[172:175], v198
	ds_read_b128 v[176:179], v199
	ds_read_b128 v[184:187], v134 offset:34816
	ds_read_b128 v[188:191], v134 offset:36864
	ds_read_b128 v[192:195], v134 offset:38912
	s_add_i32 s101, s100, s30
	v_readfirstlane_b32 s98, v146
	v_readfirstlane_b32 s99, v147
	v_readfirstlane_b32 vcc_lo, v138
	v_readfirstlane_b32 vcc_hi, v139
	s_sub_u32 s98, s98, 0x1000000
	s_subb_u32 s99, s99, 0
	s_sub_u32 vcc_lo, vcc_lo, 0x1000000
	s_subb_u32 vcc_hi, vcc_hi, 0
	v_subrev_u32_e32 v146, s98, v146
	v_subrev_u32_e32 v138, vcc_lo, v138
	v_subrev_u32_e32 v144, s98, v144
	v_subrev_u32_e32 v136, vcc_lo, v136
	v_subrev_u32_e32 v142, s98, v142
	v_subrev_u32_e32 v130, vcc_lo, v130
	v_subrev_u32_e32 v140, s98, v140
	v_subrev_u32_e32 v128, vcc_lo, v128
	s_mov_b32 m0, s101
	s_nop 0
	global_load_lds_dwordx4 v146, s[98:99]
	s_add_i32 m0, s101, 0x8000
	s_nop 0
	global_load_lds_dwordx4 v138, vcc
	s_add_i32 m0, s101, 0x2000
	s_nop 0
	global_load_lds_dwordx4 v144, s[98:99]
	s_add_i32 m0, s101, 0xa000
	s_nop 0
	global_load_lds_dwordx4 v136, vcc
	s_add_i32 m0, s101, 0x4000
	s_nop 0
	global_load_lds_dwordx4 v142, s[98:99]
	s_add_i32 m0, s101, 0xc000
	s_nop 0
	global_load_lds_dwordx4 v130, vcc
	s_add_i32 m0, s101, 0x6000
	s_nop 0
	global_load_lds_dwordx4 v140, s[98:99]
	s_add_i32 m0, s101, 0xe000
	s_nop 0
	global_load_lds_dwordx4 v128, vcc
.LBB0_177:
	s_and_b32 s27, s6, 0x10000
	s_xor_b32 s30, s27, 0x10000
	s_add_i32 s27, s27, 0
	s_add_i32 s101, s100, s30
	s_cmpk_eq_i32 s4, 0
	s_cbranch_scc1 .Lg1n_177
	s_waitcnt lgkmcnt(3)
	v_mfma_f32_16x16x32_bf16 v[108:111], v[160:163], v[180:183], v[108:111]
	v_mfma_f32_16x16x32_bf16 v[92:95], v[168:171], v[180:183], v[92:95]
	v_mfma_f32_16x16x32_bf16 v[76:79], v[172:175], v[180:183], v[76:79]
	v_mfma_f32_16x16x32_bf16 v[60:63], v[176:179], v[180:183], v[60:63]
	ds_read_b128 v[240:243], v200
	ds_read_b128 v[244:247], v201
	s_add_i32 m0, s101, 0x4000
	s_nop 0
	global_load_lds_dwordx4 v142, s[98:99]
	s_waitcnt lgkmcnt(4)
	v_mfma_f32_16x16x32_bf16 v[104:107], v[160:163], v[184:187], v[104:107]
	v_mfma_f32_16x16x32_bf16 v[88:91], v[168:171], v[184:187], v[88:91]
	v_mfma_f32_16x16x32_bf16 v[72:75], v[172:175], v[184:187], v[72:75]
	v_mfma_f32_16x16x32_bf16 v[56:59], v[176:179], v[184:187], v[56:59]
	ds_read_b128 v[248:251], v202
	ds_read_b128 v[252:255], v203
	s_add_i32 m0, s101, 0xc000
	s_nop 0
	global_load_lds_dwordx4 v130, vcc
	s_waitcnt lgkmcnt(5)
	v_mfma_f32_16x16x32_bf16 v[100:103], v[160:163], v[188:191], v[100:103]
	v_mfma_f32_16x16x32_bf16 v[84:87], v[168:171], v[188:191], v[84:87]
	v_mfma_f32_16x16x32_bf16 v[68:71], v[172:175], v[188:191], v[68:71]
	v_mfma_f32_16x16x32_bf16 v[52:55], v[176:179], v[188:191], v[52:55]
	s_add_i32 m0, s101, 0x6000
	s_nop 0
	global_load_lds_dwordx4 v140, s[98:99]
	s_waitcnt lgkmcnt(4)
	v_mfma_f32_16x16x32_bf16 v[96:99], v[160:163], v[192:195], v[96:99]
	v_mfma_f32_16x16x32_bf16 v[80:83], v[168:171], v[192:195], v[80:83]
	v_mfma_f32_16x16x32_bf16 v[64:67], v[172:175], v[192:195], v[64:67]
	v_mfma_f32_16x16x32_bf16 v[48:51], v[176:179], v[192:195], v[48:51]
	s_add_i32 m0, s101, 0xe000
	s_nop 0
	global_load_lds_dwordx4 v128, vcc
.Lg2_177:
	ds_read_b128 v[160:163], v196 offset:1024
	ds_read_b128 v[168:171], v197 offset:1024
	ds_read_b128 v[172:175], v198 offset:1024
	ds_read_b128 v[176:179], v199 offset:1024
	s_waitcnt lgkmcnt(4)
	v_mfma_f32_16x16x32_bf16 v[44:47], v[240:243], v[180:183], v[44:47]
	v_mfma_f32_16x16x32_bf16 v[28:31], v[244:247], v[180:183], v[28:31]
	v_mfma_f32_16x16x32_bf16 v[12:15], v[248:251], v[180:183], v[12:15]
	v_mfma_f32_16x16x32_bf16 v[112:115], v[252:255], v[180:183], v[112:115]
	ds_read_b128 v[180:183], v134 offset:33792
	v_mfma_f32_16x16x32_bf16 v[40:43], v[240:243], v[184:187], v[40:43]
	v_mfma_f32_16x16x32_bf16 v[24:27], v[244:247], v[184:187], v[24:27]
	v_mfma_f32_16x16x32_bf16 v[8:11], v[248:251], v[184:187], v[8:11]
	v_mfma_f32_16x16x32_bf16 v[116:119], v[252:255], v[184:187], v[116:119]
	ds_read_b128 v[184:187], v134 offset:35840
	v_mfma_f32_16x16x32_bf16 v[36:39], v[240:243], v[188:191], v[36:39]
	v_mfma_f32_16x16x32_bf16 v[20:23], v[244:247], v[188:191], v[20:23]
	v_mfma_f32_16x16x32_bf16 v[4:7], v[248:251], v[188:191], v[4:7]
	v_mfma_f32_16x16x32_bf16 v[120:123], v[252:255], v[188:191], v[120:123]
	ds_read_b128 v[188:191], v134 offset:37888
	v_mfma_f32_16x16x32_bf16 v[32:35], v[240:243], v[192:195], v[32:35]
	v_mfma_f32_16x16x32_bf16 v[16:19], v[244:247], v[192:195], v[16:19]
	v_mfma_f32_16x16x32_bf16 v[0:3], v[248:251], v[192:195], v[0:3]
	v_mfma_f32_16x16x32_bf16 v[124:127], v[252:255], v[192:195], v[124:127]
	ds_read_b128 v[192:195], v134 offset:39936
	s_waitcnt lgkmcnt(3)
	v_mfma_f32_16x16x32_bf16 v[108:111], v[160:163], v[180:183], v[108:111]
	v_mfma_f32_16x16x32_bf16 v[92:95], v[168:171], v[180:183], v[92:95]
	v_mfma_f32_16x16x32_bf16 v[76:79], v[172:175], v[180:183], v[76:79]
	v_mfma_f32_16x16x32_bf16 v[60:63], v[176:179], v[180:183], v[60:63]
	ds_read_b128 v[240:243], v200 offset:1024
	ds_read_b128 v[244:247], v201 offset:1024
	s_waitcnt lgkmcnt(4)
	v_mfma_f32_16x16x32_bf16 v[104:107], v[160:163], v[184:187], v[104:107]
	v_mfma_f32_16x16x32_bf16 v[88:91], v[168:171], v[184:187], v[88:91]
	v_mfma_f32_16x16x32_bf16 v[72:75], v[172:175], v[184:187], v[72:75]
	v_mfma_f32_16x16x32_bf16 v[56:59], v[176:179], v[184:187], v[56:59]
	ds_read_b128 v[248:251], v202 offset:1024
	ds_read_b128 v[252:255], v203 offset:1024
	s_waitcnt lgkmcnt(5)
	v_mfma_f32_16x16x32_bf16 v[100:103], v[160:163], v[188:191], v[100:103]
	v_mfma_f32_16x16x32_bf16 v[84:87], v[168:171], v[188:191], v[84:87]
	v_mfma_f32_16x16x32_bf16 v[68:71], v[172:175], v[188:191], v[68:71]
	v_mfma_f32_16x16x32_bf16 v[52:55], v[176:179], v[188:191], v[52:55]
	s_waitcnt lgkmcnt(4)
	v_mfma_f32_16x16x32_bf16 v[96:99], v[160:163], v[192:195], v[96:99]
	v_mfma_f32_16x16x32_bf16 v[80:83], v[168:171], v[192:195], v[80:83]
	v_mfma_f32_16x16x32_bf16 v[64:67], v[172:175], v[192:195], v[64:67]
	v_mfma_f32_16x16x32_bf16 v[48:51], v[176:179], v[192:195], v[48:51]
	s_waitcnt vmcnt(0) lgkmcnt(0)
	s_barrier
	s_add_i32 s101, s100, s27
	s_cmpk_eq_i32 s4, 0x700
	s_cbranch_scc1 .Lg4n_177
	s_add_u32 s98, s98, 0x80
	s_addc_u32 s99, s99, 0
	s_add_u32 vcc_lo, vcc_lo, 0x80
	s_addc_u32 vcc_hi, vcc_hi, 0
	v_mfma_f32_16x16x32_bf16 v[44:47], v[240:243], v[180:183], v[44:47]
	v_mfma_f32_16x16x32_bf16 v[28:31], v[244:247], v[180:183], v[28:31]
	v_mfma_f32_16x16x32_bf16 v[12:15], v[248:251], v[180:183], v[12:15]
	v_mfma_f32_16x16x32_bf16 v[112:115], v[252:255], v[180:183], v[112:115]
	v_add3_u32 v134, s30, v149, v150
	ds_read_b128 v[180:183], v134 offset:32768
	v_add3_u32 v196, s30, v149, v151
	v_add3_u32 v197, s30, v153, v152
	v_add3_u32 v198, s30, v153, v154
	v_add3_u32 v199, s30, v153, v155
	ds_read_b128 v[160:163], v196
	ds_read_b128 v[168:171], v197
	ds_read_b128 v[172:175], v198
	ds_read_b128 v[176:179], v199
	s_mov_b32 m0, s101
	s_nop 0
	global_load_lds_dwordx4 v146, s[98:99]
	v_mfma_f32_16x16x32_bf16 v[40:43], v[240:243], v[184:187], v[40:43]
	v_mfma_f32_16x16x32_bf16 v[24:27], v[244:247], v[184:187], v[24:27]
	v_mfma_f32_16x16x32_bf16 v[8:11], v[248:251], v[184:187], v[8:11]
	v_mfma_f32_16x16x32_bf16 v[116:119], v[252:255], v[184:187], v[116:119]
	ds_read_b128 v[184:187], v134 offset:34816
	v_add3_u32 v200, s30, v153, v156
	v_add3_u32 v201, s30, v153, v157
	v_add3_u32 v202, s30, v153, v158
	v_add3_u32 v203, s30, v153, v159
	s_add_i32 m0, s101, 0x8000
	s_nop 0
	global_load_lds_dwordx4 v138, vcc
	v_mfma_f32_16x16x32_bf16 v[36:39], v[240:243], v[188:191], v[36:39]
	v_mfma_f32_16x16x32_bf16 v[20:23], v[244:247], v[188:191], v[20:23]
	v_mfma_f32_16x16x32_bf16 v[4:7], v[248:251], v[188:191], v[4:7]
	v_mfma_f32_16x16x32_bf16 v[120:123], v[252:255], v[188:191], v[120:123]
	ds_read_b128 v[188:191], v134 offset:36864
	s_add_i32 m0, s101, 0x2000
	s_nop 0
	global_load_lds_dwordx4 v144, s[98:99]
	v_mfma_f32_16x16x32_bf16 v[32:35], v[240:243], v[192:195], v[32:35]
	v_mfma_f32_16x16x32_bf16 v[16:19], v[244:247], v[192:195], v[16:19]
	v_mfma_f32_16x16x32_bf16 v[0:3], v[248:251], v[192:195], v[0:3]
	v_mfma_f32_16x16x32_bf16 v[124:127], v[252:255], v[192:195], v[124:127]
	ds_read_b128 v[192:195], v134 offset:38912
	s_add_i32 m0, s101, 0xa000
	s_nop 0
	global_load_lds_dwordx4 v136, vcc

.LBB0_180:
	s_nop 0
	v_mov_b32_e32 v0, s19
	v_mov_b32_e32 v16, v132
	ds_read_b64 v[128:129], v0
	s_and_b64 s[4:5], exec, s[28:29]
	v_lshlrev_b32_e32 v7, 4, v16
	v_and_b32_e32 v6, 32, v16
	v_lshrrev_b32_e32 v8, 1, v16
	v_bitop3_b32 v6, v7, v6, 48 bitop3:0x6c
	s_cselect_b32 s4, 0x8000, 0
	v_bfe_u32 v17, v16, 2, 4
	v_and_b32_e32 v18, 32, v8
	v_lshrrev_b32_e32 v19, 1, v6
	v_ashrrev_i32_e32 v20, 3, v16
	s_add_i32 s4, s66, s4
	v_or_b32_e32 v10, v19, v18
	v_and_or_b32 v6, v20, s48, v17
	s_ashr_i32 s5, s4, 31
	v_and_b32_e32 v9, 0xfffffc00, v7
	v_lshl_or_b32 v134, v6, 10, v10
	v_add_u32_e32 v6, 0x2000, v7
	v_add_u32_e32 v8, 0x4000, v7
	v_add_u32_e32 v7, 0x6000, v7
	s_lshl_b64 s[4:5], s[4:5], 11
	s_ashr_i32 s27, s26, 31
	v_ashrrev_i32_e32 v21, 7, v6
	v_ashrrev_i32_e32 v22, 7, v8
	v_ashrrev_i32_e32 v23, 7, v7
	s_waitcnt lgkmcnt(0)
	v_lshl_add_u64 v[0:1], v[128:129], 0, s[4:5]
	s_lshl_b64 s[4:5], s[26:27], 19
	v_and_or_b32 v6, v21, s48, v17
	v_and_or_b32 v8, v22, s48, v17
	v_and_or_b32 v7, v23, s48, v17
	v_add_u32_e32 v150, 0, v9
	v_lshl_add_u64 v[2:3], v[0:1], 0, s[8:9]
	v_lshl_add_u64 v[4:5], v[128:129], 0, s[4:5]
	v_lshl_or_b32 v6, v6, 10, v10
	v_lshl_or_b32 v8, v8, 10, v10
	v_lshl_or_b32 v10, v7, 10, v10
	v_add_u32_e32 v7, 0x8000, v150
	v_lshlrev_b64 v[12:13], 1, v[134:135]
	v_readfirstlane_b32 s4, v150
	v_lshl_add_u64 v[14:15], v[2:3], 0, v[12:13]
	s_mov_b32 m0, s4
	v_readfirstlane_b32 s4, v7
	v_mov_b32_e32 v7, v135
	v_add_u32_e32 v9, 0x2000, v150
	global_load_lds_dwordx4 v[14:15], off
	v_lshl_add_u64 v[12:13], v[4:5], 0, v[12:13]
	s_mov_b32 m0, s4
	v_lshlrev_b64 v[6:7], 1, v[6:7]
	v_readfirstlane_b32 s4, v9
	v_add_u32_e32 v9, 0xa000, v150
	global_load_lds_dwordx4 v[12:13], off
	v_lshl_add_u64 v[12:13], v[2:3], 0, v[6:7]
	s_mov_b32 m0, s4
	v_readfirstlane_b32 s4, v9
	global_load_lds_dwordx4 v[12:13], off
	v_lshl_add_u64 v[6:7], v[4:5], 0, v[6:7]
	s_mov_b32 m0, s4
	v_mov_b32_e32 v9, v135
	v_add_u32_e32 v11, 0x4000, v150
	global_load_lds_dwordx4 v[6:7], off
	v_lshlrev_b64 v[6:7], 1, v[8:9]
	v_readfirstlane_b32 s4, v11
	v_lshl_add_u64 v[8:9], v[2:3], 0, v[6:7]
	s_mov_b32 m0, s4
	v_lshl_add_u64 v[6:7], v[4:5], 0, v[6:7]
	global_load_lds_dwordx4 v[8:9], off
	v_add_u32_e32 v8, 0xc000, v150
	v_mov_b32_e32 v11, v135
	v_readfirstlane_b32 s4, v8
	s_mov_b32 m0, s4
	v_add_u32_e32 v8, 0x6000, v150
	global_load_lds_dwordx4 v[6:7], off
	v_lshlrev_b64 v[6:7], 1, v[10:11]
	v_readfirstlane_b32 s4, v8
	v_lshl_add_u64 v[2:3], v[2:3], 0, v[6:7]
	s_mov_b32 m0, s4
	v_and_b32_e32 v24, 15, v16
	global_load_lds_dwordx4 v[2:3], off
	v_lshl_add_u64 v[2:3], v[4:5], 0, v[6:7]
	v_add_u32_e32 v6, 0xe000, v150
	v_lshlrev_b32_e32 v10, 10, v17
	v_readfirstlane_b32 s4, v6
	s_mov_b32 m0, s4
	v_lshlrev_b32_e32 v6, 2, v16
	global_load_lds_dwordx4 v[2:3], off
	v_and_b32_e32 v2, 48, v16
	v_lshlrev_b32_e32 v3, 6, v24
	v_and_b32_e32 v6, 32, v6
	v_bitop3_b32 v151, v3, v6, v2 bitop3:0x36
	v_lshlrev_b32_e32 v3, 7, v16
	v_and_b32_e32 v152, 0x6000, v3
	v_lshlrev_b32_e32 v3, 6, v16
	v_and_b32_e32 v153, 0xffffc000, v3
	v_and_b32_e32 v3, 0x3c0, v3
	v_bitop3_b32 v154, v3, v6, v2 bitop3:0x36
	v_lshlrev_b32_e32 v2, 10, v23
	v_and_or_b32 v2, v2, s49, v19
	v_lshlrev_b32_e32 v6, 10, v22
	v_or3_b32 v134, v2, v10, v18
	v_and_or_b32 v6, v6, s49, v19
	v_lshlrev_b32_e32 v8, 10, v21
	v_lshlrev_b64 v[2:3], 1, v[134:135]
	v_or3_b32 v134, v6, v10, v18
	v_and_or_b32 v8, v8, s49, v19
	v_lshlrev_b32_e32 v11, 10, v20
	v_lshlrev_b64 v[6:7], 1, v[134:135]
	v_or3_b32 v134, v8, v10, v18
	v_and_or_b32 v11, v11, s49, v19
	s_waitcnt vmcnt(0)
	v_lshl_add_u64 v[4:5], v[4:5], 0, s[10:11]
	v_lshlrev_b64 v[8:9], 1, v[134:135]
	v_or3_b32 v134, v11, v10, v18
	v_lshl_add_u64 v[0:1], v[0:1], 0, s[12:13]
	v_lshl_add_u64 v[138:139], v[4:5], 0, v[8:9]
	v_lshlrev_b64 v[10:11], 1, v[134:135]
	v_lshl_add_u64 v[146:147], v[0:1], 0, v[8:9]
	v_mov_b32_e32 v8, 0
	s_mov_b32 s6, 0
	v_lshl_add_u64 v[130:131], v[4:5], 0, v[2:3]
	v_lshl_add_u64 v[136:137], v[4:5], 0, v[6:7]
	v_lshl_add_u64 v[140:141], v[4:5], 0, v[10:11]
	v_lshl_add_u64 v[142:143], v[0:1], 0, v[2:3]
	v_lshl_add_u64 v[144:145], v[0:1], 0, v[6:7]
	v_lshl_add_u64 v[148:149], v[0:1], 0, v[10:11]
	s_mov_b64 s[4:5], 0
	v_mov_b32_e32 v9, v8
	v_mov_b32_e32 v10, v8
	v_mov_b32_e32 v11, v8
	v_mov_b32_e32 v20, v8
	v_mov_b32_e32 v21, v8
	v_mov_b32_e32 v22, v8
	v_mov_b32_e32 v23, v8
	v_mov_b32_e32 v28, v8
	v_mov_b32_e32 v29, v8
	v_mov_b32_e32 v30, v8
	v_mov_b32_e32 v31, v8
	v_mov_b32_e32 v36, v8
	v_mov_b32_e32 v37, v8
	v_mov_b32_e32 v38, v8
	v_mov_b32_e32 v39, v8
	v_mov_b32_e32 v0, v8
	v_mov_b32_e32 v1, v8
	v_mov_b32_e32 v2, v8
	v_mov_b32_e32 v3, v8
	v_mov_b32_e32 v4, v8
	v_mov_b32_e32 v5, v8
	v_mov_b32_e32 v6, v8
	v_mov_b32_e32 v7, v8
	v_mov_b32_e32 v12, v8
	v_mov_b32_e32 v13, v8
	v_mov_b32_e32 v14, v8
	v_mov_b32_e32 v15, v8
	v_mov_b32_e32 v16, v8
	v_mov_b32_e32 v17, v8
	v_mov_b32_e32 v18, v8
	v_mov_b32_e32 v19, v8
	v_mov_b32_e32 v24, v8
	v_mov_b32_e32 v25, v8
	v_mov_b32_e32 v26, v8
	v_mov_b32_e32 v27, v8
	v_mov_b32_e32 v32, v8
	v_mov_b32_e32 v33, v8
	v_mov_b32_e32 v34, v8
	v_mov_b32_e32 v35, v8
	v_mov_b32_e32 v40, v8
	v_mov_b32_e32 v41, v8
	v_mov_b32_e32 v42, v8
	v_mov_b32_e32 v43, v8
	v_mov_b32_e32 v44, v8
	v_mov_b32_e32 v45, v8
	v_mov_b32_e32 v46, v8
	v_mov_b32_e32 v47, v8
	v_mov_b32_e32 v48, v8
	v_mov_b32_e32 v49, v8
	v_mov_b32_e32 v50, v8
	v_mov_b32_e32 v51, v8
	v_mov_b32_e32 v52, v8
	v_mov_b32_e32 v53, v8
	v_mov_b32_e32 v54, v8
	v_mov_b32_e32 v55, v8
	v_mov_b32_e32 v56, v8
	v_mov_b32_e32 v57, v8
	v_mov_b32_e32 v58, v8
	v_mov_b32_e32 v59, v8
	v_mov_b32_e32 v60, v8
	v_mov_b32_e32 v61, v8
	v_mov_b32_e32 v62, v8
	v_mov_b32_e32 v63, v8
	v_mov_b32_e32 v64, v8
	v_mov_b32_e32 v65, v8
	v_mov_b32_e32 v66, v8
	v_mov_b32_e32 v67, v8
	v_mov_b32_e32 v68, v8
	v_mov_b32_e32 v69, v8
	v_mov_b32_e32 v70, v8
	v_mov_b32_e32 v71, v8
	v_mov_b32_e32 v72, v8
	v_mov_b32_e32 v73, v8
	v_mov_b32_e32 v74, v8
	v_mov_b32_e32 v75, v8
	v_mov_b32_e32 v76, v8
	v_mov_b32_e32 v77, v8
	v_mov_b32_e32 v78, v8
	v_mov_b32_e32 v79, v8
	v_mov_b32_e32 v80, v8
	v_mov_b32_e32 v81, v8
	v_mov_b32_e32 v82, v8
	v_mov_b32_e32 v83, v8
	v_mov_b32_e32 v84, v8
	v_mov_b32_e32 v85, v8
	v_mov_b32_e32 v86, v8
	v_mov_b32_e32 v87, v8
	v_mov_b32_e32 v88, v8
	v_mov_b32_e32 v89, v8
	v_mov_b32_e32 v90, v8
	v_mov_b32_e32 v91, v8
	v_mov_b32_e32 v92, v8
	v_mov_b32_e32 v93, v8
	v_mov_b32_e32 v94, v8
	v_mov_b32_e32 v95, v8
	v_mov_b32_e32 v96, v8
	v_mov_b32_e32 v97, v8
	v_mov_b32_e32 v98, v8
	v_mov_b32_e32 v99, v8
	v_mov_b32_e32 v100, v8
	v_mov_b32_e32 v101, v8
	v_mov_b32_e32 v102, v8
	v_mov_b32_e32 v103, v8
	v_mov_b32_e32 v104, v8
	v_mov_b32_e32 v105, v8
	v_mov_b32_e32 v106, v8
	v_mov_b32_e32 v107, v8
	v_mov_b32_e32 v108, v8
	v_mov_b32_e32 v109, v8
	v_mov_b32_e32 v110, v8
	v_mov_b32_e32 v111, v8
	v_mov_b32_e32 v112, v8
	v_mov_b32_e32 v113, v8
	v_mov_b32_e32 v114, v8
	v_mov_b32_e32 v115, v8
	v_mov_b32_e32 v116, v8
	v_mov_b32_e32 v117, v8
	v_mov_b32_e32 v118, v8
	v_mov_b32_e32 v119, v8
	v_mov_b32_e32 v120, v8
	v_mov_b32_e32 v121, v8
	v_mov_b32_e32 v122, v8
	v_mov_b32_e32 v123, v8
	v_mov_b32_e32 v124, v8
	v_mov_b32_e32 v125, v8
	v_mov_b32_e32 v126, v8
	v_mov_b32_e32 v127, v8
	v_or_b32_e32 v134, 0x800, v153
	v_or_b32_e32 v155, 0x1000, v153
	v_or_b32_e32 v156, 0x1800, v153
	v_or_b32_e32 v157, 0x2000, v153
	v_or_b32_e32 v158, 0x2800, v153
	v_or_b32_e32 v159, 0x3000, v153
	v_or_b32_e32 v160, 0x3800, v153
	s_waitcnt vmcnt(0) lgkmcnt(0)
	s_barrier
	v_readfirstlane_b32 s100, v150
	s_and_b32 s27, s6, 0x10000
	s_xor_b32 s28, s27, 0x10000
	s_add_i32 s27, s27, 0
	v_add3_u32 v161, s27, v151, v152
	v_add3_u32 v162, s27, v151, v153
	v_add3_u32 v163, s27, v154, v134
	v_add3_u32 v200, s27, v154, v155
	v_add3_u32 v201, s27, v154, v156
	v_add3_u32 v202, s27, v154, v157
	v_add3_u32 v203, s27, v154, v158
	v_add3_u32 v204, s27, v154, v159
	v_add3_u32 v205, s27, v154, v160
	ds_read_b128 v[184:187], v161 offset:32768
	ds_read_b128 v[168:171], v162
	ds_read_b128 v[172:175], v163
	ds_read_b128 v[176:179], v200
	ds_read_b128 v[180:183], v201
	ds_read_b128 v[188:191], v161 offset:34816
	ds_read_b128 v[192:195], v161 offset:36864
	ds_read_b128 v[196:199], v161 offset:38912
	s_add_i32 s101, s100, s28
	v_readfirstlane_b32 s98, v148
	v_readfirstlane_b32 s99, v149
	v_readfirstlane_b32 vcc_lo, v140
	v_readfirstlane_b32 vcc_hi, v141
	s_sub_u32 s98, s98, 0x1000000
	s_subb_u32 s99, s99, 0
	s_sub_u32 vcc_lo, vcc_lo, 0x1000000
	s_subb_u32 vcc_hi, vcc_hi, 0
	v_subrev_u32_e32 v148, s98, v148
	v_subrev_u32_e32 v140, vcc_lo, v140
	v_subrev_u32_e32 v146, s98, v146
	v_subrev_u32_e32 v138, vcc_lo, v138
	v_subrev_u32_e32 v144, s98, v144
	v_subrev_u32_e32 v136, vcc_lo, v136
	v_subrev_u32_e32 v142, s98, v142
	v_subrev_u32_e32 v130, vcc_lo, v130
	s_mov_b32 m0, s101
	s_nop 0
	global_load_lds_dwordx4 v148, s[98:99]
	s_add_i32 m0, s101, 0x8000
	s_nop 0
	global_load_lds_dwordx4 v140, vcc
	s_add_i32 m0, s101, 0x2000
	s_nop 0
	global_load_lds_dwordx4 v146, s[98:99]
	s_add_i32 m0, s101, 0xa000
	s_nop 0
	global_load_lds_dwordx4 v138, vcc
	s_add_i32 m0, s101, 0x4000
	s_nop 0
	global_load_lds_dwordx4 v144, s[98:99]
	s_add_i32 m0, s101, 0xc000
	s_nop 0
	global_load_lds_dwordx4 v136, vcc
	s_add_i32 m0, s101, 0x6000
	s_nop 0
	global_load_lds_dwordx4 v142, s[98:99]
	s_add_i32 m0, s101, 0xe000
	s_nop 0
	global_load_lds_dwordx4 v130, vcc
.LBB0_181:
	s_and_b32 s27, s6, 0x10000
	s_xor_b32 s28, s27, 0x10000
	s_add_i32 s27, s27, 0
	s_add_i32 s101, s100, s28
	s_cmpk_eq_i32 s4, 0
	s_cbranch_scc1 .Lg1n_181
	s_waitcnt lgkmcnt(3)
	v_mfma_f32_16x16x32_bf16 v[124:127], v[184:187], v[168:171], v[124:127]
	v_mfma_f32_16x16x32_bf16 v[108:111], v[184:187], v[172:175], v[108:111]
	v_mfma_f32_16x16x32_bf16 v[92:95], v[184:187], v[176:179], v[92:95]
	v_mfma_f32_16x16x32_bf16 v[76:79], v[184:187], v[180:183], v[76:79]
	ds_read_b128 v[240:243], v202
	ds_read_b128 v[244:247], v203
	s_add_i32 m0, s101, 0x4000
	s_nop 0
	global_load_lds_dwordx4 v144, s[98:99]
	s_waitcnt lgkmcnt(4)
	v_mfma_f32_16x16x32_bf16 v[120:123], v[188:191], v[168:171], v[120:123]
	v_mfma_f32_16x16x32_bf16 v[104:107], v[188:191], v[172:175], v[104:107]
	v_mfma_f32_16x16x32_bf16 v[88:91], v[188:191], v[176:179], v[88:91]
	v_mfma_f32_16x16x32_bf16 v[72:75], v[188:191], v[180:183], v[72:75]
	ds_read_b128 v[248:251], v204
	ds_read_b128 v[252:255], v205
	s_add_i32 m0, s101, 0xc000
	s_nop 0
	global_load_lds_dwordx4 v136, vcc
	s_waitcnt lgkmcnt(5)
	v_mfma_f32_16x16x32_bf16 v[116:119], v[192:195], v[168:171], v[116:119]
	v_mfma_f32_16x16x32_bf16 v[100:103], v[192:195], v[172:175], v[100:103]
	v_mfma_f32_16x16x32_bf16 v[84:87], v[192:195], v[176:179], v[84:87]
	v_mfma_f32_16x16x32_bf16 v[68:71], v[192:195], v[180:183], v[68:71]
	s_add_i32 m0, s101, 0x6000
	s_nop 0
	global_load_lds_dwordx4 v142, s[98:99]
	s_waitcnt lgkmcnt(4)
	v_mfma_f32_16x16x32_bf16 v[112:115], v[196:199], v[168:171], v[112:115]
	v_mfma_f32_16x16x32_bf16 v[96:99], v[196:199], v[172:175], v[96:99]
	v_mfma_f32_16x16x32_bf16 v[80:83], v[196:199], v[176:179], v[80:83]
	v_mfma_f32_16x16x32_bf16 v[64:67], v[196:199], v[180:183], v[64:67]
	s_add_i32 m0, s101, 0xe000
	s_nop 0
	global_load_lds_dwordx4 v130, vcc
.Lg2_181:
	ds_read_b128 v[168:171], v162 offset:1024
	ds_read_b128 v[172:175], v163 offset:1024
	ds_read_b128 v[176:179], v200 offset:1024
	ds_read_b128 v[180:183], v201 offset:1024
	s_waitcnt lgkmcnt(4)
	v_mfma_f32_16x16x32_bf16 v[60:63], v[184:187], v[240:243], v[60:63]
	v_mfma_f32_16x16x32_bf16 v[44:47], v[184:187], v[244:247], v[44:47]
	v_mfma_f32_16x16x32_bf16 v[16:19], v[184:187], v[248:251], v[16:19]
	v_mfma_f32_16x16x32_bf16 v[36:39], v[184:187], v[252:255], v[36:39]
	ds_read_b128 v[184:187], v161 offset:33792
	v_mfma_f32_16x16x32_bf16 v[56:59], v[188:191], v[240:243], v[56:59]
	v_mfma_f32_16x16x32_bf16 v[40:43], v[188:191], v[244:247], v[40:43]
	v_mfma_f32_16x16x32_bf16 v[12:15], v[188:191], v[248:251], v[12:15]
	v_mfma_f32_16x16x32_bf16 v[28:31], v[188:191], v[252:255], v[28:31]
	ds_read_b128 v[188:191], v161 offset:35840
	v_mfma_f32_16x16x32_bf16 v[52:55], v[192:195], v[240:243], v[52:55]
	v_mfma_f32_16x16x32_bf16 v[32:35], v[192:195], v[244:247], v[32:35]
	v_mfma_f32_16x16x32_bf16 v[4:7], v[192:195], v[248:251], v[4:7]
	v_mfma_f32_16x16x32_bf16 v[20:23], v[192:195], v[252:255], v[20:23]
	ds_read_b128 v[192:195], v161 offset:37888
	v_mfma_f32_16x16x32_bf16 v[48:51], v[196:199], v[240:243], v[48:51]
	v_mfma_f32_16x16x32_bf16 v[24:27], v[196:199], v[244:247], v[24:27]
	v_mfma_f32_16x16x32_bf16 v[0:3], v[196:199], v[248:251], v[0:3]
	v_mfma_f32_16x16x32_bf16 v[8:11], v[196:199], v[252:255], v[8:11]
	ds_read_b128 v[196:199], v161 offset:39936
	s_waitcnt lgkmcnt(3)
	v_mfma_f32_16x16x32_bf16 v[124:127], v[184:187], v[168:171], v[124:127]
	v_mfma_f32_16x16x32_bf16 v[108:111], v[184:187], v[172:175], v[108:111]
	v_mfma_f32_16x16x32_bf16 v[92:95], v[184:187], v[176:179], v[92:95]
	v_mfma_f32_16x16x32_bf16 v[76:79], v[184:187], v[180:183], v[76:79]
	ds_read_b128 v[240:243], v202 offset:1024
	ds_read_b128 v[244:247], v203 offset:1024
	s_waitcnt lgkmcnt(4)
	v_mfma_f32_16x16x32_bf16 v[120:123], v[188:191], v[168:171], v[120:123]
	v_mfma_f32_16x16x32_bf16 v[104:107], v[188:191], v[172:175], v[104:107]
	v_mfma_f32_16x16x32_bf16 v[88:91], v[188:191], v[176:179], v[88:91]
	v_mfma_f32_16x16x32_bf16 v[72:75], v[188:191], v[180:183], v[72:75]
	ds_read_b128 v[248:251], v204 offset:1024
	ds_read_b128 v[252:255], v205 offset:1024
	s_waitcnt lgkmcnt(5)
	v_mfma_f32_16x16x32_bf16 v[116:119], v[192:195], v[168:171], v[116:119]
	v_mfma_f32_16x16x32_bf16 v[100:103], v[192:195], v[172:175], v[100:103]
	v_mfma_f32_16x16x32_bf16 v[84:87], v[192:195], v[176:179], v[84:87]
	v_mfma_f32_16x16x32_bf16 v[68:71], v[192:195], v[180:183], v[68:71]
	s_waitcnt lgkmcnt(4)
	v_mfma_f32_16x16x32_bf16 v[112:115], v[196:199], v[168:171], v[112:115]
	v_mfma_f32_16x16x32_bf16 v[96:99], v[196:199], v[172:175], v[96:99]
	v_mfma_f32_16x16x32_bf16 v[80:83], v[196:199], v[176:179], v[80:83]
	v_mfma_f32_16x16x32_bf16 v[64:67], v[196:199], v[180:183], v[64:67]
	s_waitcnt vmcnt(0) lgkmcnt(0)
	s_barrier
	s_add_i32 s101, s100, s27
	s_cmpk_eq_i32 s4, 0x700
	s_cbranch_scc1 .Lg4n_181
	s_add_u32 s98, s98, 0x80
	s_addc_u32 s99, s99, 0
	s_add_u32 vcc_lo, vcc_lo, 0x80
	s_addc_u32 vcc_hi, vcc_hi, 0
	v_mfma_f32_16x16x32_bf16 v[60:63], v[184:187], v[240:243], v[60:63]
	v_mfma_f32_16x16x32_bf16 v[44:47], v[184:187], v[244:247], v[44:47]
	v_mfma_f32_16x16x32_bf16 v[16:19], v[184:187], v[248:251], v[16:19]
	v_mfma_f32_16x16x32_bf16 v[36:39], v[184:187], v[252:255], v[36:39]
	v_add3_u32 v161, s28, v151, v152
	ds_read_b128 v[184:187], v161 offset:32768
	v_add3_u32 v162, s28, v151, v153
	v_add3_u32 v163, s28, v154, v134
	v_add3_u32 v200, s28, v154, v155
	v_add3_u32 v201, s28, v154, v156
	ds_read_b128 v[168:171], v162
	ds_read_b128 v[172:175], v163
	ds_read_b128 v[176:179], v200
	ds_read_b128 v[180:183], v201
	s_mov_b32 m0, s101
	s_nop 0
	global_load_lds_dwordx4 v148, s[98:99]
	v_mfma_f32_16x16x32_bf16 v[56:59], v[188:191], v[240:243], v[56:59]
	v_mfma_f32_16x16x32_bf16 v[40:43], v[188:191], v[244:247], v[40:43]
	v_mfma_f32_16x16x32_bf16 v[12:15], v[188:191], v[248:251], v[12:15]
	v_mfma_f32_16x16x32_bf16 v[28:31], v[188:191], v[252:255], v[28:31]
	ds_read_b128 v[188:191], v161 offset:34816
	v_add3_u32 v202, s28, v154, v157
	v_add3_u32 v203, s28, v154, v158
	v_add3_u32 v204, s28, v154, v159
	v_add3_u32 v205, s28, v154, v160
	s_add_i32 m0, s101, 0x8000
	s_nop 0
	global_load_lds_dwordx4 v140, vcc
	v_mfma_f32_16x16x32_bf16 v[52:55], v[192:195], v[240:243], v[52:55]
	v_mfma_f32_16x16x32_bf16 v[32:35], v[192:195], v[244:247], v[32:35]
	v_mfma_f32_16x16x32_bf16 v[4:7], v[192:195], v[248:251], v[4:7]
	v_mfma_f32_16x16x32_bf16 v[20:23], v[192:195], v[252:255], v[20:23]
	ds_read_b128 v[192:195], v161 offset:36864
	s_add_i32 m0, s101, 0x2000
	s_nop 0
	global_load_lds_dwordx4 v146, s[98:99]
	v_mfma_f32_16x16x32_bf16 v[48:51], v[196:199], v[240:243], v[48:51]
	v_mfma_f32_16x16x32_bf16 v[24:27], v[196:199], v[244:247], v[24:27]
	v_mfma_f32_16x16x32_bf16 v[0:3], v[196:199], v[248:251], v[0:3]
	v_mfma_f32_16x16x32_bf16 v[8:11], v[196:199], v[252:255], v[8:11]
	ds_read_b128 v[196:199], v161 offset:38912
	s_add_i32 m0, s101, 0xa000
	s_nop 0
	global_load_lds_dwordx4 v138, vcc

.LBB0_792:
	s_ashr_i32 s0, s52, 31
	s_lshr_b32 s0, s0, 26
	s_add_i32 s0, s52, s0
	s_and_b32 s28, s0, 0xffc0
	s_sub_i32 s28, s52, s28
	s_bfe_i32 s29, s28, 0x80000
	s_bfe_u32 s29, s29, 0x4000b
	s_add_i32 s29, s28, s29
	v_mov_b32_e32 v150, v132
	s_bfe_i32 s30, s29, 0x80000
	s_and_b32 s29, s29, 0xf0
	ds_read_b128 v[0:3], v133
	s_sub_i32 s28, s28, s29
	s_sext_i32_i8 s28, s28
	s_lshl_b32 s0, s0, 6
	s_and_b32 s0, s0, 0xfffff000
	s_lshl_b32 s28, s28, 8
	s_sext_i32_i16 s30, s30
	s_add_i32 s28, s28, s0
	v_mov_b32_e32 v12, v132
	s_lshl_b32 s0, s30, 4
	s_waitcnt lgkmcnt(0)
	v_readfirstlane_b32 s31, v3
	v_readfirstlane_b32 s53, v2
	s_ashr_i32 s29, s28, 31
	s_and_b32 s30, s0, 0xffffff00
	v_lshlrev_b32_e32 v3, 4, v12
	v_and_b32_e32 v2, 32, v12
	s_lshl_b64 s[36:37], s[28:29], 11
	v_lshrrev_b32_e32 v4, 1, v12
	v_bitop3_b32 v2, v3, v2, 48 bitop3:0x6c
	s_add_u32 s54, s53, s36
	v_bfe_u32 v13, v12, 2, 4
	v_and_b32_e32 v14, 32, v4
	v_lshrrev_b32_e32 v15, 1, v2
	v_ashrrev_i32_e32 v16, 3, v12
	s_addc_u32 s55, s31, s37
	v_or_b32_e32 v6, v15, v14
	v_and_or_b32 v2, v16, s44, v13
	s_add_u32 s42, s54, 0x2400000
	v_and_b32_e32 v5, 0xfffffc00, v3
	v_lshl_or_b32 v130, v2, 10, v6
	v_add_u32_e32 v2, 0x2000, v3
	v_add_u32_e32 v4, 0x4000, v3
	v_add_u32_e32 v3, 0x6000, v3
	s_addc_u32 s43, s55, 0
	s_add_i32 s0, s30, 0x1200
	v_ashrrev_i32_e32 v17, 7, v2
	v_ashrrev_i32_e32 v18, 7, v4
	v_ashrrev_i32_e32 v19, 7, v3
	s_lshl_b64 s[38:39], s[0:1], 11
	v_and_or_b32 v2, v17, s44, v13
	v_and_or_b32 v4, v18, s44, v13
	v_and_or_b32 v3, v19, s44, v13
	v_add_u32_e32 v151, 0, v5
	s_add_u32 s38, s53, s38
	v_lshl_or_b32 v2, v2, 10, v6
	v_lshl_or_b32 v4, v4, 10, v6
	v_lshl_or_b32 v6, v3, 10, v6
	v_add_u32_e32 v3, 0x8000, v151
	v_lshlrev_b64 v[8:9], 1, v[130:131]
	v_readfirstlane_b32 s0, v151
	s_addc_u32 s39, s31, s39
	v_lshl_add_u64 v[10:11], s[42:43], 0, v[8:9]
	s_mov_b32 m0, s0
	v_readfirstlane_b32 s0, v3
	v_mov_b32_e32 v3, v131
	v_add_u32_e32 v5, 0x2000, v151
	global_load_lds_dwordx4 v[10:11], off
	v_lshl_add_u64 v[8:9], s[38:39], 0, v[8:9]
	s_mov_b32 m0, s0
	v_lshlrev_b64 v[2:3], 1, v[2:3]
	v_readfirstlane_b32 s0, v5
	v_add_u32_e32 v5, 0xa000, v151
	global_load_lds_dwordx4 v[8:9], off
	v_lshl_add_u64 v[8:9], s[42:43], 0, v[2:3]
	s_mov_b32 m0, s0
	v_readfirstlane_b32 s0, v5
	global_load_lds_dwordx4 v[8:9], off
	v_lshl_add_u64 v[2:3], s[38:39], 0, v[2:3]
	s_mov_b32 m0, s0
	v_mov_b32_e32 v5, v131
	v_add_u32_e32 v7, 0x4000, v151
	global_load_lds_dwordx4 v[2:3], off
	v_lshlrev_b64 v[2:3], 1, v[4:5]
	v_readfirstlane_b32 s0, v7
	v_lshl_add_u64 v[4:5], s[42:43], 0, v[2:3]
	s_mov_b32 m0, s0
	v_lshl_add_u64 v[2:3], s[38:39], 0, v[2:3]
	global_load_lds_dwordx4 v[4:5], off
	v_add_u32_e32 v4, 0xc000, v151
	v_mov_b32_e32 v7, v131
	v_readfirstlane_b32 s0, v4
	s_mov_b32 m0, s0
	v_and_b32_e32 v20, 15, v12
	global_load_lds_dwordx4 v[2:3], off
	v_lshlrev_b64 v[2:3], 1, v[6:7]
	v_add_u32_e32 v6, 0x6000, v151
	v_lshl_add_u64 v[4:5], s[42:43], 0, v[2:3]
	v_readfirstlane_b32 s0, v6
	s_mov_b32 m0, s0
	v_lshl_add_u64 v[2:3], s[38:39], 0, v[2:3]
	global_load_lds_dwordx4 v[4:5], off
	v_add_u32_e32 v4, 0xe000, v151
	v_lshlrev_b32_e32 v8, 10, v13
	v_readfirstlane_b32 s0, v4
	s_mov_b32 m0, s0
	v_lshlrev_b32_e32 v4, 2, v12
	global_load_lds_dwordx4 v[2:3], off
	v_and_b32_e32 v2, 48, v12
	v_lshlrev_b32_e32 v3, 6, v20
	v_and_b32_e32 v4, 32, v4
	v_bitop3_b32 v152, v3, v4, v2 bitop3:0x36
	v_lshlrev_b32_e32 v3, 7, v12
	v_and_b32_e32 v153, 0x6000, v3
	v_lshlrev_b32_e32 v3, 6, v12
	v_and_b32_e32 v154, 0xffffc000, v3
	v_and_b32_e32 v3, 0x3c0, v3
	v_bitop3_b32 v156, v3, v4, v2 bitop3:0x36
	v_lshlrev_b32_e32 v2, 10, v19
	v_and_or_b32 v2, v2, s45, v15
	v_lshlrev_b32_e32 v4, 10, v18
	v_or3_b32 v130, v2, v8, v14
	v_and_or_b32 v4, v4, s45, v15
	v_lshlrev_b32_e32 v6, 10, v17
	v_lshlrev_b64 v[2:3], 1, v[130:131]
	v_or3_b32 v130, v4, v8, v14
	v_and_or_b32 v6, v6, s45, v15
	v_lshlrev_b32_e32 v9, 10, v16
	v_lshlrev_b64 v[4:5], 1, v[130:131]
	v_or3_b32 v130, v6, v8, v14
	v_and_or_b32 v9, v9, s45, v15
	s_add_u32 s38, s38, 0x80
	v_lshlrev_b64 v[6:7], 1, v[130:131]
	v_or3_b32 v130, v9, v8, v14
	s_addc_u32 s39, s39, 0
	v_lshlrev_b64 v[8:9], 1, v[130:131]
	s_waitcnt vmcnt(0)
	v_lshl_add_u64 v[134:135], s[38:39], 0, v[2:3]
	v_lshl_add_u64 v[136:137], s[38:39], 0, v[4:5]
	v_lshl_add_u64 v[138:139], s[38:39], 0, v[6:7]
	v_lshl_add_u64 v[140:141], s[38:39], 0, v[8:9]
	s_add_u32 s38, s54, 0x2400080
	s_addc_u32 s39, s55, 0
	v_or_b32_e32 v155, 0x800, v154
	v_or_b32_e32 v157, 0x1000, v154
	v_or_b32_e32 v158, 0x1800, v154
	v_or_b32_e32 v159, 0x2000, v154
	v_or_b32_e32 v160, 0x2800, v154
	v_or_b32_e32 v161, 0x3000, v154
	v_or_b32_e32 v162, 0x3800, v154
	v_lshl_add_u64 v[142:143], s[38:39], 0, v[2:3]
	v_lshl_add_u64 v[144:145], s[38:39], 0, v[4:5]
	v_lshl_add_u64 v[146:147], s[38:39], 0, v[6:7]
	v_lshl_add_u64 v[148:149], s[38:39], 0, v[8:9]
	s_mov_b64 s[38:39], 0
	s_mov_b32 s0, 0
	v_mov_b32_e32 v14, 0
	v_mov_b32_e32 v15, v131
	v_mov_b32_e32 v16, v131
	v_mov_b32_e32 v17, v131
	v_mov_b32_e32 v22, 0
	v_mov_b32_e32 v23, v131
	v_mov_b32_e32 v24, v131
	v_mov_b32_e32 v25, v131
	v_mov_b32_e32 v30, 0
	v_mov_b32_e32 v31, v131
	v_mov_b32_e32 v32, v131
	v_mov_b32_e32 v33, v131
	v_mov_b32_e32 v38, 0
	v_mov_b32_e32 v39, v131
	v_mov_b32_e32 v40, v131
	v_mov_b32_e32 v41, v131
	v_mov_b32_e32 v2, 0
	v_mov_b32_e32 v3, v131
	v_mov_b32_e32 v4, v131
	v_mov_b32_e32 v5, v131
	v_mov_b32_e32 v6, 0
	v_mov_b32_e32 v7, v131
	v_mov_b32_e32 v8, v131
	v_mov_b32_e32 v9, v131
	v_mov_b32_e32 v10, 0
	v_mov_b32_e32 v11, v131
	v_mov_b32_e32 v12, v131
	v_mov_b32_e32 v13, v131
	v_mov_b32_e32 v18, 0
	v_mov_b32_e32 v19, v131
	v_mov_b32_e32 v20, v131
	v_mov_b32_e32 v21, v131
	v_mov_b32_e32 v26, 0
	v_mov_b32_e32 v27, v131
	v_mov_b32_e32 v28, v131
	v_mov_b32_e32 v29, v131
	v_mov_b32_e32 v34, 0
	v_mov_b32_e32 v35, v131
	v_mov_b32_e32 v36, v131
	v_mov_b32_e32 v37, v131
	v_mov_b32_e32 v42, 0
	v_mov_b32_e32 v43, v131
	v_mov_b32_e32 v44, v131
	v_mov_b32_e32 v45, v131
	v_mov_b32_e32 v46, 0
	v_mov_b32_e32 v47, v131
	v_mov_b32_e32 v48, v131
	v_mov_b32_e32 v49, v131
	v_mov_b32_e32 v50, 0
	v_mov_b32_e32 v51, v131
	v_mov_b32_e32 v52, v131
	v_mov_b32_e32 v53, v131
	v_mov_b32_e32 v54, 0
	v_mov_b32_e32 v55, v131
	v_mov_b32_e32 v56, v131
	v_mov_b32_e32 v57, v131
	v_mov_b32_e32 v58, 0
	v_mov_b32_e32 v59, v131
	v_mov_b32_e32 v60, v131
	v_mov_b32_e32 v61, v131
	v_mov_b32_e32 v62, 0
	v_mov_b32_e32 v63, v131
	v_mov_b32_e32 v64, v131
	v_mov_b32_e32 v65, v131
	v_mov_b32_e32 v66, 0
	v_mov_b32_e32 v67, v131
	v_mov_b32_e32 v68, v131
	v_mov_b32_e32 v69, v131
	v_mov_b32_e32 v70, 0
	v_mov_b32_e32 v71, v131
	v_mov_b32_e32 v72, v131
	v_mov_b32_e32 v73, v131
	v_mov_b32_e32 v74, 0
	v_mov_b32_e32 v75, v131
	v_mov_b32_e32 v76, v131
	v_mov_b32_e32 v77, v131
	v_mov_b32_e32 v78, 0
	v_mov_b32_e32 v79, v131
	v_mov_b32_e32 v80, v131
	v_mov_b32_e32 v81, v131
	v_mov_b32_e32 v82, 0
	v_mov_b32_e32 v83, v131
	v_mov_b32_e32 v84, v131
	v_mov_b32_e32 v85, v131
	v_mov_b32_e32 v86, 0
	v_mov_b32_e32 v87, v131
	v_mov_b32_e32 v88, v131
	v_mov_b32_e32 v89, v131
	v_mov_b32_e32 v90, 0
	v_mov_b32_e32 v91, v131
	v_mov_b32_e32 v92, v131
	v_mov_b32_e32 v93, v131
	v_mov_b32_e32 v94, 0
	v_mov_b32_e32 v95, v131
	v_mov_b32_e32 v96, v131
	v_mov_b32_e32 v97, v131
	v_mov_b32_e32 v98, 0
	v_mov_b32_e32 v99, v131
	v_mov_b32_e32 v100, v131
	v_mov_b32_e32 v101, v131
	v_mov_b32_e32 v102, 0
	v_mov_b32_e32 v103, v131
	v_mov_b32_e32 v104, v131
	v_mov_b32_e32 v105, v131
	v_mov_b32_e32 v106, 0
	v_mov_b32_e32 v107, v131
	v_mov_b32_e32 v108, v131
	v_mov_b32_e32 v109, v131
	v_mov_b32_e32 v110, 0
	v_mov_b32_e32 v111, v131
	v_mov_b32_e32 v112, v131
	v_mov_b32_e32 v113, v131
	v_mov_b32_e32 v114, 0
	v_mov_b32_e32 v115, v131
	v_mov_b32_e32 v116, v131
	v_mov_b32_e32 v117, v131
	v_mov_b32_e32 v118, 0
	v_mov_b32_e32 v119, v131
	v_mov_b32_e32 v120, v131
	v_mov_b32_e32 v121, v131
	v_mov_b32_e32 v122, 0
	v_mov_b32_e32 v123, v131
	v_mov_b32_e32 v124, v131
	v_mov_b32_e32 v125, v131
	v_mov_b32_e32 v126, 0
	v_mov_b32_e32 v127, v131
	v_mov_b32_e32 v128, v131
	v_mov_b32_e32 v129, v131
	s_waitcnt vmcnt(0) lgkmcnt(0)
	s_barrier
	v_readfirstlane_b32 s100, v151
	s_and_b32 s31, s0, 0x10000
	s_xor_b32 s42, s31, 0x10000
	s_add_i32 s31, s31, 0
	v_add3_u32 v130, s31, v152, v153
	v_add3_u32 v163, s31, v152, v154
	v_add3_u32 v196, s31, v156, v155
	v_add3_u32 v197, s31, v156, v157
	v_add3_u32 v198, s31, v156, v158
	v_add3_u32 v199, s31, v156, v159
	v_add3_u32 v200, s31, v156, v160
	v_add3_u32 v201, s31, v156, v161
	v_add3_u32 v202, s31, v156, v162
	ds_read_b128 v[180:183], v130 offset:32768
	ds_read_b128 v[164:167], v163
	ds_read_b128 v[168:171], v196
	ds_read_b128 v[172:175], v197
	ds_read_b128 v[176:179], v198
	ds_read_b128 v[184:187], v130 offset:34816
	ds_read_b128 v[188:191], v130 offset:36864
	ds_read_b128 v[192:195], v130 offset:38912
	s_add_i32 s101, s100, s42
	v_readfirstlane_b32 s98, v148
	v_readfirstlane_b32 s99, v149
	v_readfirstlane_b32 vcc_lo, v140
	v_readfirstlane_b32 vcc_hi, v141
	s_sub_u32 s98, s98, 0x1000000
	s_subb_u32 s99, s99, 0
	s_sub_u32 vcc_lo, vcc_lo, 0x1000000
	s_subb_u32 vcc_hi, vcc_hi, 0
	v_subrev_u32_e32 v148, s98, v148
	v_subrev_u32_e32 v140, vcc_lo, v140
	v_subrev_u32_e32 v146, s98, v146
	v_subrev_u32_e32 v138, vcc_lo, v138
	v_subrev_u32_e32 v144, s98, v144
	v_subrev_u32_e32 v136, vcc_lo, v136
	v_subrev_u32_e32 v142, s98, v142
	v_subrev_u32_e32 v134, vcc_lo, v134
	s_mov_b32 m0, s101
	s_nop 0
	global_load_lds_dwordx4 v148, s[98:99]
	s_add_i32 m0, s101, 0x8000
	s_nop 0
	global_load_lds_dwordx4 v140, vcc
	s_add_i32 m0, s101, 0x2000
	s_nop 0
	global_load_lds_dwordx4 v146, s[98:99]
	s_add_i32 m0, s101, 0xa000
	s_nop 0
	global_load_lds_dwordx4 v138, vcc
	s_add_i32 m0, s101, 0x4000
	s_nop 0
	global_load_lds_dwordx4 v144, s[98:99]
	s_add_i32 m0, s101, 0xc000
	s_nop 0
	global_load_lds_dwordx4 v136, vcc
	s_add_i32 m0, s101, 0x6000
	s_nop 0
	global_load_lds_dwordx4 v142, s[98:99]
	s_add_i32 m0, s101, 0xe000
	s_nop 0
	global_load_lds_dwordx4 v134, vcc
.LBB0_793:
	s_and_b32 s31, s0, 0x10000
	s_xor_b32 s42, s31, 0x10000
	s_add_i32 s31, s31, 0
	s_add_i32 s101, s100, s42
	s_cmpk_eq_i32 s38, 0
	s_cbranch_scc1 .Lg1n_793
	s_waitcnt lgkmcnt(3)
	v_mfma_f32_16x16x32_bf16 v[126:129], v[180:183], v[164:167], v[126:129]
	v_mfma_f32_16x16x32_bf16 v[110:113], v[180:183], v[168:171], v[110:113]
	v_mfma_f32_16x16x32_bf16 v[94:97], v[180:183], v[172:175], v[94:97]
	v_mfma_f32_16x16x32_bf16 v[78:81], v[180:183], v[176:179], v[78:81]
	ds_read_b128 v[240:243], v199
	ds_read_b128 v[244:247], v200
	s_add_i32 m0, s101, 0x4000
	s_nop 0
	global_load_lds_dwordx4 v144, s[98:99]
	s_waitcnt lgkmcnt(4)
	v_mfma_f32_16x16x32_bf16 v[122:125], v[184:187], v[164:167], v[122:125]
	v_mfma_f32_16x16x32_bf16 v[106:109], v[184:187], v[168:171], v[106:109]
	v_mfma_f32_16x16x32_bf16 v[90:93], v[184:187], v[172:175], v[90:93]
	v_mfma_f32_16x16x32_bf16 v[74:77], v[184:187], v[176:179], v[74:77]
	ds_read_b128 v[248:251], v201
	ds_read_b128 v[252:255], v202
	s_add_i32 m0, s101, 0xc000
	s_nop 0
	global_load_lds_dwordx4 v136, vcc
	s_waitcnt lgkmcnt(5)
	v_mfma_f32_16x16x32_bf16 v[118:121], v[188:191], v[164:167], v[118:121]
	v_mfma_f32_16x16x32_bf16 v[102:105], v[188:191], v[168:171], v[102:105]
	v_mfma_f32_16x16x32_bf16 v[86:89], v[188:191], v[172:175], v[86:89]
	v_mfma_f32_16x16x32_bf16 v[70:73], v[188:191], v[176:179], v[70:73]
	s_add_i32 m0, s101, 0x6000
	s_nop 0
	global_load_lds_dwordx4 v142, s[98:99]
	s_waitcnt lgkmcnt(4)
	v_mfma_f32_16x16x32_bf16 v[114:117], v[192:195], v[164:167], v[114:117]
	v_mfma_f32_16x16x32_bf16 v[98:101], v[192:195], v[168:171], v[98:101]
	v_mfma_f32_16x16x32_bf16 v[82:85], v[192:195], v[172:175], v[82:85]
	v_mfma_f32_16x16x32_bf16 v[66:69], v[192:195], v[176:179], v[66:69]
	s_add_i32 m0, s101, 0xe000
	s_nop 0
	global_load_lds_dwordx4 v134, vcc
.Lg2_793:
	ds_read_b128 v[164:167], v163 offset:1024
	ds_read_b128 v[168:171], v196 offset:1024
	ds_read_b128 v[172:175], v197 offset:1024
	ds_read_b128 v[176:179], v198 offset:1024
	s_waitcnt lgkmcnt(4)
	v_mfma_f32_16x16x32_bf16 v[62:65], v[180:183], v[240:243], v[62:65]
	v_mfma_f32_16x16x32_bf16 v[46:49], v[180:183], v[244:247], v[46:49]
	v_mfma_f32_16x16x32_bf16 v[18:21], v[180:183], v[248:251], v[18:21]
	v_mfma_f32_16x16x32_bf16 v[38:41], v[180:183], v[252:255], v[38:41]
	ds_read_b128 v[180:183], v130 offset:33792
	v_mfma_f32_16x16x32_bf16 v[58:61], v[184:187], v[240:243], v[58:61]
	v_mfma_f32_16x16x32_bf16 v[42:45], v[184:187], v[244:247], v[42:45]
	v_mfma_f32_16x16x32_bf16 v[10:13], v[184:187], v[248:251], v[10:13]
	v_mfma_f32_16x16x32_bf16 v[30:33], v[184:187], v[252:255], v[30:33]
	ds_read_b128 v[184:187], v130 offset:35840
	v_mfma_f32_16x16x32_bf16 v[54:57], v[188:191], v[240:243], v[54:57]
	v_mfma_f32_16x16x32_bf16 v[34:37], v[188:191], v[244:247], v[34:37]
	v_mfma_f32_16x16x32_bf16 v[6:9], v[188:191], v[248:251], v[6:9]
	v_mfma_f32_16x16x32_bf16 v[22:25], v[188:191], v[252:255], v[22:25]
	ds_read_b128 v[188:191], v130 offset:37888
	v_mfma_f32_16x16x32_bf16 v[50:53], v[192:195], v[240:243], v[50:53]
	v_mfma_f32_16x16x32_bf16 v[26:29], v[192:195], v[244:247], v[26:29]
	v_mfma_f32_16x16x32_bf16 v[2:5], v[192:195], v[248:251], v[2:5]
	v_mfma_f32_16x16x32_bf16 v[14:17], v[192:195], v[252:255], v[14:17]
	ds_read_b128 v[192:195], v130 offset:39936
	s_waitcnt lgkmcnt(3)
	v_mfma_f32_16x16x32_bf16 v[126:129], v[180:183], v[164:167], v[126:129]
	v_mfma_f32_16x16x32_bf16 v[110:113], v[180:183], v[168:171], v[110:113]
	v_mfma_f32_16x16x32_bf16 v[94:97], v[180:183], v[172:175], v[94:97]
	v_mfma_f32_16x16x32_bf16 v[78:81], v[180:183], v[176:179], v[78:81]
	ds_read_b128 v[240:243], v199 offset:1024
	ds_read_b128 v[244:247], v200 offset:1024
	s_waitcnt lgkmcnt(4)
	v_mfma_f32_16x16x32_bf16 v[122:125], v[184:187], v[164:167], v[122:125]
	v_mfma_f32_16x16x32_bf16 v[106:109], v[184:187], v[168:171], v[106:109]
	v_mfma_f32_16x16x32_bf16 v[90:93], v[184:187], v[172:175], v[90:93]
	v_mfma_f32_16x16x32_bf16 v[74:77], v[184:187], v[176:179], v[74:77]
	ds_read_b128 v[248:251], v201 offset:1024
	ds_read_b128 v[252:255], v202 offset:1024
	s_waitcnt lgkmcnt(5)
	v_mfma_f32_16x16x32_bf16 v[118:121], v[188:191], v[164:167], v[118:121]
	v_mfma_f32_16x16x32_bf16 v[102:105], v[188:191], v[168:171], v[102:105]
	v_mfma_f32_16x16x32_bf16 v[86:89], v[188:191], v[172:175], v[86:89]
	v_mfma_f32_16x16x32_bf16 v[70:73], v[188:191], v[176:179], v[70:73]
	s_waitcnt lgkmcnt(4)
	v_mfma_f32_16x16x32_bf16 v[114:117], v[192:195], v[164:167], v[114:117]
	v_mfma_f32_16x16x32_bf16 v[98:101], v[192:195], v[168:171], v[98:101]
	v_mfma_f32_16x16x32_bf16 v[82:85], v[192:195], v[172:175], v[82:85]
	v_mfma_f32_16x16x32_bf16 v[66:69], v[192:195], v[176:179], v[66:69]
	s_waitcnt vmcnt(0) lgkmcnt(0)
	s_barrier
	s_add_i32 s101, s100, s31
	s_cmpk_eq_i32 s38, 0x700
	s_cbranch_scc1 .Lg4n_793
	s_add_u32 s98, s98, 0x80
	s_addc_u32 s99, s99, 0
	s_add_u32 vcc_lo, vcc_lo, 0x80
	s_addc_u32 vcc_hi, vcc_hi, 0
	v_mfma_f32_16x16x32_bf16 v[62:65], v[180:183], v[240:243], v[62:65]
	v_mfma_f32_16x16x32_bf16 v[46:49], v[180:183], v[244:247], v[46:49]
	v_mfma_f32_16x16x32_bf16 v[18:21], v[180:183], v[248:251], v[18:21]
	v_mfma_f32_16x16x32_bf16 v[38:41], v[180:183], v[252:255], v[38:41]
	v_add3_u32 v130, s42, v152, v153
	ds_read_b128 v[180:183], v130 offset:32768
	v_add3_u32 v163, s42, v152, v154
	v_add3_u32 v196, s42, v156, v155
	v_add3_u32 v197, s42, v156, v157
	v_add3_u32 v198, s42, v156, v158
	ds_read_b128 v[164:167], v163
	ds_read_b128 v[168:171], v196
	ds_read_b128 v[172:175], v197
	ds_read_b128 v[176:179], v198
	s_mov_b32 m0, s101
	s_nop 0
	global_load_lds_dwordx4 v148, s[98:99]
	v_mfma_f32_16x16x32_bf16 v[58:61], v[184:187], v[240:243], v[58:61]
	v_mfma_f32_16x16x32_bf16 v[42:45], v[184:187], v[244:247], v[42:45]
	v_mfma_f32_16x16x32_bf16 v[10:13], v[184:187], v[248:251], v[10:13]
	v_mfma_f32_16x16x32_bf16 v[30:33], v[184:187], v[252:255], v[30:33]
	ds_read_b128 v[184:187], v130 offset:34816
	v_add3_u32 v199, s42, v156, v159
	v_add3_u32 v200, s42, v156, v160
	v_add3_u32 v201, s42, v156, v161
	v_add3_u32 v202, s42, v156, v162
	s_add_i32 m0, s101, 0x8000
	s_nop 0
	global_load_lds_dwordx4 v140, vcc
	v_mfma_f32_16x16x32_bf16 v[54:57], v[188:191], v[240:243], v[54:57]
	v_mfma_f32_16x16x32_bf16 v[34:37], v[188:191], v[244:247], v[34:37]
	v_mfma_f32_16x16x32_bf16 v[6:9], v[188:191], v[248:251], v[6:9]
	v_mfma_f32_16x16x32_bf16 v[22:25], v[188:191], v[252:255], v[22:25]
	ds_read_b128 v[188:191], v130 offset:36864
	s_add_i32 m0, s101, 0x2000
	s_nop 0
	global_load_lds_dwordx4 v146, s[98:99]
	v_mfma_f32_16x16x32_bf16 v[50:53], v[192:195], v[240:243], v[50:53]
	v_mfma_f32_16x16x32_bf16 v[26:29], v[192:195], v[244:247], v[26:29]
	v_mfma_f32_16x16x32_bf16 v[2:5], v[192:195], v[248:251], v[2:5]
	v_mfma_f32_16x16x32_bf16 v[14:17], v[192:195], v[252:255], v[14:17]
	ds_read_b128 v[192:195], v130 offset:38912
	s_add_i32 m0, s101, 0xa000
	s_nop 0
	global_load_lds_dwordx4 v138, vcc

.Lex_793:
	s_waitcnt lgkmcnt(0)
	v_add3_u32 v130, s46, v156, v162
	v_add3_u32 v151, s46, v156, v161
	v_add3_u32 v202, s46, v156, v160
	v_add3_u32 v198, s46, v156, v159
	v_add3_u32 v186, s46, v156, v158
	v_add3_u32 v187, s46, v156, v157
	v_add3_u32 v188, s46, v156, v155
	v_add3_u32 v189, s46, v152, v154
	v_add3_u32 v190, s47, v152, v153
	ds_read_b128 v[134:137], v130
	ds_read_b128 v[138:141], v151
	ds_read_b128 v[142:145], v202
	ds_read_b128 v[146:149], v198
	ds_read_b128 v[158:161], v186
	ds_read_b128 v[162:165], v187
	ds_read_b128 v[166:169], v188
	ds_read_b128 v[154:157], v189
	ds_read_b128 v[170:173], v190
	s_waitcnt lgkmcnt(0)
	v_mfma_f32_16x16x32_bf16 v[18:21], v[170:173], v[138:141], v[18:21]
	v_mfma_f32_16x16x32_bf16 v[174:177], v[170:173], v[134:137], v[38:41]
	s_nop 2
	ds_read_b128 v[38:41], v190 offset:2048
	s_waitcnt lgkmcnt(0)
	v_mfma_f32_16x16x32_bf16 v[10:13], v[38:41], v[138:141], v[10:13]
	v_mfma_f32_16x16x32_bf16 v[62:65], v[170:173], v[146:149], v[62:65]
	v_mfma_f32_16x16x32_bf16 v[30:33], v[38:41], v[134:137], v[30:33]
	v_mfma_f32_16x16x32_bf16 v[58:61], v[38:41], v[146:149], v[58:61]
	ds_read_b128 v[178:181], v190 offset:4096
	s_waitcnt lgkmcnt(0)
	v_mfma_f32_16x16x32_bf16 v[182:185], v[178:181], v[134:137], v[22:25]
	v_mfma_f32_16x16x32_bf16 v[54:57], v[178:181], v[146:149], v[54:57]
	s_nop 1
	ds_read_b128 v[22:25], v190 offset:6144
	s_waitcnt lgkmcnt(0)
	v_mfma_f32_16x16x32_bf16 v[134:137], v[22:25], v[134:137], v[14:17]
	v_mfma_f32_16x16x32_bf16 v[14:17], v[22:25], v[154:157], v[114:117]
	v_mfma_f32_16x16x32_bf16 v[114:117], v[22:25], v[158:161], v[66:69]
	v_mfma_f32_16x16x32_bf16 v[66:69], v[178:181], v[154:157], v[118:121]
	v_mfma_f32_16x16x32_bf16 v[118:121], v[178:181], v[158:161], v[70:73]
	v_mfma_f32_16x16x32_bf16 v[70:73], v[38:41], v[154:157], v[122:125]
	v_mfma_f32_16x16x32_bf16 v[122:125], v[38:41], v[158:161], v[74:77]
	v_mfma_f32_16x16x32_bf16 v[74:77], v[170:173], v[154:157], v[126:129]
	v_mfma_f32_16x16x32_bf16 v[126:129], v[170:173], v[158:161], v[78:81]
	v_mfma_f32_16x16x32_bf16 v[50:53], v[22:25], v[146:149], v[50:53]
	v_mfma_f32_16x16x32_bf16 v[146:149], v[170:173], v[142:145], v[46:49]
	v_mfma_f32_16x16x32_bf16 v[152:155], v[38:41], v[142:145], v[42:45]
	v_mfma_f32_16x16x32_bf16 v[156:159], v[178:181], v[142:145], v[34:37]
	v_mfma_f32_16x16x32_bf16 v[26:29], v[22:25], v[142:145], v[26:29]
	v_mfma_f32_16x16x32_bf16 v[142:145], v[178:181], v[138:141], v[6:9]
	v_mfma_f32_16x16x32_bf16 v[110:113], v[170:173], v[166:169], v[110:113]
	v_mfma_f32_16x16x32_bf16 v[94:97], v[170:173], v[162:165], v[94:97]
	v_mfma_f32_16x16x32_bf16 v[106:109], v[38:41], v[166:169], v[106:109]
	v_mfma_f32_16x16x32_bf16 v[90:93], v[38:41], v[162:165], v[90:93]
	v_mfma_f32_16x16x32_bf16 v[102:105], v[178:181], v[166:169], v[102:105]
	v_mfma_f32_16x16x32_bf16 v[86:89], v[178:181], v[162:165], v[86:89]
	v_mfma_f32_16x16x32_bf16 v[98:101], v[22:25], v[166:169], v[98:101]
	v_mfma_f32_16x16x32_bf16 v[82:85], v[22:25], v[162:165], v[82:85]
	v_mfma_f32_16x16x32_bf16 v[22:25], v[22:25], v[138:141], v[2:5]
	ds_read_b128 v[138:141], v190 offset:1024
	ds_read_b128 v[160:163], v190 offset:3072
	ds_read_b128 v[164:167], v190 offset:5120
	ds_read_b128 v[168:171], v190 offset:7168
	ds_read_b128 v[2:5], v189 offset:1024
	ds_read_b128 v[6:9], v188 offset:1024
	ds_read_b128 v[34:37], v187 offset:1024
	ds_read_b128 v[38:41], v186 offset:1024
	s_waitcnt lgkmcnt(3)
	v_mfma_f32_16x16x32_bf16 v[178:181], v[138:141], v[2:5], v[74:77]
	v_mfma_f32_16x16x32_bf16 v[186:189], v[160:163], v[2:5], v[70:73]
	v_mfma_f32_16x16x32_bf16 v[190:193], v[164:167], v[2:5], v[66:69]
	v_mfma_f32_16x16x32_bf16 v[194:197], v[168:171], v[2:5], v[14:17]
	ds_read_b128 v[2:5], v198 offset:1024
	s_waitcnt lgkmcnt(3)
	v_mfma_f32_16x16x32_bf16 v[110:113], v[138:141], v[6:9], v[110:113]
	v_mfma_f32_16x16x32_bf16 v[106:109], v[160:163], v[6:9], v[106:109]
	v_mfma_f32_16x16x32_bf16 v[102:105], v[164:167], v[6:9], v[102:105]
	v_mfma_f32_16x16x32_bf16 v[198:201], v[168:171], v[6:9], v[98:101]
	ds_read_b128 v[6:9], v202 offset:1024
	s_waitcnt lgkmcnt(3)
	v_mfma_f32_16x16x32_bf16 v[66:69], v[138:141], v[34:37], v[94:97]
	v_mfma_f32_16x16x32_bf16 v[70:73], v[160:163], v[34:37], v[90:93]
	v_mfma_f32_16x16x32_bf16 v[74:77], v[164:167], v[34:37], v[86:89]
	v_mfma_f32_16x16x32_bf16 v[78:81], v[168:171], v[34:37], v[82:85]
	ds_read_b128 v[14:17], v151 offset:1024
	s_waitcnt lgkmcnt(3)
	v_mfma_f32_16x16x32_bf16 v[82:85], v[138:141], v[38:41], v[126:129]
	v_mfma_f32_16x16x32_bf16 v[86:89], v[160:163], v[38:41], v[122:125]
	v_mfma_f32_16x16x32_bf16 v[90:93], v[164:167], v[38:41], v[118:121]
	v_mfma_f32_16x16x32_bf16 v[94:97], v[168:171], v[38:41], v[114:117]
	ds_read_b128 v[98:101], v130 offset:1024
	s_waitcnt lgkmcnt(3)
	v_mfma_f32_16x16x32_bf16 v[34:37], v[138:141], v[2:5], v[62:65]
	v_mfma_f32_16x16x32_bf16 v[38:41], v[160:163], v[2:5], v[58:61]
	v_mfma_f32_16x16x32_bf16 v[42:45], v[164:167], v[2:5], v[54:57]
	v_mfma_f32_16x16x32_bf16 v[46:49], v[168:171], v[2:5], v[50:53]
	s_waitcnt lgkmcnt(2)
	v_mfma_f32_16x16x32_bf16 v[50:53], v[138:141], v[6:9], v[146:149]
	v_mfma_f32_16x16x32_bf16 v[54:57], v[160:163], v[6:9], v[152:155]
	v_mfma_f32_16x16x32_bf16 v[58:61], v[164:167], v[6:9], v[156:159]
	v_mfma_f32_16x16x32_bf16 v[62:65], v[168:171], v[6:9], v[26:29]
	s_waitcnt lgkmcnt(1)
	v_mfma_f32_16x16x32_bf16 v[2:5], v[138:141], v[14:17], v[18:21]
	v_mfma_f32_16x16x32_bf16 v[6:9], v[160:163], v[14:17], v[10:13]
	v_mfma_f32_16x16x32_bf16 v[10:13], v[164:167], v[14:17], v[142:145]
	v_mfma_f32_16x16x32_bf16 v[14:17], v[168:171], v[14:17], v[22:25]
	s_waitcnt lgkmcnt(0)
	v_mfma_f32_16x16x32_bf16 v[18:21], v[138:141], v[98:101], v[174:177]
	v_mfma_f32_16x16x32_bf16 v[22:25], v[160:163], v[98:101], v[30:33]
	v_mfma_f32_16x16x32_bf16 v[26:29], v[164:167], v[98:101], v[182:185]
	v_mfma_f32_16x16x32_bf16 v[30:33], v[168:171], v[98:101], v[134:137]
	v_lshrrev_b32_e32 v98, 6, v150
	v_mul_lo_u32 v98, v98, s48
	v_add_u32_e32 v101, s46, v98
	v_lshlrev_b32_e32 v98, 2, v150
	v_and_b32_e32 v100, 15, v150
	v_and_b32_e32 v115, 60, v98
	v_ashrrev_i32_e32 v98, 1, v150
	v_bfe_u32 v99, v150, 4, 2
	v_and_b32_e32 v114, 48, v150
	v_and_b32_e32 v116, 0xffffff80, v98
	v_lshlrev_b32_e32 v98, 2, v115
	v_mul_u32_u24_e32 v117, 0x110, v99
	v_mul_u32_u24_e32 v100, 0x110, v100
	v_add3_u32 v98, v101, v98, v117
	v_add3_u32 v101, v101, v114, v100
	s_waitcnt vmcnt(0)
	s_barrier
	ds_write_b128 v101, v[178:181]
	ds_write_b128 v101, v[186:189] offset:64
	ds_write_b128 v101, v[190:193] offset:128
	ds_write_b128 v101, v[194:197] offset:192
	ds_write_b128 v101, v[110:113] offset:4352
	ds_write_b128 v101, v[106:109] offset:4416
	ds_write_b128 v101, v[102:105] offset:4480
	ds_write_b128 v101, v[198:201] offset:4544
	ds_read_b128 v[102:105], v98
	v_add_u32_e32 v100, s28, v116
	s_ashr_i32 s31, s30, 31
	v_and_or_b32 v106, v150, s49, v115
	s_lshl_b64 s[38:39], s[30:31], 1
	s_waitcnt lgkmcnt(0)
	v_mul_f32_e32 v102, 0xbfb8aa3b, v102
	v_mul_f32_e32 v103, 0xbfb8aa3b, v103
	v_mul_f32_e32 v104, 0xbfb8aa3b, v104
	v_mul_f32_e32 v105, 0xbfb8aa3b, v105
	v_exp_f32_e32 v102, v102
	v_exp_f32_e32 v103, v103
	v_exp_f32_e32 v104, v104
	v_exp_f32_e32 v105, v105
	v_add_f32_e32 v102, 1.0, v102
	v_add_f32_e32 v103, 1.0, v103
	v_add_f32_e32 v104, 1.0, v104
	v_add_f32_e32 v105, 1.0, v105
	v_rcp_f32_e32 v102, v102
	v_rcp_f32_e32 v103, v103
	v_rcp_f32_e32 v104, v104
	v_rcp_f32_e32 v105, v105
	v_lshl_add_u64 v[0:1], v[0:1], 0, s[38:39]
	v_cvt_pk_bf16_f32 v102, v102, v103
	v_lshlrev_b32_e32 v130, 1, v106
	v_cvt_pk_bf16_f32 v103, v104, v105
	v_or_b32_e32 v104, v100, v99
	v_ashrrev_i32_e32 v105, 31, v104
	v_lshl_add_u64 v[0:1], v[0:1], 0, v[130:131]
	v_lshlrev_b64 v[104:105], 11, v[104:105]
	v_lshl_add_u64 v[104:105], v[0:1], 0, v[104:105]
	flat_store_dwordx2 v[104:105], v[102:103]
	ds_read_b128 v[102:105], v98 offset:1088
	s_lshl_b64 s[42:43], s[28:29], 10
	s_mov_b32 s29, 0
	s_waitcnt lgkmcnt(0)
	v_mul_f32_e32 v102, 0xbfb8aa3b, v102
	v_exp_f32_e32 v102, v102
	v_mul_f32_e32 v103, 0xbfb8aa3b, v103
	v_exp_f32_e32 v103, v103
	v_add_f32_e32 v102, 1.0, v102
	v_rcp_f32_e32 v106, v102
	v_add_f32_e32 v102, 1.0, v103
	v_mul_f32_e32 v103, 0xbfb8aa3b, v104
	v_exp_f32_e32 v103, v103
	v_mul_f32_e32 v104, 0xbfb8aa3b, v105
	v_exp_f32_e32 v104, v104
	v_rcp_f32_e32 v105, v102
	v_add_f32_e32 v102, 1.0, v103
	v_rcp_f32_e32 v103, v102
	v_add_f32_e32 v102, 1.0, v104
	v_rcp_f32_e32 v107, v102
	v_or_b32_e32 v102, 4, v99
	v_cvt_pk_bf16_f32 v104, v106, v105
	v_or_b32_e32 v106, v100, v102
	v_cvt_pk_bf16_f32 v105, v103, v107
	v_ashrrev_i32_e32 v107, 31, v106
	v_lshlrev_b64 v[106:107], 11, v[106:107]
	v_lshl_add_u64 v[106:107], v[0:1], 0, v[106:107]
	flat_store_dwordx2 v[106:107], v[104:105]
	ds_read_b128 v[104:107], v98 offset:2176
	s_waitcnt lgkmcnt(0)
	v_mul_f32_e32 v103, 0xbfb8aa3b, v104
	v_exp_f32_e32 v103, v103
	v_mul_f32_e32 v104, 0xbfb8aa3b, v105
	v_exp_f32_e32 v104, v104
	v_add_f32_e32 v103, 1.0, v103
	v_rcp_f32_e32 v105, v103
	v_add_f32_e32 v103, 1.0, v104
	v_mul_f32_e32 v104, 0xbfb8aa3b, v106
	v_exp_f32_e32 v104, v104
	v_mul_f32_e32 v106, 0xbfb8aa3b, v107
	v_exp_f32_e32 v106, v106
	v_rcp_f32_e32 v107, v103
	v_add_f32_e32 v103, 1.0, v104
	v_rcp_f32_e32 v108, v103
	v_add_f32_e32 v103, 1.0, v106
	v_rcp_f32_e32 v106, v103
	v_or_b32_e32 v103, 8, v99
	v_cvt_pk_bf16_f32 v104, v105, v107
	v_cvt_pk_bf16_f32 v105, v108, v106
	v_or_b32_e32 v106, v100, v103
	v_ashrrev_i32_e32 v107, 31, v106
	v_lshlrev_b64 v[106:107], 11, v[106:107]
	v_lshl_add_u64 v[106:107], v[0:1], 0, v[106:107]
	flat_store_dwordx2 v[106:107], v[104:105]
	ds_read_b128 v[104:107], v98 offset:3264
	s_waitcnt lgkmcnt(0)
	v_mul_f32_e32 v104, 0xbfb8aa3b, v104
	v_exp_f32_e32 v104, v104
	v_mul_f32_e32 v105, 0xbfb8aa3b, v105
	v_exp_f32_e32 v105, v105
	v_add_f32_e32 v104, 1.0, v104
	v_rcp_f32_e32 v108, v104
	v_add_f32_e32 v104, 1.0, v105
	v_mul_f32_e32 v105, 0xbfb8aa3b, v106
	v_exp_f32_e32 v105, v105
	v_mul_f32_e32 v106, 0xbfb8aa3b, v107
	v_exp_f32_e32 v106, v106
	v_rcp_f32_e32 v107, v104
	v_add_f32_e32 v104, 1.0, v105
	v_rcp_f32_e32 v105, v104
	v_add_f32_e32 v104, 1.0, v106
	v_rcp_f32_e32 v109, v104
	v_or_b32_e32 v104, 12, v99
	v_cvt_pk_bf16_f32 v106, v108, v107
	v_or_b32_e32 v108, v100, v104
	v_cvt_pk_bf16_f32 v107, v105, v109
	v_ashrrev_i32_e32 v109, 31, v108
	v_lshlrev_b64 v[108:109], 11, v[108:109]
	v_lshl_add_u64 v[108:109], v[0:1], 0, v[108:109]
	flat_store_dwordx2 v[108:109], v[106:107]
	ds_read_b128 v[106:109], v98 offset:4352
	s_waitcnt lgkmcnt(0)
	v_mul_f32_e32 v105, 0xbfb8aa3b, v106
	v_exp_f32_e32 v105, v105
	v_mul_f32_e32 v106, 0xbfb8aa3b, v107
	v_exp_f32_e32 v106, v106
	v_add_f32_e32 v105, 1.0, v105
	v_rcp_f32_e32 v107, v105
	v_add_f32_e32 v105, 1.0, v106
	v_mul_f32_e32 v106, 0xbfb8aa3b, v108
	v_exp_f32_e32 v106, v106
	v_mul_f32_e32 v108, 0xbfb8aa3b, v109
	v_exp_f32_e32 v108, v108
	v_rcp_f32_e32 v109, v105
	v_add_f32_e32 v105, 1.0, v106
	v_rcp_f32_e32 v110, v105
	v_add_f32_e32 v105, 1.0, v108
	v_rcp_f32_e32 v108, v105
	v_or_b32_e32 v105, 16, v99
	v_cvt_pk_bf16_f32 v106, v107, v109
	v_cvt_pk_bf16_f32 v107, v110, v108
	v_or_b32_e32 v108, v100, v105
	v_ashrrev_i32_e32 v109, 31, v108
	v_lshlrev_b64 v[108:109], 11, v[108:109]
	v_lshl_add_u64 v[108:109], v[0:1], 0, v[108:109]
	flat_store_dwordx2 v[108:109], v[106:107]
	ds_read_b128 v[106:109], v98 offset:5440
	s_waitcnt lgkmcnt(0)
	v_mul_f32_e32 v106, 0xbfb8aa3b, v106
	v_exp_f32_e32 v106, v106
	v_mul_f32_e32 v107, 0xbfb8aa3b, v107
	v_exp_f32_e32 v107, v107
	v_add_f32_e32 v106, 1.0, v106
	v_rcp_f32_e32 v110, v106
	v_add_f32_e32 v106, 1.0, v107
	v_mul_f32_e32 v107, 0xbfb8aa3b, v108
	v_exp_f32_e32 v107, v107
	v_mul_f32_e32 v108, 0xbfb8aa3b, v109
	v_exp_f32_e32 v108, v108
	v_rcp_f32_e32 v109, v106
	v_add_f32_e32 v106, 1.0, v107
	v_rcp_f32_e32 v107, v106
	v_add_f32_e32 v106, 1.0, v108
	v_rcp_f32_e32 v111, v106
	v_or_b32_e32 v106, 20, v99
	v_cvt_pk_bf16_f32 v108, v110, v109
	v_or_b32_e32 v110, v100, v106
	v_cvt_pk_bf16_f32 v109, v107, v111
	v_ashrrev_i32_e32 v111, 31, v110
	v_lshlrev_b64 v[110:111], 11, v[110:111]
	v_lshl_add_u64 v[110:111], v[0:1], 0, v[110:111]
	flat_store_dwordx2 v[110:111], v[108:109]
	ds_read_b128 v[108:111], v98 offset:6528
	s_waitcnt lgkmcnt(0)
	v_mul_f32_e32 v107, 0xbfb8aa3b, v108
	v_exp_f32_e32 v107, v107
	v_mul_f32_e32 v108, 0xbfb8aa3b, v109
	v_exp_f32_e32 v108, v108
	v_add_f32_e32 v107, 1.0, v107
	v_rcp_f32_e32 v109, v107
	v_add_f32_e32 v107, 1.0, v108
	v_mul_f32_e32 v108, 0xbfb8aa3b, v110
	v_exp_f32_e32 v108, v108
	v_mul_f32_e32 v110, 0xbfb8aa3b, v111
	v_exp_f32_e32 v110, v110
	v_rcp_f32_e32 v111, v107
	v_add_f32_e32 v107, 1.0, v108
	v_rcp_f32_e32 v112, v107
	v_add_f32_e32 v107, 1.0, v110
	v_rcp_f32_e32 v110, v107
	v_or_b32_e32 v107, 24, v99
	v_cvt_pk_bf16_f32 v108, v109, v111
	v_cvt_pk_bf16_f32 v109, v112, v110
	v_or_b32_e32 v110, v100, v107
	v_ashrrev_i32_e32 v111, 31, v110
	v_lshlrev_b64 v[110:111], 11, v[110:111]
	v_lshl_add_u64 v[110:111], v[0:1], 0, v[110:111]
	flat_store_dwordx2 v[110:111], v[108:109]
	ds_read_b128 v[108:111], v98 offset:7616
	s_waitcnt lgkmcnt(0)
	v_mul_f32_e32 v108, 0xbfb8aa3b, v108
	v_exp_f32_e32 v108, v108
	v_mul_f32_e32 v109, 0xbfb8aa3b, v109
	v_exp_f32_e32 v109, v109
	v_add_f32_e32 v108, 1.0, v108
	v_rcp_f32_e32 v112, v108
	v_add_f32_e32 v108, 1.0, v109
	v_mul_f32_e32 v109, 0xbfb8aa3b, v110
	v_exp_f32_e32 v109, v109
	v_mul_f32_e32 v110, 0xbfb8aa3b, v111
	v_exp_f32_e32 v110, v110
	v_rcp_f32_e32 v111, v108
	v_add_f32_e32 v108, 1.0, v109
	v_rcp_f32_e32 v109, v108
	v_add_f32_e32 v108, 1.0, v110
	v_rcp_f32_e32 v113, v108
	v_or_b32_e32 v108, 28, v99
	v_cvt_pk_bf16_f32 v110, v112, v111
	v_or_b32_e32 v112, v100, v108
	v_cvt_pk_bf16_f32 v111, v109, v113
	v_ashrrev_i32_e32 v113, 31, v112
	v_lshlrev_b64 v[112:113], 11, v[112:113]
	v_lshl_add_u64 v[112:113], v[0:1], 0, v[112:113]
	flat_store_dwordx2 v[112:113], v[110:111]
	ds_write_b128 v101, v[66:69]
	ds_write_b128 v101, v[70:73] offset:64
	ds_write_b128 v101, v[74:77] offset:128
	ds_write_b128 v101, v[78:81] offset:192
	ds_write_b128 v101, v[82:85] offset:4352
	ds_write_b128 v101, v[86:89] offset:4416
	ds_write_b128 v101, v[90:93] offset:4480
	ds_write_b128 v101, v[94:97] offset:4544
	ds_read_b128 v[66:69], v98
	v_or_b32_e32 v70, 32, v100
	s_waitcnt lgkmcnt(0)
	v_mul_f32_e32 v66, 0xbfb8aa3b, v66
	v_mul_f32_e32 v67, 0xbfb8aa3b, v67
	v_mul_f32_e32 v68, 0xbfb8aa3b, v68
	v_mul_f32_e32 v69, 0xbfb8aa3b, v69
	v_exp_f32_e32 v66, v66
	v_exp_f32_e32 v67, v67
	v_exp_f32_e32 v68, v68
	v_exp_f32_e32 v69, v69
	v_add_f32_e32 v66, 1.0, v66
	v_add_f32_e32 v67, 1.0, v67
	v_add_f32_e32 v68, 1.0, v68
	v_add_f32_e32 v69, 1.0, v69
	v_rcp_f32_e32 v66, v66
	v_rcp_f32_e32 v67, v67
	v_rcp_f32_e32 v68, v68
	v_rcp_f32_e32 v69, v69
	v_cvt_pk_bf16_f32 v66, v66, v67
	v_cvt_pk_bf16_f32 v67, v68, v69
	v_or_b32_e32 v68, v70, v99
	v_ashrrev_i32_e32 v69, 31, v68
	v_lshlrev_b64 v[68:69], 11, v[68:69]
	v_lshl_add_u64 v[68:69], v[0:1], 0, v[68:69]
	flat_store_dwordx2 v[68:69], v[66:67]
	ds_read_b128 v[66:69], v98 offset:1088
	s_waitcnt lgkmcnt(0)
	v_mul_f32_e32 v66, 0xbfb8aa3b, v66
	v_mul_f32_e32 v67, 0xbfb8aa3b, v67
	v_mul_f32_e32 v68, 0xbfb8aa3b, v68
	v_mul_f32_e32 v69, 0xbfb8aa3b, v69
	v_exp_f32_e32 v66, v66
	v_exp_f32_e32 v67, v67
	v_exp_f32_e32 v68, v68
	v_exp_f32_e32 v69, v69
	v_add_f32_e32 v66, 1.0, v66
	v_add_f32_e32 v67, 1.0, v67
	v_add_f32_e32 v68, 1.0, v68
	v_add_f32_e32 v69, 1.0, v69
	v_rcp_f32_e32 v66, v66
	v_rcp_f32_e32 v67, v67
	v_rcp_f32_e32 v68, v68
	v_rcp_f32_e32 v69, v69
	v_cvt_pk_bf16_f32 v66, v66, v67
	v_cvt_pk_bf16_f32 v67, v68, v69
	v_or_b32_e32 v68, v70, v102
	v_ashrrev_i32_e32 v69, 31, v68
	v_lshlrev_b64 v[68:69], 11, v[68:69]
	v_lshl_add_u64 v[68:69], v[0:1], 0, v[68:69]
	flat_store_dwordx2 v[68:69], v[66:67]
	ds_read_b128 v[66:69], v98 offset:2176
	s_waitcnt lgkmcnt(0)
	v_mul_f32_e32 v66, 0xbfb8aa3b, v66
	v_mul_f32_e32 v67, 0xbfb8aa3b, v67
	v_mul_f32_e32 v68, 0xbfb8aa3b, v68
	v_mul_f32_e32 v69, 0xbfb8aa3b, v69
	v_exp_f32_e32 v66, v66
	v_exp_f32_e32 v67, v67
	v_exp_f32_e32 v68, v68
	v_exp_f32_e32 v69, v69
	v_add_f32_e32 v66, 1.0, v66
	v_add_f32_e32 v67, 1.0, v67
	v_add_f32_e32 v68, 1.0, v68
	v_add_f32_e32 v69, 1.0, v69
	v_rcp_f32_e32 v66, v66
	v_rcp_f32_e32 v67, v67
	v_rcp_f32_e32 v68, v68
	v_rcp_f32_e32 v69, v69
	v_cvt_pk_bf16_f32 v66, v66, v67
	v_cvt_pk_bf16_f32 v67, v68, v69
	v_or_b32_e32 v68, v70, v103
	v_ashrrev_i32_e32 v69, 31, v68
	v_lshlrev_b64 v[68:69], 11, v[68:69]
	v_lshl_add_u64 v[68:69], v[0:1], 0, v[68:69]
	flat_store_dwordx2 v[68:69], v[66:67]
	ds_read_b128 v[66:69], v98 offset:3264
	s_waitcnt lgkmcnt(0)
	v_mul_f32_e32 v66, 0xbfb8aa3b, v66
	v_mul_f32_e32 v67, 0xbfb8aa3b, v67
	v_mul_f32_e32 v68, 0xbfb8aa3b, v68
	v_mul_f32_e32 v69, 0xbfb8aa3b, v69
	v_exp_f32_e32 v66, v66
	v_exp_f32_e32 v67, v67
	v_exp_f32_e32 v68, v68
	v_exp_f32_e32 v69, v69
	v_add_f32_e32 v66, 1.0, v66
	v_add_f32_e32 v67, 1.0, v67
	v_add_f32_e32 v68, 1.0, v68
	v_add_f32_e32 v69, 1.0, v69
	v_rcp_f32_e32 v66, v66
	v_rcp_f32_e32 v67, v67
	v_rcp_f32_e32 v68, v68
	v_rcp_f32_e32 v69, v69
	v_cvt_pk_bf16_f32 v66, v66, v67
	v_cvt_pk_bf16_f32 v67, v68, v69
	v_or_b32_e32 v68, v70, v104
	v_ashrrev_i32_e32 v69, 31, v68
	v_lshlrev_b64 v[68:69], 11, v[68:69]
	v_lshl_add_u64 v[68:69], v[0:1], 0, v[68:69]
	flat_store_dwordx2 v[68:69], v[66:67]
	ds_read_b128 v[66:69], v98 offset:4352
	s_waitcnt lgkmcnt(0)
	v_mul_f32_e32 v66, 0xbfb8aa3b, v66
	v_mul_f32_e32 v67, 0xbfb8aa3b, v67
	v_mul_f32_e32 v68, 0xbfb8aa3b, v68
	v_mul_f32_e32 v69, 0xbfb8aa3b, v69
	v_exp_f32_e32 v66, v66
	v_exp_f32_e32 v67, v67
	v_exp_f32_e32 v68, v68
	v_exp_f32_e32 v69, v69
	v_add_f32_e32 v66, 1.0, v66
	v_add_f32_e32 v67, 1.0, v67
	v_add_f32_e32 v68, 1.0, v68
	v_add_f32_e32 v69, 1.0, v69
	v_rcp_f32_e32 v66, v66
	v_rcp_f32_e32 v67, v67
	v_rcp_f32_e32 v68, v68
	v_rcp_f32_e32 v69, v69
	v_cvt_pk_bf16_f32 v66, v66, v67
	v_cvt_pk_bf16_f32 v67, v68, v69
	v_or_b32_e32 v68, v70, v105
	v_ashrrev_i32_e32 v69, 31, v68
	v_lshlrev_b64 v[68:69], 11, v[68:69]
	v_lshl_add_u64 v[68:69], v[0:1], 0, v[68:69]
	flat_store_dwordx2 v[68:69], v[66:67]
	ds_read_b128 v[66:69], v98 offset:5440
	s_waitcnt lgkmcnt(0)
	v_mul_f32_e32 v66, 0xbfb8aa3b, v66
	v_mul_f32_e32 v67, 0xbfb8aa3b, v67
	v_mul_f32_e32 v68, 0xbfb8aa3b, v68
	v_mul_f32_e32 v69, 0xbfb8aa3b, v69
	v_exp_f32_e32 v66, v66
	v_exp_f32_e32 v67, v67
	v_exp_f32_e32 v68, v68
	v_exp_f32_e32 v69, v69
	v_add_f32_e32 v66, 1.0, v66
	v_add_f32_e32 v67, 1.0, v67
	v_add_f32_e32 v68, 1.0, v68
	v_add_f32_e32 v69, 1.0, v69
	v_rcp_f32_e32 v66, v66
	v_rcp_f32_e32 v67, v67
	v_rcp_f32_e32 v68, v68
	v_rcp_f32_e32 v69, v69
	v_cvt_pk_bf16_f32 v66, v66, v67
	v_cvt_pk_bf16_f32 v67, v68, v69
	v_or_b32_e32 v68, v70, v106
	v_ashrrev_i32_e32 v69, 31, v68
	v_lshlrev_b64 v[68:69], 11, v[68:69]
	v_lshl_add_u64 v[68:69], v[0:1], 0, v[68:69]
	flat_store_dwordx2 v[68:69], v[66:67]
	ds_read_b128 v[66:69], v98 offset:6528
	s_waitcnt lgkmcnt(0)
	v_mul_f32_e32 v66, 0xbfb8aa3b, v66
	v_mul_f32_e32 v67, 0xbfb8aa3b, v67
	v_mul_f32_e32 v68, 0xbfb8aa3b, v68
	v_mul_f32_e32 v69, 0xbfb8aa3b, v69
	v_exp_f32_e32 v66, v66
	v_exp_f32_e32 v67, v67
	v_exp_f32_e32 v68, v68
	v_exp_f32_e32 v69, v69
	v_add_f32_e32 v66, 1.0, v66
	v_add_f32_e32 v67, 1.0, v67
	v_add_f32_e32 v68, 1.0, v68
	v_add_f32_e32 v69, 1.0, v69
	v_rcp_f32_e32 v66, v66
	v_rcp_f32_e32 v67, v67
	v_rcp_f32_e32 v68, v68
	v_rcp_f32_e32 v69, v69
	v_cvt_pk_bf16_f32 v66, v66, v67
	v_cvt_pk_bf16_f32 v67, v68, v69
	v_or_b32_e32 v68, v70, v107
	v_ashrrev_i32_e32 v69, 31, v68
	v_lshlrev_b64 v[68:69], 11, v[68:69]
	v_lshl_add_u64 v[68:69], v[0:1], 0, v[68:69]
	flat_store_dwordx2 v[68:69], v[66:67]
	ds_read_b128 v[66:69], v98 offset:7616
	s_waitcnt lgkmcnt(0)
	v_mul_f32_e32 v66, 0xbfb8aa3b, v66
	v_mul_f32_e32 v67, 0xbfb8aa3b, v67
	v_mul_f32_e32 v68, 0xbfb8aa3b, v68
	v_mul_f32_e32 v69, 0xbfb8aa3b, v69
	v_exp_f32_e32 v66, v66
	v_exp_f32_e32 v67, v67
	v_exp_f32_e32 v68, v68
	v_exp_f32_e32 v69, v69
	v_add_f32_e32 v66, 1.0, v66
	v_add_f32_e32 v67, 1.0, v67
	v_add_f32_e32 v68, 1.0, v68
	v_add_f32_e32 v69, 1.0, v69
	v_rcp_f32_e32 v66, v66
	v_rcp_f32_e32 v67, v67
	v_rcp_f32_e32 v68, v68
	v_rcp_f32_e32 v69, v69
	v_cvt_pk_bf16_f32 v66, v66, v67
	v_cvt_pk_bf16_f32 v67, v68, v69
	v_or_b32_e32 v68, v70, v108
	v_ashrrev_i32_e32 v69, 31, v68
	v_lshlrev_b64 v[68:69], 11, v[68:69]
	v_lshl_add_u64 v[68:69], v[0:1], 0, v[68:69]
	flat_store_dwordx2 v[68:69], v[66:67]
	ds_write_b128 v101, v[34:37]
	ds_write_b128 v101, v[38:41] offset:64
	ds_write_b128 v101, v[42:45] offset:128
	ds_write_b128 v101, v[46:49] offset:192
	ds_write_b128 v101, v[50:53] offset:4352
	ds_write_b128 v101, v[54:57] offset:4416
	ds_write_b128 v101, v[58:61] offset:4480
	ds_write_b128 v101, v[62:65] offset:4544
	ds_read_b128 v[34:37], v98
	v_or_b32_e32 v38, 64, v100
	s_waitcnt lgkmcnt(0)
	v_mul_f32_e32 v34, 0xbfb8aa3b, v34
	v_mul_f32_e32 v35, 0xbfb8aa3b, v35
	v_mul_f32_e32 v36, 0xbfb8aa3b, v36
	v_mul_f32_e32 v37, 0xbfb8aa3b, v37
	v_exp_f32_e32 v34, v34
	v_exp_f32_e32 v35, v35
	v_exp_f32_e32 v36, v36
	v_exp_f32_e32 v37, v37
	v_add_f32_e32 v34, 1.0, v34
	v_add_f32_e32 v35, 1.0, v35
	v_add_f32_e32 v36, 1.0, v36
	v_add_f32_e32 v37, 1.0, v37
	v_rcp_f32_e32 v34, v34
	v_rcp_f32_e32 v35, v35
	v_rcp_f32_e32 v36, v36
	v_rcp_f32_e32 v37, v37
	v_cvt_pk_bf16_f32 v34, v34, v35
	v_cvt_pk_bf16_f32 v35, v36, v37
	v_or_b32_e32 v36, v38, v99
	v_ashrrev_i32_e32 v37, 31, v36
	v_lshlrev_b64 v[36:37], 11, v[36:37]
	v_lshl_add_u64 v[36:37], v[0:1], 0, v[36:37]
	flat_store_dwordx2 v[36:37], v[34:35]
	ds_read_b128 v[34:37], v98 offset:1088
	s_waitcnt lgkmcnt(0)
	v_mul_f32_e32 v34, 0xbfb8aa3b, v34
	v_mul_f32_e32 v35, 0xbfb8aa3b, v35
	v_mul_f32_e32 v36, 0xbfb8aa3b, v36
	v_mul_f32_e32 v37, 0xbfb8aa3b, v37
	v_exp_f32_e32 v34, v34
	v_exp_f32_e32 v35, v35
	v_exp_f32_e32 v36, v36
	v_exp_f32_e32 v37, v37
	v_add_f32_e32 v34, 1.0, v34
	v_add_f32_e32 v35, 1.0, v35
	v_add_f32_e32 v36, 1.0, v36
	v_add_f32_e32 v37, 1.0, v37
	v_rcp_f32_e32 v34, v34
	v_rcp_f32_e32 v35, v35
	v_rcp_f32_e32 v36, v36
	v_rcp_f32_e32 v37, v37
	v_cvt_pk_bf16_f32 v34, v34, v35
	v_cvt_pk_bf16_f32 v35, v36, v37
	v_or_b32_e32 v36, v38, v102
	v_ashrrev_i32_e32 v37, 31, v36
	v_lshlrev_b64 v[36:37], 11, v[36:37]
	v_lshl_add_u64 v[36:37], v[0:1], 0, v[36:37]
	flat_store_dwordx2 v[36:37], v[34:35]
	ds_read_b128 v[34:37], v98 offset:2176
	s_waitcnt lgkmcnt(0)
	v_mul_f32_e32 v34, 0xbfb8aa3b, v34
	v_mul_f32_e32 v35, 0xbfb8aa3b, v35
	v_mul_f32_e32 v36, 0xbfb8aa3b, v36
	v_mul_f32_e32 v37, 0xbfb8aa3b, v37
	v_exp_f32_e32 v34, v34
	v_exp_f32_e32 v35, v35
	v_exp_f32_e32 v36, v36
	v_exp_f32_e32 v37, v37
	v_add_f32_e32 v34, 1.0, v34
	v_add_f32_e32 v35, 1.0, v35
	v_add_f32_e32 v36, 1.0, v36
	v_add_f32_e32 v37, 1.0, v37
	v_rcp_f32_e32 v34, v34
	v_rcp_f32_e32 v35, v35
	v_rcp_f32_e32 v36, v36
	v_rcp_f32_e32 v37, v37
	v_cvt_pk_bf16_f32 v34, v34, v35
	v_cvt_pk_bf16_f32 v35, v36, v37
	v_or_b32_e32 v36, v38, v103
	v_ashrrev_i32_e32 v37, 31, v36
	v_lshlrev_b64 v[36:37], 11, v[36:37]
	v_lshl_add_u64 v[36:37], v[0:1], 0, v[36:37]
	flat_store_dwordx2 v[36:37], v[34:35]
	ds_read_b128 v[34:37], v98 offset:3264
	s_waitcnt lgkmcnt(0)
	v_mul_f32_e32 v34, 0xbfb8aa3b, v34
	v_mul_f32_e32 v35, 0xbfb8aa3b, v35
	v_mul_f32_e32 v36, 0xbfb8aa3b, v36
	v_mul_f32_e32 v37, 0xbfb8aa3b, v37
	v_exp_f32_e32 v34, v34
	v_exp_f32_e32 v35, v35
	v_exp_f32_e32 v36, v36
	v_exp_f32_e32 v37, v37
	v_add_f32_e32 v34, 1.0, v34
	v_add_f32_e32 v35, 1.0, v35
	v_add_f32_e32 v36, 1.0, v36
	v_add_f32_e32 v37, 1.0, v37
	v_rcp_f32_e32 v34, v34
	v_rcp_f32_e32 v35, v35
	v_rcp_f32_e32 v36, v36
	v_rcp_f32_e32 v37, v37
	v_cvt_pk_bf16_f32 v34, v34, v35
	v_cvt_pk_bf16_f32 v35, v36, v37
	v_or_b32_e32 v36, v38, v104
	v_ashrrev_i32_e32 v37, 31, v36
	v_lshlrev_b64 v[36:37], 11, v[36:37]
	v_lshl_add_u64 v[36:37], v[0:1], 0, v[36:37]
	flat_store_dwordx2 v[36:37], v[34:35]
	ds_read_b128 v[34:37], v98 offset:4352
	s_waitcnt lgkmcnt(0)
	v_mul_f32_e32 v34, 0xbfb8aa3b, v34
	v_mul_f32_e32 v35, 0xbfb8aa3b, v35
	v_mul_f32_e32 v36, 0xbfb8aa3b, v36
	v_mul_f32_e32 v37, 0xbfb8aa3b, v37
	v_exp_f32_e32 v34, v34
	v_exp_f32_e32 v35, v35
	v_exp_f32_e32 v36, v36
	v_exp_f32_e32 v37, v37
	v_add_f32_e32 v34, 1.0, v34
	v_add_f32_e32 v35, 1.0, v35
	v_add_f32_e32 v36, 1.0, v36
	v_add_f32_e32 v37, 1.0, v37
	v_rcp_f32_e32 v34, v34
	v_rcp_f32_e32 v35, v35
	v_rcp_f32_e32 v36, v36
	v_rcp_f32_e32 v37, v37
	v_cvt_pk_bf16_f32 v34, v34, v35
	v_cvt_pk_bf16_f32 v35, v36, v37
	v_or_b32_e32 v36, v38, v105
	v_ashrrev_i32_e32 v37, 31, v36
	v_lshlrev_b64 v[36:37], 11, v[36:37]
	v_lshl_add_u64 v[36:37], v[0:1], 0, v[36:37]
	flat_store_dwordx2 v[36:37], v[34:35]
	ds_read_b128 v[34:37], v98 offset:5440
	s_waitcnt lgkmcnt(0)
	v_mul_f32_e32 v34, 0xbfb8aa3b, v34
	v_mul_f32_e32 v35, 0xbfb8aa3b, v35
	v_mul_f32_e32 v36, 0xbfb8aa3b, v36
	v_mul_f32_e32 v37, 0xbfb8aa3b, v37
	v_exp_f32_e32 v34, v34
	v_exp_f32_e32 v35, v35
	v_exp_f32_e32 v36, v36
	v_exp_f32_e32 v37, v37
	v_add_f32_e32 v34, 1.0, v34
	v_add_f32_e32 v35, 1.0, v35
	v_add_f32_e32 v36, 1.0, v36
	v_add_f32_e32 v37, 1.0, v37
	v_rcp_f32_e32 v34, v34
	v_rcp_f32_e32 v35, v35
	v_rcp_f32_e32 v36, v36
	v_rcp_f32_e32 v37, v37
	v_cvt_pk_bf16_f32 v34, v34, v35
	v_cvt_pk_bf16_f32 v35, v36, v37
	v_or_b32_e32 v36, v38, v106
	v_ashrrev_i32_e32 v37, 31, v36
	v_lshlrev_b64 v[36:37], 11, v[36:37]
	v_lshl_add_u64 v[36:37], v[0:1], 0, v[36:37]
	flat_store_dwordx2 v[36:37], v[34:35]
	ds_read_b128 v[34:37], v98 offset:6528
	s_waitcnt lgkmcnt(0)
	v_mul_f32_e32 v34, 0xbfb8aa3b, v34
	v_mul_f32_e32 v35, 0xbfb8aa3b, v35
	v_mul_f32_e32 v36, 0xbfb8aa3b, v36
	v_mul_f32_e32 v37, 0xbfb8aa3b, v37
	v_exp_f32_e32 v34, v34
	v_exp_f32_e32 v35, v35
	v_exp_f32_e32 v36, v36
	v_exp_f32_e32 v37, v37
	v_add_f32_e32 v34, 1.0, v34
	v_add_f32_e32 v35, 1.0, v35
	v_add_f32_e32 v36, 1.0, v36
	v_add_f32_e32 v37, 1.0, v37
	v_rcp_f32_e32 v34, v34
	v_rcp_f32_e32 v35, v35
	v_rcp_f32_e32 v36, v36
	v_rcp_f32_e32 v37, v37
	v_cvt_pk_bf16_f32 v34, v34, v35
	v_cvt_pk_bf16_f32 v35, v36, v37
	v_or_b32_e32 v36, v38, v107
	v_ashrrev_i32_e32 v37, 31, v36
	v_lshlrev_b64 v[36:37], 11, v[36:37]
	v_lshl_add_u64 v[36:37], v[0:1], 0, v[36:37]
	flat_store_dwordx2 v[36:37], v[34:35]
	ds_read_b128 v[34:37], v98 offset:7616
	s_waitcnt lgkmcnt(0)
	v_mul_f32_e32 v34, 0xbfb8aa3b, v34
	v_mul_f32_e32 v35, 0xbfb8aa3b, v35
	v_mul_f32_e32 v36, 0xbfb8aa3b, v36
	v_mul_f32_e32 v37, 0xbfb8aa3b, v37
	v_exp_f32_e32 v34, v34
	v_exp_f32_e32 v35, v35
	v_exp_f32_e32 v36, v36
	v_exp_f32_e32 v37, v37
	v_add_f32_e32 v34, 1.0, v34
	v_add_f32_e32 v35, 1.0, v35
	v_add_f32_e32 v36, 1.0, v36
	v_add_f32_e32 v37, 1.0, v37
	v_rcp_f32_e32 v34, v34
	v_rcp_f32_e32 v35, v35
	v_rcp_f32_e32 v36, v36
	v_rcp_f32_e32 v37, v37
	v_cvt_pk_bf16_f32 v34, v34, v35
	v_cvt_pk_bf16_f32 v35, v36, v37
	v_or_b32_e32 v36, v38, v108
	v_ashrrev_i32_e32 v37, 31, v36
	v_lshlrev_b64 v[36:37], 11, v[36:37]
	v_lshl_add_u64 v[36:37], v[0:1], 0, v[36:37]
	flat_store_dwordx2 v[36:37], v[34:35]
	ds_write_b128 v101, v[2:5]
	ds_write_b128 v101, v[6:9] offset:64
	ds_write_b128 v101, v[10:13] offset:128
	ds_write_b128 v101, v[14:17] offset:192
	ds_write_b128 v101, v[18:21] offset:4352
	ds_write_b128 v101, v[22:25] offset:4416
	ds_write_b128 v101, v[26:29] offset:4480
	ds_write_b128 v101, v[30:33] offset:4544
	ds_read_b128 v[2:5], v98
	v_or_b32_e32 v6, 0x60, v100
	v_mov_b32_e32 v20, v132
	v_mov_b32_e32 v7, v131
	v_mov_b32_e32 v11, v131
	s_waitcnt lgkmcnt(0)
	v_mul_f32_e32 v2, 0xbfb8aa3b, v2
	v_mul_f32_e32 v3, 0xbfb8aa3b, v3
	v_mul_f32_e32 v4, 0xbfb8aa3b, v4
	v_mul_f32_e32 v5, 0xbfb8aa3b, v5
	v_exp_f32_e32 v2, v2
	v_exp_f32_e32 v3, v3
	v_exp_f32_e32 v4, v4
	v_exp_f32_e32 v5, v5
	v_add_f32_e32 v2, 1.0, v2
	v_add_f32_e32 v3, 1.0, v3
	v_add_f32_e32 v4, 1.0, v4
	v_add_f32_e32 v5, 1.0, v5
	v_rcp_f32_e32 v2, v2
	v_rcp_f32_e32 v3, v3
	v_rcp_f32_e32 v4, v4
	v_rcp_f32_e32 v5, v5
	v_mov_b32_e32 v19, v131
	v_cvt_pk_bf16_f32 v2, v2, v3
	v_cvt_pk_bf16_f32 v3, v4, v5
	v_or_b32_e32 v4, v6, v99
	v_ashrrev_i32_e32 v5, 31, v4
	v_lshlrev_b64 v[4:5], 11, v[4:5]
	v_lshl_add_u64 v[4:5], v[0:1], 0, v[4:5]
	flat_store_dwordx2 v[4:5], v[2:3]
	ds_read_b128 v[2:5], v98 offset:1088
	s_waitcnt lgkmcnt(0)
	v_mul_f32_e32 v2, 0xbfb8aa3b, v2
	v_mul_f32_e32 v3, 0xbfb8aa3b, v3
	v_mul_f32_e32 v4, 0xbfb8aa3b, v4
	v_mul_f32_e32 v5, 0xbfb8aa3b, v5
	v_exp_f32_e32 v2, v2
	v_exp_f32_e32 v3, v3
	v_exp_f32_e32 v4, v4
	v_exp_f32_e32 v5, v5
	v_add_f32_e32 v2, 1.0, v2
	v_add_f32_e32 v3, 1.0, v3
	v_add_f32_e32 v4, 1.0, v4
	v_add_f32_e32 v5, 1.0, v5
	v_rcp_f32_e32 v2, v2
	v_rcp_f32_e32 v3, v3
	v_rcp_f32_e32 v4, v4
	v_rcp_f32_e32 v5, v5
	v_cvt_pk_bf16_f32 v2, v2, v3
	v_cvt_pk_bf16_f32 v3, v4, v5
	v_or_b32_e32 v4, v6, v102
	v_ashrrev_i32_e32 v5, 31, v4
	v_lshlrev_b64 v[4:5], 11, v[4:5]
	v_lshl_add_u64 v[4:5], v[0:1], 0, v[4:5]
	flat_store_dwordx2 v[4:5], v[2:3]
	ds_read_b128 v[2:5], v98 offset:2176
	s_waitcnt lgkmcnt(0)
	v_mul_f32_e32 v2, 0xbfb8aa3b, v2
	v_mul_f32_e32 v3, 0xbfb8aa3b, v3
	v_mul_f32_e32 v4, 0xbfb8aa3b, v4
	v_mul_f32_e32 v5, 0xbfb8aa3b, v5
	v_exp_f32_e32 v2, v2
	v_exp_f32_e32 v3, v3
	v_exp_f32_e32 v4, v4
	v_exp_f32_e32 v5, v5
	v_add_f32_e32 v2, 1.0, v2
	v_add_f32_e32 v3, 1.0, v3
	v_add_f32_e32 v4, 1.0, v4
	v_add_f32_e32 v5, 1.0, v5
	v_rcp_f32_e32 v2, v2
	v_rcp_f32_e32 v3, v3
	v_rcp_f32_e32 v4, v4
	v_rcp_f32_e32 v5, v5
	v_cvt_pk_bf16_f32 v2, v2, v3
	v_cvt_pk_bf16_f32 v3, v4, v5
	v_or_b32_e32 v4, v6, v103
	v_ashrrev_i32_e32 v5, 31, v4
	v_lshlrev_b64 v[4:5], 11, v[4:5]
	v_lshl_add_u64 v[4:5], v[0:1], 0, v[4:5]
	flat_store_dwordx2 v[4:5], v[2:3]
	ds_read_b128 v[2:5], v98 offset:3264
	s_waitcnt lgkmcnt(0)
	v_mul_f32_e32 v2, 0xbfb8aa3b, v2
	v_mul_f32_e32 v3, 0xbfb8aa3b, v3
	v_mul_f32_e32 v4, 0xbfb8aa3b, v4
	v_mul_f32_e32 v5, 0xbfb8aa3b, v5
	v_exp_f32_e32 v2, v2
	v_exp_f32_e32 v3, v3
	v_exp_f32_e32 v4, v4
	v_exp_f32_e32 v5, v5
	v_add_f32_e32 v2, 1.0, v2
	v_add_f32_e32 v3, 1.0, v3
	v_add_f32_e32 v4, 1.0, v4
	v_add_f32_e32 v5, 1.0, v5
	v_rcp_f32_e32 v2, v2
	v_rcp_f32_e32 v3, v3
	v_rcp_f32_e32 v4, v4
	v_rcp_f32_e32 v5, v5
	v_cvt_pk_bf16_f32 v2, v2, v3
	v_cvt_pk_bf16_f32 v3, v4, v5
	v_or_b32_e32 v4, v6, v104
	v_ashrrev_i32_e32 v5, 31, v4
	v_lshlrev_b64 v[4:5], 11, v[4:5]
	v_lshl_add_u64 v[4:5], v[0:1], 0, v[4:5]
	flat_store_dwordx2 v[4:5], v[2:3]
	ds_read_b128 v[2:5], v98 offset:4352
	s_waitcnt lgkmcnt(0)
	v_mul_f32_e32 v2, 0xbfb8aa3b, v2
	v_mul_f32_e32 v3, 0xbfb8aa3b, v3
	v_mul_f32_e32 v4, 0xbfb8aa3b, v4
	v_mul_f32_e32 v5, 0xbfb8aa3b, v5
	v_exp_f32_e32 v2, v2
	v_exp_f32_e32 v3, v3
	v_exp_f32_e32 v4, v4
	v_exp_f32_e32 v5, v5
	v_add_f32_e32 v2, 1.0, v2
	v_add_f32_e32 v3, 1.0, v3
	v_add_f32_e32 v4, 1.0, v4
	v_add_f32_e32 v5, 1.0, v5
	v_rcp_f32_e32 v2, v2
	v_rcp_f32_e32 v3, v3
	v_rcp_f32_e32 v4, v4
	v_rcp_f32_e32 v5, v5
	v_cvt_pk_bf16_f32 v2, v2, v3
	v_cvt_pk_bf16_f32 v3, v4, v5
	v_or_b32_e32 v4, v6, v105
	v_ashrrev_i32_e32 v5, 31, v4
	v_lshlrev_b64 v[4:5], 11, v[4:5]
	v_lshl_add_u64 v[4:5], v[0:1], 0, v[4:5]
	flat_store_dwordx2 v[4:5], v[2:3]
	ds_read_b128 v[2:5], v98 offset:5440
	s_waitcnt lgkmcnt(0)
	v_mul_f32_e32 v2, 0xbfb8aa3b, v2
	v_mul_f32_e32 v3, 0xbfb8aa3b, v3
	v_mul_f32_e32 v4, 0xbfb8aa3b, v4
	v_mul_f32_e32 v5, 0xbfb8aa3b, v5
	v_exp_f32_e32 v2, v2
	v_exp_f32_e32 v3, v3
	v_exp_f32_e32 v4, v4
	v_exp_f32_e32 v5, v5
	v_add_f32_e32 v2, 1.0, v2
	v_add_f32_e32 v3, 1.0, v3
	v_add_f32_e32 v4, 1.0, v4
	v_add_f32_e32 v5, 1.0, v5
	v_rcp_f32_e32 v2, v2
	v_rcp_f32_e32 v3, v3
	v_rcp_f32_e32 v4, v4
	v_rcp_f32_e32 v5, v5
	v_cvt_pk_bf16_f32 v2, v2, v3
	v_cvt_pk_bf16_f32 v3, v4, v5
	v_or_b32_e32 v4, v6, v106
	v_ashrrev_i32_e32 v5, 31, v4
	v_lshlrev_b64 v[4:5], 11, v[4:5]
	v_lshl_add_u64 v[4:5], v[0:1], 0, v[4:5]
	flat_store_dwordx2 v[4:5], v[2:3]
	ds_read_b128 v[2:5], v98 offset:6528
	s_waitcnt lgkmcnt(0)
	v_mul_f32_e32 v2, 0xbfb8aa3b, v2
	v_mul_f32_e32 v3, 0xbfb8aa3b, v3
	v_mul_f32_e32 v4, 0xbfb8aa3b, v4
	v_mul_f32_e32 v5, 0xbfb8aa3b, v5
	v_exp_f32_e32 v2, v2
	v_exp_f32_e32 v3, v3
	v_exp_f32_e32 v4, v4
	v_exp_f32_e32 v5, v5
	v_add_f32_e32 v2, 1.0, v2
	v_add_f32_e32 v3, 1.0, v3
	v_add_f32_e32 v4, 1.0, v4
	v_add_f32_e32 v5, 1.0, v5
	v_rcp_f32_e32 v2, v2
	v_rcp_f32_e32 v3, v3
	v_rcp_f32_e32 v4, v4
	v_rcp_f32_e32 v5, v5
	v_cvt_pk_bf16_f32 v2, v2, v3
	v_cvt_pk_bf16_f32 v3, v4, v5
	v_or_b32_e32 v4, v6, v107
	v_ashrrev_i32_e32 v5, 31, v4
	v_lshlrev_b64 v[4:5], 11, v[4:5]
	v_lshl_add_u64 v[4:5], v[0:1], 0, v[4:5]
	flat_store_dwordx2 v[4:5], v[2:3]
	ds_read_b128 v[2:5], v98 offset:7616
	v_mov_b32_e32 v98, v132
	s_waitcnt lgkmcnt(0)
	v_mul_f32_e32 v2, 0xbfb8aa3b, v2
	v_mul_f32_e32 v3, 0xbfb8aa3b, v3
	v_mul_f32_e32 v4, 0xbfb8aa3b, v4
	v_mul_f32_e32 v5, 0xbfb8aa3b, v5
	v_exp_f32_e32 v2, v2
	v_exp_f32_e32 v3, v3
	v_exp_f32_e32 v4, v4
	v_exp_f32_e32 v5, v5
	v_add_f32_e32 v2, 1.0, v2
	v_add_f32_e32 v3, 1.0, v3
	v_add_f32_e32 v4, 1.0, v4
	v_add_f32_e32 v5, 1.0, v5
	v_rcp_f32_e32 v2, v2
	v_rcp_f32_e32 v3, v3
	v_rcp_f32_e32 v4, v4
	v_rcp_f32_e32 v5, v5
	v_cvt_pk_bf16_f32 v2, v2, v3
	v_cvt_pk_bf16_f32 v3, v4, v5
	v_or_b32_e32 v4, v6, v108
	v_ashrrev_i32_e32 v5, 31, v4
	v_lshlrev_b64 v[4:5], 11, v[4:5]
	v_lshl_add_u64 v[0:1], v[0:1], 0, v[4:5]
	flat_store_dwordx2 v[0:1], v[2:3]
	v_mov_b32_e32 v0, s3
	ds_read_b128 v[0:3], v0
	s_waitcnt lgkmcnt(0)
	v_lshl_add_u64 v[4:5], v[2:3], 0, s[42:43]
	s_lshl_b64 s[42:43], s[30:31], 10
	v_lshl_add_u64 v[2:3], v[2:3], 0, s[42:43]
	v_lshl_add_u64 v[16:17], v[2:3], 0, s[12:13]
	v_lshlrev_b32_e32 v2, 4, v20
	v_and_b32_e32 v3, 32, v20
	v_bitop3_b32 v3, v2, v3, 48 bitop3:0x6c
	v_lshl_add_u64 v[14:15], v[4:5], 0, s[10:11]
	v_lshrrev_b32_e32 v5, 1, v20
	v_lshrrev_b32_e32 v3, 1, v3
	v_bfe_u32 v4, v20, 2, 4
	v_and_or_b32 v3, v5, 32, v3
	v_lshrrev_b32_e32 v5, 3, v20
	v_and_or_b32 v5, v5, s50, v4
	v_lshl_or_b32 v130, v5, 9, v3
	v_add_u32_e32 v5, 0x2000, v2
	v_lshrrev_b32_e32 v5, 7, v5
	v_and_or_b32 v5, v5, s50, v4
	v_lshl_or_b32 v6, v5, 9, v3
	v_add_u32_e32 v5, 0x4000, v2
	v_and_b32_e32 v21, 0xfffffc00, v2
	v_lshrrev_b32_e32 v5, 7, v5
	v_add_u32_e32 v2, 0x6000, v2
	v_and_or_b32 v5, v5, s50, v4
	v_lshrrev_b32_e32 v2, 7, v2
	v_add_u32_e32 v45, 0, v21
	v_lshl_or_b32 v10, v5, 9, v3
	v_and_or_b32 v2, v2, s50, v4
	v_add_u32_e32 v44, 0x8000, v45
	v_lshlrev_b64 v[4:5], 1, v[130:131]
	v_readfirstlane_b32 s60, v45
	v_lshl_or_b32 v18, v2, 9, v3
	v_lshl_add_u64 v[2:3], v[14:15], 0, v[4:5]
	s_mov_b32 m0, s60
	v_readfirstlane_b32 s58, v44
	v_add_u32_e32 v46, 0x2000, v45
	global_load_lds_dwordx4 v[2:3], off
	v_lshl_add_u64 v[4:5], v[16:17], 0, v[4:5]
	s_mov_b32 m0, s58
	v_lshlrev_b64 v[8:9], 1, v[6:7]
	v_readfirstlane_b32 s59, v46
	v_add_u32_e32 v47, 0xa000, v45
	global_load_lds_dwordx4 v[4:5], off
	v_lshl_add_u64 v[6:7], v[14:15], 0, v[8:9]
	s_mov_b32 m0, s59
	v_readfirstlane_b32 s61, v47
	v_add_u32_e32 v48, 0x4000, v45
	global_load_lds_dwordx4 v[6:7], off
	v_lshl_add_u64 v[8:9], v[16:17], 0, v[8:9]
	s_mov_b32 m0, s61
	v_lshlrev_b64 v[12:13], 1, v[10:11]
	v_readfirstlane_b32 s62, v48
	v_add_u32_e32 v49, 0xc000, v45
	v_lshlrev_b64 v[18:19], 1, v[18:19]
	v_and_b32_e32 v22, 15, v20
	global_load_lds_dwordx4 v[8:9], off
	v_lshl_add_u64 v[10:11], v[14:15], 0, v[12:13]
	s_mov_b32 m0, s62
	v_lshl_add_u64 v[12:13], v[16:17], 0, v[12:13]
	v_readfirstlane_b32 s63, v49
	v_lshl_add_u64 v[14:15], v[14:15], 0, v[18:19]
	v_add_u32_e32 v50, 0x6000, v45
	v_lshl_add_u64 v[16:17], v[16:17], 0, v[18:19]
	v_lshlrev_b32_e32 v19, 2, v20
	global_load_lds_dwordx4 v[10:11], off
	s_mov_b32 m0, s63
	v_readfirstlane_b32 s64, v50
	v_add_u32_e32 v51, 0xe000, v45
	v_and_b32_e32 v23, 48, v20
	v_lshlrev_b32_e32 v18, 6, v22
	v_and_b32_e32 v22, 32, v19
	global_load_lds_dwordx4 v[12:13], off
	s_mov_b32 m0, s64
	v_readfirstlane_b32 s65, v51
	v_bitop3_b32 v96, v18, v22, v23 bitop3:0x36
	v_lshlrev_b32_e32 v18, 7, v20
	v_add_u32_e32 v37, s46, v21
	global_load_lds_dwordx4 v[14:15], off
	s_mov_b32 m0, s65
	v_and_b32_e32 v97, 0x6000, v18
	v_lshlrev_b32_e32 v18, 6, v20
	v_add_u32_e32 v36, s47, v21
	v_readfirstlane_b32 s53, v37
	global_load_lds_dwordx4 v[16:17], off
	v_and_b32_e32 v99, 0xffffc000, v18
	v_and_b32_e32 v20, 0x3c0, v18
	v_lshl_add_u64 v[18:19], v[2:3], 0, s[6:7]
	s_mov_b32 m0, s53
	v_readfirstlane_b32 s0, v36
	v_add_u32_e32 v38, 0x2000, v37
	s_waitcnt vmcnt(0)
	s_waitcnt vmcnt(0) lgkmcnt(0)
	s_barrier
	global_load_lds_dwordx4 v[18:19], off
	v_lshl_add_u64 v[18:19], v[4:5], 0, s[6:7]
	s_mov_b32 m0, s0
	v_readfirstlane_b32 s42, v38
	v_add_u32_e32 v39, 0x2000, v36
	global_load_lds_dwordx4 v[18:19], off
	v_lshl_add_u64 v[18:19], v[6:7], 0, s[6:7]
	s_mov_b32 m0, s42
	v_readfirstlane_b32 s43, v39
	v_add_u32_e32 v40, 0x4000, v37
	global_load_lds_dwordx4 v[18:19], off
	v_lshl_add_u64 v[18:19], v[8:9], 0, s[6:7]
	s_mov_b32 m0, s43
	v_readfirstlane_b32 s54, v40
	v_add_u32_e32 v41, 0x4000, v36
	global_load_lds_dwordx4 v[18:19], off
	v_lshl_add_u64 v[18:19], v[10:11], 0, s[6:7]
	s_mov_b32 m0, s54
	v_readfirstlane_b32 s55, v41
	v_add_u32_e32 v42, 0x6000, v37
	global_load_lds_dwordx4 v[18:19], off
	v_lshl_add_u64 v[18:19], v[12:13], 0, s[6:7]
	s_mov_b32 m0, s55
	v_readfirstlane_b32 s56, v42
	v_add_u32_e32 v43, 0x6000, v36
	global_load_lds_dwordx4 v[18:19], off
	v_lshl_add_u64 v[18:19], v[14:15], 0, s[6:7]
	s_mov_b32 m0, s56
	v_readfirstlane_b32 s57, v43
	global_load_lds_dwordx4 v[18:19], off
	v_lshl_add_u64 v[18:19], v[16:17], 0, s[6:7]
	s_mov_b32 m0, s57
	v_add_u32_e32 v129, 0, v96
	global_load_lds_dwordx4 v[18:19], off
	v_add_u32_e32 v18, v129, v97
	ds_read_b128 v[24:27], v18 offset:32768
	ds_read_b128 v[56:59], v18 offset:34816
	ds_read_b128 v[64:67], v18 offset:36864
	ds_read_b128 v[72:75], v18 offset:38912
	v_bitop3_b32 v130, v20, v22, v23 bitop3:0x36
	v_add_u32_e32 v23, 0, v130
	v_or_b32_e32 v222, 0x3000, v99
	v_add_u32_e32 v20, v23, v222
	ds_read_b128 v[32:35], v20
	v_or_b32_e32 v223, 0x2800, v99
	v_add_u32_e32 v21, v23, v223
	s_waitcnt lgkmcnt(0)
	v_mfma_f32_16x16x32_bf16 v[76:79], v[24:27], v[32:35], 0
	v_or_b32_e32 v128, 0x3800, v99
	v_or_b32_e32 v218, 0x2000, v99
	v_or_b32_e32 v219, 0x1000, v99
	v_mfma_f32_16x16x32_bf16 v[80:83], v[56:59], v[32:35], 0
	v_or_b32_e32 v220, 0x1800, v99
	v_add_u32_e32 v19, v23, v128
	v_add_u32_e32 v22, v23, v218
	v_mfma_f32_16x16x32_bf16 v[84:87], v[64:67], v[32:35], 0
	ds_read_b128 v[28:31], v19
	ds_read_b128 v[112:115], v22
	v_mfma_f32_16x16x32_bf16 v[88:91], v[72:75], v[32:35], 0
	ds_read_b128 v[32:35], v21
	s_waitcnt lgkmcnt(0)
	v_mfma_f32_16x16x32_bf16 v[92:95], v[24:27], v[32:35], 0
	v_mfma_f32_16x16x32_bf16 v[100:103], v[56:59], v[32:35], 0
	v_mfma_f32_16x16x32_bf16 v[104:107], v[64:67], v[32:35], 0
	v_mfma_f32_16x16x32_bf16 v[108:111], v[72:75], v[32:35], 0
	v_add_u32_e32 v32, v129, v99
	v_or_b32_e32 v129, 0x800, v99
	v_add_u32_e32 v33, v23, v129
	v_add_u32_e32 v34, v23, v219
	v_add_u32_e32 v35, v23, v220
	ds_read_b128 v[134:137], v32
	ds_read_b128 v[150:153], v33
	ds_read_b128 v[166:169], v34
	ds_read_b128 v[182:185], v35
	s_waitcnt lgkmcnt(0)
	v_mfma_f32_16x16x32_bf16 v[178:181], v[64:67], v[166:169], 0
	v_mfma_f32_16x16x32_bf16 v[162:165], v[64:67], v[150:153], 0
	v_mfma_f32_16x16x32_bf16 v[146:149], v[64:67], v[134:137], 0
	v_mfma_f32_16x16x32_bf16 v[68:71], v[64:67], v[28:31], 0
	v_mfma_f32_16x16x32_bf16 v[124:127], v[64:67], v[112:115], 0
	v_mfma_f32_16x16x32_bf16 v[64:67], v[64:67], v[182:185], 0
	v_mfma_f32_16x16x32_bf16 v[174:177], v[56:59], v[166:169], 0
	v_mfma_f32_16x16x32_bf16 v[158:161], v[56:59], v[150:153], 0
	v_mfma_f32_16x16x32_bf16 v[142:145], v[56:59], v[134:137], 0
	v_mfma_f32_16x16x32_bf16 v[60:63], v[56:59], v[28:31], 0
	v_mfma_f32_16x16x32_bf16 v[120:123], v[56:59], v[112:115], 0
	v_mfma_f32_16x16x32_bf16 v[56:59], v[56:59], v[182:185], 0
	v_mfma_f32_16x16x32_bf16 v[170:173], v[24:27], v[166:169], 0
	v_mfma_f32_16x16x32_bf16 v[154:157], v[24:27], v[150:153], 0
	v_mfma_f32_16x16x32_bf16 v[138:141], v[24:27], v[134:137], 0
	v_mfma_f32_16x16x32_bf16 v[52:55], v[24:27], v[28:31], 0
	v_mfma_f32_16x16x32_bf16 v[116:119], v[24:27], v[112:115], 0
	v_mfma_f32_16x16x32_bf16 v[24:27], v[24:27], v[182:185], 0
	v_mfma_f32_16x16x32_bf16 v[166:169], v[72:75], v[166:169], 0
	v_mfma_f32_16x16x32_bf16 v[150:153], v[72:75], v[150:153], 0
	v_mfma_f32_16x16x32_bf16 v[134:137], v[72:75], v[134:137], 0
	v_mfma_f32_16x16x32_bf16 v[28:31], v[72:75], v[28:31], 0
	v_mfma_f32_16x16x32_bf16 v[112:115], v[72:75], v[112:115], 0
	v_mfma_f32_16x16x32_bf16 v[72:75], v[72:75], v[182:185], 0
	ds_read_b128 v[182:185], v18 offset:33792
	ds_read_b128 v[186:189], v18 offset:35840
	ds_read_b128 v[190:193], v18 offset:37888
	ds_read_b128 v[198:201], v18 offset:39936
	ds_read_b128 v[194:197], v32 offset:1024
	ds_read_b128 v[202:205], v33 offset:1024
	ds_read_b128 v[206:209], v34 offset:1024
	ds_read_b128 v[210:213], v35 offset:1024
	s_waitcnt lgkmcnt(0)
	v_mfma_f32_16x16x32_bf16 v[138:141], v[182:185], v[194:197], v[138:141]
	v_mfma_f32_16x16x32_bf16 v[142:145], v[186:189], v[194:197], v[142:145]
	v_mfma_f32_16x16x32_bf16 v[146:149], v[190:193], v[194:197], v[146:149]
	v_mfma_f32_16x16x32_bf16 v[134:137], v[198:201], v[194:197], v[134:137]
	ds_read_b128 v[194:197], v22 offset:1024
	v_mfma_f32_16x16x32_bf16 v[154:157], v[182:185], v[202:205], v[154:157]
	v_mfma_f32_16x16x32_bf16 v[158:161], v[186:189], v[202:205], v[158:161]
	v_mfma_f32_16x16x32_bf16 v[162:165], v[190:193], v[202:205], v[162:165]
	v_mfma_f32_16x16x32_bf16 v[150:153], v[198:201], v[202:205], v[150:153]
	ds_read_b128 v[202:205], v21 offset:1024
	v_mfma_f32_16x16x32_bf16 v[170:173], v[182:185], v[206:209], v[170:173]
	v_mfma_f32_16x16x32_bf16 v[174:177], v[186:189], v[206:209], v[174:177]
	v_mfma_f32_16x16x32_bf16 v[178:181], v[190:193], v[206:209], v[178:181]
	v_mfma_f32_16x16x32_bf16 v[166:169], v[198:201], v[206:209], v[166:169]
	ds_read_b128 v[206:209], v20 offset:1024
	v_mfma_f32_16x16x32_bf16 v[214:217], v[182:185], v[210:213], v[24:27]
	v_mfma_f32_16x16x32_bf16 v[56:59], v[186:189], v[210:213], v[56:59]
	v_mfma_f32_16x16x32_bf16 v[64:67], v[190:193], v[210:213], v[64:67]
	v_mfma_f32_16x16x32_bf16 v[72:75], v[198:201], v[210:213], v[72:75]
	ds_read_b128 v[24:27], v19 offset:1024
	s_waitcnt lgkmcnt(0)
	v_mfma_f32_16x16x32_bf16 v[116:119], v[182:185], v[194:197], v[116:119]
	v_mfma_f32_16x16x32_bf16 v[120:123], v[186:189], v[194:197], v[120:123]
	v_mfma_f32_16x16x32_bf16 v[124:127], v[190:193], v[194:197], v[124:127]
	v_mfma_f32_16x16x32_bf16 v[112:115], v[198:201], v[194:197], v[112:115]
	v_mfma_f32_16x16x32_bf16 v[92:95], v[182:185], v[202:205], v[92:95]
	v_mfma_f32_16x16x32_bf16 v[100:103], v[186:189], v[202:205], v[100:103]
	v_mfma_f32_16x16x32_bf16 v[104:107], v[190:193], v[202:205], v[104:107]
	v_mfma_f32_16x16x32_bf16 v[108:111], v[198:201], v[202:205], v[108:111]
	v_mfma_f32_16x16x32_bf16 v[76:79], v[182:185], v[206:209], v[76:79]
	v_mfma_f32_16x16x32_bf16 v[80:83], v[186:189], v[206:209], v[80:83]
	v_mfma_f32_16x16x32_bf16 v[84:87], v[190:193], v[206:209], v[84:87]
	v_mfma_f32_16x16x32_bf16 v[88:91], v[198:201], v[206:209], v[88:91]
	v_mfma_f32_16x16x32_bf16 v[52:55], v[182:185], v[24:27], v[52:55]
	v_mfma_f32_16x16x32_bf16 v[60:63], v[186:189], v[24:27], v[60:63]
	v_mfma_f32_16x16x32_bf16 v[68:71], v[190:193], v[24:27], v[68:71]
	v_mfma_f32_16x16x32_bf16 v[182:185], v[198:201], v[24:27], v[28:31]
	s_mov_b32 m0, s60
	v_lshl_add_u64 v[24:25], v[2:3], 0, s[14:15]
	s_waitcnt vmcnt(0)
	s_waitcnt vmcnt(0)
	s_barrier
	global_load_lds_dwordx4 v[24:25], off
	v_lshl_add_u64 v[24:25], v[4:5], 0, s[14:15]
	s_mov_b32 m0, s58
	v_add3_u32 v23, s47, v96, v97
	global_load_lds_dwordx4 v[24:25], off
	v_lshl_add_u64 v[24:25], v[6:7], 0, s[14:15]
	s_mov_b32 m0, s59
	s_nop 0
	global_load_lds_dwordx4 v[24:25], off
	v_lshl_add_u64 v[24:25], v[8:9], 0, s[14:15]
	s_mov_b32 m0, s61
	s_nop 0
	global_load_lds_dwordx4 v[24:25], off
	v_lshl_add_u64 v[24:25], v[10:11], 0, s[14:15]
	s_mov_b32 m0, s62
	s_nop 0
	global_load_lds_dwordx4 v[24:25], off
	v_lshl_add_u64 v[24:25], v[12:13], 0, s[14:15]
	s_mov_b32 m0, s63
	s_nop 0
	global_load_lds_dwordx4 v[24:25], off
	v_lshl_add_u64 v[24:25], v[14:15], 0, s[14:15]
	s_mov_b32 m0, s64
	s_nop 0
	global_load_lds_dwordx4 v[24:25], off
	v_lshl_add_u64 v[24:25], v[16:17], 0, s[14:15]
	s_mov_b32 m0, s65
	s_nop 0
	global_load_lds_dwordx4 v[24:25], off
	ds_read_b128 v[186:189], v23
	ds_read_b128 v[190:193], v23 offset:2048
	ds_read_b128 v[194:197], v23 offset:4096
	ds_read_b128 v[198:201], v23 offset:6144
	v_add3_u32 v24, s46, v96, v99
	v_add_u32_e32 v96, s46, v130
	ds_read_b128 v[28:31], v24
	v_add_u32_e32 v25, v96, v129
	v_add_u32_e32 v26, v96, v219
	v_add_u32_e32 v27, v96, v220
	ds_read_b128 v[202:205], v25
	ds_read_b128 v[206:209], v26
	ds_read_b128 v[210:213], v27
	s_waitcnt lgkmcnt(0)
	v_mfma_f32_16x16x32_bf16 v[138:141], v[186:189], v[28:31], v[138:141]
	v_mfma_f32_16x16x32_bf16 v[142:145], v[190:193], v[28:31], v[142:145]
	v_mfma_f32_16x16x32_bf16 v[146:149], v[194:197], v[28:31], v[146:149]
	v_mfma_f32_16x16x32_bf16 v[134:137], v[198:201], v[28:31], v[134:137]
	v_add_u32_e32 v28, v96, v218
	v_add_u32_e32 v29, v96, v223
	v_add_u32_e32 v30, v96, v222
	v_add_u32_e32 v31, v96, v128
	ds_read_b128 v[218:221], v28
	v_mfma_f32_16x16x32_bf16 v[154:157], v[186:189], v[202:205], v[154:157]
	v_mfma_f32_16x16x32_bf16 v[158:161], v[190:193], v[202:205], v[158:161]
	v_mfma_f32_16x16x32_bf16 v[162:165], v[194:197], v[202:205], v[162:165]
	v_mfma_f32_16x16x32_bf16 v[150:153], v[198:201], v[202:205], v[150:153]
	ds_read_b128 v[202:205], v29
	v_mfma_f32_16x16x32_bf16 v[170:173], v[186:189], v[206:209], v[170:173]
	v_mfma_f32_16x16x32_bf16 v[174:177], v[190:193], v[206:209], v[174:177]
	v_mfma_f32_16x16x32_bf16 v[178:181], v[194:197], v[206:209], v[178:181]
	v_mfma_f32_16x16x32_bf16 v[166:169], v[198:201], v[206:209], v[166:169]
	ds_read_b128 v[206:209], v30
	v_mfma_f32_16x16x32_bf16 v[214:217], v[186:189], v[210:213], v[214:217]
	v_mfma_f32_16x16x32_bf16 v[56:59], v[190:193], v[210:213], v[56:59]
	v_mfma_f32_16x16x32_bf16 v[64:67], v[194:197], v[210:213], v[64:67]
	v_mfma_f32_16x16x32_bf16 v[72:75], v[198:201], v[210:213], v[72:75]
	ds_read_b128 v[210:213], v31
	s_waitcnt lgkmcnt(0)
	v_mfma_f32_16x16x32_bf16 v[116:119], v[186:189], v[218:221], v[116:119]
	v_mfma_f32_16x16x32_bf16 v[120:123], v[190:193], v[218:221], v[120:123]
	v_mfma_f32_16x16x32_bf16 v[124:127], v[194:197], v[218:221], v[124:127]
	v_mfma_f32_16x16x32_bf16 v[112:115], v[198:201], v[218:221], v[112:115]
	v_mfma_f32_16x16x32_bf16 v[92:95], v[186:189], v[202:205], v[92:95]
	v_mfma_f32_16x16x32_bf16 v[100:103], v[190:193], v[202:205], v[100:103]
	v_mfma_f32_16x16x32_bf16 v[104:107], v[194:197], v[202:205], v[104:107]
	v_mfma_f32_16x16x32_bf16 v[108:111], v[198:201], v[202:205], v[108:111]
	v_mfma_f32_16x16x32_bf16 v[76:79], v[186:189], v[206:209], v[76:79]
	v_mfma_f32_16x16x32_bf16 v[80:83], v[190:193], v[206:209], v[80:83]
	v_mfma_f32_16x16x32_bf16 v[84:87], v[194:197], v[206:209], v[84:87]
	v_mfma_f32_16x16x32_bf16 v[88:91], v[198:201], v[206:209], v[88:91]
	v_mfma_f32_16x16x32_bf16 v[52:55], v[186:189], v[210:213], v[52:55]
	v_mfma_f32_16x16x32_bf16 v[60:63], v[190:193], v[210:213], v[60:63]
	v_mfma_f32_16x16x32_bf16 v[68:71], v[194:197], v[210:213], v[68:71]
	v_mfma_f32_16x16x32_bf16 v[182:185], v[198:201], v[210:213], v[182:185]
	ds_read_b128 v[186:189], v23 offset:1024
	ds_read_b128 v[190:193], v23 offset:3072
	ds_read_b128 v[194:197], v23 offset:5120
	ds_read_b128 v[202:205], v23 offset:7168
	ds_read_b128 v[198:201], v24 offset:1024
	ds_read_b128 v[206:209], v25 offset:1024
	ds_read_b128 v[210:213], v26 offset:1024
	ds_read_b128 v[218:221], v27 offset:1024
	s_waitcnt lgkmcnt(0)
	v_mfma_f32_16x16x32_bf16 v[138:141], v[186:189], v[198:201], v[138:141]
	v_mfma_f32_16x16x32_bf16 v[142:145], v[190:193], v[198:201], v[142:145]
	v_mfma_f32_16x16x32_bf16 v[146:149], v[194:197], v[198:201], v[146:149]
	v_mfma_f32_16x16x32_bf16 v[134:137], v[202:205], v[198:201], v[134:137]
	ds_read_b128 v[198:201], v28 offset:1024
	v_mfma_f32_16x16x32_bf16 v[154:157], v[186:189], v[206:209], v[154:157]
	v_mfma_f32_16x16x32_bf16 v[158:161], v[190:193], v[206:209], v[158:161]
	v_mfma_f32_16x16x32_bf16 v[162:165], v[194:197], v[206:209], v[162:165]
	v_mfma_f32_16x16x32_bf16 v[150:153], v[202:205], v[206:209], v[150:153]
	ds_read_b128 v[206:209], v29 offset:1024
	v_mfma_f32_16x16x32_bf16 v[170:173], v[186:189], v[210:213], v[170:173]
	v_mfma_f32_16x16x32_bf16 v[174:177], v[190:193], v[210:213], v[174:177]
	v_mfma_f32_16x16x32_bf16 v[178:181], v[194:197], v[210:213], v[178:181]
	v_mfma_f32_16x16x32_bf16 v[166:169], v[202:205], v[210:213], v[166:169]
	ds_read_b128 v[210:213], v30 offset:1024
	v_mfma_f32_16x16x32_bf16 v[214:217], v[186:189], v[218:221], v[214:217]
	v_mfma_f32_16x16x32_bf16 v[56:59], v[190:193], v[218:221], v[56:59]
	v_mfma_f32_16x16x32_bf16 v[64:67], v[194:197], v[218:221], v[64:67]
	v_mfma_f32_16x16x32_bf16 v[72:75], v[202:205], v[218:221], v[72:75]
	ds_read_b128 v[218:221], v31 offset:1024
	s_waitcnt lgkmcnt(0)
	v_mfma_f32_16x16x32_bf16 v[116:119], v[186:189], v[198:201], v[116:119]
	v_mfma_f32_16x16x32_bf16 v[120:123], v[190:193], v[198:201], v[120:123]
	v_mfma_f32_16x16x32_bf16 v[124:127], v[194:197], v[198:201], v[124:127]
	v_mfma_f32_16x16x32_bf16 v[112:115], v[202:205], v[198:201], v[112:115]
	v_mfma_f32_16x16x32_bf16 v[92:95], v[186:189], v[206:209], v[92:95]
	v_mfma_f32_16x16x32_bf16 v[100:103], v[190:193], v[206:209], v[100:103]
	v_mfma_f32_16x16x32_bf16 v[104:107], v[194:197], v[206:209], v[104:107]
	v_mfma_f32_16x16x32_bf16 v[108:111], v[202:205], v[206:209], v[108:111]
	v_mfma_f32_16x16x32_bf16 v[76:79], v[186:189], v[210:213], v[76:79]
	v_mfma_f32_16x16x32_bf16 v[80:83], v[190:193], v[210:213], v[80:83]
	v_mfma_f32_16x16x32_bf16 v[84:87], v[194:197], v[210:213], v[84:87]
	v_mfma_f32_16x16x32_bf16 v[88:91], v[202:205], v[210:213], v[88:91]
	v_mfma_f32_16x16x32_bf16 v[52:55], v[186:189], v[218:221], v[52:55]
	v_mfma_f32_16x16x32_bf16 v[60:63], v[190:193], v[218:221], v[60:63]
	v_mfma_f32_16x16x32_bf16 v[68:71], v[194:197], v[218:221], v[68:71]
	v_mfma_f32_16x16x32_bf16 v[182:185], v[202:205], v[218:221], v[182:185]
	s_mov_b32 m0, s53
	v_lshl_add_u64 v[96:97], v[2:3], 0, s[16:17]
	s_waitcnt vmcnt(0)
	s_waitcnt vmcnt(0)
	s_barrier
	global_load_lds_dwordx4 v[96:97], off
	v_lshl_add_u64 v[96:97], v[4:5], 0, s[16:17]
	s_mov_b32 m0, s0
	s_nop 0
	global_load_lds_dwordx4 v[96:97], off
	v_lshl_add_u64 v[96:97], v[6:7], 0, s[16:17]
	s_mov_b32 m0, s42
	s_nop 0
	global_load_lds_dwordx4 v[96:97], off
	v_lshl_add_u64 v[96:97], v[8:9], 0, s[16:17]
	s_mov_b32 m0, s43
	s_nop 0
	global_load_lds_dwordx4 v[96:97], off
	v_lshl_add_u64 v[96:97], v[10:11], 0, s[16:17]
	s_mov_b32 m0, s54
	s_nop 0
	global_load_lds_dwordx4 v[96:97], off
	v_lshl_add_u64 v[96:97], v[12:13], 0, s[16:17]
	s_mov_b32 m0, s55
	s_nop 0
	global_load_lds_dwordx4 v[96:97], off
	v_lshl_add_u64 v[96:97], v[14:15], 0, s[16:17]
	s_mov_b32 m0, s56
	s_nop 0
	global_load_lds_dwordx4 v[96:97], off
	v_lshl_add_u64 v[96:97], v[16:17], 0, s[16:17]
	s_mov_b32 m0, s57
	s_nop 0
	global_load_lds_dwordx4 v[96:97], off
	ds_read_b128 v[186:189], v18 offset:32768
	ds_read_b128 v[190:193], v18 offset:34816
	ds_read_b128 v[194:197], v18 offset:36864
	ds_read_b128 v[202:205], v18 offset:38912
	ds_read_b128 v[198:201], v32
	ds_read_b128 v[206:209], v33
	ds_read_b128 v[210:213], v34
	ds_read_b128 v[218:221], v35
	s_waitcnt lgkmcnt(0)
	v_mfma_f32_16x16x32_bf16 v[138:141], v[186:189], v[198:201], v[138:141]
	v_mfma_f32_16x16x32_bf16 v[142:145], v[190:193], v[198:201], v[142:145]
	v_mfma_f32_16x16x32_bf16 v[146:149], v[194:197], v[198:201], v[146:149]
	v_mfma_f32_16x16x32_bf16 v[134:137], v[202:205], v[198:201], v[134:137]
	ds_read_b128 v[198:201], v22
	v_mfma_f32_16x16x32_bf16 v[154:157], v[186:189], v[206:209], v[154:157]
	v_mfma_f32_16x16x32_bf16 v[158:161], v[190:193], v[206:209], v[158:161]
	v_mfma_f32_16x16x32_bf16 v[162:165], v[194:197], v[206:209], v[162:165]
	v_mfma_f32_16x16x32_bf16 v[150:153], v[202:205], v[206:209], v[150:153]
	ds_read_b128 v[206:209], v21
	v_mfma_f32_16x16x32_bf16 v[170:173], v[186:189], v[210:213], v[170:173]
	v_mfma_f32_16x16x32_bf16 v[174:177], v[190:193], v[210:213], v[174:177]
	v_mfma_f32_16x16x32_bf16 v[178:181], v[194:197], v[210:213], v[178:181]
	v_mfma_f32_16x16x32_bf16 v[166:169], v[202:205], v[210:213], v[166:169]
	ds_read_b128 v[210:213], v20
	v_mfma_f32_16x16x32_bf16 v[214:217], v[186:189], v[218:221], v[214:217]
	v_mfma_f32_16x16x32_bf16 v[56:59], v[190:193], v[218:221], v[56:59]
	v_mfma_f32_16x16x32_bf16 v[64:67], v[194:197], v[218:221], v[64:67]
	v_mfma_f32_16x16x32_bf16 v[72:75], v[202:205], v[218:221], v[72:75]
	ds_read_b128 v[218:221], v19
	s_waitcnt lgkmcnt(0)
	v_mfma_f32_16x16x32_bf16 v[116:119], v[186:189], v[198:201], v[116:119]
	v_mfma_f32_16x16x32_bf16 v[120:123], v[190:193], v[198:201], v[120:123]
	v_mfma_f32_16x16x32_bf16 v[124:127], v[194:197], v[198:201], v[124:127]
	v_mfma_f32_16x16x32_bf16 v[112:115], v[202:205], v[198:201], v[112:115]
	v_mfma_f32_16x16x32_bf16 v[92:95], v[186:189], v[206:209], v[92:95]
	v_mfma_f32_16x16x32_bf16 v[100:103], v[190:193], v[206:209], v[100:103]
	v_mfma_f32_16x16x32_bf16 v[104:107], v[194:197], v[206:209], v[104:107]
	v_mfma_f32_16x16x32_bf16 v[108:111], v[202:205], v[206:209], v[108:111]
	v_mfma_f32_16x16x32_bf16 v[76:79], v[186:189], v[210:213], v[76:79]
	v_mfma_f32_16x16x32_bf16 v[80:83], v[190:193], v[210:213], v[80:83]
	v_mfma_f32_16x16x32_bf16 v[84:87], v[194:197], v[210:213], v[84:87]
	v_mfma_f32_16x16x32_bf16 v[88:91], v[202:205], v[210:213], v[88:91]
	v_mfma_f32_16x16x32_bf16 v[52:55], v[186:189], v[218:221], v[52:55]
	v_mfma_f32_16x16x32_bf16 v[60:63], v[190:193], v[218:221], v[60:63]
	v_mfma_f32_16x16x32_bf16 v[68:71], v[194:197], v[218:221], v[68:71]
	v_mfma_f32_16x16x32_bf16 v[182:185], v[202:205], v[218:221], v[182:185]
	ds_read_b128 v[186:189], v18 offset:33792
	ds_read_b128 v[190:193], v18 offset:35840
	ds_read_b128 v[194:197], v18 offset:37888
	ds_read_b128 v[202:205], v18 offset:39936
	ds_read_b128 v[198:201], v32 offset:1024
	ds_read_b128 v[206:209], v33 offset:1024
	ds_read_b128 v[210:213], v34 offset:1024
	ds_read_b128 v[218:221], v35 offset:1024
	s_waitcnt lgkmcnt(0)
	v_mfma_f32_16x16x32_bf16 v[138:141], v[186:189], v[198:201], v[138:141]
	v_mfma_f32_16x16x32_bf16 v[142:145], v[190:193], v[198:201], v[142:145]
	v_mfma_f32_16x16x32_bf16 v[146:149], v[194:197], v[198:201], v[146:149]
	v_mfma_f32_16x16x32_bf16 v[134:137], v[202:205], v[198:201], v[134:137]
	ds_read_b128 v[198:201], v22 offset:1024
	v_mfma_f32_16x16x32_bf16 v[154:157], v[186:189], v[206:209], v[154:157]
	v_mfma_f32_16x16x32_bf16 v[158:161], v[190:193], v[206:209], v[158:161]
	v_mfma_f32_16x16x32_bf16 v[162:165], v[194:197], v[206:209], v[162:165]
	v_mfma_f32_16x16x32_bf16 v[150:153], v[202:205], v[206:209], v[150:153]
	ds_read_b128 v[206:209], v21 offset:1024
	v_mfma_f32_16x16x32_bf16 v[170:173], v[186:189], v[210:213], v[170:173]
	v_mfma_f32_16x16x32_bf16 v[174:177], v[190:193], v[210:213], v[174:177]
	v_mfma_f32_16x16x32_bf16 v[178:181], v[194:197], v[210:213], v[178:181]
	v_mfma_f32_16x16x32_bf16 v[166:169], v[202:205], v[210:213], v[166:169]
	ds_read_b128 v[210:213], v20 offset:1024
	v_mfma_f32_16x16x32_bf16 v[214:217], v[186:189], v[218:221], v[214:217]
	v_mfma_f32_16x16x32_bf16 v[56:59], v[190:193], v[218:221], v[56:59]
	v_mfma_f32_16x16x32_bf16 v[64:67], v[194:197], v[218:221], v[64:67]
	v_mfma_f32_16x16x32_bf16 v[72:75], v[202:205], v[218:221], v[72:75]
	ds_read_b128 v[218:221], v19 offset:1024
	s_waitcnt lgkmcnt(0)
	v_mfma_f32_16x16x32_bf16 v[116:119], v[186:189], v[198:201], v[116:119]
	v_mfma_f32_16x16x32_bf16 v[120:123], v[190:193], v[198:201], v[120:123]
	v_mfma_f32_16x16x32_bf16 v[124:127], v[194:197], v[198:201], v[124:127]
	v_mfma_f32_16x16x32_bf16 v[112:115], v[202:205], v[198:201], v[112:115]
	v_mfma_f32_16x16x32_bf16 v[92:95], v[186:189], v[206:209], v[92:95]
	v_mfma_f32_16x16x32_bf16 v[100:103], v[190:193], v[206:209], v[100:103]
	v_mfma_f32_16x16x32_bf16 v[104:107], v[194:197], v[206:209], v[104:107]
	v_mfma_f32_16x16x32_bf16 v[108:111], v[202:205], v[206:209], v[108:111]
	v_mfma_f32_16x16x32_bf16 v[76:79], v[186:189], v[210:213], v[76:79]
	v_mfma_f32_16x16x32_bf16 v[80:83], v[190:193], v[210:213], v[80:83]
	v_mfma_f32_16x16x32_bf16 v[84:87], v[194:197], v[210:213], v[84:87]
	v_mfma_f32_16x16x32_bf16 v[88:91], v[202:205], v[210:213], v[88:91]
	v_mfma_f32_16x16x32_bf16 v[52:55], v[186:189], v[218:221], v[52:55]
	v_mfma_f32_16x16x32_bf16 v[60:63], v[190:193], v[218:221], v[60:63]
	v_mfma_f32_16x16x32_bf16 v[68:71], v[194:197], v[218:221], v[68:71]
	v_mfma_f32_16x16x32_bf16 v[182:185], v[202:205], v[218:221], v[182:185]
	v_readfirstlane_b32 s56, v45
	v_lshl_add_u64 v[96:97], v[2:3], 0, s[18:19]
	s_mov_b32 m0, s56
	v_readfirstlane_b32 s0, v44
	s_waitcnt vmcnt(0)
	s_waitcnt vmcnt(0)
	s_barrier
	global_load_lds_dwordx4 v[96:97], off
	v_lshl_add_u64 v[96:97], v[4:5], 0, s[18:19]
	s_mov_b32 m0, s0
	v_readfirstlane_b32 s42, v46
	global_load_lds_dwordx4 v[96:97], off
	v_lshl_add_u64 v[44:45], v[6:7], 0, s[18:19]
	s_mov_b32 m0, s42
	v_readfirstlane_b32 s43, v47
	global_load_lds_dwordx4 v[44:45], off
	v_lshl_add_u64 v[44:45], v[8:9], 0, s[18:19]
	s_mov_b32 m0, s43
	v_readfirstlane_b32 s53, v48
	global_load_lds_dwordx4 v[44:45], off
	v_lshl_add_u64 v[44:45], v[10:11], 0, s[18:19]
	s_mov_b32 m0, s53
	v_readfirstlane_b32 s54, v49
	global_load_lds_dwordx4 v[44:45], off
	v_lshl_add_u64 v[44:45], v[12:13], 0, s[18:19]
	s_mov_b32 m0, s54
	v_readfirstlane_b32 s55, v50
	global_load_lds_dwordx4 v[44:45], off
	v_lshl_add_u64 v[44:45], v[14:15], 0, s[18:19]
	s_mov_b32 m0, s55
	v_readfirstlane_b32 s57, v51
	global_load_lds_dwordx4 v[44:45], off
	v_lshl_add_u64 v[44:45], v[16:17], 0, s[18:19]
	s_mov_b32 m0, s57
	s_nop 0
	global_load_lds_dwordx4 v[44:45], off
	ds_read_b128 v[44:47], v23
	ds_read_b128 v[48:51], v23 offset:2048
	ds_read_b128 v[186:189], v23 offset:4096
	ds_read_b128 v[194:197], v23 offset:6144
	ds_read_b128 v[190:193], v24
	ds_read_b128 v[198:201], v25
	ds_read_b128 v[202:205], v26
	ds_read_b128 v[206:209], v27
	s_waitcnt lgkmcnt(0)
	v_mfma_f32_16x16x32_bf16 v[138:141], v[44:47], v[190:193], v[138:141]
	v_mfma_f32_16x16x32_bf16 v[142:145], v[48:51], v[190:193], v[142:145]
	v_mfma_f32_16x16x32_bf16 v[146:149], v[186:189], v[190:193], v[146:149]
	v_mfma_f32_16x16x32_bf16 v[134:137], v[194:197], v[190:193], v[134:137]
	ds_read_b128 v[190:193], v28
	v_mfma_f32_16x16x32_bf16 v[154:157], v[44:47], v[198:201], v[154:157]
	v_mfma_f32_16x16x32_bf16 v[158:161], v[48:51], v[198:201], v[158:161]
	v_mfma_f32_16x16x32_bf16 v[162:165], v[186:189], v[198:201], v[162:165]
	v_mfma_f32_16x16x32_bf16 v[150:153], v[194:197], v[198:201], v[150:153]
	ds_read_b128 v[198:201], v29
	v_mfma_f32_16x16x32_bf16 v[170:173], v[44:47], v[202:205], v[170:173]
	v_mfma_f32_16x16x32_bf16 v[174:177], v[48:51], v[202:205], v[174:177]
	v_mfma_f32_16x16x32_bf16 v[178:181], v[186:189], v[202:205], v[178:181]
	v_mfma_f32_16x16x32_bf16 v[166:169], v[194:197], v[202:205], v[166:169]
	ds_read_b128 v[202:205], v30
	v_mfma_f32_16x16x32_bf16 v[210:213], v[44:47], v[206:209], v[214:217]
	v_mfma_f32_16x16x32_bf16 v[56:59], v[48:51], v[206:209], v[56:59]
	v_mfma_f32_16x16x32_bf16 v[64:67], v[186:189], v[206:209], v[64:67]
	v_mfma_f32_16x16x32_bf16 v[72:75], v[194:197], v[206:209], v[72:75]
	ds_read_b128 v[206:209], v31
	s_waitcnt lgkmcnt(0)
	v_mfma_f32_16x16x32_bf16 v[116:119], v[44:47], v[190:193], v[116:119]
	v_mfma_f32_16x16x32_bf16 v[120:123], v[48:51], v[190:193], v[120:123]
	v_mfma_f32_16x16x32_bf16 v[124:127], v[186:189], v[190:193], v[124:127]
	v_mfma_f32_16x16x32_bf16 v[112:115], v[194:197], v[190:193], v[112:115]
	v_mfma_f32_16x16x32_bf16 v[92:95], v[44:47], v[198:201], v[92:95]
	v_mfma_f32_16x16x32_bf16 v[100:103], v[48:51], v[198:201], v[100:103]
	v_mfma_f32_16x16x32_bf16 v[104:107], v[186:189], v[198:201], v[104:107]
	v_mfma_f32_16x16x32_bf16 v[108:111], v[194:197], v[198:201], v[108:111]
	v_mfma_f32_16x16x32_bf16 v[76:79], v[44:47], v[202:205], v[76:79]
	v_mfma_f32_16x16x32_bf16 v[80:83], v[48:51], v[202:205], v[80:83]
	v_mfma_f32_16x16x32_bf16 v[84:87], v[186:189], v[202:205], v[84:87]
	v_mfma_f32_16x16x32_bf16 v[88:91], v[194:197], v[202:205], v[88:91]
	v_mfma_f32_16x16x32_bf16 v[44:47], v[44:47], v[206:209], v[52:55]
	v_mfma_f32_16x16x32_bf16 v[48:51], v[48:51], v[206:209], v[60:63]
	v_mfma_f32_16x16x32_bf16 v[52:55], v[186:189], v[206:209], v[68:71]
	v_mfma_f32_16x16x32_bf16 v[60:63], v[194:197], v[206:209], v[182:185]
	s_nop 1
	ds_read_b128 v[68:71], v23 offset:1024
	ds_read_b128 v[182:185], v23 offset:3072
	ds_read_b128 v[186:189], v23 offset:5120
	ds_read_b128 v[194:197], v23 offset:7168
	ds_read_b128 v[190:193], v24 offset:1024
	ds_read_b128 v[198:201], v25 offset:1024
	ds_read_b128 v[202:205], v26 offset:1024
	ds_read_b128 v[206:209], v27 offset:1024
	s_waitcnt lgkmcnt(0)
	v_mfma_f32_16x16x32_bf16 v[138:141], v[68:71], v[190:193], v[138:141]
	v_mfma_f32_16x16x32_bf16 v[142:145], v[182:185], v[190:193], v[142:145]
	v_mfma_f32_16x16x32_bf16 v[146:149], v[186:189], v[190:193], v[146:149]
	v_mfma_f32_16x16x32_bf16 v[134:137], v[194:197], v[190:193], v[134:137]
	ds_read_b128 v[190:193], v28 offset:1024
	v_mfma_f32_16x16x32_bf16 v[154:157], v[68:71], v[198:201], v[154:157]
	v_mfma_f32_16x16x32_bf16 v[158:161], v[182:185], v[198:201], v[158:161]
	v_mfma_f32_16x16x32_bf16 v[162:165], v[186:189], v[198:201], v[162:165]
	v_mfma_f32_16x16x32_bf16 v[150:153], v[194:197], v[198:201], v[150:153]
	ds_read_b128 v[198:201], v29 offset:1024
	v_mfma_f32_16x16x32_bf16 v[170:173], v[68:71], v[202:205], v[170:173]
	v_mfma_f32_16x16x32_bf16 v[174:177], v[182:185], v[202:205], v[174:177]
	v_mfma_f32_16x16x32_bf16 v[178:181], v[186:189], v[202:205], v[178:181]
	v_mfma_f32_16x16x32_bf16 v[166:169], v[194:197], v[202:205], v[166:169]
	ds_read_b128 v[202:205], v30 offset:1024
	v_mfma_f32_16x16x32_bf16 v[210:213], v[68:71], v[206:209], v[210:213]
	v_mfma_f32_16x16x32_bf16 v[56:59], v[182:185], v[206:209], v[56:59]
	v_mfma_f32_16x16x32_bf16 v[64:67], v[186:189], v[206:209], v[64:67]
	v_mfma_f32_16x16x32_bf16 v[72:75], v[194:197], v[206:209], v[72:75]
	ds_read_b128 v[206:209], v31 offset:1024
	s_waitcnt lgkmcnt(0)
	v_mfma_f32_16x16x32_bf16 v[116:119], v[68:71], v[190:193], v[116:119]
	v_mfma_f32_16x16x32_bf16 v[120:123], v[182:185], v[190:193], v[120:123]
	v_mfma_f32_16x16x32_bf16 v[124:127], v[186:189], v[190:193], v[124:127]
	v_mfma_f32_16x16x32_bf16 v[112:115], v[194:197], v[190:193], v[112:115]
	v_mfma_f32_16x16x32_bf16 v[92:95], v[68:71], v[198:201], v[92:95]
	v_mfma_f32_16x16x32_bf16 v[100:103], v[182:185], v[198:201], v[100:103]
	v_mfma_f32_16x16x32_bf16 v[104:107], v[186:189], v[198:201], v[104:107]
	v_mfma_f32_16x16x32_bf16 v[108:111], v[194:197], v[198:201], v[108:111]
	v_mfma_f32_16x16x32_bf16 v[76:79], v[68:71], v[202:205], v[76:79]
	v_mfma_f32_16x16x32_bf16 v[80:83], v[182:185], v[202:205], v[80:83]
	v_mfma_f32_16x16x32_bf16 v[84:87], v[186:189], v[202:205], v[84:87]
	v_mfma_f32_16x16x32_bf16 v[88:91], v[194:197], v[202:205], v[88:91]
	v_mfma_f32_16x16x32_bf16 v[44:47], v[68:71], v[206:209], v[44:47]
	v_mfma_f32_16x16x32_bf16 v[48:51], v[182:185], v[206:209], v[48:51]
	v_mfma_f32_16x16x32_bf16 v[52:55], v[186:189], v[206:209], v[52:55]
	v_mfma_f32_16x16x32_bf16 v[60:63], v[194:197], v[206:209], v[60:63]
	v_readfirstlane_b32 s64, v37
	v_lshl_add_u64 v[68:69], v[2:3], 0, s[20:21]
	s_mov_b32 m0, s64
	v_readfirstlane_b32 s58, v36
	s_waitcnt vmcnt(0)
	s_waitcnt vmcnt(0)
	s_barrier
	global_load_lds_dwordx4 v[68:69], off
	v_lshl_add_u64 v[68:69], v[4:5], 0, s[20:21]
	s_mov_b32 m0, s58
	v_readfirstlane_b32 s59, v38
	global_load_lds_dwordx4 v[68:69], off
	v_lshl_add_u64 v[36:37], v[6:7], 0, s[20:21]
	s_mov_b32 m0, s59
	v_readfirstlane_b32 s60, v39
	global_load_lds_dwordx4 v[36:37], off
	v_lshl_add_u64 v[36:37], v[8:9], 0, s[20:21]
	s_mov_b32 m0, s60
	v_readfirstlane_b32 s61, v40
	global_load_lds_dwordx4 v[36:37], off
	v_lshl_add_u64 v[36:37], v[10:11], 0, s[20:21]
	s_mov_b32 m0, s61
	v_readfirstlane_b32 s62, v41
	global_load_lds_dwordx4 v[36:37], off
	v_lshl_add_u64 v[36:37], v[12:13], 0, s[20:21]
	s_mov_b32 m0, s62
	v_readfirstlane_b32 s63, v42
	global_load_lds_dwordx4 v[36:37], off
	v_lshl_add_u64 v[36:37], v[14:15], 0, s[20:21]
	s_mov_b32 m0, s63
	v_readfirstlane_b32 s65, v43
	global_load_lds_dwordx4 v[36:37], off
	v_lshl_add_u64 v[36:37], v[16:17], 0, s[20:21]
	s_mov_b32 m0, s65
	s_nop 0
	global_load_lds_dwordx4 v[36:37], off
	ds_read_b128 v[36:39], v18 offset:32768
	ds_read_b128 v[40:43], v18 offset:34816
	ds_read_b128 v[68:71], v18 offset:36864
	ds_read_b128 v[186:189], v18 offset:38912
	ds_read_b128 v[182:185], v32
	ds_read_b128 v[190:193], v33
	ds_read_b128 v[194:197], v34
	ds_read_b128 v[198:201], v35
	s_waitcnt lgkmcnt(0)
	v_mfma_f32_16x16x32_bf16 v[138:141], v[36:39], v[182:185], v[138:141]
	v_mfma_f32_16x16x32_bf16 v[142:145], v[40:43], v[182:185], v[142:145]
	v_mfma_f32_16x16x32_bf16 v[146:149], v[68:71], v[182:185], v[146:149]
	v_mfma_f32_16x16x32_bf16 v[134:137], v[186:189], v[182:185], v[134:137]
	ds_read_b128 v[182:185], v22
	v_mfma_f32_16x16x32_bf16 v[154:157], v[36:39], v[190:193], v[154:157]
	v_mfma_f32_16x16x32_bf16 v[158:161], v[40:43], v[190:193], v[158:161]
	v_mfma_f32_16x16x32_bf16 v[162:165], v[68:71], v[190:193], v[162:165]
	v_mfma_f32_16x16x32_bf16 v[150:153], v[186:189], v[190:193], v[150:153]
	ds_read_b128 v[190:193], v21
	v_mfma_f32_16x16x32_bf16 v[170:173], v[36:39], v[194:197], v[170:173]
	v_mfma_f32_16x16x32_bf16 v[174:177], v[40:43], v[194:197], v[174:177]
	v_mfma_f32_16x16x32_bf16 v[178:181], v[68:71], v[194:197], v[178:181]
	v_mfma_f32_16x16x32_bf16 v[166:169], v[186:189], v[194:197], v[166:169]
	ds_read_b128 v[194:197], v20
	v_mfma_f32_16x16x32_bf16 v[202:205], v[36:39], v[198:201], v[210:213]
	v_mfma_f32_16x16x32_bf16 v[56:59], v[40:43], v[198:201], v[56:59]
	v_mfma_f32_16x16x32_bf16 v[64:67], v[68:71], v[198:201], v[64:67]
	v_mfma_f32_16x16x32_bf16 v[72:75], v[186:189], v[198:201], v[72:75]
	ds_read_b128 v[198:201], v19
	s_waitcnt lgkmcnt(0)
	v_mfma_f32_16x16x32_bf16 v[116:119], v[36:39], v[182:185], v[116:119]
	v_mfma_f32_16x16x32_bf16 v[120:123], v[40:43], v[182:185], v[120:123]
	v_mfma_f32_16x16x32_bf16 v[124:127], v[68:71], v[182:185], v[124:127]
	v_mfma_f32_16x16x32_bf16 v[112:115], v[186:189], v[182:185], v[112:115]
	v_mfma_f32_16x16x32_bf16 v[92:95], v[36:39], v[190:193], v[92:95]
	v_mfma_f32_16x16x32_bf16 v[100:103], v[40:43], v[190:193], v[100:103]
	v_mfma_f32_16x16x32_bf16 v[104:107], v[68:71], v[190:193], v[104:107]
	v_mfma_f32_16x16x32_bf16 v[108:111], v[186:189], v[190:193], v[108:111]
	v_mfma_f32_16x16x32_bf16 v[76:79], v[36:39], v[194:197], v[76:79]
	v_mfma_f32_16x16x32_bf16 v[80:83], v[40:43], v[194:197], v[80:83]
	v_mfma_f32_16x16x32_bf16 v[84:87], v[68:71], v[194:197], v[84:87]
	v_mfma_f32_16x16x32_bf16 v[88:91], v[186:189], v[194:197], v[88:91]
	v_mfma_f32_16x16x32_bf16 v[36:39], v[36:39], v[198:201], v[44:47]
	v_mfma_f32_16x16x32_bf16 v[40:43], v[40:43], v[198:201], v[48:51]
	v_mfma_f32_16x16x32_bf16 v[44:47], v[68:71], v[198:201], v[52:55]
	v_mfma_f32_16x16x32_bf16 v[48:51], v[186:189], v[198:201], v[60:63]
	s_nop 1
	ds_read_b128 v[52:55], v18 offset:33792
	ds_read_b128 v[60:63], v18 offset:35840
	ds_read_b128 v[68:71], v18 offset:37888
	ds_read_b128 v[186:189], v18 offset:39936
	ds_read_b128 v[182:185], v32 offset:1024
	ds_read_b128 v[190:193], v33 offset:1024
	ds_read_b128 v[194:197], v34 offset:1024
	ds_read_b128 v[198:201], v35 offset:1024
	s_waitcnt lgkmcnt(0)
	v_mfma_f32_16x16x32_bf16 v[138:141], v[52:55], v[182:185], v[138:141]
	v_mfma_f32_16x16x32_bf16 v[142:145], v[60:63], v[182:185], v[142:145]
	v_mfma_f32_16x16x32_bf16 v[146:149], v[68:71], v[182:185], v[146:149]
	v_mfma_f32_16x16x32_bf16 v[134:137], v[186:189], v[182:185], v[134:137]
	ds_read_b128 v[182:185], v22 offset:1024
	v_mfma_f32_16x16x32_bf16 v[154:157], v[52:55], v[190:193], v[154:157]
	v_mfma_f32_16x16x32_bf16 v[158:161], v[60:63], v[190:193], v[158:161]
	v_mfma_f32_16x16x32_bf16 v[162:165], v[68:71], v[190:193], v[162:165]
	v_mfma_f32_16x16x32_bf16 v[150:153], v[186:189], v[190:193], v[150:153]
	ds_read_b128 v[190:193], v21 offset:1024
	v_mfma_f32_16x16x32_bf16 v[170:173], v[52:55], v[194:197], v[170:173]
	v_mfma_f32_16x16x32_bf16 v[174:177], v[60:63], v[194:197], v[174:177]
	v_mfma_f32_16x16x32_bf16 v[178:181], v[68:71], v[194:197], v[178:181]
	v_mfma_f32_16x16x32_bf16 v[166:169], v[186:189], v[194:197], v[166:169]
	ds_read_b128 v[194:197], v20 offset:1024
	v_mfma_f32_16x16x32_bf16 v[202:205], v[52:55], v[198:201], v[202:205]
	v_mfma_f32_16x16x32_bf16 v[56:59], v[60:63], v[198:201], v[56:59]
	v_mfma_f32_16x16x32_bf16 v[64:67], v[68:71], v[198:201], v[64:67]
	v_mfma_f32_16x16x32_bf16 v[72:75], v[186:189], v[198:201], v[72:75]
	ds_read_b128 v[198:201], v19 offset:1024
	s_waitcnt lgkmcnt(0)
	v_mfma_f32_16x16x32_bf16 v[116:119], v[52:55], v[182:185], v[116:119]
	v_mfma_f32_16x16x32_bf16 v[120:123], v[60:63], v[182:185], v[120:123]
	v_mfma_f32_16x16x32_bf16 v[124:127], v[68:71], v[182:185], v[124:127]
	v_mfma_f32_16x16x32_bf16 v[112:115], v[186:189], v[182:185], v[112:115]
	v_mfma_f32_16x16x32_bf16 v[92:95], v[52:55], v[190:193], v[92:95]
	v_mfma_f32_16x16x32_bf16 v[100:103], v[60:63], v[190:193], v[100:103]
	v_mfma_f32_16x16x32_bf16 v[104:107], v[68:71], v[190:193], v[104:107]
	v_mfma_f32_16x16x32_bf16 v[108:111], v[186:189], v[190:193], v[108:111]
	v_mfma_f32_16x16x32_bf16 v[76:79], v[52:55], v[194:197], v[76:79]
	v_mfma_f32_16x16x32_bf16 v[80:83], v[60:63], v[194:197], v[80:83]
	v_mfma_f32_16x16x32_bf16 v[84:87], v[68:71], v[194:197], v[84:87]
	v_mfma_f32_16x16x32_bf16 v[88:91], v[186:189], v[194:197], v[88:91]
	v_mfma_f32_16x16x32_bf16 v[36:39], v[52:55], v[198:201], v[36:39]
	v_mfma_f32_16x16x32_bf16 v[40:43], v[60:63], v[198:201], v[40:43]
	v_mfma_f32_16x16x32_bf16 v[44:47], v[68:71], v[198:201], v[44:47]
	v_mfma_f32_16x16x32_bf16 v[48:51], v[186:189], v[198:201], v[48:51]
	s_mov_b32 m0, s56
	v_lshl_add_u64 v[52:53], v[2:3], 0, s[22:23]
	s_waitcnt vmcnt(0)
	s_waitcnt vmcnt(0)
	s_barrier
	global_load_lds_dwordx4 v[52:53], off
	v_lshl_add_u64 v[52:53], v[4:5], 0, s[22:23]
	s_mov_b32 m0, s0
	s_nop 0
	global_load_lds_dwordx4 v[52:53], off
	v_lshl_add_u64 v[52:53], v[6:7], 0, s[22:23]
	s_mov_b32 m0, s42
	s_nop 0
	global_load_lds_dwordx4 v[52:53], off
	v_lshl_add_u64 v[52:53], v[8:9], 0, s[22:23]
	s_mov_b32 m0, s43
	s_nop 0
	global_load_lds_dwordx4 v[52:53], off
	v_lshl_add_u64 v[52:53], v[10:11], 0, s[22:23]
	s_mov_b32 m0, s53
	s_nop 0
	global_load_lds_dwordx4 v[52:53], off
	v_lshl_add_u64 v[52:53], v[12:13], 0, s[22:23]
	s_mov_b32 m0, s54
	s_nop 0
	global_load_lds_dwordx4 v[52:53], off
	v_lshl_add_u64 v[52:53], v[14:15], 0, s[22:23]
	s_mov_b32 m0, s55
	s_nop 0
	global_load_lds_dwordx4 v[52:53], off
	v_lshl_add_u64 v[52:53], v[16:17], 0, s[22:23]
	s_mov_b32 m0, s57
	s_nop 0
	global_load_lds_dwordx4 v[52:53], off
	ds_read_b128 v[52:55], v23
	ds_read_b128 v[60:63], v23 offset:2048
	ds_read_b128 v[68:71], v23 offset:4096
	ds_read_b128 v[186:189], v23 offset:6144
	ds_read_b128 v[182:185], v24
	ds_read_b128 v[190:193], v25
	ds_read_b128 v[194:197], v26
	ds_read_b128 v[198:201], v27
	s_waitcnt lgkmcnt(0)
	v_mfma_f32_16x16x32_bf16 v[138:141], v[52:55], v[182:185], v[138:141]
	v_mfma_f32_16x16x32_bf16 v[142:145], v[60:63], v[182:185], v[142:145]
	v_mfma_f32_16x16x32_bf16 v[146:149], v[68:71], v[182:185], v[146:149]
	v_mfma_f32_16x16x32_bf16 v[134:137], v[186:189], v[182:185], v[134:137]
	ds_read_b128 v[182:185], v28
	v_mfma_f32_16x16x32_bf16 v[154:157], v[52:55], v[190:193], v[154:157]
	v_mfma_f32_16x16x32_bf16 v[158:161], v[60:63], v[190:193], v[158:161]
	v_mfma_f32_16x16x32_bf16 v[162:165], v[68:71], v[190:193], v[162:165]
	v_mfma_f32_16x16x32_bf16 v[150:153], v[186:189], v[190:193], v[150:153]
	ds_read_b128 v[190:193], v29
	v_mfma_f32_16x16x32_bf16 v[170:173], v[52:55], v[194:197], v[170:173]
	v_mfma_f32_16x16x32_bf16 v[174:177], v[60:63], v[194:197], v[174:177]
	v_mfma_f32_16x16x32_bf16 v[178:181], v[68:71], v[194:197], v[178:181]
	v_mfma_f32_16x16x32_bf16 v[166:169], v[186:189], v[194:197], v[166:169]
	ds_read_b128 v[194:197], v30
	v_mfma_f32_16x16x32_bf16 v[202:205], v[52:55], v[198:201], v[202:205]
	v_mfma_f32_16x16x32_bf16 v[56:59], v[60:63], v[198:201], v[56:59]
	v_mfma_f32_16x16x32_bf16 v[64:67], v[68:71], v[198:201], v[64:67]
	v_mfma_f32_16x16x32_bf16 v[72:75], v[186:189], v[198:201], v[72:75]
	ds_read_b128 v[198:201], v31
	s_waitcnt lgkmcnt(0)
	v_mfma_f32_16x16x32_bf16 v[116:119], v[52:55], v[182:185], v[116:119]
	v_mfma_f32_16x16x32_bf16 v[120:123], v[60:63], v[182:185], v[120:123]
	v_mfma_f32_16x16x32_bf16 v[124:127], v[68:71], v[182:185], v[124:127]
	v_mfma_f32_16x16x32_bf16 v[112:115], v[186:189], v[182:185], v[112:115]
	v_mfma_f32_16x16x32_bf16 v[92:95], v[52:55], v[190:193], v[92:95]
	v_mfma_f32_16x16x32_bf16 v[100:103], v[60:63], v[190:193], v[100:103]
	v_mfma_f32_16x16x32_bf16 v[104:107], v[68:71], v[190:193], v[104:107]
	v_mfma_f32_16x16x32_bf16 v[108:111], v[186:189], v[190:193], v[108:111]
	v_mfma_f32_16x16x32_bf16 v[76:79], v[52:55], v[194:197], v[76:79]
	v_mfma_f32_16x16x32_bf16 v[80:83], v[60:63], v[194:197], v[80:83]
	v_mfma_f32_16x16x32_bf16 v[84:87], v[68:71], v[194:197], v[84:87]
	v_mfma_f32_16x16x32_bf16 v[88:91], v[186:189], v[194:197], v[88:91]
	v_mfma_f32_16x16x32_bf16 v[36:39], v[52:55], v[198:201], v[36:39]
	v_mfma_f32_16x16x32_bf16 v[40:43], v[60:63], v[198:201], v[40:43]
	v_mfma_f32_16x16x32_bf16 v[44:47], v[68:71], v[198:201], v[44:47]
	v_mfma_f32_16x16x32_bf16 v[48:51], v[186:189], v[198:201], v[48:51]
	ds_read_b128 v[52:55], v23 offset:1024
	ds_read_b128 v[60:63], v23 offset:3072
	ds_read_b128 v[68:71], v23 offset:5120
	ds_read_b128 v[186:189], v23 offset:7168
	ds_read_b128 v[182:185], v24 offset:1024
	ds_read_b128 v[190:193], v25 offset:1024
	ds_read_b128 v[194:197], v26 offset:1024
	ds_read_b128 v[198:201], v27 offset:1024
	s_waitcnt lgkmcnt(0)
	v_mfma_f32_16x16x32_bf16 v[138:141], v[52:55], v[182:185], v[138:141]
	v_mfma_f32_16x16x32_bf16 v[142:145], v[60:63], v[182:185], v[142:145]
	v_mfma_f32_16x16x32_bf16 v[146:149], v[68:71], v[182:185], v[146:149]
	v_mfma_f32_16x16x32_bf16 v[134:137], v[186:189], v[182:185], v[134:137]
	ds_read_b128 v[182:185], v28 offset:1024
	v_mfma_f32_16x16x32_bf16 v[154:157], v[52:55], v[190:193], v[154:157]
	v_mfma_f32_16x16x32_bf16 v[158:161], v[60:63], v[190:193], v[158:161]
	v_mfma_f32_16x16x32_bf16 v[162:165], v[68:71], v[190:193], v[162:165]
	v_mfma_f32_16x16x32_bf16 v[150:153], v[186:189], v[190:193], v[150:153]
	ds_read_b128 v[190:193], v29 offset:1024
	v_mfma_f32_16x16x32_bf16 v[170:173], v[52:55], v[194:197], v[170:173]
	v_mfma_f32_16x16x32_bf16 v[174:177], v[60:63], v[194:197], v[174:177]
	v_mfma_f32_16x16x32_bf16 v[178:181], v[68:71], v[194:197], v[178:181]
	v_mfma_f32_16x16x32_bf16 v[166:169], v[186:189], v[194:197], v[166:169]
	ds_read_b128 v[194:197], v30 offset:1024
	v_mfma_f32_16x16x32_bf16 v[202:205], v[52:55], v[198:201], v[202:205]
	v_mfma_f32_16x16x32_bf16 v[56:59], v[60:63], v[198:201], v[56:59]
	v_mfma_f32_16x16x32_bf16 v[64:67], v[68:71], v[198:201], v[64:67]
	v_mfma_f32_16x16x32_bf16 v[72:75], v[186:189], v[198:201], v[72:75]
	ds_read_b128 v[198:201], v31 offset:1024
	s_waitcnt lgkmcnt(0)
	v_mfma_f32_16x16x32_bf16 v[116:119], v[52:55], v[182:185], v[116:119]
	v_mfma_f32_16x16x32_bf16 v[120:123], v[60:63], v[182:185], v[120:123]
	v_mfma_f32_16x16x32_bf16 v[124:127], v[68:71], v[182:185], v[124:127]
	v_mfma_f32_16x16x32_bf16 v[112:115], v[186:189], v[182:185], v[112:115]
	v_mfma_f32_16x16x32_bf16 v[92:95], v[52:55], v[190:193], v[92:95]
	v_mfma_f32_16x16x32_bf16 v[100:103], v[60:63], v[190:193], v[100:103]
	v_mfma_f32_16x16x32_bf16 v[104:107], v[68:71], v[190:193], v[104:107]
	v_mfma_f32_16x16x32_bf16 v[108:111], v[186:189], v[190:193], v[108:111]
	v_mfma_f32_16x16x32_bf16 v[76:79], v[52:55], v[194:197], v[76:79]
	v_mfma_f32_16x16x32_bf16 v[80:83], v[60:63], v[194:197], v[80:83]
	v_mfma_f32_16x16x32_bf16 v[84:87], v[68:71], v[194:197], v[84:87]
	v_mfma_f32_16x16x32_bf16 v[88:91], v[186:189], v[194:197], v[88:91]
	v_mfma_f32_16x16x32_bf16 v[36:39], v[52:55], v[198:201], v[36:39]
	v_mfma_f32_16x16x32_bf16 v[40:43], v[60:63], v[198:201], v[40:43]
	v_mfma_f32_16x16x32_bf16 v[44:47], v[68:71], v[198:201], v[44:47]
	v_mfma_f32_16x16x32_bf16 v[48:51], v[186:189], v[198:201], v[48:51]
	s_mov_b32 m0, s64
	v_lshl_add_u64 v[2:3], v[2:3], 0, s[24:25]
	s_waitcnt vmcnt(0)
	s_waitcnt vmcnt(0)
	s_barrier
	global_load_lds_dwordx4 v[2:3], off
	v_lshl_add_u64 v[2:3], v[4:5], 0, s[24:25]
	s_mov_b32 m0, s58
	s_nop 0
	global_load_lds_dwordx4 v[2:3], off
	v_lshl_add_u64 v[2:3], v[6:7], 0, s[24:25]
	s_mov_b32 m0, s59
	s_nop 0
	global_load_lds_dwordx4 v[2:3], off
	v_lshl_add_u64 v[2:3], v[8:9], 0, s[24:25]
	s_mov_b32 m0, s60
	s_nop 0
	global_load_lds_dwordx4 v[2:3], off
	v_lshl_add_u64 v[2:3], v[10:11], 0, s[24:25]
	s_mov_b32 m0, s61
	s_nop 0
	global_load_lds_dwordx4 v[2:3], off
	v_lshl_add_u64 v[2:3], v[12:13], 0, s[24:25]
	s_mov_b32 m0, s62
	s_nop 0
	global_load_lds_dwordx4 v[2:3], off
	v_lshl_add_u64 v[2:3], v[14:15], 0, s[24:25]
	s_mov_b32 m0, s63
	s_nop 0
	global_load_lds_dwordx4 v[2:3], off
	v_lshl_add_u64 v[2:3], v[16:17], 0, s[24:25]
	s_mov_b32 m0, s65
	s_nop 0
	global_load_lds_dwordx4 v[2:3], off
	ds_read_b128 v[2:5], v18 offset:32768
	ds_read_b128 v[6:9], v18 offset:34816
	ds_read_b128 v[10:13], v18 offset:36864
	ds_read_b128 v[52:55], v18 offset:38912
	ds_read_b128 v[14:17], v32
	ds_read_b128 v[60:63], v33
	ds_read_b128 v[68:71], v34
	ds_read_b128 v[182:185], v35
	s_waitcnt lgkmcnt(0)
	v_mfma_f32_16x16x32_bf16 v[138:141], v[2:5], v[14:17], v[138:141]
	v_mfma_f32_16x16x32_bf16 v[142:145], v[6:9], v[14:17], v[142:145]
	v_mfma_f32_16x16x32_bf16 v[146:149], v[10:13], v[14:17], v[146:149]
	v_mfma_f32_16x16x32_bf16 v[14:17], v[52:55], v[14:17], v[134:137]
	s_nop 2
	ds_read_b128 v[134:137], v22
	v_mfma_f32_16x16x32_bf16 v[154:157], v[2:5], v[60:63], v[154:157]
	v_mfma_f32_16x16x32_bf16 v[158:161], v[6:9], v[60:63], v[158:161]
	v_mfma_f32_16x16x32_bf16 v[162:165], v[10:13], v[60:63], v[162:165]
	v_mfma_f32_16x16x32_bf16 v[60:63], v[52:55], v[60:63], v[150:153]
	s_nop 2
	ds_read_b128 v[150:153], v21
	v_mfma_f32_16x16x32_bf16 v[170:173], v[2:5], v[68:71], v[170:173]
	v_mfma_f32_16x16x32_bf16 v[174:177], v[6:9], v[68:71], v[174:177]
	v_mfma_f32_16x16x32_bf16 v[178:181], v[10:13], v[68:71], v[178:181]
	v_mfma_f32_16x16x32_bf16 v[68:71], v[52:55], v[68:71], v[166:169]
	s_nop 2
	ds_read_b128 v[166:169], v20
	v_mfma_f32_16x16x32_bf16 v[186:189], v[2:5], v[182:185], v[202:205]
	v_mfma_f32_16x16x32_bf16 v[56:59], v[6:9], v[182:185], v[56:59]
	v_mfma_f32_16x16x32_bf16 v[64:67], v[10:13], v[182:185], v[64:67]
	v_mfma_f32_16x16x32_bf16 v[72:75], v[52:55], v[182:185], v[72:75]
	ds_read_b128 v[182:185], v19
	s_waitcnt lgkmcnt(0)
	v_mfma_f32_16x16x32_bf16 v[116:119], v[2:5], v[134:137], v[116:119]
	v_mfma_f32_16x16x32_bf16 v[120:123], v[6:9], v[134:137], v[120:123]
	v_mfma_f32_16x16x32_bf16 v[124:127], v[10:13], v[134:137], v[124:127]
	v_mfma_f32_16x16x32_bf16 v[112:115], v[52:55], v[134:137], v[112:115]
	v_mfma_f32_16x16x32_bf16 v[92:95], v[2:5], v[150:153], v[92:95]
	v_mfma_f32_16x16x32_bf16 v[100:103], v[6:9], v[150:153], v[100:103]
	v_mfma_f32_16x16x32_bf16 v[104:107], v[10:13], v[150:153], v[104:107]
	v_mfma_f32_16x16x32_bf16 v[108:111], v[52:55], v[150:153], v[108:111]
	v_mfma_f32_16x16x32_bf16 v[76:79], v[2:5], v[166:169], v[76:79]
	v_mfma_f32_16x16x32_bf16 v[80:83], v[6:9], v[166:169], v[80:83]
	v_mfma_f32_16x16x32_bf16 v[84:87], v[10:13], v[166:169], v[84:87]
	v_mfma_f32_16x16x32_bf16 v[88:91], v[52:55], v[166:169], v[88:91]
	v_mfma_f32_16x16x32_bf16 v[2:5], v[2:5], v[182:185], v[36:39]
	v_mfma_f32_16x16x32_bf16 v[6:9], v[6:9], v[182:185], v[40:43]
	v_mfma_f32_16x16x32_bf16 v[10:13], v[10:13], v[182:185], v[44:47]
	v_mfma_f32_16x16x32_bf16 v[36:39], v[52:55], v[182:185], v[48:51]
	s_nop 0
	ds_read_b128 v[40:43], v18 offset:33792
	ds_read_b128 v[44:47], v18 offset:35840
	ds_read_b128 v[48:51], v18 offset:37888
	ds_read_b128 v[134:137], v18 offset:39936
	ds_read_b128 v[52:55], v32 offset:1024
	ds_read_b128 v[150:153], v33 offset:1024
	ds_read_b128 v[166:169], v34 offset:1024
	ds_read_b128 v[32:35], v35 offset:1024
	s_waitcnt lgkmcnt(0)
	v_mfma_f32_16x16x32_bf16 v[138:141], v[40:43], v[52:55], v[138:141]
	v_mfma_f32_16x16x32_bf16 v[142:145], v[44:47], v[52:55], v[142:145]
	v_mfma_f32_16x16x32_bf16 v[146:149], v[48:51], v[52:55], v[146:149]
	v_mfma_f32_16x16x32_bf16 v[14:17], v[134:137], v[52:55], v[14:17]
	ds_read_b128 v[52:55], v22 offset:1024
	v_mfma_f32_16x16x32_bf16 v[154:157], v[40:43], v[150:153], v[154:157]
	v_mfma_f32_16x16x32_bf16 v[158:161], v[44:47], v[150:153], v[158:161]
	v_mfma_f32_16x16x32_bf16 v[162:165], v[48:51], v[150:153], v[162:165]
	v_mfma_f32_16x16x32_bf16 v[60:63], v[134:137], v[150:153], v[60:63]
	ds_read_b128 v[150:153], v21 offset:1024
	v_mfma_f32_16x16x32_bf16 v[170:173], v[40:43], v[166:169], v[170:173]
	v_mfma_f32_16x16x32_bf16 v[174:177], v[44:47], v[166:169], v[174:177]
	v_mfma_f32_16x16x32_bf16 v[178:181], v[48:51], v[166:169], v[178:181]
	v_mfma_f32_16x16x32_bf16 v[68:71], v[134:137], v[166:169], v[68:71]
	ds_read_b128 v[166:169], v20 offset:1024
	v_mfma_f32_16x16x32_bf16 v[182:185], v[40:43], v[32:35], v[186:189]
	v_mfma_f32_16x16x32_bf16 v[56:59], v[44:47], v[32:35], v[56:59]
	v_mfma_f32_16x16x32_bf16 v[64:67], v[48:51], v[32:35], v[64:67]
	v_mfma_f32_16x16x32_bf16 v[32:35], v[134:137], v[32:35], v[72:75]
	ds_read_b128 v[18:21], v19 offset:1024
	s_waitcnt lgkmcnt(0)
	v_mfma_f32_16x16x32_bf16 v[72:75], v[40:43], v[52:55], v[116:119]
	v_mfma_f32_16x16x32_bf16 v[116:119], v[44:47], v[52:55], v[120:123]
	v_mfma_f32_16x16x32_bf16 v[120:123], v[48:51], v[52:55], v[124:127]
	v_mfma_f32_16x16x32_bf16 v[52:55], v[134:137], v[52:55], v[112:115]
	v_mfma_f32_16x16x32_bf16 v[92:95], v[40:43], v[150:153], v[92:95]
	v_mfma_f32_16x16x32_bf16 v[100:103], v[44:47], v[150:153], v[100:103]
	v_mfma_f32_16x16x32_bf16 v[104:107], v[48:51], v[150:153], v[104:107]
	v_mfma_f32_16x16x32_bf16 v[108:111], v[134:137], v[150:153], v[108:111]
	v_mfma_f32_16x16x32_bf16 v[76:79], v[40:43], v[166:169], v[76:79]
	v_mfma_f32_16x16x32_bf16 v[80:83], v[44:47], v[166:169], v[80:83]
	v_mfma_f32_16x16x32_bf16 v[84:87], v[48:51], v[166:169], v[84:87]
	v_mfma_f32_16x16x32_bf16 v[88:91], v[134:137], v[166:169], v[88:91]
	v_mfma_f32_16x16x32_bf16 v[2:5], v[40:43], v[18:21], v[2:5]
	v_mfma_f32_16x16x32_bf16 v[6:9], v[44:47], v[18:21], v[6:9]
	v_mfma_f32_16x16x32_bf16 v[10:13], v[48:51], v[18:21], v[10:13]
	v_mfma_f32_16x16x32_bf16 v[18:21], v[134:137], v[18:21], v[36:39]
	s_waitcnt vmcnt(0)
	s_waitcnt vmcnt(0)
	s_barrier
	s_nop 0
	ds_read_b128 v[36:39], v31
	ds_read_b128 v[40:43], v30
	ds_read_b128 v[44:47], v29
	ds_read_b128 v[48:51], v28
	ds_read_b128 v[112:115], v27
	ds_read_b128 v[124:127], v26
	ds_read_b128 v[134:137], v25
	ds_read_b128 v[150:153], v24
	ds_read_b128 v[166:169], v23
	s_waitcnt lgkmcnt(0)
	v_mfma_f32_16x16x32_bf16 v[186:189], v[166:169], v[36:39], v[2:5]
	s_nop 2
	ds_read_b128 v[2:5], v23 offset:2048
	s_waitcnt lgkmcnt(0)
	v_mfma_f32_16x16x32_bf16 v[190:193], v[2:5], v[36:39], v[6:9]
	s_nop 2
	ds_read_b128 v[6:9], v23 offset:4096
	s_waitcnt lgkmcnt(0)
	v_mfma_f32_16x16x32_bf16 v[194:197], v[6:9], v[36:39], v[10:13]
	s_nop 2
	ds_read_b128 v[10:13], v23 offset:6144
	s_waitcnt lgkmcnt(0)
	v_mfma_f32_16x16x32_bf16 v[198:201], v[10:13], v[36:39], v[18:21]
	v_mfma_f32_16x16x32_bf16 v[18:21], v[10:13], v[134:137], v[60:63]
	v_mfma_f32_16x16x32_bf16 v[36:39], v[10:13], v[124:127], v[68:71]
	v_mfma_f32_16x16x32_bf16 v[68:71], v[6:9], v[134:137], v[162:165]
	v_mfma_f32_16x16x32_bf16 v[162:165], v[6:9], v[112:115], v[64:67]
	v_mfma_f32_16x16x32_bf16 v[64:67], v[2:5], v[150:153], v[142:145]
	v_mfma_f32_16x16x32_bf16 v[142:145], v[2:5], v[134:137], v[158:161]
	v_mfma_f32_16x16x32_bf16 v[134:137], v[166:169], v[134:137], v[154:157]
	v_mfma_f32_16x16x32_bf16 v[154:157], v[166:169], v[40:43], v[76:79]
	v_mfma_f32_16x16x32_bf16 v[60:63], v[6:9], v[150:153], v[146:149]
	v_mfma_f32_16x16x32_bf16 v[146:149], v[6:9], v[124:127], v[178:181]
	v_mfma_f32_16x16x32_bf16 v[158:161], v[2:5], v[124:127], v[174:177]
	v_mfma_f32_16x16x32_bf16 v[124:127], v[166:169], v[124:127], v[170:173]
	v_mfma_f32_16x16x32_bf16 v[170:173], v[6:9], v[40:43], v[84:87]
	v_mfma_f32_16x16x32_bf16 v[138:141], v[166:169], v[150:153], v[138:141]
	v_mfma_f32_16x16x32_bf16 v[56:59], v[2:5], v[112:115], v[56:59]
	v_mfma_f32_16x16x32_bf16 v[116:119], v[2:5], v[48:51], v[116:119]
	v_mfma_f32_16x16x32_bf16 v[120:123], v[6:9], v[48:51], v[120:123]
	v_mfma_f32_16x16x32_bf16 v[14:17], v[10:13], v[150:153], v[14:17]
	v_mfma_f32_16x16x32_bf16 v[150:153], v[166:169], v[48:51], v[72:75]
	v_mfma_f32_16x16x32_bf16 v[48:51], v[10:13], v[48:51], v[52:55]
	v_mfma_f32_16x16x32_bf16 v[52:55], v[166:169], v[44:47], v[92:95]
	v_mfma_f32_16x16x32_bf16 v[32:35], v[10:13], v[112:115], v[32:35]
	v_mfma_f32_16x16x32_bf16 v[112:115], v[166:169], v[112:115], v[182:185]
	v_mfma_f32_16x16x32_bf16 v[166:169], v[2:5], v[40:43], v[80:83]
	v_mfma_f32_16x16x32_bf16 v[104:107], v[6:9], v[44:47], v[104:107]
	v_mfma_f32_16x16x32_bf16 v[108:111], v[10:13], v[44:47], v[108:111]
	v_mfma_f32_16x16x32_bf16 v[100:103], v[2:5], v[44:47], v[100:103]
	v_mfma_f32_16x16x32_bf16 v[174:177], v[10:13], v[40:43], v[88:91]
	ds_read_b128 v[178:181], v23 offset:1024
	ds_read_b128 v[182:185], v23 offset:3072
	ds_read_b128 v[202:205], v23 offset:5120
	ds_read_b128 v[206:209], v23 offset:7168
	ds_read_b128 v[2:5], v24 offset:1024
	ds_read_b128 v[6:9], v25 offset:1024
	ds_read_b128 v[10:13], v26 offset:1024
	ds_read_b128 v[22:25], v27 offset:1024
	s_waitcnt lgkmcnt(3)
	v_mfma_f32_16x16x32_bf16 v[138:141], v[178:181], v[2:5], v[138:141]
	v_mfma_f32_16x16x32_bf16 v[210:213], v[182:185], v[2:5], v[64:67]
	v_mfma_f32_16x16x32_bf16 v[214:217], v[202:205], v[2:5], v[60:63]
	v_mfma_f32_16x16x32_bf16 v[218:221], v[206:209], v[2:5], v[14:17]
	ds_read_b128 v[2:5], v28 offset:1024
	s_waitcnt lgkmcnt(3)
	v_mfma_f32_16x16x32_bf16 v[134:137], v[178:181], v[6:9], v[134:137]
	v_mfma_f32_16x16x32_bf16 v[142:145], v[182:185], v[6:9], v[142:145]
	v_mfma_f32_16x16x32_bf16 v[222:225], v[202:205], v[6:9], v[68:71]
	v_mfma_f32_16x16x32_bf16 v[226:229], v[206:209], v[6:9], v[18:21]
	ds_read_b128 v[6:9], v29 offset:1024
	s_waitcnt lgkmcnt(3)
	v_mfma_f32_16x16x32_bf16 v[66:69], v[178:181], v[10:13], v[124:127]
	v_mfma_f32_16x16x32_bf16 v[70:73], v[182:185], v[10:13], v[158:161]
	v_mfma_f32_16x16x32_bf16 v[74:77], v[202:205], v[10:13], v[146:149]
	v_mfma_f32_16x16x32_bf16 v[78:81], v[206:209], v[10:13], v[36:39]
	ds_read_b128 v[14:17], v30 offset:1024
	s_waitcnt lgkmcnt(3)
	v_mfma_f32_16x16x32_bf16 v[82:85], v[178:181], v[22:25], v[112:115]
	v_mfma_f32_16x16x32_bf16 v[86:89], v[182:185], v[22:25], v[56:59]
	v_mfma_f32_16x16x32_bf16 v[90:93], v[202:205], v[22:25], v[162:165]
	v_mfma_f32_16x16x32_bf16 v[94:97], v[206:209], v[22:25], v[32:35]
	s_nop 2
	ds_read_b128 v[30:33], v31 offset:1024
	s_waitcnt lgkmcnt(3)
	v_mfma_f32_16x16x32_bf16 v[34:37], v[178:181], v[2:5], v[150:153]
	v_mfma_f32_16x16x32_bf16 v[38:41], v[182:185], v[2:5], v[116:119]
	v_mfma_f32_16x16x32_bf16 v[42:45], v[202:205], v[2:5], v[120:123]
	v_mfma_f32_16x16x32_bf16 v[46:49], v[206:209], v[2:5], v[48:51]
	s_waitcnt lgkmcnt(2)
	v_mfma_f32_16x16x32_bf16 v[50:53], v[178:181], v[6:9], v[52:55]
	v_mfma_f32_16x16x32_bf16 v[54:57], v[182:185], v[6:9], v[100:103]
	v_mfma_f32_16x16x32_bf16 v[58:61], v[202:205], v[6:9], v[104:107]
	v_mfma_f32_16x16x32_bf16 v[62:65], v[206:209], v[6:9], v[108:111]
	s_waitcnt lgkmcnt(1)
	v_mfma_f32_16x16x32_bf16 v[2:5], v[178:181], v[14:17], v[154:157]
	v_mfma_f32_16x16x32_bf16 v[6:9], v[182:185], v[14:17], v[166:169]
	v_mfma_f32_16x16x32_bf16 v[10:13], v[202:205], v[14:17], v[170:173]
	v_mfma_f32_16x16x32_bf16 v[14:17], v[206:209], v[14:17], v[174:177]
	s_waitcnt lgkmcnt(0)
	v_mfma_f32_16x16x32_bf16 v[18:21], v[178:181], v[30:33], v[186:189]
	v_mfma_f32_16x16x32_bf16 v[22:25], v[182:185], v[30:33], v[190:193]
	v_mfma_f32_16x16x32_bf16 v[26:29], v[202:205], v[30:33], v[194:197]
	v_mfma_f32_16x16x32_bf16 v[30:33], v[206:209], v[30:33], v[198:201]
	v_lshlrev_b32_e32 v101, 2, v98
	v_and_b32_e32 v112, 60, v101
	v_ashrrev_i32_e32 v101, 1, v98
	v_lshrrev_b32_e32 v99, 6, v98
	v_and_b32_e32 v101, 0xffffff80, v101
	v_and_b32_e32 v100, 15, v98
	v_mul_lo_u32 v99, v99, s48
	v_add_u32_e32 v107, s28, v101
	v_bfe_u32 v108, v98, 4, 2
	v_add_u32_e32 v109, s46, v99
	v_and_b32_e32 v99, 48, v98
	v_and_or_b32 v102, v98, s49, v112
	v_mul_u32_u24_e32 v98, 0x110, v100
	v_or_b32_e32 v100, v107, v108
	v_lshl_add_u64 v[0:1], v[0:1], 0, s[38:39]
	v_lshlrev_b32_e32 v130, 1, v102
	v_ashrrev_i32_e32 v101, 31, v100
	v_lshl_add_u64 v[0:1], v[0:1], 0, v[130:131]
	v_add3_u32 v99, v109, v99, v98
	v_lshlrev_b64 v[100:101], 11, v[100:101]
	s_waitcnt vmcnt(0)
	s_barrier
	ds_write_b128 v99, v[138:141]
	ds_write_b128 v99, v[210:213] offset:64
	ds_write_b128 v99, v[214:217] offset:128
	ds_write_b128 v99, v[218:221] offset:192
	ds_write_b128 v99, v[134:137] offset:4352
	ds_write_b128 v99, v[142:145] offset:4416
	ds_write_b128 v99, v[222:225] offset:4480
	ds_write_b128 v99, v[226:229] offset:4544
	v_lshl_add_u64 v[114:115], v[0:1], 0, v[100:101]
	flat_load_dwordx2 v[116:117], v[114:115]
	v_or_b32_e32 v100, 4, v108
	v_or_b32_e32 v102, v107, v100
	v_ashrrev_i32_e32 v103, 31, v102
	v_lshlrev_b64 v[102:103], 11, v[102:103]
	v_lshl_add_u64 v[118:119], v[0:1], 0, v[102:103]
	flat_load_dwordx2 v[120:121], v[118:119]
	v_or_b32_e32 v101, 8, v108
	v_or_b32_e32 v102, v107, v101
	v_ashrrev_i32_e32 v103, 31, v102
	v_lshlrev_b64 v[102:103], 11, v[102:103]
	v_lshl_add_u64 v[122:123], v[0:1], 0, v[102:103]
	flat_load_dwordx2 v[124:125], v[122:123]
	v_or_b32_e32 v102, 12, v108
	v_or_b32_e32 v104, v107, v102
	v_ashrrev_i32_e32 v105, 31, v104
	v_lshlrev_b64 v[104:105], 11, v[104:105]
	v_lshl_add_u64 v[126:127], v[0:1], 0, v[104:105]
	flat_load_dwordx2 v[128:129], v[126:127]
	v_or_b32_e32 v103, 16, v108
	v_or_b32_e32 v104, v107, v103
	v_ashrrev_i32_e32 v105, 31, v104
	v_lshlrev_b64 v[104:105], 11, v[104:105]
	v_lshl_add_u64 v[134:135], v[0:1], 0, v[104:105]
	flat_load_dwordx2 v[136:137], v[134:135]
	v_or_b32_e32 v104, 20, v108
	v_or_b32_e32 v110, v107, v104
	v_ashrrev_i32_e32 v111, 31, v110
	v_lshlrev_b64 v[110:111], 11, v[110:111]
	v_lshl_add_u64 v[138:139], v[0:1], 0, v[110:111]
	flat_load_dwordx2 v[140:141], v[138:139]
	v_or_b32_e32 v105, 24, v108
	v_or_b32_e32 v110, v107, v105
	v_ashrrev_i32_e32 v111, 31, v110
	v_lshlrev_b64 v[110:111], 11, v[110:111]
	v_lshl_add_u64 v[142:143], v[0:1], 0, v[110:111]
	flat_load_dwordx2 v[144:145], v[142:143]
	v_or_b32_e32 v106, 28, v108
	v_or_b32_e32 v146, v107, v106
	v_ashrrev_i32_e32 v147, 31, v146
	v_lshlrev_b64 v[146:147], 11, v[146:147]
	v_lshl_add_u64 v[146:147], v[0:1], 0, v[146:147]
	flat_load_dwordx2 v[148:149], v[146:147]
	v_mul_u32_u24_e32 v98, 0x110, v108
	v_lshlrev_b32_e32 v110, 2, v112
	v_add3_u32 v98, v109, v110, v98
	ds_read_b128 v[110:113], v98
	s_add_i32 s0, s30, 0x1600
	s_lshl_b64 s[42:43], s[0:1], 11
	s_waitcnt vmcnt(0) lgkmcnt(0)
	v_and_b32_e32 v151, 0xffff0000, v116
	v_lshlrev_b32_e32 v150, 16, v116
	v_and_b32_e32 v153, 0xffff0000, v117
	v_lshlrev_b32_e32 v152, 16, v117
	v_pk_mul_f32 v[110:111], v[110:111], v[150:151]
	v_pk_mul_f32 v[112:113], v[112:113], v[152:153]
	v_cvt_pk_bf16_f32 v110, v110, v111
	v_cvt_pk_bf16_f32 v111, v112, v113
	flat_store_dwordx2 v[114:115], v[110:111]
	ds_read_b128 v[110:113], v98 offset:1088
	v_and_b32_e32 v115, 0xffff0000, v120
	v_lshlrev_b32_e32 v114, 16, v120
	v_and_b32_e32 v117, 0xffff0000, v121
	v_lshlrev_b32_e32 v116, 16, v121
	s_waitcnt lgkmcnt(0)
	v_pk_mul_f32 v[110:111], v[110:111], v[114:115]
	v_pk_mul_f32 v[112:113], v[112:113], v[116:117]
	v_cvt_pk_bf16_f32 v110, v110, v111
	v_cvt_pk_bf16_f32 v111, v112, v113
	flat_store_dwordx2 v[118:119], v[110:111]
	ds_read_b128 v[110:113], v98 offset:2176
	v_and_b32_e32 v115, 0xffff0000, v124
	v_lshlrev_b32_e32 v114, 16, v124
	v_and_b32_e32 v117, 0xffff0000, v125
	v_lshlrev_b32_e32 v116, 16, v125
	s_waitcnt lgkmcnt(0)
	v_pk_mul_f32 v[110:111], v[110:111], v[114:115]
	v_pk_mul_f32 v[112:113], v[112:113], v[116:117]
	v_cvt_pk_bf16_f32 v110, v110, v111
	v_cvt_pk_bf16_f32 v111, v112, v113
	flat_store_dwordx2 v[122:123], v[110:111]
	ds_read_b128 v[110:113], v98 offset:3264
	v_and_b32_e32 v115, 0xffff0000, v128
	v_lshlrev_b32_e32 v114, 16, v128
	v_mov_b32_e32 v150, v132
	s_waitcnt lgkmcnt(0)
	v_pk_mul_f32 v[110:111], v[110:111], v[114:115]
	v_and_b32_e32 v115, 0xffff0000, v129
	v_lshlrev_b32_e32 v114, 16, v129
	v_pk_mul_f32 v[112:113], v[112:113], v[114:115]
	v_cvt_pk_bf16_f32 v110, v110, v111
	v_cvt_pk_bf16_f32 v111, v112, v113
	flat_store_dwordx2 v[126:127], v[110:111]
	ds_read_b128 v[110:113], v98 offset:4352
	v_and_b32_e32 v115, 0xffff0000, v136
	v_lshlrev_b32_e32 v114, 16, v136
	s_waitcnt lgkmcnt(0)
	v_pk_mul_f32 v[110:111], v[110:111], v[114:115]
	v_and_b32_e32 v115, 0xffff0000, v137
	v_lshlrev_b32_e32 v114, 16, v137
	v_pk_mul_f32 v[112:113], v[112:113], v[114:115]
	v_cvt_pk_bf16_f32 v110, v110, v111
	v_cvt_pk_bf16_f32 v111, v112, v113
	flat_store_dwordx2 v[134:135], v[110:111]
	ds_read_b128 v[110:113], v98 offset:5440
	v_and_b32_e32 v115, 0xffff0000, v140
	v_lshlrev_b32_e32 v114, 16, v140
	s_waitcnt lgkmcnt(0)
	v_pk_mul_f32 v[110:111], v[110:111], v[114:115]
	v_and_b32_e32 v115, 0xffff0000, v141
	v_lshlrev_b32_e32 v114, 16, v141
	v_pk_mul_f32 v[112:113], v[112:113], v[114:115]
	v_cvt_pk_bf16_f32 v110, v110, v111
	v_cvt_pk_bf16_f32 v111, v112, v113
	flat_store_dwordx2 v[138:139], v[110:111]
	ds_read_b128 v[110:113], v98 offset:6528
	v_and_b32_e32 v115, 0xffff0000, v144
	v_lshlrev_b32_e32 v114, 16, v144
	s_waitcnt lgkmcnt(0)
	v_pk_mul_f32 v[110:111], v[110:111], v[114:115]
	v_and_b32_e32 v115, 0xffff0000, v145
	v_lshlrev_b32_e32 v114, 16, v145
	v_pk_mul_f32 v[112:113], v[112:113], v[114:115]
	v_cvt_pk_bf16_f32 v110, v110, v111
	v_cvt_pk_bf16_f32 v111, v112, v113
	flat_store_dwordx2 v[142:143], v[110:111]
	ds_read_b128 v[110:113], v98 offset:7616
	v_and_b32_e32 v115, 0xffff0000, v148
	v_lshlrev_b32_e32 v114, 16, v148
	s_waitcnt lgkmcnt(0)
	v_pk_mul_f32 v[110:111], v[110:111], v[114:115]
	v_and_b32_e32 v115, 0xffff0000, v149
	v_lshlrev_b32_e32 v114, 16, v149
	v_pk_mul_f32 v[112:113], v[112:113], v[114:115]
	v_cvt_pk_bf16_f32 v110, v110, v111
	v_cvt_pk_bf16_f32 v111, v112, v113
	flat_store_dwordx2 v[146:147], v[110:111]
	ds_write_b128 v99, v[66:69]
	v_or_b32_e32 v68, 32, v107
	v_or_b32_e32 v66, v68, v108
	v_ashrrev_i32_e32 v67, 31, v66
	v_lshlrev_b64 v[66:67], 11, v[66:67]
	ds_write_b128 v99, v[70:73] offset:64
	ds_write_b128 v99, v[74:77] offset:128
	ds_write_b128 v99, v[78:81] offset:192
	ds_write_b128 v99, v[82:85] offset:4352
	ds_write_b128 v99, v[86:89] offset:4416
	ds_write_b128 v99, v[90:93] offset:4480
	ds_write_b128 v99, v[94:97] offset:4544
	v_lshl_add_u64 v[70:71], v[0:1], 0, v[66:67]
	flat_load_dwordx2 v[72:73], v[70:71]
	v_or_b32_e32 v66, v68, v100
	v_ashrrev_i32_e32 v67, 31, v66
	v_lshlrev_b64 v[66:67], 11, v[66:67]
	v_lshl_add_u64 v[74:75], v[0:1], 0, v[66:67]
	flat_load_dwordx2 v[76:77], v[74:75]
	v_or_b32_e32 v66, v68, v101
	v_ashrrev_i32_e32 v67, 31, v66
	v_lshlrev_b64 v[66:67], 11, v[66:67]
	v_lshl_add_u64 v[78:79], v[0:1], 0, v[66:67]
	flat_load_dwordx2 v[80:81], v[78:79]
	v_or_b32_e32 v66, v68, v102
	v_ashrrev_i32_e32 v67, 31, v66
	v_lshlrev_b64 v[66:67], 11, v[66:67]
	v_lshl_add_u64 v[82:83], v[0:1], 0, v[66:67]
	flat_load_dwordx2 v[84:85], v[82:83]
	v_or_b32_e32 v66, v68, v103
	v_ashrrev_i32_e32 v67, 31, v66
	v_lshlrev_b64 v[66:67], 11, v[66:67]
	v_lshl_add_u64 v[86:87], v[0:1], 0, v[66:67]
	flat_load_dwordx2 v[88:89], v[86:87]
	v_or_b32_e32 v66, v68, v104
	v_ashrrev_i32_e32 v67, 31, v66
	v_lshlrev_b64 v[66:67], 11, v[66:67]
	v_lshl_add_u64 v[90:91], v[0:1], 0, v[66:67]
	flat_load_dwordx2 v[92:93], v[90:91]
	v_or_b32_e32 v66, v68, v105
	v_ashrrev_i32_e32 v67, 31, v66
	v_lshlrev_b64 v[66:67], 11, v[66:67]
	v_lshl_add_u64 v[94:95], v[0:1], 0, v[66:67]
	flat_load_dwordx2 v[96:97], v[94:95]
	v_or_b32_e32 v66, v68, v106
	v_ashrrev_i32_e32 v67, 31, v66
	v_lshlrev_b64 v[66:67], 11, v[66:67]
	v_lshl_add_u64 v[110:111], v[0:1], 0, v[66:67]
	flat_load_dwordx2 v[112:113], v[110:111]
	ds_read_b128 v[66:69], v98
	s_waitcnt vmcnt(0) lgkmcnt(0)
	v_and_b32_e32 v115, 0xffff0000, v72
	v_lshlrev_b32_e32 v114, 16, v72
	v_and_b32_e32 v117, 0xffff0000, v73
	v_lshlrev_b32_e32 v116, 16, v73
	v_pk_mul_f32 v[66:67], v[66:67], v[114:115]
	v_pk_mul_f32 v[68:69], v[68:69], v[116:117]
	v_cvt_pk_bf16_f32 v66, v66, v67
	v_cvt_pk_bf16_f32 v67, v68, v69
	flat_store_dwordx2 v[70:71], v[66:67]
	ds_read_b128 v[66:69], v98 offset:1088
	v_and_b32_e32 v71, 0xffff0000, v76
	v_lshlrev_b32_e32 v70, 16, v76
	v_and_b32_e32 v73, 0xffff0000, v77
	v_lshlrev_b32_e32 v72, 16, v77
	s_waitcnt lgkmcnt(0)
	v_pk_mul_f32 v[66:67], v[66:67], v[70:71]
	v_pk_mul_f32 v[68:69], v[68:69], v[72:73]
	v_cvt_pk_bf16_f32 v66, v66, v67
	v_cvt_pk_bf16_f32 v67, v68, v69
	flat_store_dwordx2 v[74:75], v[66:67]
	ds_read_b128 v[66:69], v98 offset:2176
	v_and_b32_e32 v71, 0xffff0000, v80
	v_lshlrev_b32_e32 v70, 16, v80
	v_and_b32_e32 v73, 0xffff0000, v81
	v_lshlrev_b32_e32 v72, 16, v81
	s_waitcnt lgkmcnt(0)
	v_pk_mul_f32 v[66:67], v[66:67], v[70:71]
	v_pk_mul_f32 v[68:69], v[68:69], v[72:73]
	v_cvt_pk_bf16_f32 v66, v66, v67
	v_cvt_pk_bf16_f32 v67, v68, v69
	flat_store_dwordx2 v[78:79], v[66:67]
	ds_read_b128 v[66:69], v98 offset:3264
	v_and_b32_e32 v71, 0xffff0000, v84
	v_lshlrev_b32_e32 v70, 16, v84
	v_and_b32_e32 v73, 0xffff0000, v85
	v_lshlrev_b32_e32 v72, 16, v85
	s_waitcnt lgkmcnt(0)
	v_pk_mul_f32 v[66:67], v[66:67], v[70:71]
	v_pk_mul_f32 v[68:69], v[68:69], v[72:73]
	v_cvt_pk_bf16_f32 v66, v66, v67
	v_cvt_pk_bf16_f32 v67, v68, v69
	flat_store_dwordx2 v[82:83], v[66:67]
	ds_read_b128 v[66:69], v98 offset:4352
	v_and_b32_e32 v71, 0xffff0000, v88
	v_lshlrev_b32_e32 v70, 16, v88
	v_and_b32_e32 v73, 0xffff0000, v89
	v_lshlrev_b32_e32 v72, 16, v89
	s_waitcnt lgkmcnt(0)
	v_pk_mul_f32 v[66:67], v[66:67], v[70:71]
	v_pk_mul_f32 v[68:69], v[68:69], v[72:73]
	v_cvt_pk_bf16_f32 v66, v66, v67
	v_cvt_pk_bf16_f32 v67, v68, v69
	flat_store_dwordx2 v[86:87], v[66:67]
	ds_read_b128 v[66:69], v98 offset:5440
	v_and_b32_e32 v71, 0xffff0000, v92
	v_lshlrev_b32_e32 v70, 16, v92
	v_and_b32_e32 v73, 0xffff0000, v93
	v_lshlrev_b32_e32 v72, 16, v93
	s_waitcnt lgkmcnt(0)
	v_pk_mul_f32 v[66:67], v[66:67], v[70:71]
	v_pk_mul_f32 v[68:69], v[68:69], v[72:73]
	v_cvt_pk_bf16_f32 v66, v66, v67
	v_cvt_pk_bf16_f32 v67, v68, v69
	flat_store_dwordx2 v[90:91], v[66:67]
	ds_read_b128 v[66:69], v98 offset:6528
	v_and_b32_e32 v71, 0xffff0000, v96
	v_lshlrev_b32_e32 v70, 16, v96
	v_and_b32_e32 v73, 0xffff0000, v97
	v_lshlrev_b32_e32 v72, 16, v97
	s_waitcnt lgkmcnt(0)
	v_pk_mul_f32 v[66:67], v[66:67], v[70:71]
	v_pk_mul_f32 v[68:69], v[68:69], v[72:73]
	v_cvt_pk_bf16_f32 v66, v66, v67
	v_cvt_pk_bf16_f32 v67, v68, v69
	flat_store_dwordx2 v[94:95], v[66:67]
	ds_read_b128 v[66:69], v98 offset:7616
	v_and_b32_e32 v71, 0xffff0000, v112
	v_lshlrev_b32_e32 v70, 16, v112
	v_and_b32_e32 v73, 0xffff0000, v113
	v_lshlrev_b32_e32 v72, 16, v113
	s_waitcnt lgkmcnt(0)
	v_pk_mul_f32 v[66:67], v[66:67], v[70:71]
	v_pk_mul_f32 v[68:69], v[68:69], v[72:73]
	v_cvt_pk_bf16_f32 v66, v66, v67
	v_cvt_pk_bf16_f32 v67, v68, v69
	flat_store_dwordx2 v[110:111], v[66:67]
	ds_write_b128 v99, v[34:37]
	v_or_b32_e32 v36, 64, v107
	v_or_b32_e32 v34, v36, v108
	v_ashrrev_i32_e32 v35, 31, v34
	v_lshlrev_b64 v[34:35], 11, v[34:35]
	ds_write_b128 v99, v[38:41] offset:64
	ds_write_b128 v99, v[42:45] offset:128
	ds_write_b128 v99, v[46:49] offset:192
	ds_write_b128 v99, v[50:53] offset:4352
	ds_write_b128 v99, v[54:57] offset:4416
	ds_write_b128 v99, v[58:61] offset:4480
	ds_write_b128 v99, v[62:65] offset:4544
	v_lshl_add_u64 v[38:39], v[0:1], 0, v[34:35]
	flat_load_dwordx2 v[40:41], v[38:39]
	v_or_b32_e32 v34, v36, v100
	v_ashrrev_i32_e32 v35, 31, v34
	v_lshlrev_b64 v[34:35], 11, v[34:35]
	v_lshl_add_u64 v[42:43], v[0:1], 0, v[34:35]
	flat_load_dwordx2 v[44:45], v[42:43]
	v_or_b32_e32 v34, v36, v101
	v_ashrrev_i32_e32 v35, 31, v34
	v_lshlrev_b64 v[34:35], 11, v[34:35]
	v_lshl_add_u64 v[46:47], v[0:1], 0, v[34:35]
	flat_load_dwordx2 v[48:49], v[46:47]
	v_or_b32_e32 v34, v36, v102
	v_ashrrev_i32_e32 v35, 31, v34
	v_lshlrev_b64 v[34:35], 11, v[34:35]
	v_lshl_add_u64 v[50:51], v[0:1], 0, v[34:35]
	flat_load_dwordx2 v[52:53], v[50:51]
	v_or_b32_e32 v34, v36, v103
	v_ashrrev_i32_e32 v35, 31, v34
	v_lshlrev_b64 v[34:35], 11, v[34:35]
	v_lshl_add_u64 v[54:55], v[0:1], 0, v[34:35]
	flat_load_dwordx2 v[56:57], v[54:55]
	v_or_b32_e32 v34, v36, v104
	v_ashrrev_i32_e32 v35, 31, v34
	v_lshlrev_b64 v[34:35], 11, v[34:35]
	v_lshl_add_u64 v[58:59], v[0:1], 0, v[34:35]
	flat_load_dwordx2 v[60:61], v[58:59]
	v_or_b32_e32 v34, v36, v105
	v_ashrrev_i32_e32 v35, 31, v34
	v_lshlrev_b64 v[34:35], 11, v[34:35]
	v_lshl_add_u64 v[62:63], v[0:1], 0, v[34:35]
	flat_load_dwordx2 v[64:65], v[62:63]
	v_or_b32_e32 v34, v36, v106
	v_ashrrev_i32_e32 v35, 31, v34
	v_lshlrev_b64 v[34:35], 11, v[34:35]
	v_lshl_add_u64 v[66:67], v[0:1], 0, v[34:35]
	flat_load_dwordx2 v[68:69], v[66:67]
	ds_read_b128 v[34:37], v98
	v_or_b32_e32 v76, 0x60, v107
	v_or_b32_e32 v70, v76, v108
	v_ashrrev_i32_e32 v71, 31, v70
	s_waitcnt vmcnt(0) lgkmcnt(0)
	v_and_b32_e32 v73, 0xffff0000, v40
	v_lshlrev_b32_e32 v72, 16, v40
	v_and_b32_e32 v75, 0xffff0000, v41
	v_lshlrev_b32_e32 v74, 16, v41
	v_pk_mul_f32 v[34:35], v[34:35], v[72:73]
	v_pk_mul_f32 v[36:37], v[36:37], v[74:75]
	v_cvt_pk_bf16_f32 v34, v34, v35
	v_cvt_pk_bf16_f32 v35, v36, v37
	flat_store_dwordx2 v[38:39], v[34:35]
	ds_read_b128 v[34:37], v98 offset:1088
	v_and_b32_e32 v39, 0xffff0000, v44
	v_lshlrev_b32_e32 v38, 16, v44
	v_and_b32_e32 v41, 0xffff0000, v45
	v_lshlrev_b32_e32 v40, 16, v45
	s_waitcnt lgkmcnt(0)
	v_pk_mul_f32 v[34:35], v[34:35], v[38:39]
	v_pk_mul_f32 v[36:37], v[36:37], v[40:41]
	v_cvt_pk_bf16_f32 v34, v34, v35
	v_cvt_pk_bf16_f32 v35, v36, v37
	flat_store_dwordx2 v[42:43], v[34:35]
	ds_read_b128 v[34:37], v98 offset:2176
	v_and_b32_e32 v39, 0xffff0000, v48
	v_lshlrev_b32_e32 v38, 16, v48
	v_and_b32_e32 v41, 0xffff0000, v49
	v_lshlrev_b32_e32 v40, 16, v49
	s_waitcnt lgkmcnt(0)
	v_pk_mul_f32 v[34:35], v[34:35], v[38:39]
	v_pk_mul_f32 v[36:37], v[36:37], v[40:41]
	v_cvt_pk_bf16_f32 v34, v34, v35
	v_cvt_pk_bf16_f32 v35, v36, v37
	flat_store_dwordx2 v[46:47], v[34:35]
	ds_read_b128 v[34:37], v98 offset:3264
	v_and_b32_e32 v39, 0xffff0000, v52
	v_lshlrev_b32_e32 v38, 16, v52
	v_and_b32_e32 v41, 0xffff0000, v53
	v_lshlrev_b32_e32 v40, 16, v53
	s_waitcnt lgkmcnt(0)
	v_pk_mul_f32 v[34:35], v[34:35], v[38:39]
	v_pk_mul_f32 v[36:37], v[36:37], v[40:41]
	v_cvt_pk_bf16_f32 v34, v34, v35
	v_cvt_pk_bf16_f32 v35, v36, v37
	flat_store_dwordx2 v[50:51], v[34:35]
	ds_read_b128 v[34:37], v98 offset:4352
	v_and_b32_e32 v39, 0xffff0000, v56
	v_lshlrev_b32_e32 v38, 16, v56
	v_and_b32_e32 v41, 0xffff0000, v57
	v_lshlrev_b32_e32 v40, 16, v57
	s_waitcnt lgkmcnt(0)
	v_pk_mul_f32 v[34:35], v[34:35], v[38:39]
	v_pk_mul_f32 v[36:37], v[36:37], v[40:41]
	v_cvt_pk_bf16_f32 v34, v34, v35
	v_cvt_pk_bf16_f32 v35, v36, v37
	flat_store_dwordx2 v[54:55], v[34:35]
	ds_read_b128 v[34:37], v98 offset:5440
	v_and_b32_e32 v39, 0xffff0000, v60
	v_lshlrev_b32_e32 v38, 16, v60
	v_and_b32_e32 v41, 0xffff0000, v61
	v_lshlrev_b32_e32 v40, 16, v61
	s_waitcnt lgkmcnt(0)
	v_pk_mul_f32 v[34:35], v[34:35], v[38:39]
	v_pk_mul_f32 v[36:37], v[36:37], v[40:41]
	v_cvt_pk_bf16_f32 v34, v34, v35
	v_cvt_pk_bf16_f32 v35, v36, v37
	flat_store_dwordx2 v[58:59], v[34:35]
	ds_read_b128 v[34:37], v98 offset:6528
	v_and_b32_e32 v39, 0xffff0000, v64
	v_lshlrev_b32_e32 v38, 16, v64
	v_and_b32_e32 v41, 0xffff0000, v65
	v_lshlrev_b32_e32 v40, 16, v65
	s_waitcnt lgkmcnt(0)
	v_pk_mul_f32 v[34:35], v[34:35], v[38:39]
	v_pk_mul_f32 v[36:37], v[36:37], v[40:41]
	v_cvt_pk_bf16_f32 v34, v34, v35
	v_cvt_pk_bf16_f32 v35, v36, v37
	flat_store_dwordx2 v[62:63], v[34:35]
	ds_read_b128 v[34:37], v98 offset:7616
	v_and_b32_e32 v39, 0xffff0000, v68
	v_lshlrev_b32_e32 v38, 16, v68
	v_and_b32_e32 v41, 0xffff0000, v69
	v_lshlrev_b32_e32 v40, 16, v69
	s_waitcnt lgkmcnt(0)
	v_pk_mul_f32 v[34:35], v[34:35], v[38:39]
	v_pk_mul_f32 v[36:37], v[36:37], v[40:41]
	v_cvt_pk_bf16_f32 v34, v34, v35
	v_cvt_pk_bf16_f32 v35, v36, v37
	flat_store_dwordx2 v[66:67], v[34:35]
	ds_write_b128 v99, v[2:5]
	v_lshlrev_b64 v[2:3], 11, v[70:71]
	ds_write_b128 v99, v[6:9] offset:64
	ds_write_b128 v99, v[10:13] offset:128
	ds_write_b128 v99, v[14:17] offset:192
	ds_write_b128 v99, v[18:21] offset:4352
	ds_write_b128 v99, v[22:25] offset:4416
	ds_write_b128 v99, v[26:29] offset:4480
	ds_write_b128 v99, v[30:33] offset:4544
	v_lshl_add_u64 v[4:5], v[0:1], 0, v[2:3]
	flat_load_dwordx2 v[6:7], v[4:5]
	v_or_b32_e32 v2, v76, v100
	v_ashrrev_i32_e32 v3, 31, v2
	v_lshlrev_b64 v[2:3], 11, v[2:3]
	v_lshl_add_u64 v[8:9], v[0:1], 0, v[2:3]
	flat_load_dwordx2 v[10:11], v[8:9]
	v_or_b32_e32 v2, v76, v101
	v_ashrrev_i32_e32 v3, 31, v2
	v_lshlrev_b64 v[2:3], 11, v[2:3]
	v_lshl_add_u64 v[12:13], v[0:1], 0, v[2:3]
	flat_load_dwordx2 v[14:15], v[12:13]
	v_or_b32_e32 v2, v76, v102
	v_ashrrev_i32_e32 v3, 31, v2
	v_lshlrev_b64 v[2:3], 11, v[2:3]
	v_lshl_add_u64 v[16:17], v[0:1], 0, v[2:3]
	flat_load_dwordx2 v[18:19], v[16:17]
	v_or_b32_e32 v2, v76, v103
	v_ashrrev_i32_e32 v3, 31, v2
	v_lshlrev_b64 v[2:3], 11, v[2:3]
	v_lshl_add_u64 v[20:21], v[0:1], 0, v[2:3]
	flat_load_dwordx2 v[22:23], v[20:21]
	v_or_b32_e32 v2, v76, v104
	v_ashrrev_i32_e32 v3, 31, v2
	v_lshlrev_b64 v[2:3], 11, v[2:3]
	v_lshl_add_u64 v[24:25], v[0:1], 0, v[2:3]
	flat_load_dwordx2 v[26:27], v[24:25]
	v_or_b32_e32 v2, v76, v105
	v_ashrrev_i32_e32 v3, 31, v2
	v_lshlrev_b64 v[2:3], 11, v[2:3]
	v_lshl_add_u64 v[28:29], v[0:1], 0, v[2:3]
	flat_load_dwordx2 v[30:31], v[28:29]
	v_or_b32_e32 v2, v76, v106
	v_ashrrev_i32_e32 v3, 31, v2
	v_lshlrev_b64 v[2:3], 11, v[2:3]
	v_lshl_add_u64 v[32:33], v[0:1], 0, v[2:3]
	flat_load_dwordx2 v[34:35], v[32:33]
	ds_read_b128 v[0:3], v98
	v_mov_b32_e32 v40, s51
	v_mov_b32_e32 v41, v132
	s_waitcnt vmcnt(0) lgkmcnt(0)
	v_and_b32_e32 v37, 0xffff0000, v6
	v_lshlrev_b32_e32 v36, 16, v6
	v_and_b32_e32 v39, 0xffff0000, v7
	v_lshlrev_b32_e32 v38, 16, v7
	v_pk_mul_f32 v[0:1], v[0:1], v[36:37]
	v_pk_mul_f32 v[2:3], v[2:3], v[38:39]
	v_cvt_pk_bf16_f32 v0, v0, v1
	v_cvt_pk_bf16_f32 v1, v2, v3
	flat_store_dwordx2 v[4:5], v[0:1]
	ds_read_b128 v[0:3], v98 offset:1088
	v_and_b32_e32 v5, 0xffff0000, v10
	v_lshlrev_b32_e32 v4, 16, v10
	v_and_b32_e32 v7, 0xffff0000, v11
	v_lshlrev_b32_e32 v6, 16, v11
	s_waitcnt lgkmcnt(0)
	v_pk_mul_f32 v[0:1], v[0:1], v[4:5]
	v_pk_mul_f32 v[2:3], v[2:3], v[6:7]
	v_cvt_pk_bf16_f32 v0, v0, v1
	v_cvt_pk_bf16_f32 v1, v2, v3
	flat_store_dwordx2 v[8:9], v[0:1]
	ds_read_b128 v[0:3], v98 offset:2176
	v_and_b32_e32 v5, 0xffff0000, v14
	v_lshlrev_b32_e32 v4, 16, v14
	v_and_b32_e32 v7, 0xffff0000, v15
	v_lshlrev_b32_e32 v6, 16, v15
	s_waitcnt lgkmcnt(0)
	v_pk_mul_f32 v[0:1], v[0:1], v[4:5]
	v_pk_mul_f32 v[2:3], v[2:3], v[6:7]
	v_cvt_pk_bf16_f32 v0, v0, v1
	v_cvt_pk_bf16_f32 v1, v2, v3
	flat_store_dwordx2 v[12:13], v[0:1]
	ds_read_b128 v[0:3], v98 offset:3264
	v_and_b32_e32 v5, 0xffff0000, v18
	v_lshlrev_b32_e32 v4, 16, v18
	v_and_b32_e32 v7, 0xffff0000, v19
	v_lshlrev_b32_e32 v6, 16, v19
	s_waitcnt lgkmcnt(0)
	v_pk_mul_f32 v[0:1], v[0:1], v[4:5]
	v_pk_mul_f32 v[2:3], v[2:3], v[6:7]
	v_cvt_pk_bf16_f32 v0, v0, v1
	v_cvt_pk_bf16_f32 v1, v2, v3
	flat_store_dwordx2 v[16:17], v[0:1]
	ds_read_b128 v[0:3], v98 offset:4352
	v_and_b32_e32 v5, 0xffff0000, v22
	v_lshlrev_b32_e32 v4, 16, v22
	v_and_b32_e32 v7, 0xffff0000, v23
	v_lshlrev_b32_e32 v6, 16, v23
	s_waitcnt lgkmcnt(0)
	v_pk_mul_f32 v[0:1], v[0:1], v[4:5]
	v_pk_mul_f32 v[2:3], v[2:3], v[6:7]
	v_cvt_pk_bf16_f32 v0, v0, v1
	v_cvt_pk_bf16_f32 v1, v2, v3
	flat_store_dwordx2 v[20:21], v[0:1]
	ds_read_b128 v[0:3], v98 offset:5440
	v_and_b32_e32 v5, 0xffff0000, v26
	v_lshlrev_b32_e32 v4, 16, v26
	v_and_b32_e32 v7, 0xffff0000, v27
	v_lshlrev_b32_e32 v6, 16, v27
	s_waitcnt lgkmcnt(0)
	v_pk_mul_f32 v[0:1], v[0:1], v[4:5]
	v_pk_mul_f32 v[2:3], v[2:3], v[6:7]
	v_cvt_pk_bf16_f32 v0, v0, v1
	v_cvt_pk_bf16_f32 v1, v2, v3
	flat_store_dwordx2 v[24:25], v[0:1]
	ds_read_b128 v[0:3], v98 offset:6528
	v_and_b32_e32 v5, 0xffff0000, v30
	v_lshlrev_b32_e32 v4, 16, v30
	v_and_b32_e32 v7, 0xffff0000, v31
	v_lshlrev_b32_e32 v6, 16, v31
	s_waitcnt lgkmcnt(0)
	v_pk_mul_f32 v[0:1], v[0:1], v[4:5]
	v_pk_mul_f32 v[2:3], v[2:3], v[6:7]
	v_cvt_pk_bf16_f32 v0, v0, v1
	v_cvt_pk_bf16_f32 v1, v2, v3
	flat_store_dwordx2 v[28:29], v[0:1]
	ds_read_b128 v[0:3], v98 offset:7616
	v_and_b32_e32 v5, 0xffff0000, v34
	v_lshlrev_b32_e32 v4, 16, v34
	v_and_b32_e32 v7, 0xffff0000, v35
	v_lshlrev_b32_e32 v6, 16, v35
	s_waitcnt lgkmcnt(0)
	v_pk_mul_f32 v[0:1], v[0:1], v[4:5]
	v_pk_mul_f32 v[2:3], v[2:3], v[6:7]
	v_cvt_pk_bf16_f32 v0, v0, v1
	v_cvt_pk_bf16_f32 v1, v2, v3
	flat_store_dwordx2 v[32:33], v[0:1]
	ds_read_b64 v[128:129], v40
	s_waitcnt lgkmcnt(0)
	v_lshl_add_u64 v[2:3], v[128:129], 0, s[42:43]
	v_lshlrev_b32_e32 v5, 4, v41
	v_and_b32_e32 v0, 32, v41
	v_lshrrev_b32_e32 v1, 1, v41
	v_bitop3_b32 v0, v5, v0, 48 bitop3:0x6c
	v_bfe_u32 v16, v41, 2, 4
	v_ashrrev_i32_e32 v17, 3, v41
	v_and_b32_e32 v9, 0xfffffc00, v5
	v_and_b32_e32 v18, 32, v1
	v_add_u32_e32 v1, 0x2000, v5
	v_lshrrev_b32_e32 v19, 1, v0
	v_add_u32_e32 v8, 0x4000, v5
	v_add_u32_e32 v5, 0x6000, v5
	v_and_or_b32 v4, v17, s44, v16
	v_ashrrev_i32_e32 v20, 7, v1
	v_or_b32_e32 v10, v19, v18
	v_ashrrev_i32_e32 v21, 7, v8
	v_ashrrev_i32_e32 v22, 7, v5
	v_and_or_b32 v6, v20, s44, v16
	v_lshl_add_u64 v[0:1], v[128:129], 0, s[36:37]
	v_lshl_or_b32 v130, v4, 10, v10
	v_and_or_b32 v8, v21, s44, v16
	v_and_or_b32 v5, v22, s44, v16
	v_add_u32_e32 v151, 0, v9
	v_lshl_or_b32 v4, v6, 10, v10
	v_lshl_add_u64 v[6:7], v[0:1], 0, s[4:5]
	v_lshl_or_b32 v8, v8, 10, v10
	v_lshl_or_b32 v10, v5, 10, v10
	v_add_u32_e32 v5, 0x8000, v151
	v_lshlrev_b64 v[12:13], 1, v[130:131]
	v_readfirstlane_b32 s0, v151
	v_lshl_add_u64 v[14:15], v[6:7], 0, v[12:13]
	s_mov_b32 m0, s0
	v_readfirstlane_b32 s0, v5
	v_mov_b32_e32 v5, v131
	v_add_u32_e32 v9, 0x2000, v151
	global_load_lds_dwordx4 v[14:15], off
	v_lshl_add_u64 v[12:13], v[2:3], 0, v[12:13]
	s_mov_b32 m0, s0
	v_lshlrev_b64 v[4:5], 1, v[4:5]
	v_readfirstlane_b32 s0, v9
	v_add_u32_e32 v9, 0xa000, v151
	global_load_lds_dwordx4 v[12:13], off
	v_lshl_add_u64 v[12:13], v[6:7], 0, v[4:5]
	s_mov_b32 m0, s0
	v_readfirstlane_b32 s0, v9
	global_load_lds_dwordx4 v[12:13], off
	v_lshl_add_u64 v[4:5], v[2:3], 0, v[4:5]
	s_mov_b32 m0, s0
	v_mov_b32_e32 v9, v131
	v_add_u32_e32 v11, 0x4000, v151
	global_load_lds_dwordx4 v[4:5], off
	v_lshlrev_b64 v[4:5], 1, v[8:9]
	v_readfirstlane_b32 s0, v11
	v_lshl_add_u64 v[8:9], v[6:7], 0, v[4:5]
	s_mov_b32 m0, s0
	v_lshl_add_u64 v[4:5], v[2:3], 0, v[4:5]
	global_load_lds_dwordx4 v[8:9], off
	v_add_u32_e32 v8, 0xc000, v151
	v_mov_b32_e32 v11, v131
	v_readfirstlane_b32 s0, v8
	s_mov_b32 m0, s0
	v_add_u32_e32 v8, 0x6000, v151
	global_load_lds_dwordx4 v[4:5], off
	v_lshlrev_b64 v[4:5], 1, v[10:11]
	v_readfirstlane_b32 s0, v8
	v_lshl_add_u64 v[6:7], v[6:7], 0, v[4:5]
	s_mov_b32 m0, s0
	v_lshl_add_u64 v[4:5], v[2:3], 0, v[4:5]
	global_load_lds_dwordx4 v[6:7], off
	v_add_u32_e32 v6, 0xe000, v151
	v_and_b32_e32 v23, 15, v41
	v_readfirstlane_b32 s0, v6
	s_mov_b32 m0, s0
	v_lshlrev_b32_e32 v6, 2, v41
	global_load_lds_dwordx4 v[4:5], off
	v_and_b32_e32 v4, 48, v41
	v_lshlrev_b32_e32 v5, 6, v23
	v_and_b32_e32 v6, 32, v6
	v_bitop3_b32 v152, v5, v6, v4 bitop3:0x36
	v_lshlrev_b32_e32 v5, 7, v41
	v_and_b32_e32 v153, 0x6000, v5
	v_lshlrev_b32_e32 v5, 6, v41
	v_and_b32_e32 v154, 0xffffc000, v5
	v_and_b32_e32 v5, 0x3c0, v5
	v_bitop3_b32 v156, v5, v6, v4 bitop3:0x36
	v_lshlrev_b32_e32 v4, 10, v22
	v_and_or_b32 v4, v4, s45, v19
	v_lshlrev_b32_e32 v10, 10, v16
	v_lshlrev_b32_e32 v6, 10, v21
	v_or3_b32 v130, v4, v10, v18
	v_and_or_b32 v6, v6, s45, v19
	v_lshlrev_b32_e32 v8, 10, v20
	v_lshlrev_b64 v[4:5], 1, v[130:131]
	v_or3_b32 v130, v6, v10, v18
	v_and_or_b32 v8, v8, s45, v19
	v_lshlrev_b32_e32 v11, 10, v17
	v_lshlrev_b64 v[6:7], 1, v[130:131]
	v_or3_b32 v130, v8, v10, v18
	v_and_or_b32 v11, v11, s45, v19
	s_waitcnt vmcnt(0)
	v_lshl_add_u64 v[2:3], v[2:3], 0, s[6:7]
	v_lshlrev_b64 v[8:9], 1, v[130:131]
	v_or3_b32 v130, v11, v10, v18
	v_lshl_add_u64 v[0:1], v[0:1], 0, s[8:9]
	v_lshl_add_u64 v[138:139], v[2:3], 0, v[8:9]
	v_lshlrev_b64 v[10:11], 1, v[130:131]
	v_lshl_add_u64 v[146:147], v[0:1], 0, v[8:9]
	v_mov_b32_e32 v8, 0
	v_or_b32_e32 v155, 0x800, v154
	v_or_b32_e32 v157, 0x1000, v154
	v_or_b32_e32 v158, 0x1800, v154
	v_or_b32_e32 v159, 0x2000, v154
	v_or_b32_e32 v160, 0x2800, v154
	v_or_b32_e32 v161, 0x3000, v154
	v_or_b32_e32 v162, 0x3800, v154
	v_lshl_add_u64 v[134:135], v[2:3], 0, v[4:5]
	v_lshl_add_u64 v[136:137], v[2:3], 0, v[6:7]
	v_lshl_add_u64 v[140:141], v[2:3], 0, v[10:11]
	v_lshl_add_u64 v[142:143], v[0:1], 0, v[4:5]
	v_lshl_add_u64 v[144:145], v[0:1], 0, v[6:7]
	v_lshl_add_u64 v[148:149], v[0:1], 0, v[10:11]
	s_mov_b64 s[42:43], 0
	v_mov_b32_e32 v9, v8
	v_mov_b32_e32 v10, v8
	v_mov_b32_e32 v11, v8
	v_mov_b32_e32 v20, v8
	v_mov_b32_e32 v21, v8
	v_mov_b32_e32 v22, v8
	v_mov_b32_e32 v23, v8
	v_mov_b32_e32 v28, v8
	v_mov_b32_e32 v29, v8
	v_mov_b32_e32 v30, v8
	v_mov_b32_e32 v31, v8
	v_mov_b32_e32 v36, v8
	v_mov_b32_e32 v37, v8
	v_mov_b32_e32 v38, v8
	v_mov_b32_e32 v39, v8
	v_mov_b32_e32 v0, v8
	v_mov_b32_e32 v1, v8
	v_mov_b32_e32 v2, v8
	v_mov_b32_e32 v3, v8
	v_mov_b32_e32 v4, v8
	v_mov_b32_e32 v5, v8
	v_mov_b32_e32 v6, v8
	v_mov_b32_e32 v7, v8
	v_mov_b32_e32 v12, v8
	v_mov_b32_e32 v13, v8
	v_mov_b32_e32 v14, v8
	v_mov_b32_e32 v15, v8
	v_mov_b32_e32 v16, v8
	v_mov_b32_e32 v17, v8
	v_mov_b32_e32 v18, v8
	v_mov_b32_e32 v19, v8
	v_mov_b32_e32 v24, v8
	v_mov_b32_e32 v25, v8
	v_mov_b32_e32 v26, v8
	v_mov_b32_e32 v27, v8
	v_mov_b32_e32 v32, v8
	v_mov_b32_e32 v33, v8
	v_mov_b32_e32 v34, v8
	v_mov_b32_e32 v35, v8
	v_mov_b32_e32 v40, v8
	v_mov_b32_e32 v41, v8
	v_mov_b32_e32 v42, v8
	v_mov_b32_e32 v43, v8
	v_mov_b32_e32 v44, v8
	v_mov_b32_e32 v45, v8
	v_mov_b32_e32 v46, v8
	v_mov_b32_e32 v47, v8
	v_mov_b32_e32 v48, v8
	v_mov_b32_e32 v49, v8
	v_mov_b32_e32 v50, v8
	v_mov_b32_e32 v51, v8
	v_mov_b32_e32 v52, v8
	v_mov_b32_e32 v53, v8
	v_mov_b32_e32 v54, v8
	v_mov_b32_e32 v55, v8
	v_mov_b32_e32 v56, v8
	v_mov_b32_e32 v57, v8
	v_mov_b32_e32 v58, v8
	v_mov_b32_e32 v59, v8
	v_mov_b32_e32 v60, v8
	v_mov_b32_e32 v61, v8
	v_mov_b32_e32 v62, v8
	v_mov_b32_e32 v63, v8
	v_mov_b32_e32 v64, v8
	v_mov_b32_e32 v65, v8
	v_mov_b32_e32 v66, v8
	v_mov_b32_e32 v67, v8
	v_mov_b32_e32 v68, v8
	v_mov_b32_e32 v69, v8
	v_mov_b32_e32 v70, v8
	v_mov_b32_e32 v71, v8
	v_mov_b32_e32 v72, v8
	v_mov_b32_e32 v73, v8
	v_mov_b32_e32 v74, v8
	v_mov_b32_e32 v75, v8
	v_mov_b32_e32 v76, v8
	v_mov_b32_e32 v77, v8
	v_mov_b32_e32 v78, v8
	v_mov_b32_e32 v79, v8
	v_mov_b32_e32 v80, v8
	v_mov_b32_e32 v81, v8
	v_mov_b32_e32 v82, v8
	v_mov_b32_e32 v83, v8
	v_mov_b32_e32 v84, v8
	v_mov_b32_e32 v85, v8
	v_mov_b32_e32 v86, v8
	v_mov_b32_e32 v87, v8
	v_mov_b32_e32 v88, v8
	v_mov_b32_e32 v89, v8
	v_mov_b32_e32 v90, v8
	v_mov_b32_e32 v91, v8
	v_mov_b32_e32 v92, v8
	v_mov_b32_e32 v93, v8
	v_mov_b32_e32 v94, v8
	v_mov_b32_e32 v95, v8
	v_mov_b32_e32 v96, v8
	v_mov_b32_e32 v97, v8
	v_mov_b32_e32 v98, v8
	v_mov_b32_e32 v99, v8
	v_mov_b32_e32 v100, v8
	v_mov_b32_e32 v101, v8
	v_mov_b32_e32 v102, v8
	v_mov_b32_e32 v103, v8
	v_mov_b32_e32 v104, v8
	v_mov_b32_e32 v105, v8
	v_mov_b32_e32 v106, v8
	v_mov_b32_e32 v107, v8
	v_mov_b32_e32 v108, v8
	v_mov_b32_e32 v109, v8
	v_mov_b32_e32 v110, v8
	v_mov_b32_e32 v111, v8
	v_mov_b32_e32 v112, v8
	v_mov_b32_e32 v113, v8
	v_mov_b32_e32 v114, v8
	v_mov_b32_e32 v115, v8
	v_mov_b32_e32 v116, v8
	v_mov_b32_e32 v117, v8
	v_mov_b32_e32 v118, v8
	v_mov_b32_e32 v119, v8
	v_mov_b32_e32 v120, v8
	v_mov_b32_e32 v121, v8
	v_mov_b32_e32 v122, v8
	v_mov_b32_e32 v123, v8
	v_mov_b32_e32 v124, v8
	v_mov_b32_e32 v125, v8
	v_mov_b32_e32 v126, v8
	v_mov_b32_e32 v127, v8
	s_waitcnt vmcnt(0) lgkmcnt(0)
	s_barrier
	v_readfirstlane_b32 s100, v151
	s_and_b32 s0, s29, 0x10000
	s_xor_b32 s53, s0, 0x10000
	s_add_i32 s0, s0, 0
	v_add3_u32 v130, s0, v152, v153
	v_add3_u32 v163, s0, v152, v154
	v_add3_u32 v196, s0, v156, v155
	v_add3_u32 v197, s0, v156, v157
	v_add3_u32 v198, s0, v156, v158
	v_add3_u32 v199, s0, v156, v159
	v_add3_u32 v200, s0, v156, v160
	v_add3_u32 v201, s0, v156, v161
	v_add3_u32 v202, s0, v156, v162
	ds_read_b128 v[180:183], v130 offset:32768
	ds_read_b128 v[164:167], v163
	ds_read_b128 v[168:171], v196
	ds_read_b128 v[172:175], v197
	ds_read_b128 v[176:179], v198
	ds_read_b128 v[184:187], v130 offset:34816
	ds_read_b128 v[188:191], v130 offset:36864
	ds_read_b128 v[192:195], v130 offset:38912
	s_add_i32 s101, s100, s53
	v_readfirstlane_b32 s98, v148
	v_readfirstlane_b32 s99, v149
	v_readfirstlane_b32 vcc_lo, v140
	v_readfirstlane_b32 vcc_hi, v141
	s_sub_u32 s98, s98, 0x1000000
	s_subb_u32 s99, s99, 0
	s_sub_u32 vcc_lo, vcc_lo, 0x1000000
	s_subb_u32 vcc_hi, vcc_hi, 0
	v_subrev_u32_e32 v148, s98, v148
	v_subrev_u32_e32 v140, vcc_lo, v140
	v_subrev_u32_e32 v146, s98, v146
	v_subrev_u32_e32 v138, vcc_lo, v138
	v_subrev_u32_e32 v144, s98, v144
	v_subrev_u32_e32 v136, vcc_lo, v136
	v_subrev_u32_e32 v142, s98, v142
	v_subrev_u32_e32 v134, vcc_lo, v134
	s_mov_b32 m0, s101
	s_nop 0
	global_load_lds_dwordx4 v148, s[98:99]
	s_add_i32 m0, s101, 0x8000
	s_nop 0
	global_load_lds_dwordx4 v140, vcc
	s_add_i32 m0, s101, 0x2000
	s_nop 0
	global_load_lds_dwordx4 v146, s[98:99]
	s_add_i32 m0, s101, 0xa000
	s_nop 0
	global_load_lds_dwordx4 v138, vcc
	s_add_i32 m0, s101, 0x4000
	s_nop 0
	global_load_lds_dwordx4 v144, s[98:99]
	s_add_i32 m0, s101, 0xc000
	s_nop 0
	global_load_lds_dwordx4 v136, vcc
	s_add_i32 m0, s101, 0x6000
	s_nop 0
	global_load_lds_dwordx4 v142, s[98:99]
	s_add_i32 m0, s101, 0xe000
	s_nop 0
	global_load_lds_dwordx4 v134, vcc
.LBB0_795:
	s_and_b32 s0, s29, 0x10000
	s_xor_b32 s53, s0, 0x10000
	s_add_i32 s0, s0, 0
	s_add_i32 s101, s100, s53
	s_cmpk_eq_i32 s42, 0
	s_cbranch_scc1 .Lg1n_795
	s_waitcnt lgkmcnt(3)
	v_mfma_f32_16x16x32_bf16 v[124:127], v[180:183], v[164:167], v[124:127]
	v_mfma_f32_16x16x32_bf16 v[108:111], v[180:183], v[168:171], v[108:111]
	v_mfma_f32_16x16x32_bf16 v[92:95], v[180:183], v[172:175], v[92:95]
	v_mfma_f32_16x16x32_bf16 v[76:79], v[180:183], v[176:179], v[76:79]
	ds_read_b128 v[240:243], v199
	ds_read_b128 v[244:247], v200
	s_add_i32 m0, s101, 0x4000
	s_nop 0
	global_load_lds_dwordx4 v144, s[98:99]
	s_waitcnt lgkmcnt(4)
	v_mfma_f32_16x16x32_bf16 v[120:123], v[184:187], v[164:167], v[120:123]
	v_mfma_f32_16x16x32_bf16 v[104:107], v[184:187], v[168:171], v[104:107]
	v_mfma_f32_16x16x32_bf16 v[88:91], v[184:187], v[172:175], v[88:91]
	v_mfma_f32_16x16x32_bf16 v[72:75], v[184:187], v[176:179], v[72:75]
	ds_read_b128 v[248:251], v201
	ds_read_b128 v[252:255], v202
	s_add_i32 m0, s101, 0xc000
	s_nop 0
	global_load_lds_dwordx4 v136, vcc
	s_waitcnt lgkmcnt(5)
	v_mfma_f32_16x16x32_bf16 v[116:119], v[188:191], v[164:167], v[116:119]
	v_mfma_f32_16x16x32_bf16 v[100:103], v[188:191], v[168:171], v[100:103]
	v_mfma_f32_16x16x32_bf16 v[84:87], v[188:191], v[172:175], v[84:87]
	v_mfma_f32_16x16x32_bf16 v[68:71], v[188:191], v[176:179], v[68:71]
	s_add_i32 m0, s101, 0x6000
	s_nop 0
	global_load_lds_dwordx4 v142, s[98:99]
	s_waitcnt lgkmcnt(4)
	v_mfma_f32_16x16x32_bf16 v[112:115], v[192:195], v[164:167], v[112:115]
	v_mfma_f32_16x16x32_bf16 v[96:99], v[192:195], v[168:171], v[96:99]
	v_mfma_f32_16x16x32_bf16 v[80:83], v[192:195], v[172:175], v[80:83]
	v_mfma_f32_16x16x32_bf16 v[64:67], v[192:195], v[176:179], v[64:67]
	s_add_i32 m0, s101, 0xe000
	s_nop 0
	global_load_lds_dwordx4 v134, vcc
.Lg2_795:
	ds_read_b128 v[164:167], v163 offset:1024
	ds_read_b128 v[168:171], v196 offset:1024
	ds_read_b128 v[172:175], v197 offset:1024
	ds_read_b128 v[176:179], v198 offset:1024
	s_waitcnt lgkmcnt(4)
	v_mfma_f32_16x16x32_bf16 v[60:63], v[180:183], v[240:243], v[60:63]
	v_mfma_f32_16x16x32_bf16 v[44:47], v[180:183], v[244:247], v[44:47]
	v_mfma_f32_16x16x32_bf16 v[16:19], v[180:183], v[248:251], v[16:19]
	v_mfma_f32_16x16x32_bf16 v[36:39], v[180:183], v[252:255], v[36:39]
	ds_read_b128 v[180:183], v130 offset:33792
	v_mfma_f32_16x16x32_bf16 v[56:59], v[184:187], v[240:243], v[56:59]
	v_mfma_f32_16x16x32_bf16 v[40:43], v[184:187], v[244:247], v[40:43]
	v_mfma_f32_16x16x32_bf16 v[12:15], v[184:187], v[248:251], v[12:15]
	v_mfma_f32_16x16x32_bf16 v[28:31], v[184:187], v[252:255], v[28:31]
	ds_read_b128 v[184:187], v130 offset:35840
	v_mfma_f32_16x16x32_bf16 v[52:55], v[188:191], v[240:243], v[52:55]
	v_mfma_f32_16x16x32_bf16 v[32:35], v[188:191], v[244:247], v[32:35]
	v_mfma_f32_16x16x32_bf16 v[4:7], v[188:191], v[248:251], v[4:7]
	v_mfma_f32_16x16x32_bf16 v[20:23], v[188:191], v[252:255], v[20:23]
	ds_read_b128 v[188:191], v130 offset:37888
	v_mfma_f32_16x16x32_bf16 v[48:51], v[192:195], v[240:243], v[48:51]
	v_mfma_f32_16x16x32_bf16 v[24:27], v[192:195], v[244:247], v[24:27]
	v_mfma_f32_16x16x32_bf16 v[0:3], v[192:195], v[248:251], v[0:3]
	v_mfma_f32_16x16x32_bf16 v[8:11], v[192:195], v[252:255], v[8:11]
	ds_read_b128 v[192:195], v130 offset:39936
	s_waitcnt lgkmcnt(3)
	v_mfma_f32_16x16x32_bf16 v[124:127], v[180:183], v[164:167], v[124:127]
	v_mfma_f32_16x16x32_bf16 v[108:111], v[180:183], v[168:171], v[108:111]
	v_mfma_f32_16x16x32_bf16 v[92:95], v[180:183], v[172:175], v[92:95]
	v_mfma_f32_16x16x32_bf16 v[76:79], v[180:183], v[176:179], v[76:79]
	ds_read_b128 v[240:243], v199 offset:1024
	ds_read_b128 v[244:247], v200 offset:1024
	s_waitcnt lgkmcnt(4)
	v_mfma_f32_16x16x32_bf16 v[120:123], v[184:187], v[164:167], v[120:123]
	v_mfma_f32_16x16x32_bf16 v[104:107], v[184:187], v[168:171], v[104:107]
	v_mfma_f32_16x16x32_bf16 v[88:91], v[184:187], v[172:175], v[88:91]
	v_mfma_f32_16x16x32_bf16 v[72:75], v[184:187], v[176:179], v[72:75]
	ds_read_b128 v[248:251], v201 offset:1024
	ds_read_b128 v[252:255], v202 offset:1024
	s_waitcnt lgkmcnt(5)
	v_mfma_f32_16x16x32_bf16 v[116:119], v[188:191], v[164:167], v[116:119]
	v_mfma_f32_16x16x32_bf16 v[100:103], v[188:191], v[168:171], v[100:103]
	v_mfma_f32_16x16x32_bf16 v[84:87], v[188:191], v[172:175], v[84:87]
	v_mfma_f32_16x16x32_bf16 v[68:71], v[188:191], v[176:179], v[68:71]
	s_waitcnt lgkmcnt(4)
	v_mfma_f32_16x16x32_bf16 v[112:115], v[192:195], v[164:167], v[112:115]
	v_mfma_f32_16x16x32_bf16 v[96:99], v[192:195], v[168:171], v[96:99]
	v_mfma_f32_16x16x32_bf16 v[80:83], v[192:195], v[172:175], v[80:83]
	v_mfma_f32_16x16x32_bf16 v[64:67], v[192:195], v[176:179], v[64:67]
	s_waitcnt vmcnt(0) lgkmcnt(0)
	s_barrier
	s_add_i32 s101, s100, s0
	s_cmpk_eq_i32 s42, 0x700
	s_cbranch_scc1 .Lg4n_795
	s_add_u32 s98, s98, 0x80
	s_addc_u32 s99, s99, 0
	s_add_u32 vcc_lo, vcc_lo, 0x80
	s_addc_u32 vcc_hi, vcc_hi, 0
	v_mfma_f32_16x16x32_bf16 v[60:63], v[180:183], v[240:243], v[60:63]
	v_mfma_f32_16x16x32_bf16 v[44:47], v[180:183], v[244:247], v[44:47]
	v_mfma_f32_16x16x32_bf16 v[16:19], v[180:183], v[248:251], v[16:19]
	v_mfma_f32_16x16x32_bf16 v[36:39], v[180:183], v[252:255], v[36:39]
	v_add3_u32 v130, s53, v152, v153
	ds_read_b128 v[180:183], v130 offset:32768
	v_add3_u32 v163, s53, v152, v154
	v_add3_u32 v196, s53, v156, v155
	v_add3_u32 v197, s53, v156, v157
	v_add3_u32 v198, s53, v156, v158
	ds_read_b128 v[164:167], v163
	ds_read_b128 v[168:171], v196
	ds_read_b128 v[172:175], v197
	ds_read_b128 v[176:179], v198
	s_mov_b32 m0, s101
	s_nop 0
	global_load_lds_dwordx4 v148, s[98:99]
	v_mfma_f32_16x16x32_bf16 v[56:59], v[184:187], v[240:243], v[56:59]
	v_mfma_f32_16x16x32_bf16 v[40:43], v[184:187], v[244:247], v[40:43]
	v_mfma_f32_16x16x32_bf16 v[12:15], v[184:187], v[248:251], v[12:15]
	v_mfma_f32_16x16x32_bf16 v[28:31], v[184:187], v[252:255], v[28:31]
	ds_read_b128 v[184:187], v130 offset:34816
	v_add3_u32 v199, s53, v156, v159
	v_add3_u32 v200, s53, v156, v160
	v_add3_u32 v201, s53, v156, v161
	v_add3_u32 v202, s53, v156, v162
	s_add_i32 m0, s101, 0x8000
	s_nop 0
	global_load_lds_dwordx4 v140, vcc
	v_mfma_f32_16x16x32_bf16 v[52:55], v[188:191], v[240:243], v[52:55]
	v_mfma_f32_16x16x32_bf16 v[32:35], v[188:191], v[244:247], v[32:35]
	v_mfma_f32_16x16x32_bf16 v[4:7], v[188:191], v[248:251], v[4:7]
	v_mfma_f32_16x16x32_bf16 v[20:23], v[188:191], v[252:255], v[20:23]
	ds_read_b128 v[188:191], v130 offset:36864
	s_add_i32 m0, s101, 0x2000
	s_nop 0
	global_load_lds_dwordx4 v146, s[98:99]
	v_mfma_f32_16x16x32_bf16 v[48:51], v[192:195], v[240:243], v[48:51]
	v_mfma_f32_16x16x32_bf16 v[24:27], v[192:195], v[244:247], v[24:27]
	v_mfma_f32_16x16x32_bf16 v[0:3], v[192:195], v[248:251], v[0:3]
	v_mfma_f32_16x16x32_bf16 v[8:11], v[192:195], v[252:255], v[8:11]
	ds_read_b128 v[192:195], v130 offset:38912
	s_add_i32 m0, s101, 0xa000
	s_nop 0
	global_load_lds_dwordx4 v138, vcc

.Lex_795:
	s_waitcnt lgkmcnt(0)
	v_add3_u32 v130, s46, v156, v162
	v_add3_u32 v151, s46, v156, v161
	v_add3_u32 v206, s46, v156, v160
	v_add3_u32 v198, s46, v156, v159
	v_add3_u32 v186, s46, v156, v158
	v_add3_u32 v187, s46, v156, v157
	v_add3_u32 v188, s46, v156, v155
	v_add3_u32 v189, s46, v152, v154
	v_add3_u32 v190, s47, v152, v153
	ds_read_b128 v[134:137], v130
	ds_read_b128 v[138:141], v151
	ds_read_b128 v[142:145], v206
	ds_read_b128 v[146:149], v198
	ds_read_b128 v[158:161], v186
	ds_read_b128 v[162:165], v187
	ds_read_b128 v[166:169], v188
	ds_read_b128 v[154:157], v189
	ds_read_b128 v[170:173], v190
	s_waitcnt lgkmcnt(0)
	v_mfma_f32_16x16x32_bf16 v[16:19], v[170:173], v[138:141], v[16:19]
	v_mfma_f32_16x16x32_bf16 v[174:177], v[170:173], v[134:137], v[36:39]
	s_nop 2
	ds_read_b128 v[36:39], v190 offset:2048
	s_waitcnt lgkmcnt(0)
	v_mfma_f32_16x16x32_bf16 v[12:15], v[36:39], v[138:141], v[12:15]
	v_mfma_f32_16x16x32_bf16 v[60:63], v[170:173], v[146:149], v[60:63]
	v_mfma_f32_16x16x32_bf16 v[28:31], v[36:39], v[134:137], v[28:31]
	v_mfma_f32_16x16x32_bf16 v[56:59], v[36:39], v[146:149], v[56:59]
	ds_read_b128 v[178:181], v190 offset:4096
	s_waitcnt lgkmcnt(0)
	v_mfma_f32_16x16x32_bf16 v[182:185], v[178:181], v[134:137], v[20:23]
	v_mfma_f32_16x16x32_bf16 v[52:55], v[178:181], v[146:149], v[52:55]
	s_nop 1
	ds_read_b128 v[20:23], v190 offset:6144
	s_waitcnt lgkmcnt(0)
	v_mfma_f32_16x16x32_bf16 v[134:137], v[20:23], v[134:137], v[8:11]
	v_mfma_f32_16x16x32_bf16 v[8:11], v[20:23], v[154:157], v[112:115]
	v_mfma_f32_16x16x32_bf16 v[112:115], v[20:23], v[158:161], v[64:67]
	v_mfma_f32_16x16x32_bf16 v[64:67], v[178:181], v[154:157], v[116:119]
	v_mfma_f32_16x16x32_bf16 v[116:119], v[178:181], v[158:161], v[68:71]
	v_mfma_f32_16x16x32_bf16 v[68:71], v[36:39], v[154:157], v[120:123]
	v_mfma_f32_16x16x32_bf16 v[120:123], v[36:39], v[158:161], v[72:75]
	v_mfma_f32_16x16x32_bf16 v[72:75], v[170:173], v[154:157], v[124:127]
	v_mfma_f32_16x16x32_bf16 v[124:127], v[170:173], v[158:161], v[76:79]
	v_mfma_f32_16x16x32_bf16 v[48:51], v[20:23], v[146:149], v[48:51]
	v_mfma_f32_16x16x32_bf16 v[146:149], v[170:173], v[142:145], v[44:47]
	v_mfma_f32_16x16x32_bf16 v[152:155], v[36:39], v[142:145], v[40:43]
	v_mfma_f32_16x16x32_bf16 v[156:159], v[178:181], v[142:145], v[32:35]
	v_mfma_f32_16x16x32_bf16 v[24:27], v[20:23], v[142:145], v[24:27]
	v_mfma_f32_16x16x32_bf16 v[142:145], v[178:181], v[138:141], v[4:7]
	v_mfma_f32_16x16x32_bf16 v[108:111], v[170:173], v[166:169], v[108:111]
	v_mfma_f32_16x16x32_bf16 v[92:95], v[170:173], v[162:165], v[92:95]
	v_mfma_f32_16x16x32_bf16 v[104:107], v[36:39], v[166:169], v[104:107]
	v_mfma_f32_16x16x32_bf16 v[88:91], v[36:39], v[162:165], v[88:91]
	v_mfma_f32_16x16x32_bf16 v[100:103], v[178:181], v[166:169], v[100:103]
	v_mfma_f32_16x16x32_bf16 v[84:87], v[178:181], v[162:165], v[84:87]
	v_mfma_f32_16x16x32_bf16 v[96:99], v[20:23], v[166:169], v[96:99]
	v_mfma_f32_16x16x32_bf16 v[80:83], v[20:23], v[162:165], v[80:83]
	v_mfma_f32_16x16x32_bf16 v[20:23], v[20:23], v[138:141], v[0:3]
	ds_read_b128 v[138:141], v190 offset:1024
	ds_read_b128 v[160:163], v190 offset:3072
	ds_read_b128 v[164:167], v190 offset:5120
	ds_read_b128 v[168:171], v190 offset:7168
	ds_read_b128 v[0:3], v189 offset:1024
	ds_read_b128 v[4:7], v188 offset:1024
	ds_read_b128 v[32:35], v187 offset:1024
	ds_read_b128 v[36:39], v186 offset:1024
	s_waitcnt lgkmcnt(3)
	v_mfma_f32_16x16x32_bf16 v[178:181], v[138:141], v[0:3], v[72:75]
	v_mfma_f32_16x16x32_bf16 v[186:189], v[160:163], v[0:3], v[68:71]
	v_mfma_f32_16x16x32_bf16 v[190:193], v[164:167], v[0:3], v[64:67]
	v_mfma_f32_16x16x32_bf16 v[194:197], v[168:171], v[0:3], v[8:11]
	ds_read_b128 v[0:3], v198 offset:1024
	s_waitcnt lgkmcnt(3)
	v_mfma_f32_16x16x32_bf16 v[108:111], v[138:141], v[4:7], v[108:111]
	v_mfma_f32_16x16x32_bf16 v[104:107], v[160:163], v[4:7], v[104:107]
	v_mfma_f32_16x16x32_bf16 v[198:201], v[164:167], v[4:7], v[100:103]
	v_mfma_f32_16x16x32_bf16 v[202:205], v[168:171], v[4:7], v[96:99]
	ds_read_b128 v[4:7], v206 offset:1024
	s_waitcnt lgkmcnt(3)
	v_mfma_f32_16x16x32_bf16 v[64:67], v[138:141], v[32:35], v[92:95]
	v_mfma_f32_16x16x32_bf16 v[68:71], v[160:163], v[32:35], v[88:91]
	v_mfma_f32_16x16x32_bf16 v[72:75], v[164:167], v[32:35], v[84:87]
	v_mfma_f32_16x16x32_bf16 v[76:79], v[168:171], v[32:35], v[80:83]
	ds_read_b128 v[96:99], v151 offset:1024
	s_waitcnt lgkmcnt(3)
	v_mfma_f32_16x16x32_bf16 v[80:83], v[138:141], v[36:39], v[124:127]
	v_mfma_f32_16x16x32_bf16 v[84:87], v[160:163], v[36:39], v[120:123]
	v_mfma_f32_16x16x32_bf16 v[88:91], v[164:167], v[36:39], v[116:119]
	v_mfma_f32_16x16x32_bf16 v[92:95], v[168:171], v[36:39], v[112:115]
	ds_read_b128 v[100:103], v130 offset:1024
	s_waitcnt lgkmcnt(3)
	v_mfma_f32_16x16x32_bf16 v[32:35], v[138:141], v[0:3], v[60:63]
	v_mfma_f32_16x16x32_bf16 v[36:39], v[160:163], v[0:3], v[56:59]
	v_mfma_f32_16x16x32_bf16 v[40:43], v[164:167], v[0:3], v[52:55]
	v_mfma_f32_16x16x32_bf16 v[44:47], v[168:171], v[0:3], v[48:51]
	s_waitcnt lgkmcnt(2)
	v_mfma_f32_16x16x32_bf16 v[48:51], v[138:141], v[4:7], v[146:149]
	v_mfma_f32_16x16x32_bf16 v[52:55], v[160:163], v[4:7], v[152:155]
	v_mfma_f32_16x16x32_bf16 v[56:59], v[164:167], v[4:7], v[156:159]
	v_mfma_f32_16x16x32_bf16 v[60:63], v[168:171], v[4:7], v[24:27]
	s_waitcnt lgkmcnt(1)
	v_mfma_f32_16x16x32_bf16 v[0:3], v[138:141], v[96:99], v[16:19]
	v_mfma_f32_16x16x32_bf16 v[4:7], v[160:163], v[96:99], v[12:15]
	v_mfma_f32_16x16x32_bf16 v[8:11], v[164:167], v[96:99], v[142:145]
	v_mfma_f32_16x16x32_bf16 v[12:15], v[168:171], v[96:99], v[20:23]
	s_waitcnt lgkmcnt(0)
	v_mfma_f32_16x16x32_bf16 v[16:19], v[138:141], v[100:103], v[174:177]
	v_mfma_f32_16x16x32_bf16 v[20:23], v[160:163], v[100:103], v[28:31]
	v_mfma_f32_16x16x32_bf16 v[24:27], v[164:167], v[100:103], v[182:185]
	v_mfma_f32_16x16x32_bf16 v[28:31], v[168:171], v[100:103], v[134:137]
	v_lshrrev_b32_e32 v96, 6, v150
	v_lshlrev_b32_e32 v98, 2, v150
	v_and_b32_e32 v97, 15, v150
	v_mul_lo_u32 v96, v96, s48
	v_and_b32_e32 v112, 60, v98
	v_bfe_u32 v99, v150, 4, 2
	v_add_u32_e32 v96, s46, v96
	v_and_b32_e32 v100, 48, v150
	v_lshlrev_b32_e32 v98, 2, v112
	v_mul_u32_u24_e32 v101, 0x110, v99
	v_mul_u32_u24_e32 v97, 0x110, v97
	v_add3_u32 v98, v96, v98, v101
	v_add3_u32 v101, v96, v100, v97
	s_waitcnt vmcnt(0)
	s_barrier
	ds_write_b128 v101, v[178:181]
	ds_write_b128 v101, v[186:189] offset:64
	ds_write_b128 v101, v[190:193] offset:128
	ds_write_b128 v101, v[194:197] offset:192
	ds_write_b128 v101, v[108:111] offset:4352
	ds_write_b128 v101, v[104:107] offset:4416
	ds_write_b128 v101, v[198:201] offset:4480
	ds_write_b128 v101, v[202:205] offset:4544
	ds_read_b128 v[102:105], v98
	v_ashrrev_i32_e32 v113, 1, v150
	v_and_b32_e32 v96, 0xffffff80, v113
	v_and_or_b32 v106, v150, s49, v112
	v_add_u32_e32 v100, s28, v96
	s_waitcnt lgkmcnt(0)
	v_mul_f32_e32 v102, 0xbfb8aa3b, v102
	v_mul_f32_e32 v103, 0xbfb8aa3b, v103
	v_mul_f32_e32 v104, 0xbfb8aa3b, v104
	v_mul_f32_e32 v105, 0xbfb8aa3b, v105
	v_exp_f32_e32 v102, v102
	v_exp_f32_e32 v103, v103
	v_exp_f32_e32 v104, v104
	v_exp_f32_e32 v105, v105
	v_add_f32_e32 v102, 1.0, v102
	v_add_f32_e32 v103, 1.0, v103
	v_add_f32_e32 v104, 1.0, v104
	v_add_f32_e32 v105, 1.0, v105
	v_rcp_f32_e32 v102, v102
	v_rcp_f32_e32 v103, v103
	v_rcp_f32_e32 v104, v104
	v_rcp_f32_e32 v105, v105
	v_lshl_add_u64 v[96:97], v[128:129], 0, s[38:39]
	v_lshlrev_b32_e32 v130, 1, v106
	v_cvt_pk_bf16_f32 v102, v102, v103
	v_cvt_pk_bf16_f32 v103, v104, v105
	v_or_b32_e32 v104, v100, v99
	v_lshl_add_u64 v[96:97], v[96:97], 0, v[130:131]
	v_ashrrev_i32_e32 v105, 31, v104
	v_lshl_add_u64 v[96:97], v[96:97], 0, s[26:27]
	v_lshlrev_b64 v[104:105], 11, v[104:105]
	v_lshl_add_u64 v[104:105], v[96:97], 0, v[104:105]
	flat_store_dwordx2 v[104:105], v[102:103]
	ds_read_b128 v[102:105], v98 offset:1088
	v_mov_b32_e32 v150, v132
	s_waitcnt lgkmcnt(0)
	v_mul_f32_e32 v102, 0xbfb8aa3b, v102
	v_exp_f32_e32 v102, v102
	v_mul_f32_e32 v103, 0xbfb8aa3b, v103
	v_exp_f32_e32 v103, v103
	v_add_f32_e32 v102, 1.0, v102
	v_rcp_f32_e32 v106, v102
	v_add_f32_e32 v102, 1.0, v103
	v_mul_f32_e32 v103, 0xbfb8aa3b, v104
	v_exp_f32_e32 v103, v103
	v_mul_f32_e32 v104, 0xbfb8aa3b, v105
	v_exp_f32_e32 v104, v104
	v_rcp_f32_e32 v105, v102
	v_add_f32_e32 v102, 1.0, v103
	v_rcp_f32_e32 v103, v102
	v_add_f32_e32 v102, 1.0, v104
	v_rcp_f32_e32 v107, v102
	v_or_b32_e32 v102, 4, v99
	v_cvt_pk_bf16_f32 v104, v106, v105
	v_or_b32_e32 v106, v100, v102
	v_cvt_pk_bf16_f32 v105, v103, v107
	v_ashrrev_i32_e32 v107, 31, v106
	v_lshlrev_b64 v[106:107], 11, v[106:107]
	v_lshl_add_u64 v[106:107], v[96:97], 0, v[106:107]
	flat_store_dwordx2 v[106:107], v[104:105]
	ds_read_b128 v[104:107], v98 offset:2176
	s_waitcnt lgkmcnt(0)
	v_mul_f32_e32 v103, 0xbfb8aa3b, v104
	v_exp_f32_e32 v103, v103
	v_mul_f32_e32 v104, 0xbfb8aa3b, v105
	v_exp_f32_e32 v104, v104
	v_add_f32_e32 v103, 1.0, v103
	v_rcp_f32_e32 v105, v103
	v_add_f32_e32 v103, 1.0, v104
	v_mul_f32_e32 v104, 0xbfb8aa3b, v106
	v_exp_f32_e32 v104, v104
	v_mul_f32_e32 v106, 0xbfb8aa3b, v107
	v_exp_f32_e32 v106, v106
	v_rcp_f32_e32 v107, v103
	v_add_f32_e32 v103, 1.0, v104
	v_rcp_f32_e32 v108, v103
	v_add_f32_e32 v103, 1.0, v106
	v_rcp_f32_e32 v106, v103
	v_or_b32_e32 v103, 8, v99
	v_cvt_pk_bf16_f32 v104, v105, v107
	v_cvt_pk_bf16_f32 v105, v108, v106
	v_or_b32_e32 v106, v100, v103
	v_ashrrev_i32_e32 v107, 31, v106
	v_lshlrev_b64 v[106:107], 11, v[106:107]
	v_lshl_add_u64 v[106:107], v[96:97], 0, v[106:107]
	flat_store_dwordx2 v[106:107], v[104:105]
	ds_read_b128 v[104:107], v98 offset:3264
	s_waitcnt lgkmcnt(0)
	v_mul_f32_e32 v104, 0xbfb8aa3b, v104
	v_exp_f32_e32 v104, v104
	v_mul_f32_e32 v105, 0xbfb8aa3b, v105
	v_exp_f32_e32 v105, v105
	v_add_f32_e32 v104, 1.0, v104
	v_rcp_f32_e32 v108, v104
	v_add_f32_e32 v104, 1.0, v105
	v_mul_f32_e32 v105, 0xbfb8aa3b, v106
	v_exp_f32_e32 v105, v105
	v_mul_f32_e32 v106, 0xbfb8aa3b, v107
	v_exp_f32_e32 v106, v106
	v_rcp_f32_e32 v107, v104
	v_add_f32_e32 v104, 1.0, v105
	v_rcp_f32_e32 v105, v104
	v_add_f32_e32 v104, 1.0, v106
	v_rcp_f32_e32 v109, v104
	v_or_b32_e32 v104, 12, v99
	v_cvt_pk_bf16_f32 v106, v108, v107
	v_or_b32_e32 v108, v100, v104
	v_cvt_pk_bf16_f32 v107, v105, v109
	v_ashrrev_i32_e32 v109, 31, v108
	v_lshlrev_b64 v[108:109], 11, v[108:109]
	v_lshl_add_u64 v[108:109], v[96:97], 0, v[108:109]
	flat_store_dwordx2 v[108:109], v[106:107]
	ds_read_b128 v[106:109], v98 offset:4352
	s_waitcnt lgkmcnt(0)
	v_mul_f32_e32 v105, 0xbfb8aa3b, v106
	v_exp_f32_e32 v105, v105
	v_mul_f32_e32 v106, 0xbfb8aa3b, v107
	v_exp_f32_e32 v106, v106
	v_add_f32_e32 v105, 1.0, v105
	v_rcp_f32_e32 v107, v105
	v_add_f32_e32 v105, 1.0, v106
	v_mul_f32_e32 v106, 0xbfb8aa3b, v108
	v_exp_f32_e32 v106, v106
	v_mul_f32_e32 v108, 0xbfb8aa3b, v109
	v_exp_f32_e32 v108, v108
	v_rcp_f32_e32 v109, v105
	v_add_f32_e32 v105, 1.0, v106
	v_rcp_f32_e32 v110, v105
	v_add_f32_e32 v105, 1.0, v108
	v_rcp_f32_e32 v108, v105
	v_or_b32_e32 v105, 16, v99
	v_cvt_pk_bf16_f32 v106, v107, v109
	v_cvt_pk_bf16_f32 v107, v110, v108
	v_or_b32_e32 v108, v100, v105
	v_ashrrev_i32_e32 v109, 31, v108
	v_lshlrev_b64 v[108:109], 11, v[108:109]
	v_lshl_add_u64 v[108:109], v[96:97], 0, v[108:109]
	flat_store_dwordx2 v[108:109], v[106:107]
	ds_read_b128 v[106:109], v98 offset:5440
	s_waitcnt lgkmcnt(0)
	v_mul_f32_e32 v106, 0xbfb8aa3b, v106
	v_exp_f32_e32 v106, v106
	v_mul_f32_e32 v107, 0xbfb8aa3b, v107
	v_exp_f32_e32 v107, v107
	v_add_f32_e32 v106, 1.0, v106
	v_rcp_f32_e32 v110, v106
	v_add_f32_e32 v106, 1.0, v107
	v_mul_f32_e32 v107, 0xbfb8aa3b, v108
	v_exp_f32_e32 v107, v107
	v_mul_f32_e32 v108, 0xbfb8aa3b, v109
	v_exp_f32_e32 v108, v108
	v_rcp_f32_e32 v109, v106
	v_add_f32_e32 v106, 1.0, v107
	v_rcp_f32_e32 v107, v106
	v_add_f32_e32 v106, 1.0, v108
	v_rcp_f32_e32 v111, v106
	v_or_b32_e32 v106, 20, v99
	v_cvt_pk_bf16_f32 v108, v110, v109
	v_or_b32_e32 v110, v100, v106
	v_cvt_pk_bf16_f32 v109, v107, v111
	v_ashrrev_i32_e32 v111, 31, v110
	v_lshlrev_b64 v[110:111], 11, v[110:111]
	v_lshl_add_u64 v[110:111], v[96:97], 0, v[110:111]
	flat_store_dwordx2 v[110:111], v[108:109]
	ds_read_b128 v[108:111], v98 offset:6528
	s_waitcnt lgkmcnt(0)
	v_mul_f32_e32 v107, 0xbfb8aa3b, v108
	v_exp_f32_e32 v107, v107
	v_mul_f32_e32 v108, 0xbfb8aa3b, v109
	v_exp_f32_e32 v108, v108
	v_add_f32_e32 v107, 1.0, v107
	v_rcp_f32_e32 v109, v107
	v_add_f32_e32 v107, 1.0, v108
	v_mul_f32_e32 v108, 0xbfb8aa3b, v110
	v_exp_f32_e32 v108, v108
	v_mul_f32_e32 v110, 0xbfb8aa3b, v111
	v_exp_f32_e32 v110, v110
	v_rcp_f32_e32 v111, v107
	v_add_f32_e32 v107, 1.0, v108
	v_rcp_f32_e32 v112, v107
	v_add_f32_e32 v107, 1.0, v110
	v_rcp_f32_e32 v110, v107
	v_or_b32_e32 v107, 24, v99
	v_cvt_pk_bf16_f32 v108, v109, v111
	v_cvt_pk_bf16_f32 v109, v112, v110
	v_or_b32_e32 v110, v100, v107
	v_ashrrev_i32_e32 v111, 31, v110
	v_lshlrev_b64 v[110:111], 11, v[110:111]
	v_lshl_add_u64 v[110:111], v[96:97], 0, v[110:111]
	flat_store_dwordx2 v[110:111], v[108:109]
	ds_read_b128 v[108:111], v98 offset:7616
	s_waitcnt lgkmcnt(0)
	v_mul_f32_e32 v108, 0xbfb8aa3b, v108
	v_exp_f32_e32 v108, v108
	v_mul_f32_e32 v109, 0xbfb8aa3b, v109
	v_exp_f32_e32 v109, v109
	v_add_f32_e32 v108, 1.0, v108
	v_rcp_f32_e32 v112, v108
	v_add_f32_e32 v108, 1.0, v109
	v_mul_f32_e32 v109, 0xbfb8aa3b, v110
	v_exp_f32_e32 v109, v109
	v_mul_f32_e32 v110, 0xbfb8aa3b, v111
	v_exp_f32_e32 v110, v110
	v_rcp_f32_e32 v111, v108
	v_add_f32_e32 v108, 1.0, v109
	v_rcp_f32_e32 v109, v108
	v_add_f32_e32 v108, 1.0, v110
	v_rcp_f32_e32 v113, v108
	v_or_b32_e32 v108, 28, v99
	v_cvt_pk_bf16_f32 v110, v112, v111
	v_or_b32_e32 v112, v100, v108
	v_cvt_pk_bf16_f32 v111, v109, v113
	v_ashrrev_i32_e32 v113, 31, v112
	v_lshlrev_b64 v[112:113], 11, v[112:113]
	v_lshl_add_u64 v[112:113], v[96:97], 0, v[112:113]
	flat_store_dwordx2 v[112:113], v[110:111]
	ds_write_b128 v101, v[64:67]
	ds_write_b128 v101, v[68:71] offset:64
	ds_write_b128 v101, v[72:75] offset:128
	ds_write_b128 v101, v[76:79] offset:192
	ds_write_b128 v101, v[80:83] offset:4352
	ds_write_b128 v101, v[84:87] offset:4416
	ds_write_b128 v101, v[88:91] offset:4480
	ds_write_b128 v101, v[92:95] offset:4544
	ds_read_b128 v[64:67], v98
	v_or_b32_e32 v68, 32, v100
	s_waitcnt lgkmcnt(0)
	v_mul_f32_e32 v64, 0xbfb8aa3b, v64
	v_mul_f32_e32 v65, 0xbfb8aa3b, v65
	v_mul_f32_e32 v66, 0xbfb8aa3b, v66
	v_mul_f32_e32 v67, 0xbfb8aa3b, v67
	v_exp_f32_e32 v64, v64
	v_exp_f32_e32 v65, v65
	v_exp_f32_e32 v66, v66
	v_exp_f32_e32 v67, v67
	v_add_f32_e32 v64, 1.0, v64
	v_add_f32_e32 v65, 1.0, v65
	v_add_f32_e32 v66, 1.0, v66
	v_add_f32_e32 v67, 1.0, v67
	v_rcp_f32_e32 v64, v64
	v_rcp_f32_e32 v65, v65
	v_rcp_f32_e32 v66, v66
	v_rcp_f32_e32 v67, v67
	v_cvt_pk_bf16_f32 v64, v64, v65
	v_cvt_pk_bf16_f32 v65, v66, v67
	v_or_b32_e32 v66, v68, v99
	v_ashrrev_i32_e32 v67, 31, v66
	v_lshlrev_b64 v[66:67], 11, v[66:67]
	v_lshl_add_u64 v[66:67], v[96:97], 0, v[66:67]
	flat_store_dwordx2 v[66:67], v[64:65]
	ds_read_b128 v[64:67], v98 offset:1088
	s_waitcnt lgkmcnt(0)
	v_mul_f32_e32 v64, 0xbfb8aa3b, v64
	v_mul_f32_e32 v65, 0xbfb8aa3b, v65
	v_mul_f32_e32 v66, 0xbfb8aa3b, v66
	v_mul_f32_e32 v67, 0xbfb8aa3b, v67
	v_exp_f32_e32 v64, v64
	v_exp_f32_e32 v65, v65
	v_exp_f32_e32 v66, v66
	v_exp_f32_e32 v67, v67
	v_add_f32_e32 v64, 1.0, v64
	v_add_f32_e32 v65, 1.0, v65
	v_add_f32_e32 v66, 1.0, v66
	v_add_f32_e32 v67, 1.0, v67
	v_rcp_f32_e32 v64, v64
	v_rcp_f32_e32 v65, v65
	v_rcp_f32_e32 v66, v66
	v_rcp_f32_e32 v67, v67
	v_cvt_pk_bf16_f32 v64, v64, v65
	v_cvt_pk_bf16_f32 v65, v66, v67
	v_or_b32_e32 v66, v68, v102
	v_ashrrev_i32_e32 v67, 31, v66
	v_lshlrev_b64 v[66:67], 11, v[66:67]
	v_lshl_add_u64 v[66:67], v[96:97], 0, v[66:67]
	flat_store_dwordx2 v[66:67], v[64:65]
	ds_read_b128 v[64:67], v98 offset:2176
	s_waitcnt lgkmcnt(0)
	v_mul_f32_e32 v64, 0xbfb8aa3b, v64
	v_mul_f32_e32 v65, 0xbfb8aa3b, v65
	v_mul_f32_e32 v66, 0xbfb8aa3b, v66
	v_mul_f32_e32 v67, 0xbfb8aa3b, v67
	v_exp_f32_e32 v64, v64
	v_exp_f32_e32 v65, v65
	v_exp_f32_e32 v66, v66
	v_exp_f32_e32 v67, v67
	v_add_f32_e32 v64, 1.0, v64
	v_add_f32_e32 v65, 1.0, v65
	v_add_f32_e32 v66, 1.0, v66
	v_add_f32_e32 v67, 1.0, v67
	v_rcp_f32_e32 v64, v64
	v_rcp_f32_e32 v65, v65
	v_rcp_f32_e32 v66, v66
	v_rcp_f32_e32 v67, v67
	v_cvt_pk_bf16_f32 v64, v64, v65
	v_cvt_pk_bf16_f32 v65, v66, v67
	v_or_b32_e32 v66, v68, v103
	v_ashrrev_i32_e32 v67, 31, v66
	v_lshlrev_b64 v[66:67], 11, v[66:67]
	v_lshl_add_u64 v[66:67], v[96:97], 0, v[66:67]
	flat_store_dwordx2 v[66:67], v[64:65]
	ds_read_b128 v[64:67], v98 offset:3264
	s_waitcnt lgkmcnt(0)
	v_mul_f32_e32 v64, 0xbfb8aa3b, v64
	v_mul_f32_e32 v65, 0xbfb8aa3b, v65
	v_mul_f32_e32 v66, 0xbfb8aa3b, v66
	v_mul_f32_e32 v67, 0xbfb8aa3b, v67
	v_exp_f32_e32 v64, v64
	v_exp_f32_e32 v65, v65
	v_exp_f32_e32 v66, v66
	v_exp_f32_e32 v67, v67
	v_add_f32_e32 v64, 1.0, v64
	v_add_f32_e32 v65, 1.0, v65
	v_add_f32_e32 v66, 1.0, v66
	v_add_f32_e32 v67, 1.0, v67
	v_rcp_f32_e32 v64, v64
	v_rcp_f32_e32 v65, v65
	v_rcp_f32_e32 v66, v66
	v_rcp_f32_e32 v67, v67
	v_cvt_pk_bf16_f32 v64, v64, v65
	v_cvt_pk_bf16_f32 v65, v66, v67
	v_or_b32_e32 v66, v68, v104
	v_ashrrev_i32_e32 v67, 31, v66
	v_lshlrev_b64 v[66:67], 11, v[66:67]
	v_lshl_add_u64 v[66:67], v[96:97], 0, v[66:67]
	flat_store_dwordx2 v[66:67], v[64:65]
	ds_read_b128 v[64:67], v98 offset:4352
	s_waitcnt lgkmcnt(0)
	v_mul_f32_e32 v64, 0xbfb8aa3b, v64
	v_mul_f32_e32 v65, 0xbfb8aa3b, v65
	v_mul_f32_e32 v66, 0xbfb8aa3b, v66
	v_mul_f32_e32 v67, 0xbfb8aa3b, v67
	v_exp_f32_e32 v64, v64
	v_exp_f32_e32 v65, v65
	v_exp_f32_e32 v66, v66
	v_exp_f32_e32 v67, v67
	v_add_f32_e32 v64, 1.0, v64
	v_add_f32_e32 v65, 1.0, v65
	v_add_f32_e32 v66, 1.0, v66
	v_add_f32_e32 v67, 1.0, v67
	v_rcp_f32_e32 v64, v64
	v_rcp_f32_e32 v65, v65
	v_rcp_f32_e32 v66, v66
	v_rcp_f32_e32 v67, v67
	v_cvt_pk_bf16_f32 v64, v64, v65
	v_cvt_pk_bf16_f32 v65, v66, v67
	v_or_b32_e32 v66, v68, v105
	v_ashrrev_i32_e32 v67, 31, v66
	v_lshlrev_b64 v[66:67], 11, v[66:67]
	v_lshl_add_u64 v[66:67], v[96:97], 0, v[66:67]
	flat_store_dwordx2 v[66:67], v[64:65]
	ds_read_b128 v[64:67], v98 offset:5440
	s_waitcnt lgkmcnt(0)
	v_mul_f32_e32 v64, 0xbfb8aa3b, v64
	v_mul_f32_e32 v65, 0xbfb8aa3b, v65
	v_mul_f32_e32 v66, 0xbfb8aa3b, v66
	v_mul_f32_e32 v67, 0xbfb8aa3b, v67
	v_exp_f32_e32 v64, v64
	v_exp_f32_e32 v65, v65
	v_exp_f32_e32 v66, v66
	v_exp_f32_e32 v67, v67
	v_add_f32_e32 v64, 1.0, v64
	v_add_f32_e32 v65, 1.0, v65
	v_add_f32_e32 v66, 1.0, v66
	v_add_f32_e32 v67, 1.0, v67
	v_rcp_f32_e32 v64, v64
	v_rcp_f32_e32 v65, v65
	v_rcp_f32_e32 v66, v66
	v_rcp_f32_e32 v67, v67
	v_cvt_pk_bf16_f32 v64, v64, v65
	v_cvt_pk_bf16_f32 v65, v66, v67
	v_or_b32_e32 v66, v68, v106
	v_ashrrev_i32_e32 v67, 31, v66
	v_lshlrev_b64 v[66:67], 11, v[66:67]
	v_lshl_add_u64 v[66:67], v[96:97], 0, v[66:67]
	flat_store_dwordx2 v[66:67], v[64:65]
	ds_read_b128 v[64:67], v98 offset:6528
	s_waitcnt lgkmcnt(0)
	v_mul_f32_e32 v64, 0xbfb8aa3b, v64
	v_mul_f32_e32 v65, 0xbfb8aa3b, v65
	v_mul_f32_e32 v66, 0xbfb8aa3b, v66
	v_mul_f32_e32 v67, 0xbfb8aa3b, v67
	v_exp_f32_e32 v64, v64
	v_exp_f32_e32 v65, v65
	v_exp_f32_e32 v66, v66
	v_exp_f32_e32 v67, v67
	v_add_f32_e32 v64, 1.0, v64
	v_add_f32_e32 v65, 1.0, v65
	v_add_f32_e32 v66, 1.0, v66
	v_add_f32_e32 v67, 1.0, v67
	v_rcp_f32_e32 v64, v64
	v_rcp_f32_e32 v65, v65
	v_rcp_f32_e32 v66, v66
	v_rcp_f32_e32 v67, v67
	v_cvt_pk_bf16_f32 v64, v64, v65
	v_cvt_pk_bf16_f32 v65, v66, v67
	v_or_b32_e32 v66, v68, v107
	v_ashrrev_i32_e32 v67, 31, v66
	v_lshlrev_b64 v[66:67], 11, v[66:67]
	v_lshl_add_u64 v[66:67], v[96:97], 0, v[66:67]
	flat_store_dwordx2 v[66:67], v[64:65]
	ds_read_b128 v[64:67], v98 offset:7616
	s_waitcnt lgkmcnt(0)
	v_mul_f32_e32 v64, 0xbfb8aa3b, v64
	v_mul_f32_e32 v65, 0xbfb8aa3b, v65
	v_mul_f32_e32 v66, 0xbfb8aa3b, v66
	v_mul_f32_e32 v67, 0xbfb8aa3b, v67
	v_exp_f32_e32 v64, v64
	v_exp_f32_e32 v65, v65
	v_exp_f32_e32 v66, v66
	v_exp_f32_e32 v67, v67
	v_add_f32_e32 v64, 1.0, v64
	v_add_f32_e32 v65, 1.0, v65
	v_add_f32_e32 v66, 1.0, v66
	v_add_f32_e32 v67, 1.0, v67
	v_rcp_f32_e32 v64, v64
	v_rcp_f32_e32 v65, v65
	v_rcp_f32_e32 v66, v66
	v_rcp_f32_e32 v67, v67
	v_cvt_pk_bf16_f32 v64, v64, v65
	v_cvt_pk_bf16_f32 v65, v66, v67
	v_or_b32_e32 v66, v68, v108
	v_ashrrev_i32_e32 v67, 31, v66
	v_lshlrev_b64 v[66:67], 11, v[66:67]
	v_lshl_add_u64 v[66:67], v[96:97], 0, v[66:67]
	flat_store_dwordx2 v[66:67], v[64:65]
	ds_write_b128 v101, v[32:35]
	ds_write_b128 v101, v[36:39] offset:64
	ds_write_b128 v101, v[40:43] offset:128
	ds_write_b128 v101, v[44:47] offset:192
	ds_write_b128 v101, v[48:51] offset:4352
	ds_write_b128 v101, v[52:55] offset:4416
	ds_write_b128 v101, v[56:59] offset:4480
	ds_write_b128 v101, v[60:63] offset:4544
	ds_read_b128 v[32:35], v98
	v_or_b32_e32 v36, 64, v100
	s_waitcnt lgkmcnt(0)
	v_mul_f32_e32 v32, 0xbfb8aa3b, v32
	v_mul_f32_e32 v33, 0xbfb8aa3b, v33
	v_mul_f32_e32 v34, 0xbfb8aa3b, v34
	v_mul_f32_e32 v35, 0xbfb8aa3b, v35
	v_exp_f32_e32 v32, v32
	v_exp_f32_e32 v33, v33
	v_exp_f32_e32 v34, v34
	v_exp_f32_e32 v35, v35
	v_add_f32_e32 v32, 1.0, v32
	v_add_f32_e32 v33, 1.0, v33
	v_add_f32_e32 v34, 1.0, v34
	v_add_f32_e32 v35, 1.0, v35
	v_rcp_f32_e32 v32, v32
	v_rcp_f32_e32 v33, v33
	v_rcp_f32_e32 v34, v34
	v_rcp_f32_e32 v35, v35
	v_cvt_pk_bf16_f32 v32, v32, v33
	v_cvt_pk_bf16_f32 v33, v34, v35
	v_or_b32_e32 v34, v36, v99
	v_ashrrev_i32_e32 v35, 31, v34
	v_lshlrev_b64 v[34:35], 11, v[34:35]
	v_lshl_add_u64 v[34:35], v[96:97], 0, v[34:35]
	flat_store_dwordx2 v[34:35], v[32:33]
	ds_read_b128 v[32:35], v98 offset:1088
	s_waitcnt lgkmcnt(0)
	v_mul_f32_e32 v32, 0xbfb8aa3b, v32
	v_mul_f32_e32 v33, 0xbfb8aa3b, v33
	v_mul_f32_e32 v34, 0xbfb8aa3b, v34
	v_mul_f32_e32 v35, 0xbfb8aa3b, v35
	v_exp_f32_e32 v32, v32
	v_exp_f32_e32 v33, v33
	v_exp_f32_e32 v34, v34
	v_exp_f32_e32 v35, v35
	v_add_f32_e32 v32, 1.0, v32
	v_add_f32_e32 v33, 1.0, v33
	v_add_f32_e32 v34, 1.0, v34
	v_add_f32_e32 v35, 1.0, v35
	v_rcp_f32_e32 v32, v32
	v_rcp_f32_e32 v33, v33
	v_rcp_f32_e32 v34, v34
	v_rcp_f32_e32 v35, v35
	v_cvt_pk_bf16_f32 v32, v32, v33
	v_cvt_pk_bf16_f32 v33, v34, v35
	v_or_b32_e32 v34, v36, v102
	v_ashrrev_i32_e32 v35, 31, v34
	v_lshlrev_b64 v[34:35], 11, v[34:35]
	v_lshl_add_u64 v[34:35], v[96:97], 0, v[34:35]
	flat_store_dwordx2 v[34:35], v[32:33]
	ds_read_b128 v[32:35], v98 offset:2176
	s_waitcnt lgkmcnt(0)
	v_mul_f32_e32 v32, 0xbfb8aa3b, v32
	v_mul_f32_e32 v33, 0xbfb8aa3b, v33
	v_mul_f32_e32 v34, 0xbfb8aa3b, v34
	v_mul_f32_e32 v35, 0xbfb8aa3b, v35
	v_exp_f32_e32 v32, v32
	v_exp_f32_e32 v33, v33
	v_exp_f32_e32 v34, v34
	v_exp_f32_e32 v35, v35
	v_add_f32_e32 v32, 1.0, v32
	v_add_f32_e32 v33, 1.0, v33
	v_add_f32_e32 v34, 1.0, v34
	v_add_f32_e32 v35, 1.0, v35
	v_rcp_f32_e32 v32, v32
	v_rcp_f32_e32 v33, v33
	v_rcp_f32_e32 v34, v34
	v_rcp_f32_e32 v35, v35
	v_cvt_pk_bf16_f32 v32, v32, v33
	v_cvt_pk_bf16_f32 v33, v34, v35
	v_or_b32_e32 v34, v36, v103
	v_ashrrev_i32_e32 v35, 31, v34
	v_lshlrev_b64 v[34:35], 11, v[34:35]
	v_lshl_add_u64 v[34:35], v[96:97], 0, v[34:35]
	flat_store_dwordx2 v[34:35], v[32:33]
	ds_read_b128 v[32:35], v98 offset:3264
	s_waitcnt lgkmcnt(0)
	v_mul_f32_e32 v32, 0xbfb8aa3b, v32
	v_mul_f32_e32 v33, 0xbfb8aa3b, v33
	v_mul_f32_e32 v34, 0xbfb8aa3b, v34
	v_mul_f32_e32 v35, 0xbfb8aa3b, v35
	v_exp_f32_e32 v32, v32
	v_exp_f32_e32 v33, v33
	v_exp_f32_e32 v34, v34
	v_exp_f32_e32 v35, v35
	v_add_f32_e32 v32, 1.0, v32
	v_add_f32_e32 v33, 1.0, v33
	v_add_f32_e32 v34, 1.0, v34
	v_add_f32_e32 v35, 1.0, v35
	v_rcp_f32_e32 v32, v32
	v_rcp_f32_e32 v33, v33
	v_rcp_f32_e32 v34, v34
	v_rcp_f32_e32 v35, v35
	v_cvt_pk_bf16_f32 v32, v32, v33
	v_cvt_pk_bf16_f32 v33, v34, v35
	v_or_b32_e32 v34, v36, v104
	v_ashrrev_i32_e32 v35, 31, v34
	v_lshlrev_b64 v[34:35], 11, v[34:35]
	v_lshl_add_u64 v[34:35], v[96:97], 0, v[34:35]
	flat_store_dwordx2 v[34:35], v[32:33]
	ds_read_b128 v[32:35], v98 offset:4352
	s_waitcnt lgkmcnt(0)
	v_mul_f32_e32 v32, 0xbfb8aa3b, v32
	v_mul_f32_e32 v33, 0xbfb8aa3b, v33
	v_mul_f32_e32 v34, 0xbfb8aa3b, v34
	v_mul_f32_e32 v35, 0xbfb8aa3b, v35
	v_exp_f32_e32 v32, v32
	v_exp_f32_e32 v33, v33
	v_exp_f32_e32 v34, v34
	v_exp_f32_e32 v35, v35
	v_add_f32_e32 v32, 1.0, v32
	v_add_f32_e32 v33, 1.0, v33
	v_add_f32_e32 v34, 1.0, v34
	v_add_f32_e32 v35, 1.0, v35
	v_rcp_f32_e32 v32, v32
	v_rcp_f32_e32 v33, v33
	v_rcp_f32_e32 v34, v34
	v_rcp_f32_e32 v35, v35
	v_cvt_pk_bf16_f32 v32, v32, v33
	v_cvt_pk_bf16_f32 v33, v34, v35
	v_or_b32_e32 v34, v36, v105
	v_ashrrev_i32_e32 v35, 31, v34
	v_lshlrev_b64 v[34:35], 11, v[34:35]
	v_lshl_add_u64 v[34:35], v[96:97], 0, v[34:35]
	flat_store_dwordx2 v[34:35], v[32:33]
	ds_read_b128 v[32:35], v98 offset:5440
	s_waitcnt lgkmcnt(0)
	v_mul_f32_e32 v32, 0xbfb8aa3b, v32
	v_mul_f32_e32 v33, 0xbfb8aa3b, v33
	v_mul_f32_e32 v34, 0xbfb8aa3b, v34
	v_mul_f32_e32 v35, 0xbfb8aa3b, v35
	v_exp_f32_e32 v32, v32
	v_exp_f32_e32 v33, v33
	v_exp_f32_e32 v34, v34
	v_exp_f32_e32 v35, v35
	v_add_f32_e32 v32, 1.0, v32
	v_add_f32_e32 v33, 1.0, v33
	v_add_f32_e32 v34, 1.0, v34
	v_add_f32_e32 v35, 1.0, v35
	v_rcp_f32_e32 v32, v32
	v_rcp_f32_e32 v33, v33
	v_rcp_f32_e32 v34, v34
	v_rcp_f32_e32 v35, v35
	v_cvt_pk_bf16_f32 v32, v32, v33
	v_cvt_pk_bf16_f32 v33, v34, v35
	v_or_b32_e32 v34, v36, v106
	v_ashrrev_i32_e32 v35, 31, v34
	v_lshlrev_b64 v[34:35], 11, v[34:35]
	v_lshl_add_u64 v[34:35], v[96:97], 0, v[34:35]
	flat_store_dwordx2 v[34:35], v[32:33]
	ds_read_b128 v[32:35], v98 offset:6528
	s_waitcnt lgkmcnt(0)
	v_mul_f32_e32 v32, 0xbfb8aa3b, v32
	v_mul_f32_e32 v33, 0xbfb8aa3b, v33
	v_mul_f32_e32 v34, 0xbfb8aa3b, v34
	v_mul_f32_e32 v35, 0xbfb8aa3b, v35
	v_exp_f32_e32 v32, v32
	v_exp_f32_e32 v33, v33
	v_exp_f32_e32 v34, v34
	v_exp_f32_e32 v35, v35
	v_add_f32_e32 v32, 1.0, v32
	v_add_f32_e32 v33, 1.0, v33
	v_add_f32_e32 v34, 1.0, v34
	v_add_f32_e32 v35, 1.0, v35
	v_rcp_f32_e32 v32, v32
	v_rcp_f32_e32 v33, v33
	v_rcp_f32_e32 v34, v34
	v_rcp_f32_e32 v35, v35
	v_cvt_pk_bf16_f32 v32, v32, v33
	v_cvt_pk_bf16_f32 v33, v34, v35
	v_or_b32_e32 v34, v36, v107
	v_ashrrev_i32_e32 v35, 31, v34
	v_lshlrev_b64 v[34:35], 11, v[34:35]
	v_lshl_add_u64 v[34:35], v[96:97], 0, v[34:35]
	flat_store_dwordx2 v[34:35], v[32:33]
	ds_read_b128 v[32:35], v98 offset:7616
	s_waitcnt lgkmcnt(0)
	v_mul_f32_e32 v32, 0xbfb8aa3b, v32
	v_mul_f32_e32 v33, 0xbfb8aa3b, v33
	v_mul_f32_e32 v34, 0xbfb8aa3b, v34
	v_mul_f32_e32 v35, 0xbfb8aa3b, v35
	v_exp_f32_e32 v32, v32
	v_exp_f32_e32 v33, v33
	v_exp_f32_e32 v34, v34
	v_exp_f32_e32 v35, v35
	v_add_f32_e32 v32, 1.0, v32
	v_add_f32_e32 v33, 1.0, v33
	v_add_f32_e32 v34, 1.0, v34
	v_add_f32_e32 v35, 1.0, v35
	v_rcp_f32_e32 v32, v32
	v_rcp_f32_e32 v33, v33
	v_rcp_f32_e32 v34, v34
	v_rcp_f32_e32 v35, v35
	v_cvt_pk_bf16_f32 v32, v32, v33
	v_cvt_pk_bf16_f32 v33, v34, v35
	v_or_b32_e32 v34, v36, v108
	v_ashrrev_i32_e32 v35, 31, v34
	v_lshlrev_b64 v[34:35], 11, v[34:35]
	v_lshl_add_u64 v[34:35], v[96:97], 0, v[34:35]
	flat_store_dwordx2 v[34:35], v[32:33]
	ds_write_b128 v101, v[0:3]
	ds_write_b128 v101, v[4:7] offset:64
	ds_write_b128 v101, v[8:11] offset:128
	ds_write_b128 v101, v[12:15] offset:192
	ds_write_b128 v101, v[16:19] offset:4352
	ds_write_b128 v101, v[20:23] offset:4416
	ds_write_b128 v101, v[24:27] offset:4480
	ds_write_b128 v101, v[28:31] offset:4544
	ds_read_b128 v[0:3], v98
	v_or_b32_e32 v4, 0x60, v100
	v_mov_b32_e32 v12, v132
	s_waitcnt lgkmcnt(0)
	v_mul_f32_e32 v0, 0xbfb8aa3b, v0
	v_mul_f32_e32 v1, 0xbfb8aa3b, v1
	v_mul_f32_e32 v2, 0xbfb8aa3b, v2
	v_mul_f32_e32 v3, 0xbfb8aa3b, v3
	v_exp_f32_e32 v0, v0
	v_exp_f32_e32 v1, v1
	v_exp_f32_e32 v2, v2
	v_exp_f32_e32 v3, v3
	v_add_f32_e32 v0, 1.0, v0
	v_add_f32_e32 v1, 1.0, v1
	v_add_f32_e32 v2, 1.0, v2
	v_add_f32_e32 v3, 1.0, v3
	v_rcp_f32_e32 v0, v0
	v_rcp_f32_e32 v1, v1
	v_rcp_f32_e32 v2, v2
	v_rcp_f32_e32 v3, v3
	v_cvt_pk_bf16_f32 v0, v0, v1
	v_cvt_pk_bf16_f32 v1, v2, v3
	v_or_b32_e32 v2, v4, v99
	v_ashrrev_i32_e32 v3, 31, v2
	v_lshlrev_b64 v[2:3], 11, v[2:3]
	v_lshl_add_u64 v[2:3], v[96:97], 0, v[2:3]
	flat_store_dwordx2 v[2:3], v[0:1]
	ds_read_b128 v[0:3], v98 offset:1088
	s_waitcnt lgkmcnt(0)
	v_mul_f32_e32 v0, 0xbfb8aa3b, v0
	v_mul_f32_e32 v1, 0xbfb8aa3b, v1
	v_mul_f32_e32 v2, 0xbfb8aa3b, v2
	v_mul_f32_e32 v3, 0xbfb8aa3b, v3
	v_exp_f32_e32 v0, v0
	v_exp_f32_e32 v1, v1
	v_exp_f32_e32 v2, v2
	v_exp_f32_e32 v3, v3
	v_add_f32_e32 v0, 1.0, v0
	v_add_f32_e32 v1, 1.0, v1
	v_add_f32_e32 v2, 1.0, v2
	v_add_f32_e32 v3, 1.0, v3
	v_rcp_f32_e32 v0, v0
	v_rcp_f32_e32 v1, v1
	v_rcp_f32_e32 v2, v2
	v_rcp_f32_e32 v3, v3
	v_cvt_pk_bf16_f32 v0, v0, v1
	v_cvt_pk_bf16_f32 v1, v2, v3
	v_or_b32_e32 v2, v4, v102
	v_ashrrev_i32_e32 v3, 31, v2
	v_lshlrev_b64 v[2:3], 11, v[2:3]
	v_lshl_add_u64 v[2:3], v[96:97], 0, v[2:3]
	flat_store_dwordx2 v[2:3], v[0:1]
	ds_read_b128 v[0:3], v98 offset:2176
	s_waitcnt lgkmcnt(0)
	v_mul_f32_e32 v0, 0xbfb8aa3b, v0
	v_mul_f32_e32 v1, 0xbfb8aa3b, v1
	v_mul_f32_e32 v2, 0xbfb8aa3b, v2
	v_mul_f32_e32 v3, 0xbfb8aa3b, v3
	v_exp_f32_e32 v0, v0
	v_exp_f32_e32 v1, v1
	v_exp_f32_e32 v2, v2
	v_exp_f32_e32 v3, v3
	v_add_f32_e32 v0, 1.0, v0
	v_add_f32_e32 v1, 1.0, v1
	v_add_f32_e32 v2, 1.0, v2
	v_add_f32_e32 v3, 1.0, v3
	v_rcp_f32_e32 v0, v0
	v_rcp_f32_e32 v1, v1
	v_rcp_f32_e32 v2, v2
	v_rcp_f32_e32 v3, v3
	v_cvt_pk_bf16_f32 v0, v0, v1
	v_cvt_pk_bf16_f32 v1, v2, v3
	v_or_b32_e32 v2, v4, v103
	v_ashrrev_i32_e32 v3, 31, v2
	v_lshlrev_b64 v[2:3], 11, v[2:3]
	v_lshl_add_u64 v[2:3], v[96:97], 0, v[2:3]
	flat_store_dwordx2 v[2:3], v[0:1]
	ds_read_b128 v[0:3], v98 offset:3264
	s_waitcnt lgkmcnt(0)
	v_mul_f32_e32 v0, 0xbfb8aa3b, v0
	v_mul_f32_e32 v1, 0xbfb8aa3b, v1
	v_mul_f32_e32 v2, 0xbfb8aa3b, v2
	v_mul_f32_e32 v3, 0xbfb8aa3b, v3
	v_exp_f32_e32 v0, v0
	v_exp_f32_e32 v1, v1
	v_exp_f32_e32 v2, v2
	v_exp_f32_e32 v3, v3
	v_add_f32_e32 v0, 1.0, v0
	v_add_f32_e32 v1, 1.0, v1
	v_add_f32_e32 v2, 1.0, v2
	v_add_f32_e32 v3, 1.0, v3
	v_rcp_f32_e32 v0, v0
	v_rcp_f32_e32 v1, v1
	v_rcp_f32_e32 v2, v2
	v_rcp_f32_e32 v3, v3
	v_cvt_pk_bf16_f32 v0, v0, v1
	v_cvt_pk_bf16_f32 v1, v2, v3
	v_or_b32_e32 v2, v4, v104
	v_ashrrev_i32_e32 v3, 31, v2
	v_lshlrev_b64 v[2:3], 11, v[2:3]
	v_lshl_add_u64 v[2:3], v[96:97], 0, v[2:3]
	flat_store_dwordx2 v[2:3], v[0:1]
	ds_read_b128 v[0:3], v98 offset:4352
	s_waitcnt lgkmcnt(0)
	v_mul_f32_e32 v0, 0xbfb8aa3b, v0
	v_mul_f32_e32 v1, 0xbfb8aa3b, v1
	v_mul_f32_e32 v2, 0xbfb8aa3b, v2
	v_mul_f32_e32 v3, 0xbfb8aa3b, v3
	v_exp_f32_e32 v0, v0
	v_exp_f32_e32 v1, v1
	v_exp_f32_e32 v2, v2
	v_exp_f32_e32 v3, v3
	v_add_f32_e32 v0, 1.0, v0
	v_add_f32_e32 v1, 1.0, v1
	v_add_f32_e32 v2, 1.0, v2
	v_add_f32_e32 v3, 1.0, v3
	v_rcp_f32_e32 v0, v0
	v_rcp_f32_e32 v1, v1
	v_rcp_f32_e32 v2, v2
	v_rcp_f32_e32 v3, v3
	v_cvt_pk_bf16_f32 v0, v0, v1
	v_cvt_pk_bf16_f32 v1, v2, v3
	v_or_b32_e32 v2, v4, v105
	v_ashrrev_i32_e32 v3, 31, v2
	v_lshlrev_b64 v[2:3], 11, v[2:3]
	v_lshl_add_u64 v[2:3], v[96:97], 0, v[2:3]
	flat_store_dwordx2 v[2:3], v[0:1]
	ds_read_b128 v[0:3], v98 offset:5440
	s_waitcnt lgkmcnt(0)
	v_mul_f32_e32 v0, 0xbfb8aa3b, v0
	v_mul_f32_e32 v1, 0xbfb8aa3b, v1
	v_mul_f32_e32 v2, 0xbfb8aa3b, v2
	v_mul_f32_e32 v3, 0xbfb8aa3b, v3
	v_exp_f32_e32 v0, v0
	v_exp_f32_e32 v1, v1
	v_exp_f32_e32 v2, v2
	v_exp_f32_e32 v3, v3
	v_add_f32_e32 v0, 1.0, v0
	v_add_f32_e32 v1, 1.0, v1
	v_add_f32_e32 v2, 1.0, v2
	v_add_f32_e32 v3, 1.0, v3
	v_rcp_f32_e32 v0, v0
	v_rcp_f32_e32 v1, v1
	v_rcp_f32_e32 v2, v2
	v_rcp_f32_e32 v3, v3
	v_cvt_pk_bf16_f32 v0, v0, v1
	v_cvt_pk_bf16_f32 v1, v2, v3
	v_or_b32_e32 v2, v4, v106
	v_ashrrev_i32_e32 v3, 31, v2
	v_lshlrev_b64 v[2:3], 11, v[2:3]
	v_lshl_add_u64 v[2:3], v[96:97], 0, v[2:3]
	flat_store_dwordx2 v[2:3], v[0:1]
	ds_read_b128 v[0:3], v98 offset:6528
	s_waitcnt lgkmcnt(0)
	v_mul_f32_e32 v0, 0xbfb8aa3b, v0
	v_mul_f32_e32 v1, 0xbfb8aa3b, v1
	v_mul_f32_e32 v2, 0xbfb8aa3b, v2
	v_mul_f32_e32 v3, 0xbfb8aa3b, v3
	v_exp_f32_e32 v0, v0
	v_exp_f32_e32 v1, v1
	v_exp_f32_e32 v2, v2
	v_exp_f32_e32 v3, v3
	v_add_f32_e32 v0, 1.0, v0
	v_add_f32_e32 v1, 1.0, v1
	v_add_f32_e32 v2, 1.0, v2
	v_add_f32_e32 v3, 1.0, v3
	v_rcp_f32_e32 v0, v0
	v_rcp_f32_e32 v1, v1
	v_rcp_f32_e32 v2, v2
	v_rcp_f32_e32 v3, v3
	v_cvt_pk_bf16_f32 v0, v0, v1
	v_cvt_pk_bf16_f32 v1, v2, v3
	v_or_b32_e32 v2, v4, v107
	v_ashrrev_i32_e32 v3, 31, v2
	v_lshlrev_b64 v[2:3], 11, v[2:3]
	v_lshl_add_u64 v[2:3], v[96:97], 0, v[2:3]
	flat_store_dwordx2 v[2:3], v[0:1]
	ds_read_b128 v[0:3], v98 offset:7616
	s_waitcnt lgkmcnt(0)
	v_mul_f32_e32 v0, 0xbfb8aa3b, v0
	v_mul_f32_e32 v1, 0xbfb8aa3b, v1
	v_mul_f32_e32 v2, 0xbfb8aa3b, v2
	v_mul_f32_e32 v3, 0xbfb8aa3b, v3
	v_exp_f32_e32 v0, v0
	v_exp_f32_e32 v1, v1
	v_exp_f32_e32 v2, v2
	v_exp_f32_e32 v3, v3
	v_add_f32_e32 v0, 1.0, v0
	v_add_f32_e32 v1, 1.0, v1
	v_add_f32_e32 v2, 1.0, v2
	v_add_f32_e32 v3, 1.0, v3
	v_rcp_f32_e32 v0, v0
	v_rcp_f32_e32 v1, v1
	v_rcp_f32_e32 v2, v2
	v_rcp_f32_e32 v3, v3
	v_cvt_pk_bf16_f32 v0, v0, v1
	v_cvt_pk_bf16_f32 v1, v2, v3
	v_or_b32_e32 v2, v4, v108
	v_ashrrev_i32_e32 v3, 31, v2
	v_lshlrev_b64 v[2:3], 11, v[2:3]
	v_lshl_add_u64 v[2:3], v[96:97], 0, v[2:3]
	flat_store_dwordx2 v[2:3], v[0:1]
	v_mov_b32_e32 v0, s3
	ds_read_b128 v[0:3], v0
	s_waitcnt lgkmcnt(0)
	v_readfirstlane_b32 s0, v3
	v_readfirstlane_b32 s29, v2
	v_lshlrev_b32_e32 v3, 4, v12
	v_and_b32_e32 v2, 32, v12
	s_add_u32 s42, s29, s36
	v_lshrrev_b32_e32 v4, 1, v12
	v_bitop3_b32 v2, v3, v2, 48 bitop3:0x6c
	s_addc_u32 s43, s0, s37
	v_bfe_u32 v13, v12, 2, 4
	v_and_b32_e32 v14, 32, v4
	v_lshrrev_b32_e32 v15, 1, v2
	v_ashrrev_i32_e32 v16, 3, v12
	s_add_u32 s36, s42, 0x18800000
	v_or_b32_e32 v6, v15, v14
	v_and_or_b32 v2, v16, s44, v13
	s_addc_u32 s37, s43, 0
	s_lshl_b64 s[38:39], s[30:31], 11
	v_and_b32_e32 v5, 0xfffffc00, v3
	v_lshl_or_b32 v130, v2, 10, v6
	v_add_u32_e32 v2, 0x2000, v3
	v_add_u32_e32 v4, 0x4000, v3
	v_add_u32_e32 v3, 0x6000, v3
	s_add_u32 s53, s29, s38
	v_ashrrev_i32_e32 v17, 7, v2
	v_ashrrev_i32_e32 v18, 7, v4
	v_ashrrev_i32_e32 v19, 7, v3
	s_addc_u32 s54, s0, s39
	v_and_or_b32 v2, v17, s44, v13
	v_and_or_b32 v4, v18, s44, v13
	v_and_or_b32 v3, v19, s44, v13
	v_add_u32_e32 v151, 0, v5
	s_add_u32 s38, s53, 0xe00000
	v_lshl_or_b32 v2, v2, 10, v6
	v_lshl_or_b32 v4, v4, 10, v6
	v_lshl_or_b32 v6, v3, 10, v6
	v_add_u32_e32 v3, 0x8000, v151
	v_lshlrev_b64 v[8:9], 1, v[130:131]
	v_readfirstlane_b32 s55, v151
	s_addc_u32 s39, s54, 0
	v_lshl_add_u64 v[10:11], s[36:37], 0, v[8:9]
	s_mov_b32 m0, s55
	v_readfirstlane_b32 s55, v3
	v_mov_b32_e32 v3, v131
	v_add_u32_e32 v5, 0x2000, v151
	global_load_lds_dwordx4 v[10:11], off
	v_lshl_add_u64 v[8:9], s[38:39], 0, v[8:9]
	s_mov_b32 m0, s55
	v_lshlrev_b64 v[2:3], 1, v[2:3]
	v_readfirstlane_b32 s55, v5
	v_add_u32_e32 v5, 0xa000, v151
	global_load_lds_dwordx4 v[8:9], off
	v_lshl_add_u64 v[8:9], s[36:37], 0, v[2:3]
	s_mov_b32 m0, s55
	v_readfirstlane_b32 s55, v5
	global_load_lds_dwordx4 v[8:9], off
	v_lshl_add_u64 v[2:3], s[38:39], 0, v[2:3]
	s_mov_b32 m0, s55
	v_mov_b32_e32 v5, v131
	v_add_u32_e32 v7, 0x4000, v151
	global_load_lds_dwordx4 v[2:3], off
	v_lshlrev_b64 v[2:3], 1, v[4:5]
	v_readfirstlane_b32 s55, v7
	v_lshl_add_u64 v[4:5], s[36:37], 0, v[2:3]
	s_mov_b32 m0, s55
	v_lshl_add_u64 v[2:3], s[38:39], 0, v[2:3]
	global_load_lds_dwordx4 v[4:5], off
	v_add_u32_e32 v4, 0xc000, v151
	v_mov_b32_e32 v7, v131
	v_readfirstlane_b32 s55, v4
	s_mov_b32 m0, s55
	v_and_b32_e32 v20, 15, v12
	global_load_lds_dwordx4 v[2:3], off
	v_lshlrev_b64 v[2:3], 1, v[6:7]
	v_add_u32_e32 v6, 0x6000, v151
	v_lshl_add_u64 v[4:5], s[36:37], 0, v[2:3]
	v_readfirstlane_b32 s36, v6
	s_mov_b32 m0, s36
	v_lshl_add_u64 v[2:3], s[38:39], 0, v[2:3]
	global_load_lds_dwordx4 v[4:5], off
	v_add_u32_e32 v4, 0xe000, v151
	v_lshlrev_b32_e32 v8, 10, v13
	v_readfirstlane_b32 s36, v4
	s_mov_b32 m0, s36
	v_lshlrev_b32_e32 v4, 2, v12
	global_load_lds_dwordx4 v[2:3], off
	v_and_b32_e32 v2, 48, v12
	v_lshlrev_b32_e32 v3, 6, v20
	v_and_b32_e32 v4, 32, v4
	v_bitop3_b32 v152, v3, v4, v2 bitop3:0x36
	v_lshlrev_b32_e32 v3, 7, v12
	v_and_b32_e32 v153, 0x6000, v3
	v_lshlrev_b32_e32 v3, 6, v12
	v_and_b32_e32 v154, 0xffffc000, v3
	v_and_b32_e32 v3, 0x3c0, v3
	v_bitop3_b32 v156, v3, v4, v2 bitop3:0x36
	v_lshlrev_b32_e32 v2, 10, v19
	v_and_or_b32 v2, v2, s45, v15
	v_lshlrev_b32_e32 v4, 10, v18
	v_or3_b32 v130, v2, v8, v14
	v_and_or_b32 v4, v4, s45, v15
	v_lshlrev_b32_e32 v6, 10, v17
	v_lshlrev_b64 v[2:3], 1, v[130:131]
	v_or3_b32 v130, v4, v8, v14
	v_and_or_b32 v6, v6, s45, v15
	v_lshlrev_b32_e32 v9, 10, v16
	v_lshlrev_b64 v[4:5], 1, v[130:131]
	v_or3_b32 v130, v6, v8, v14
	v_and_or_b32 v9, v9, s45, v15
	s_add_u32 s36, s53, 0xe00080
	v_lshlrev_b64 v[6:7], 1, v[130:131]
	v_or3_b32 v130, v9, v8, v14
	s_addc_u32 s37, s54, 0
	v_lshlrev_b64 v[8:9], 1, v[130:131]
	s_waitcnt vmcnt(0)
	v_lshl_add_u64 v[134:135], s[36:37], 0, v[2:3]
	v_lshl_add_u64 v[136:137], s[36:37], 0, v[4:5]
	v_lshl_add_u64 v[138:139], s[36:37], 0, v[6:7]
	v_lshl_add_u64 v[140:141], s[36:37], 0, v[8:9]
	s_add_u32 s36, s42, 0x18800080
	s_addc_u32 s37, s43, 0
	v_mov_b32_e32 v10, 0
	v_or_b32_e32 v155, 0x800, v154
	v_or_b32_e32 v157, 0x1000, v154
	v_or_b32_e32 v158, 0x1800, v154
	v_or_b32_e32 v159, 0x2000, v154
	v_or_b32_e32 v160, 0x2800, v154
	v_or_b32_e32 v161, 0x3000, v154
	v_or_b32_e32 v162, 0x3800, v154
	v_lshl_add_u64 v[142:143], s[36:37], 0, v[2:3]
	v_lshl_add_u64 v[144:145], s[36:37], 0, v[4:5]
	v_lshl_add_u64 v[146:147], s[36:37], 0, v[6:7]
	v_lshl_add_u64 v[148:149], s[36:37], 0, v[8:9]
	s_mov_b32 s38, 0
	s_mov_b64 s[36:37], 0
	v_mov_b32_e32 v11, v10
	v_mov_b32_e32 v12, v10
	v_mov_b32_e32 v13, v10
	v_mov_b32_e32 v22, v10
	v_mov_b32_e32 v23, v10
	v_mov_b32_e32 v24, v10
	v_mov_b32_e32 v25, v10
	v_mov_b32_e32 v30, v10
	v_mov_b32_e32 v31, v10
	v_mov_b32_e32 v32, v10
	v_mov_b32_e32 v33, v10
	v_mov_b32_e32 v38, v10
	v_mov_b32_e32 v39, v10
	v_mov_b32_e32 v40, v10
	v_mov_b32_e32 v41, v10
	v_mov_b32_e32 v2, v10
	v_mov_b32_e32 v3, v10
	v_mov_b32_e32 v4, v10
	v_mov_b32_e32 v5, v10
	v_mov_b32_e32 v6, v10
	v_mov_b32_e32 v7, v10
	v_mov_b32_e32 v8, v10
	v_mov_b32_e32 v9, v10
	v_mov_b32_e32 v14, v10
	v_mov_b32_e32 v15, v10
	v_mov_b32_e32 v16, v10
	v_mov_b32_e32 v17, v10
	v_mov_b32_e32 v18, v10
	v_mov_b32_e32 v19, v10
	v_mov_b32_e32 v20, v10
	v_mov_b32_e32 v21, v10
	v_mov_b32_e32 v26, v10
	v_mov_b32_e32 v27, v10
	v_mov_b32_e32 v28, v10
	v_mov_b32_e32 v29, v10
	v_mov_b32_e32 v34, v10
	v_mov_b32_e32 v35, v10
	v_mov_b32_e32 v36, v10
	v_mov_b32_e32 v37, v10
	v_mov_b32_e32 v42, v10
	v_mov_b32_e32 v43, v10
	v_mov_b32_e32 v44, v10
	v_mov_b32_e32 v45, v10
	v_mov_b32_e32 v46, v10
	v_mov_b32_e32 v47, v10
	v_mov_b32_e32 v48, v10
	v_mov_b32_e32 v49, v10
	v_mov_b32_e32 v50, v10
	v_mov_b32_e32 v51, v10
	v_mov_b32_e32 v52, v10
	v_mov_b32_e32 v53, v10
	v_mov_b32_e32 v54, v10
	v_mov_b32_e32 v55, v10
	v_mov_b32_e32 v56, v10
	v_mov_b32_e32 v57, v10
	v_mov_b32_e32 v58, v10
	v_mov_b32_e32 v59, v10
	v_mov_b32_e32 v60, v10
	v_mov_b32_e32 v61, v10
	v_mov_b32_e32 v62, v10
	v_mov_b32_e32 v63, v10
	v_mov_b32_e32 v64, v10
	v_mov_b32_e32 v65, v10
	v_mov_b32_e32 v66, v10
	v_mov_b32_e32 v67, v10
	v_mov_b32_e32 v68, v10
	v_mov_b32_e32 v69, v10
	v_mov_b32_e32 v70, v10
	v_mov_b32_e32 v71, v10
	v_mov_b32_e32 v72, v10
	v_mov_b32_e32 v73, v10
	v_mov_b32_e32 v74, v10
	v_mov_b32_e32 v75, v10
	v_mov_b32_e32 v76, v10
	v_mov_b32_e32 v77, v10
	v_mov_b32_e32 v78, v10
	v_mov_b32_e32 v79, v10
	v_mov_b32_e32 v80, v10
	v_mov_b32_e32 v81, v10
	v_mov_b32_e32 v82, v10
	v_mov_b32_e32 v83, v10
	v_mov_b32_e32 v84, v10
	v_mov_b32_e32 v85, v10
	v_mov_b32_e32 v86, v10
	v_mov_b32_e32 v87, v10
	v_mov_b32_e32 v88, v10
	v_mov_b32_e32 v89, v10
	v_mov_b32_e32 v90, v10
	v_mov_b32_e32 v91, v10
	v_mov_b32_e32 v92, v10
	v_mov_b32_e32 v93, v10
	v_mov_b32_e32 v94, v10
	v_mov_b32_e32 v95, v10
	v_mov_b32_e32 v96, v10
	v_mov_b32_e32 v97, v10
	v_mov_b32_e32 v98, v10
	v_mov_b32_e32 v99, v10
	v_mov_b32_e32 v100, v10
	v_mov_b32_e32 v101, v10
	v_mov_b32_e32 v102, v10
	v_mov_b32_e32 v103, v10
	v_mov_b32_e32 v104, v10
	v_mov_b32_e32 v105, v10
	v_mov_b32_e32 v106, v10
	v_mov_b32_e32 v107, v10
	v_mov_b32_e32 v108, v10
	v_mov_b32_e32 v109, v10
	v_mov_b32_e32 v110, v10
	v_mov_b32_e32 v111, v10
	v_mov_b32_e32 v112, v10
	v_mov_b32_e32 v113, v10
	v_mov_b32_e32 v114, v10
	v_mov_b32_e32 v115, v10
	v_mov_b32_e32 v116, v10
	v_mov_b32_e32 v117, v10
	v_mov_b32_e32 v118, v10
	v_mov_b32_e32 v119, v10
	v_mov_b32_e32 v120, v10
	v_mov_b32_e32 v121, v10
	v_mov_b32_e32 v122, v10
	v_mov_b32_e32 v123, v10
	v_mov_b32_e32 v124, v10
	v_mov_b32_e32 v125, v10
	v_mov_b32_e32 v126, v10
	v_mov_b32_e32 v127, v10
	v_mov_b32_e32 v128, v10
	v_mov_b32_e32 v129, v10
	s_waitcnt vmcnt(0) lgkmcnt(0)
	s_barrier
	v_readfirstlane_b32 s100, v151
	s_and_b32 s39, s38, 0x10000
	s_xor_b32 s42, s39, 0x10000
	s_add_i32 s39, s39, 0
	v_add3_u32 v130, s39, v152, v153
	v_add3_u32 v163, s39, v152, v154
	v_add3_u32 v196, s39, v156, v155
	v_add3_u32 v197, s39, v156, v157
	v_add3_u32 v198, s39, v156, v158
	v_add3_u32 v199, s39, v156, v159
	v_add3_u32 v200, s39, v156, v160
	v_add3_u32 v201, s39, v156, v161
	v_add3_u32 v202, s39, v156, v162
	ds_read_b128 v[180:183], v130 offset:32768
	ds_read_b128 v[164:167], v163
	ds_read_b128 v[168:171], v196
	ds_read_b128 v[172:175], v197
	ds_read_b128 v[176:179], v198
	ds_read_b128 v[184:187], v130 offset:34816
	ds_read_b128 v[188:191], v130 offset:36864
	ds_read_b128 v[192:195], v130 offset:38912
	s_add_i32 s101, s100, s42
	v_readfirstlane_b32 s98, v148
	v_readfirstlane_b32 s99, v149
	v_readfirstlane_b32 vcc_lo, v140
	v_readfirstlane_b32 vcc_hi, v141
	s_sub_u32 s98, s98, 0x1000000
	s_subb_u32 s99, s99, 0
	s_sub_u32 vcc_lo, vcc_lo, 0x1000000
	s_subb_u32 vcc_hi, vcc_hi, 0
	v_subrev_u32_e32 v148, s98, v148
	v_subrev_u32_e32 v140, vcc_lo, v140
	v_subrev_u32_e32 v146, s98, v146
	v_subrev_u32_e32 v138, vcc_lo, v138
	v_subrev_u32_e32 v144, s98, v144
	v_subrev_u32_e32 v136, vcc_lo, v136
	v_subrev_u32_e32 v142, s98, v142
	v_subrev_u32_e32 v134, vcc_lo, v134
	s_mov_b32 m0, s101
	s_nop 0
	global_load_lds_dwordx4 v148, s[98:99]
	s_add_i32 m0, s101, 0x8000
	s_nop 0
	global_load_lds_dwordx4 v140, vcc
	s_add_i32 m0, s101, 0x2000
	s_nop 0
	global_load_lds_dwordx4 v146, s[98:99]
	s_add_i32 m0, s101, 0xa000
	s_nop 0
	global_load_lds_dwordx4 v138, vcc
	s_add_i32 m0, s101, 0x4000
	s_nop 0
	global_load_lds_dwordx4 v144, s[98:99]
	s_add_i32 m0, s101, 0xc000
	s_nop 0
	global_load_lds_dwordx4 v136, vcc
	s_add_i32 m0, s101, 0x6000
	s_nop 0
	global_load_lds_dwordx4 v142, s[98:99]
	s_add_i32 m0, s101, 0xe000
	s_nop 0
	global_load_lds_dwordx4 v134, vcc
.LBB0_797:
	s_and_b32 s39, s38, 0x10000
	s_xor_b32 s42, s39, 0x10000
	s_add_i32 s39, s39, 0
	s_add_i32 s101, s100, s42
	s_cmpk_eq_i32 s36, 0
	s_cbranch_scc1 .Lg1n_797
	s_waitcnt lgkmcnt(3)
	v_mfma_f32_16x16x32_bf16 v[126:129], v[180:183], v[164:167], v[126:129]
	v_mfma_f32_16x16x32_bf16 v[110:113], v[180:183], v[168:171], v[110:113]
	v_mfma_f32_16x16x32_bf16 v[94:97], v[180:183], v[172:175], v[94:97]
	v_mfma_f32_16x16x32_bf16 v[78:81], v[180:183], v[176:179], v[78:81]
	ds_read_b128 v[240:243], v199
	ds_read_b128 v[244:247], v200
	s_add_i32 m0, s101, 0x4000
	s_nop 0
	global_load_lds_dwordx4 v144, s[98:99]
	s_waitcnt lgkmcnt(4)
	v_mfma_f32_16x16x32_bf16 v[122:125], v[184:187], v[164:167], v[122:125]
	v_mfma_f32_16x16x32_bf16 v[106:109], v[184:187], v[168:171], v[106:109]
	v_mfma_f32_16x16x32_bf16 v[90:93], v[184:187], v[172:175], v[90:93]
	v_mfma_f32_16x16x32_bf16 v[74:77], v[184:187], v[176:179], v[74:77]
	ds_read_b128 v[248:251], v201
	ds_read_b128 v[252:255], v202
	s_add_i32 m0, s101, 0xc000
	s_nop 0
	global_load_lds_dwordx4 v136, vcc
	s_waitcnt lgkmcnt(5)
	v_mfma_f32_16x16x32_bf16 v[118:121], v[188:191], v[164:167], v[118:121]
	v_mfma_f32_16x16x32_bf16 v[102:105], v[188:191], v[168:171], v[102:105]
	v_mfma_f32_16x16x32_bf16 v[86:89], v[188:191], v[172:175], v[86:89]
	v_mfma_f32_16x16x32_bf16 v[70:73], v[188:191], v[176:179], v[70:73]
	s_add_i32 m0, s101, 0x6000
	s_nop 0
	global_load_lds_dwordx4 v142, s[98:99]
	s_waitcnt lgkmcnt(4)
	v_mfma_f32_16x16x32_bf16 v[114:117], v[192:195], v[164:167], v[114:117]
	v_mfma_f32_16x16x32_bf16 v[98:101], v[192:195], v[168:171], v[98:101]
	v_mfma_f32_16x16x32_bf16 v[82:85], v[192:195], v[172:175], v[82:85]
	v_mfma_f32_16x16x32_bf16 v[66:69], v[192:195], v[176:179], v[66:69]
	s_add_i32 m0, s101, 0xe000
	s_nop 0
	global_load_lds_dwordx4 v134, vcc
.Lg2_797:
	ds_read_b128 v[164:167], v163 offset:1024
	ds_read_b128 v[168:171], v196 offset:1024
	ds_read_b128 v[172:175], v197 offset:1024
	ds_read_b128 v[176:179], v198 offset:1024
	s_waitcnt lgkmcnt(4)
	v_mfma_f32_16x16x32_bf16 v[62:65], v[180:183], v[240:243], v[62:65]
	v_mfma_f32_16x16x32_bf16 v[46:49], v[180:183], v[244:247], v[46:49]
	v_mfma_f32_16x16x32_bf16 v[18:21], v[180:183], v[248:251], v[18:21]
	v_mfma_f32_16x16x32_bf16 v[38:41], v[180:183], v[252:255], v[38:41]
	ds_read_b128 v[180:183], v130 offset:33792
	v_mfma_f32_16x16x32_bf16 v[58:61], v[184:187], v[240:243], v[58:61]
	v_mfma_f32_16x16x32_bf16 v[42:45], v[184:187], v[244:247], v[42:45]
	v_mfma_f32_16x16x32_bf16 v[14:17], v[184:187], v[248:251], v[14:17]
	v_mfma_f32_16x16x32_bf16 v[30:33], v[184:187], v[252:255], v[30:33]
	ds_read_b128 v[184:187], v130 offset:35840
	v_mfma_f32_16x16x32_bf16 v[54:57], v[188:191], v[240:243], v[54:57]
	v_mfma_f32_16x16x32_bf16 v[34:37], v[188:191], v[244:247], v[34:37]
	v_mfma_f32_16x16x32_bf16 v[6:9], v[188:191], v[248:251], v[6:9]
	v_mfma_f32_16x16x32_bf16 v[22:25], v[188:191], v[252:255], v[22:25]
	ds_read_b128 v[188:191], v130 offset:37888
	v_mfma_f32_16x16x32_bf16 v[50:53], v[192:195], v[240:243], v[50:53]
	v_mfma_f32_16x16x32_bf16 v[26:29], v[192:195], v[244:247], v[26:29]
	v_mfma_f32_16x16x32_bf16 v[2:5], v[192:195], v[248:251], v[2:5]
	v_mfma_f32_16x16x32_bf16 v[10:13], v[192:195], v[252:255], v[10:13]
	ds_read_b128 v[192:195], v130 offset:39936
	s_waitcnt lgkmcnt(3)
	v_mfma_f32_16x16x32_bf16 v[126:129], v[180:183], v[164:167], v[126:129]
	v_mfma_f32_16x16x32_bf16 v[110:113], v[180:183], v[168:171], v[110:113]
	v_mfma_f32_16x16x32_bf16 v[94:97], v[180:183], v[172:175], v[94:97]
	v_mfma_f32_16x16x32_bf16 v[78:81], v[180:183], v[176:179], v[78:81]
	ds_read_b128 v[240:243], v199 offset:1024
	ds_read_b128 v[244:247], v200 offset:1024
	s_waitcnt lgkmcnt(4)
	v_mfma_f32_16x16x32_bf16 v[122:125], v[184:187], v[164:167], v[122:125]
	v_mfma_f32_16x16x32_bf16 v[106:109], v[184:187], v[168:171], v[106:109]
	v_mfma_f32_16x16x32_bf16 v[90:93], v[184:187], v[172:175], v[90:93]
	v_mfma_f32_16x16x32_bf16 v[74:77], v[184:187], v[176:179], v[74:77]
	ds_read_b128 v[248:251], v201 offset:1024
	ds_read_b128 v[252:255], v202 offset:1024
	s_waitcnt lgkmcnt(5)
	v_mfma_f32_16x16x32_bf16 v[118:121], v[188:191], v[164:167], v[118:121]
	v_mfma_f32_16x16x32_bf16 v[102:105], v[188:191], v[168:171], v[102:105]
	v_mfma_f32_16x16x32_bf16 v[86:89], v[188:191], v[172:175], v[86:89]
	v_mfma_f32_16x16x32_bf16 v[70:73], v[188:191], v[176:179], v[70:73]
	s_waitcnt lgkmcnt(4)
	v_mfma_f32_16x16x32_bf16 v[114:117], v[192:195], v[164:167], v[114:117]
	v_mfma_f32_16x16x32_bf16 v[98:101], v[192:195], v[168:171], v[98:101]
	v_mfma_f32_16x16x32_bf16 v[82:85], v[192:195], v[172:175], v[82:85]
	v_mfma_f32_16x16x32_bf16 v[66:69], v[192:195], v[176:179], v[66:69]
	s_waitcnt vmcnt(0) lgkmcnt(0)
	s_barrier
	s_add_i32 s101, s100, s39
	s_cmpk_eq_i32 s36, 0x700
	s_cbranch_scc1 .Lg4n_797
	s_add_u32 s98, s98, 0x80
	s_addc_u32 s99, s99, 0
	s_add_u32 vcc_lo, vcc_lo, 0x80
	s_addc_u32 vcc_hi, vcc_hi, 0
	v_mfma_f32_16x16x32_bf16 v[62:65], v[180:183], v[240:243], v[62:65]
	v_mfma_f32_16x16x32_bf16 v[46:49], v[180:183], v[244:247], v[46:49]
	v_mfma_f32_16x16x32_bf16 v[18:21], v[180:183], v[248:251], v[18:21]
	v_mfma_f32_16x16x32_bf16 v[38:41], v[180:183], v[252:255], v[38:41]
	v_add3_u32 v130, s42, v152, v153
	ds_read_b128 v[180:183], v130 offset:32768
	v_add3_u32 v163, s42, v152, v154
	v_add3_u32 v196, s42, v156, v155
	v_add3_u32 v197, s42, v156, v157
	v_add3_u32 v198, s42, v156, v158
	ds_read_b128 v[164:167], v163
	ds_read_b128 v[168:171], v196
	ds_read_b128 v[172:175], v197
	ds_read_b128 v[176:179], v198
	s_mov_b32 m0, s101
	s_nop 0
	global_load_lds_dwordx4 v148, s[98:99]
	v_mfma_f32_16x16x32_bf16 v[58:61], v[184:187], v[240:243], v[58:61]
	v_mfma_f32_16x16x32_bf16 v[42:45], v[184:187], v[244:247], v[42:45]
	v_mfma_f32_16x16x32_bf16 v[14:17], v[184:187], v[248:251], v[14:17]
	v_mfma_f32_16x16x32_bf16 v[30:33], v[184:187], v[252:255], v[30:33]
	ds_read_b128 v[184:187], v130 offset:34816
	v_add3_u32 v199, s42, v156, v159
	v_add3_u32 v200, s42, v156, v160
	v_add3_u32 v201, s42, v156, v161
	v_add3_u32 v202, s42, v156, v162
	s_add_i32 m0, s101, 0x8000
	s_nop 0
	global_load_lds_dwordx4 v140, vcc
	v_mfma_f32_16x16x32_bf16 v[54:57], v[188:191], v[240:243], v[54:57]
	v_mfma_f32_16x16x32_bf16 v[34:37], v[188:191], v[244:247], v[34:37]
	v_mfma_f32_16x16x32_bf16 v[6:9], v[188:191], v[248:251], v[6:9]
	v_mfma_f32_16x16x32_bf16 v[22:25], v[188:191], v[252:255], v[22:25]
	ds_read_b128 v[188:191], v130 offset:36864
	s_add_i32 m0, s101, 0x2000
	s_nop 0
	global_load_lds_dwordx4 v146, s[98:99]
	v_mfma_f32_16x16x32_bf16 v[50:53], v[192:195], v[240:243], v[50:53]
	v_mfma_f32_16x16x32_bf16 v[26:29], v[192:195], v[244:247], v[26:29]
	v_mfma_f32_16x16x32_bf16 v[2:5], v[192:195], v[248:251], v[2:5]
	v_mfma_f32_16x16x32_bf16 v[10:13], v[192:195], v[252:255], v[10:13]
	ds_read_b128 v[192:195], v130 offset:38912
	s_add_i32 m0, s101, 0xa000
	s_nop 0
	global_load_lds_dwordx4 v138, vcc

.LBB0_845:
	s_ashr_i32 s12, s27, 31
	s_lshr_b32 s12, s12, 26
	s_add_i32 s12, s27, s12
	s_ashr_i32 s13, s12, 6
	s_and_b32 s12, s12, 0xffc0
	s_sub_i32 s12, s27, s12
	s_bfe_i32 s14, s12, 0x80000
	s_bfe_u32 s14, s14, 0x4000b
	s_add_i32 s14, s12, s14
	s_lshl_b32 s28, s13, 4
	s_and_b32 s13, s14, 0xf0
	v_mov_b32_e32 v148, v132
	v_mov_b32_e32 v18, v132
	s_sub_i32 s12, s12, s13
	ds_read_b64 v[0:1], v133
	s_bfe_i32 s15, s14, 0x80000
	v_lshlrev_b32_e32 v9, 4, v18
	v_and_b32_e32 v8, 32, v18
	s_sext_i32_i8 s12, s12
	v_lshrrev_b32_e32 v10, 1, v18
	v_bitop3_b32 v8, v9, v8, 48 bitop3:0x6c
	s_sext_i32_i16 s15, s15
	s_add_i32 s28, s28, s12
	v_bfe_u32 v19, v18, 2, 4
	v_and_b32_e32 v20, 32, v10
	v_lshrrev_b32_e32 v21, 1, v8
	v_ashrrev_i32_e32 v22, 3, v18
	s_lshl_b32 s14, s28, 8
	s_lshl_b32 s12, s15, 4
	v_or_b32_e32 v12, v21, v20
	v_and_or_b32 v8, v22, s18, v19
	s_and_b32 s12, s12, 0xffffff00
	s_ashr_i32 s15, s14, 31
	v_and_b32_e32 v11, 0xfffffc00, v9
	v_lshl_or_b32 v128, v8, 10, v12
	v_add_u32_e32 v8, 0x2000, v9
	v_add_u32_e32 v10, 0x4000, v9
	v_add_u32_e32 v9, 0x6000, v9
	s_lshl_b64 s[16:17], s[14:15], 11
	s_ashr_i32 s13, s12, 31
	v_ashrrev_i32_e32 v23, 7, v8
	v_ashrrev_i32_e32 v24, 7, v10
	v_ashrrev_i32_e32 v25, 7, v9
	s_waitcnt lgkmcnt(0)
	v_lshl_add_u64 v[2:3], v[0:1], 0, s[16:17]
	s_lshl_b64 s[16:17], s[12:13], 11
	v_and_or_b32 v8, v23, s18, v19
	v_and_or_b32 v10, v24, s18, v19
	v_and_or_b32 v9, v25, s18, v19
	v_add_u32_e32 v149, 0, v11
	v_lshl_add_u64 v[4:5], v[2:3], 0, s[4:5]
	v_lshl_add_u64 v[0:1], v[0:1], 0, s[16:17]
	v_lshl_or_b32 v8, v8, 10, v12
	v_lshl_or_b32 v10, v10, 10, v12
	v_lshl_or_b32 v12, v9, 10, v12
	v_add_u32_e32 v9, 0x8000, v149
	v_lshlrev_b64 v[14:15], 1, v[128:129]
	v_readfirstlane_b32 s15, v149
	v_lshl_add_u64 v[6:7], v[0:1], 0, s[6:7]
	v_lshl_add_u64 v[16:17], v[4:5], 0, v[14:15]
	s_mov_b32 m0, s15
	v_readfirstlane_b32 s15, v9
	v_mov_b32_e32 v9, v129
	v_add_u32_e32 v11, 0x2000, v149
	global_load_lds_dwordx4 v[16:17], off
	v_lshl_add_u64 v[14:15], v[6:7], 0, v[14:15]
	s_mov_b32 m0, s15
	v_lshlrev_b64 v[8:9], 1, v[8:9]
	v_readfirstlane_b32 s15, v11
	v_add_u32_e32 v11, 0xa000, v149
	global_load_lds_dwordx4 v[14:15], off
	v_lshl_add_u64 v[14:15], v[4:5], 0, v[8:9]
	s_mov_b32 m0, s15
	v_readfirstlane_b32 s15, v11
	global_load_lds_dwordx4 v[14:15], off
	v_lshl_add_u64 v[8:9], v[6:7], 0, v[8:9]
	s_mov_b32 m0, s15
	v_mov_b32_e32 v11, v129
	v_add_u32_e32 v13, 0x4000, v149
	global_load_lds_dwordx4 v[8:9], off
	v_lshlrev_b64 v[8:9], 1, v[10:11]
	v_readfirstlane_b32 s15, v13
	v_lshl_add_u64 v[10:11], v[4:5], 0, v[8:9]
	s_mov_b32 m0, s15
	v_lshl_add_u64 v[8:9], v[6:7], 0, v[8:9]
	global_load_lds_dwordx4 v[10:11], off
	v_add_u32_e32 v10, 0xc000, v149
	v_mov_b32_e32 v13, v129
	v_readfirstlane_b32 s15, v10
	s_mov_b32 m0, s15
	v_add_u32_e32 v10, 0x6000, v149
	global_load_lds_dwordx4 v[8:9], off
	v_lshlrev_b64 v[8:9], 1, v[12:13]
	v_readfirstlane_b32 s15, v10
	v_lshl_add_u64 v[4:5], v[4:5], 0, v[8:9]
	s_mov_b32 m0, s15
	v_and_b32_e32 v26, 15, v18
	global_load_lds_dwordx4 v[4:5], off
	v_lshl_add_u64 v[4:5], v[6:7], 0, v[8:9]
	v_add_u32_e32 v6, 0xe000, v149
	v_lshlrev_b32_e32 v10, 10, v19
	v_readfirstlane_b32 s15, v6
	s_mov_b32 m0, s15
	v_lshlrev_b32_e32 v6, 2, v18
	global_load_lds_dwordx4 v[4:5], off
	v_and_b32_e32 v4, 48, v18
	v_lshlrev_b32_e32 v5, 6, v26
	v_and_b32_e32 v6, 32, v6
	v_bitop3_b32 v150, v5, v6, v4 bitop3:0x36
	v_lshlrev_b32_e32 v5, 7, v18
	v_and_b32_e32 v151, 0x6000, v5
	v_lshlrev_b32_e32 v5, 6, v18
	v_and_b32_e32 v152, 0xffffc000, v5
	v_and_b32_e32 v5, 0x3c0, v5
	v_bitop3_b32 v154, v5, v6, v4 bitop3:0x36
	v_lshlrev_b32_e32 v4, 10, v25
	v_and_or_b32 v4, v4, s19, v21
	v_lshlrev_b32_e32 v6, 10, v24
	v_or3_b32 v128, v4, v10, v20
	v_and_or_b32 v6, v6, s19, v21
	v_lshlrev_b32_e32 v8, 10, v23
	v_lshlrev_b64 v[4:5], 1, v[128:129]
	v_or3_b32 v128, v6, v10, v20
	v_and_or_b32 v8, v8, s19, v21
	v_lshlrev_b32_e32 v11, 10, v22
	v_lshlrev_b64 v[6:7], 1, v[128:129]
	v_or3_b32 v128, v8, v10, v20
	v_and_or_b32 v11, v11, s19, v21
	v_lshlrev_b64 v[8:9], 1, v[128:129]
	v_or3_b32 v128, v11, v10, v20
	s_waitcnt vmcnt(0)
	v_lshl_add_u64 v[0:1], v[0:1], 0, s[8:9]
	v_lshlrev_b64 v[10:11], 1, v[128:129]
	v_lshl_add_u64 v[130:131], v[0:1], 0, v[4:5]
	v_lshl_add_u64 v[134:135], v[0:1], 0, v[6:7]
	v_lshl_add_u64 v[136:137], v[0:1], 0, v[8:9]
	v_lshl_add_u64 v[138:139], v[0:1], 0, v[10:11]
	v_lshl_add_u64 v[0:1], v[2:3], 0, s[10:11]
	v_or_b32_e32 v153, 0x800, v152
	v_or_b32_e32 v155, 0x1000, v152
	v_or_b32_e32 v156, 0x1800, v152
	v_or_b32_e32 v157, 0x2000, v152
	v_or_b32_e32 v158, 0x2800, v152
	v_or_b32_e32 v159, 0x3000, v152
	v_or_b32_e32 v160, 0x3800, v152
	v_lshl_add_u64 v[140:141], v[0:1], 0, v[4:5]
	v_lshl_add_u64 v[142:143], v[0:1], 0, v[6:7]
	v_lshl_add_u64 v[144:145], v[0:1], 0, v[8:9]
	v_lshl_add_u64 v[146:147], v[0:1], 0, v[10:11]
	s_mov_b64 s[16:17], 0
	s_mov_b32 s15, 0
	v_mov_b32_e32 v12, 0
	v_mov_b32_e32 v14, v129
	v_mov_b32_e32 v15, v129
	v_mov_b32_e32 v20, 0
	v_mov_b32_e32 v21, v129
	v_mov_b32_e32 v22, v129
	v_mov_b32_e32 v23, v129
	v_mov_b32_e32 v28, 0
	v_mov_b32_e32 v29, v129
	v_mov_b32_e32 v30, v129
	v_mov_b32_e32 v31, v129
	v_mov_b32_e32 v36, 0
	v_mov_b32_e32 v37, v129
	v_mov_b32_e32 v38, v129
	v_mov_b32_e32 v39, v129
	v_mov_b32_e32 v0, 0
	v_mov_b32_e32 v1, v129
	v_mov_b32_e32 v2, v129
	v_mov_b32_e32 v3, v129
	v_mov_b32_e32 v4, 0
	v_mov_b32_e32 v5, v129
	v_mov_b32_e32 v6, v129
	v_mov_b32_e32 v7, v129
	v_mov_b32_e32 v8, 0
	v_mov_b32_e32 v9, v129
	v_mov_b32_e32 v10, v129
	v_mov_b32_e32 v11, v129
	v_mov_b32_e32 v16, 0
	v_mov_b32_e32 v17, v129
	v_mov_b32_e32 v18, v129
	v_mov_b32_e32 v19, v129
	v_mov_b32_e32 v24, 0
	v_mov_b32_e32 v25, v129
	v_mov_b32_e32 v26, v129
	v_mov_b32_e32 v27, v129
	v_mov_b32_e32 v32, 0
	v_mov_b32_e32 v33, v129
	v_mov_b32_e32 v34, v129
	v_mov_b32_e32 v35, v129
	v_mov_b32_e32 v40, 0
	v_mov_b32_e32 v41, v129
	v_mov_b32_e32 v42, v129
	v_mov_b32_e32 v43, v129
	v_mov_b32_e32 v44, 0
	v_mov_b32_e32 v45, v129
	v_mov_b32_e32 v46, v129
	v_mov_b32_e32 v47, v129
	v_mov_b32_e32 v48, 0
	v_mov_b32_e32 v49, v129
	v_mov_b32_e32 v50, v129
	v_mov_b32_e32 v51, v129
	v_mov_b32_e32 v52, 0
	v_mov_b32_e32 v53, v129
	v_mov_b32_e32 v54, v129
	v_mov_b32_e32 v55, v129
	v_mov_b32_e32 v56, 0
	v_mov_b32_e32 v57, v129
	v_mov_b32_e32 v58, v129
	v_mov_b32_e32 v59, v129
	v_mov_b32_e32 v60, 0
	v_mov_b32_e32 v61, v129
	v_mov_b32_e32 v62, v129
	v_mov_b32_e32 v63, v129
	v_mov_b32_e32 v64, 0
	v_mov_b32_e32 v65, v129
	v_mov_b32_e32 v66, v129
	v_mov_b32_e32 v67, v129
	v_mov_b32_e32 v68, 0
	v_mov_b32_e32 v69, v129
	v_mov_b32_e32 v70, v129
	v_mov_b32_e32 v71, v129
	v_mov_b32_e32 v72, 0
	v_mov_b32_e32 v73, v129
	v_mov_b32_e32 v74, v129
	v_mov_b32_e32 v75, v129
	v_mov_b32_e32 v76, 0
	v_mov_b32_e32 v77, v129
	v_mov_b32_e32 v78, v129
	v_mov_b32_e32 v79, v129
	v_mov_b32_e32 v80, 0
	v_mov_b32_e32 v81, v129
	v_mov_b32_e32 v82, v129
	v_mov_b32_e32 v83, v129
	v_mov_b32_e32 v84, 0
	v_mov_b32_e32 v85, v129
	v_mov_b32_e32 v86, v129
	v_mov_b32_e32 v87, v129
	v_mov_b32_e32 v88, 0
	v_mov_b32_e32 v89, v129
	v_mov_b32_e32 v90, v129
	v_mov_b32_e32 v91, v129
	v_mov_b32_e32 v92, 0
	v_mov_b32_e32 v93, v129
	v_mov_b32_e32 v94, v129
	v_mov_b32_e32 v95, v129
	v_mov_b32_e32 v96, 0
	v_mov_b32_e32 v97, v129
	v_mov_b32_e32 v98, v129
	v_mov_b32_e32 v99, v129
	v_mov_b32_e32 v100, 0
	v_mov_b32_e32 v101, v129
	v_mov_b32_e32 v102, v129
	v_mov_b32_e32 v103, v129
	v_mov_b32_e32 v104, 0
	v_mov_b32_e32 v105, v129
	v_mov_b32_e32 v106, v129
	v_mov_b32_e32 v107, v129
	v_mov_b32_e32 v108, 0
	v_mov_b32_e32 v109, v129
	v_mov_b32_e32 v110, v129
	v_mov_b32_e32 v111, v129
	v_mov_b32_e32 v112, 0
	v_mov_b32_e32 v113, v129
	v_mov_b32_e32 v114, v129
	v_mov_b32_e32 v115, v129
	v_mov_b32_e32 v116, 0
	v_mov_b32_e32 v117, v129
	v_mov_b32_e32 v118, v129
	v_mov_b32_e32 v119, v129
	v_mov_b32_e32 v120, 0
	v_mov_b32_e32 v121, v129
	v_mov_b32_e32 v122, v129
	v_mov_b32_e32 v123, v129
	v_mov_b32_e32 v124, 0
	v_mov_b32_e32 v125, v129
	v_mov_b32_e32 v126, v129
	v_mov_b32_e32 v127, v129
	s_waitcnt vmcnt(0) lgkmcnt(0)
	s_barrier
	v_readfirstlane_b32 s100, v149
	s_and_b32 s29, s15, 0x10000
	s_xor_b32 s30, s29, 0x10000
	s_add_i32 s29, s29, 0
	v_add3_u32 v128, s29, v150, v151
	v_add3_u32 v161, s29, v150, v152
	v_add3_u32 v194, s29, v154, v153
	v_add3_u32 v195, s29, v154, v155
	v_add3_u32 v196, s29, v154, v156
	v_add3_u32 v197, s29, v154, v157
	v_add3_u32 v198, s29, v154, v158
	v_add3_u32 v199, s29, v154, v159
	v_add3_u32 v200, s29, v154, v160
	ds_read_b128 v[178:181], v128 offset:32768
	ds_read_b128 v[162:165], v161
	ds_read_b128 v[166:169], v194
	ds_read_b128 v[170:173], v195
	ds_read_b128 v[174:177], v196
	ds_read_b128 v[182:185], v128 offset:34816
	ds_read_b128 v[186:189], v128 offset:36864
	ds_read_b128 v[190:193], v128 offset:38912
	s_add_i32 s101, s100, s30
	v_readfirstlane_b32 s98, v146
	v_readfirstlane_b32 s99, v147
	v_readfirstlane_b32 vcc_lo, v138
	v_readfirstlane_b32 vcc_hi, v139
	s_sub_u32 s98, s98, 0x1000000
	s_subb_u32 s99, s99, 0
	s_sub_u32 vcc_lo, vcc_lo, 0x1000000
	s_subb_u32 vcc_hi, vcc_hi, 0
	v_subrev_u32_e32 v146, s98, v146
	v_subrev_u32_e32 v138, vcc_lo, v138
	v_subrev_u32_e32 v144, s98, v144
	v_subrev_u32_e32 v136, vcc_lo, v136
	v_subrev_u32_e32 v142, s98, v142
	v_subrev_u32_e32 v134, vcc_lo, v134
	v_subrev_u32_e32 v140, s98, v140
	v_subrev_u32_e32 v130, vcc_lo, v130
	s_mov_b32 m0, s101
	s_nop 0
	global_load_lds_dwordx4 v146, s[98:99]
	s_add_i32 m0, s101, 0x8000
	s_nop 0
	global_load_lds_dwordx4 v138, vcc
	s_add_i32 m0, s101, 0x2000
	s_nop 0
	global_load_lds_dwordx4 v144, s[98:99]
	s_add_i32 m0, s101, 0xa000
	s_nop 0
	global_load_lds_dwordx4 v136, vcc
	s_add_i32 m0, s101, 0x4000
	s_nop 0
	global_load_lds_dwordx4 v142, s[98:99]
	s_add_i32 m0, s101, 0xc000
	s_nop 0
	global_load_lds_dwordx4 v134, vcc
	s_add_i32 m0, s101, 0x6000
	s_nop 0
	global_load_lds_dwordx4 v140, s[98:99]
	s_add_i32 m0, s101, 0xe000
	s_nop 0
	global_load_lds_dwordx4 v130, vcc
.LBB0_846:
	s_and_b32 s29, s15, 0x10000
	s_xor_b32 s30, s29, 0x10000
	s_add_i32 s29, s29, 0
	s_add_i32 s101, s100, s30
	s_cmpk_eq_i32 s16, 0
	s_cbranch_scc1 .Lg1n_846
	s_waitcnt lgkmcnt(3)
	v_mfma_f32_16x16x32_bf16 v[124:127], v[178:181], v[162:165], v[124:127]
	v_mfma_f32_16x16x32_bf16 v[108:111], v[178:181], v[166:169], v[108:111]
	v_mfma_f32_16x16x32_bf16 v[92:95], v[178:181], v[170:173], v[92:95]
	v_mfma_f32_16x16x32_bf16 v[76:79], v[178:181], v[174:177], v[76:79]
	ds_read_b128 v[240:243], v197
	ds_read_b128 v[244:247], v198
	s_add_i32 m0, s101, 0x4000
	s_nop 0
	global_load_lds_dwordx4 v142, s[98:99]
	s_waitcnt lgkmcnt(4)
	v_mfma_f32_16x16x32_bf16 v[120:123], v[182:185], v[162:165], v[120:123]
	v_mfma_f32_16x16x32_bf16 v[104:107], v[182:185], v[166:169], v[104:107]
	v_mfma_f32_16x16x32_bf16 v[88:91], v[182:185], v[170:173], v[88:91]
	v_mfma_f32_16x16x32_bf16 v[72:75], v[182:185], v[174:177], v[72:75]
	ds_read_b128 v[248:251], v199
	ds_read_b128 v[252:255], v200
	s_add_i32 m0, s101, 0xc000
	s_nop 0
	global_load_lds_dwordx4 v134, vcc
	s_waitcnt lgkmcnt(5)
	v_mfma_f32_16x16x32_bf16 v[116:119], v[186:189], v[162:165], v[116:119]
	v_mfma_f32_16x16x32_bf16 v[100:103], v[186:189], v[166:169], v[100:103]
	v_mfma_f32_16x16x32_bf16 v[84:87], v[186:189], v[170:173], v[84:87]
	v_mfma_f32_16x16x32_bf16 v[68:71], v[186:189], v[174:177], v[68:71]
	s_add_i32 m0, s101, 0x6000
	s_nop 0
	global_load_lds_dwordx4 v140, s[98:99]
	s_waitcnt lgkmcnt(4)
	v_mfma_f32_16x16x32_bf16 v[112:115], v[190:193], v[162:165], v[112:115]
	v_mfma_f32_16x16x32_bf16 v[96:99], v[190:193], v[166:169], v[96:99]
	v_mfma_f32_16x16x32_bf16 v[80:83], v[190:193], v[170:173], v[80:83]
	v_mfma_f32_16x16x32_bf16 v[64:67], v[190:193], v[174:177], v[64:67]
	s_add_i32 m0, s101, 0xe000
	s_nop 0
	global_load_lds_dwordx4 v130, vcc
.Lg2_846:
	ds_read_b128 v[162:165], v161 offset:1024
	ds_read_b128 v[166:169], v194 offset:1024
	ds_read_b128 v[170:173], v195 offset:1024
	ds_read_b128 v[174:177], v196 offset:1024
	s_waitcnt lgkmcnt(4)
	v_mfma_f32_16x16x32_bf16 v[60:63], v[178:181], v[240:243], v[60:63]
	v_mfma_f32_16x16x32_bf16 v[44:47], v[178:181], v[244:247], v[44:47]
	v_mfma_f32_16x16x32_bf16 v[16:19], v[178:181], v[248:251], v[16:19]
	v_mfma_f32_16x16x32_bf16 v[36:39], v[178:181], v[252:255], v[36:39]
	ds_read_b128 v[178:181], v128 offset:33792
	v_mfma_f32_16x16x32_bf16 v[56:59], v[182:185], v[240:243], v[56:59]
	v_mfma_f32_16x16x32_bf16 v[40:43], v[182:185], v[244:247], v[40:43]
	v_mfma_f32_16x16x32_bf16 v[8:11], v[182:185], v[248:251], v[8:11]
	v_mfma_f32_16x16x32_bf16 v[28:31], v[182:185], v[252:255], v[28:31]
	ds_read_b128 v[182:185], v128 offset:35840
	v_mfma_f32_16x16x32_bf16 v[52:55], v[186:189], v[240:243], v[52:55]
	v_mfma_f32_16x16x32_bf16 v[32:35], v[186:189], v[244:247], v[32:35]
	v_mfma_f32_16x16x32_bf16 v[4:7], v[186:189], v[248:251], v[4:7]
	v_mfma_f32_16x16x32_bf16 v[20:23], v[186:189], v[252:255], v[20:23]
	ds_read_b128 v[186:189], v128 offset:37888
	v_mfma_f32_16x16x32_bf16 v[48:51], v[190:193], v[240:243], v[48:51]
	v_mfma_f32_16x16x32_bf16 v[24:27], v[190:193], v[244:247], v[24:27]
	v_mfma_f32_16x16x32_bf16 v[0:3], v[190:193], v[248:251], v[0:3]
	v_mfma_f32_16x16x32_bf16 v[12:15], v[190:193], v[252:255], v[12:15]
	ds_read_b128 v[190:193], v128 offset:39936
	s_waitcnt lgkmcnt(3)
	v_mfma_f32_16x16x32_bf16 v[124:127], v[178:181], v[162:165], v[124:127]
	v_mfma_f32_16x16x32_bf16 v[108:111], v[178:181], v[166:169], v[108:111]
	v_mfma_f32_16x16x32_bf16 v[92:95], v[178:181], v[170:173], v[92:95]
	v_mfma_f32_16x16x32_bf16 v[76:79], v[178:181], v[174:177], v[76:79]
	ds_read_b128 v[240:243], v197 offset:1024
	ds_read_b128 v[244:247], v198 offset:1024
	s_waitcnt lgkmcnt(4)
	v_mfma_f32_16x16x32_bf16 v[120:123], v[182:185], v[162:165], v[120:123]
	v_mfma_f32_16x16x32_bf16 v[104:107], v[182:185], v[166:169], v[104:107]
	v_mfma_f32_16x16x32_bf16 v[88:91], v[182:185], v[170:173], v[88:91]
	v_mfma_f32_16x16x32_bf16 v[72:75], v[182:185], v[174:177], v[72:75]
	ds_read_b128 v[248:251], v199 offset:1024
	ds_read_b128 v[252:255], v200 offset:1024
	s_waitcnt lgkmcnt(5)
	v_mfma_f32_16x16x32_bf16 v[116:119], v[186:189], v[162:165], v[116:119]
	v_mfma_f32_16x16x32_bf16 v[100:103], v[186:189], v[166:169], v[100:103]
	v_mfma_f32_16x16x32_bf16 v[84:87], v[186:189], v[170:173], v[84:87]
	v_mfma_f32_16x16x32_bf16 v[68:71], v[186:189], v[174:177], v[68:71]
	s_waitcnt lgkmcnt(4)
	v_mfma_f32_16x16x32_bf16 v[112:115], v[190:193], v[162:165], v[112:115]
	v_mfma_f32_16x16x32_bf16 v[96:99], v[190:193], v[166:169], v[96:99]
	v_mfma_f32_16x16x32_bf16 v[80:83], v[190:193], v[170:173], v[80:83]
	v_mfma_f32_16x16x32_bf16 v[64:67], v[190:193], v[174:177], v[64:67]
	s_waitcnt vmcnt(0) lgkmcnt(0)
	s_barrier
	s_add_i32 s101, s100, s29
	s_cmpk_eq_i32 s16, 0x700
	s_cbranch_scc1 .Lg4n_846
	s_add_u32 s98, s98, 0x80
	s_addc_u32 s99, s99, 0
	s_add_u32 vcc_lo, vcc_lo, 0x80
	s_addc_u32 vcc_hi, vcc_hi, 0
	v_mfma_f32_16x16x32_bf16 v[60:63], v[178:181], v[240:243], v[60:63]
	v_mfma_f32_16x16x32_bf16 v[44:47], v[178:181], v[244:247], v[44:47]
	v_mfma_f32_16x16x32_bf16 v[16:19], v[178:181], v[248:251], v[16:19]
	v_mfma_f32_16x16x32_bf16 v[36:39], v[178:181], v[252:255], v[36:39]
	v_add3_u32 v128, s30, v150, v151
	ds_read_b128 v[178:181], v128 offset:32768
	v_add3_u32 v161, s30, v150, v152
	v_add3_u32 v194, s30, v154, v153
	v_add3_u32 v195, s30, v154, v155
	v_add3_u32 v196, s30, v154, v156
	ds_read_b128 v[162:165], v161
	ds_read_b128 v[166:169], v194
	ds_read_b128 v[170:173], v195
	ds_read_b128 v[174:177], v196
	s_mov_b32 m0, s101
	s_nop 0
	global_load_lds_dwordx4 v146, s[98:99]
	v_mfma_f32_16x16x32_bf16 v[56:59], v[182:185], v[240:243], v[56:59]
	v_mfma_f32_16x16x32_bf16 v[40:43], v[182:185], v[244:247], v[40:43]
	v_mfma_f32_16x16x32_bf16 v[8:11], v[182:185], v[248:251], v[8:11]
	v_mfma_f32_16x16x32_bf16 v[28:31], v[182:185], v[252:255], v[28:31]
	ds_read_b128 v[182:185], v128 offset:34816
	v_add3_u32 v197, s30, v154, v157
	v_add3_u32 v198, s30, v154, v158
	v_add3_u32 v199, s30, v154, v159
	v_add3_u32 v200, s30, v154, v160
	s_add_i32 m0, s101, 0x8000
	s_nop 0
	global_load_lds_dwordx4 v138, vcc
	v_mfma_f32_16x16x32_bf16 v[52:55], v[186:189], v[240:243], v[52:55]
	v_mfma_f32_16x16x32_bf16 v[32:35], v[186:189], v[244:247], v[32:35]
	v_mfma_f32_16x16x32_bf16 v[4:7], v[186:189], v[248:251], v[4:7]
	v_mfma_f32_16x16x32_bf16 v[20:23], v[186:189], v[252:255], v[20:23]
	ds_read_b128 v[186:189], v128 offset:36864
	s_add_i32 m0, s101, 0x2000
	s_nop 0
	global_load_lds_dwordx4 v144, s[98:99]
	v_mfma_f32_16x16x32_bf16 v[48:51], v[190:193], v[240:243], v[48:51]
	v_mfma_f32_16x16x32_bf16 v[24:27], v[190:193], v[244:247], v[24:27]
	v_mfma_f32_16x16x32_bf16 v[0:3], v[190:193], v[248:251], v[0:3]
	v_mfma_f32_16x16x32_bf16 v[12:15], v[190:193], v[252:255], v[12:15]
	ds_read_b128 v[190:193], v128 offset:38912
	s_add_i32 m0, s101, 0xa000
	s_nop 0
	global_load_lds_dwordx4 v136, vcc

.Lnxw_942:
	s_waitcnt vmcnt(16) lgkmcnt(0)
	s_barrier
	v_readfirstlane_b32 s100, v149
	s_and_b32 s17, s15, 0x10000
	s_xor_b32 s42, s17, 0x10000
	s_add_i32 s17, s17, 0
	v_add3_u32 v128, s17, v150, v151
	v_add3_u32 v161, s17, v150, v152
	v_add3_u32 v194, s17, v154, v153
	v_add3_u32 v195, s17, v154, v155
	v_add3_u32 v196, s17, v154, v156
	v_add3_u32 v197, s17, v154, v157
	v_add3_u32 v198, s17, v154, v158
	v_add3_u32 v199, s17, v154, v159
	v_add3_u32 v200, s17, v154, v160
	ds_read_b128 v[178:181], v128 offset:32768
	ds_read_b128 v[162:165], v161
	ds_read_b128 v[166:169], v194
	ds_read_b128 v[170:173], v195
	ds_read_b128 v[174:177], v196
	ds_read_b128 v[182:185], v128 offset:34816
	ds_read_b128 v[186:189], v128 offset:36864
	ds_read_b128 v[190:193], v128 offset:38912
	s_add_i32 s101, s100, s42
	v_readfirstlane_b32 s98, v146
	v_readfirstlane_b32 s99, v147
	v_readfirstlane_b32 vcc_lo, v138
	v_readfirstlane_b32 vcc_hi, v139
	s_sub_u32 s98, s98, 0x1000000
	s_subb_u32 s99, s99, 0
	s_sub_u32 vcc_lo, vcc_lo, 0x1000000
	s_subb_u32 vcc_hi, vcc_hi, 0
	v_subrev_u32_e32 v146, s98, v146
	v_subrev_u32_e32 v138, vcc_lo, v138
	v_subrev_u32_e32 v144, s98, v144
	v_subrev_u32_e32 v136, vcc_lo, v136
	v_subrev_u32_e32 v142, s98, v142
	v_subrev_u32_e32 v134, vcc_lo, v134
	v_subrev_u32_e32 v140, s98, v140
	v_subrev_u32_e32 v130, vcc_lo, v130
	s_mov_b32 m0, s101
	s_nop 0
	global_load_lds_dwordx4 v146, s[98:99]
	s_add_i32 m0, s101, 0x8000
	s_nop 0
	global_load_lds_dwordx4 v138, vcc
	s_add_i32 m0, s101, 0x2000
	s_nop 0
	global_load_lds_dwordx4 v144, s[98:99]
	s_add_i32 m0, s101, 0xa000
	s_nop 0
	global_load_lds_dwordx4 v136, vcc
	s_add_i32 m0, s101, 0x4000
	s_nop 0
	global_load_lds_dwordx4 v142, s[98:99]
	s_add_i32 m0, s101, 0xc000
	s_nop 0
	global_load_lds_dwordx4 v134, vcc
	s_add_i32 m0, s101, 0x6000
	s_nop 0
	global_load_lds_dwordx4 v140, s[98:99]
	s_add_i32 m0, s101, 0xe000
	s_nop 0
	global_load_lds_dwordx4 v130, vcc
.LBB0_942:
	s_and_b32 s17, s15, 0x10000
	s_xor_b32 s42, s17, 0x10000
	s_add_i32 s17, s17, 0
	s_add_i32 s101, s100, s42
	s_cmpk_eq_i32 s18, 0
	s_cbranch_scc1 .Lg1n_942
	s_waitcnt lgkmcnt(3)
	v_mfma_f32_16x16x32_bf16 v[108:111], v[178:181], v[162:165], v[108:111]
	v_mfma_f32_16x16x32_bf16 v[92:95], v[178:181], v[166:169], v[92:95]
	v_mfma_f32_16x16x32_bf16 v[76:79], v[178:181], v[170:173], v[76:79]
	v_mfma_f32_16x16x32_bf16 v[60:63], v[178:181], v[174:177], v[60:63]
	ds_read_b128 v[240:243], v197
	ds_read_b128 v[244:247], v198
	s_add_i32 m0, s101, 0x4000
	s_nop 0
	global_load_lds_dwordx4 v142, s[98:99]
	s_waitcnt lgkmcnt(4)
	v_mfma_f32_16x16x32_bf16 v[104:107], v[182:185], v[162:165], v[104:107]
	v_mfma_f32_16x16x32_bf16 v[88:91], v[182:185], v[166:169], v[88:91]
	v_mfma_f32_16x16x32_bf16 v[72:75], v[182:185], v[170:173], v[72:75]
	v_mfma_f32_16x16x32_bf16 v[56:59], v[182:185], v[174:177], v[56:59]
	ds_read_b128 v[248:251], v199
	ds_read_b128 v[252:255], v200
	s_add_i32 m0, s101, 0xc000
	s_nop 0
	global_load_lds_dwordx4 v134, vcc
	s_waitcnt lgkmcnt(5)
	v_mfma_f32_16x16x32_bf16 v[100:103], v[186:189], v[162:165], v[100:103]
	v_mfma_f32_16x16x32_bf16 v[84:87], v[186:189], v[166:169], v[84:87]
	v_mfma_f32_16x16x32_bf16 v[68:71], v[186:189], v[170:173], v[68:71]
	v_mfma_f32_16x16x32_bf16 v[52:55], v[186:189], v[174:177], v[52:55]
	s_add_i32 m0, s101, 0x6000
	s_nop 0
	global_load_lds_dwordx4 v140, s[98:99]
	s_waitcnt lgkmcnt(4)
	v_mfma_f32_16x16x32_bf16 v[96:99], v[190:193], v[162:165], v[96:99]
	v_mfma_f32_16x16x32_bf16 v[80:83], v[190:193], v[166:169], v[80:83]
	v_mfma_f32_16x16x32_bf16 v[64:67], v[190:193], v[170:173], v[64:67]
	v_mfma_f32_16x16x32_bf16 v[48:51], v[190:193], v[174:177], v[48:51]
	s_add_i32 m0, s101, 0xe000
	s_nop 0
	global_load_lds_dwordx4 v130, vcc
.Lg2_942:
	ds_read_b128 v[162:165], v161 offset:1024
	ds_read_b128 v[166:169], v194 offset:1024
	ds_read_b128 v[170:173], v195 offset:1024
	ds_read_b128 v[174:177], v196 offset:1024
	s_waitcnt lgkmcnt(4)
	v_mfma_f32_16x16x32_bf16 v[44:47], v[178:181], v[240:243], v[44:47]
	v_mfma_f32_16x16x32_bf16 v[28:31], v[178:181], v[244:247], v[28:31]
	v_mfma_f32_16x16x32_bf16 v[12:15], v[178:181], v[248:251], v[12:15]
	v_mfma_f32_16x16x32_bf16 v[112:115], v[178:181], v[252:255], v[112:115]
	ds_read_b128 v[178:181], v128 offset:33792
	v_mfma_f32_16x16x32_bf16 v[40:43], v[182:185], v[240:243], v[40:43]
	v_mfma_f32_16x16x32_bf16 v[24:27], v[182:185], v[244:247], v[24:27]
	v_mfma_f32_16x16x32_bf16 v[8:11], v[182:185], v[248:251], v[8:11]
	v_mfma_f32_16x16x32_bf16 v[116:119], v[182:185], v[252:255], v[116:119]
	ds_read_b128 v[182:185], v128 offset:35840
	v_mfma_f32_16x16x32_bf16 v[36:39], v[186:189], v[240:243], v[36:39]
	v_mfma_f32_16x16x32_bf16 v[20:23], v[186:189], v[244:247], v[20:23]
	v_mfma_f32_16x16x32_bf16 v[4:7], v[186:189], v[248:251], v[4:7]
	v_mfma_f32_16x16x32_bf16 v[120:123], v[186:189], v[252:255], v[120:123]
	ds_read_b128 v[186:189], v128 offset:37888
	v_mfma_f32_16x16x32_bf16 v[32:35], v[190:193], v[240:243], v[32:35]
	v_mfma_f32_16x16x32_bf16 v[16:19], v[190:193], v[244:247], v[16:19]
	v_mfma_f32_16x16x32_bf16 v[0:3], v[190:193], v[248:251], v[0:3]
	v_mfma_f32_16x16x32_bf16 v[124:127], v[190:193], v[252:255], v[124:127]
	ds_read_b128 v[190:193], v128 offset:39936
	s_waitcnt lgkmcnt(3)
	v_mfma_f32_16x16x32_bf16 v[108:111], v[178:181], v[162:165], v[108:111]
	v_mfma_f32_16x16x32_bf16 v[92:95], v[178:181], v[166:169], v[92:95]
	v_mfma_f32_16x16x32_bf16 v[76:79], v[178:181], v[170:173], v[76:79]
	v_mfma_f32_16x16x32_bf16 v[60:63], v[178:181], v[174:177], v[60:63]
	ds_read_b128 v[240:243], v197 offset:1024
	ds_read_b128 v[244:247], v198 offset:1024
	s_waitcnt lgkmcnt(4)
	v_mfma_f32_16x16x32_bf16 v[104:107], v[182:185], v[162:165], v[104:107]
	v_mfma_f32_16x16x32_bf16 v[88:91], v[182:185], v[166:169], v[88:91]
	v_mfma_f32_16x16x32_bf16 v[72:75], v[182:185], v[170:173], v[72:75]
	v_mfma_f32_16x16x32_bf16 v[56:59], v[182:185], v[174:177], v[56:59]
	ds_read_b128 v[248:251], v199 offset:1024
	ds_read_b128 v[252:255], v200 offset:1024
	s_waitcnt lgkmcnt(5)
	v_mfma_f32_16x16x32_bf16 v[100:103], v[186:189], v[162:165], v[100:103]
	v_mfma_f32_16x16x32_bf16 v[84:87], v[186:189], v[166:169], v[84:87]
	v_mfma_f32_16x16x32_bf16 v[68:71], v[186:189], v[170:173], v[68:71]
	v_mfma_f32_16x16x32_bf16 v[52:55], v[186:189], v[174:177], v[52:55]
	s_waitcnt lgkmcnt(4)
	v_mfma_f32_16x16x32_bf16 v[96:99], v[190:193], v[162:165], v[96:99]
	v_mfma_f32_16x16x32_bf16 v[80:83], v[190:193], v[166:169], v[80:83]
	v_mfma_f32_16x16x32_bf16 v[64:67], v[190:193], v[170:173], v[64:67]
	v_mfma_f32_16x16x32_bf16 v[48:51], v[190:193], v[174:177], v[48:51]
	s_waitcnt vmcnt(0) lgkmcnt(0)
	s_barrier
	s_add_i32 s101, s100, s17
	s_cmpk_eq_i32 s18, 0x700
	s_cbranch_scc1 .Lg4n_942
	s_add_u32 s98, s98, 0x80
	s_addc_u32 s99, s99, 0
	s_add_u32 vcc_lo, vcc_lo, 0x80
	s_addc_u32 vcc_hi, vcc_hi, 0
	v_mfma_f32_16x16x32_bf16 v[44:47], v[178:181], v[240:243], v[44:47]
	v_mfma_f32_16x16x32_bf16 v[28:31], v[178:181], v[244:247], v[28:31]
	v_mfma_f32_16x16x32_bf16 v[12:15], v[178:181], v[248:251], v[12:15]
	v_mfma_f32_16x16x32_bf16 v[112:115], v[178:181], v[252:255], v[112:115]
	v_add3_u32 v128, s42, v150, v151
	ds_read_b128 v[178:181], v128 offset:32768
	v_add3_u32 v161, s42, v150, v152
	v_add3_u32 v194, s42, v154, v153
	v_add3_u32 v195, s42, v154, v155
	v_add3_u32 v196, s42, v154, v156
	ds_read_b128 v[162:165], v161
	ds_read_b128 v[166:169], v194
	ds_read_b128 v[170:173], v195
	ds_read_b128 v[174:177], v196
	s_mov_b32 m0, s101
	s_nop 0
	global_load_lds_dwordx4 v146, s[98:99]
	v_mfma_f32_16x16x32_bf16 v[40:43], v[182:185], v[240:243], v[40:43]
	v_mfma_f32_16x16x32_bf16 v[24:27], v[182:185], v[244:247], v[24:27]
	v_mfma_f32_16x16x32_bf16 v[8:11], v[182:185], v[248:251], v[8:11]
	v_mfma_f32_16x16x32_bf16 v[116:119], v[182:185], v[252:255], v[116:119]
	ds_read_b128 v[182:185], v128 offset:34816
	v_add3_u32 v197, s42, v154, v157
	v_add3_u32 v198, s42, v154, v158
	v_add3_u32 v199, s42, v154, v159
	v_add3_u32 v200, s42, v154, v160
	s_add_i32 m0, s101, 0x8000
	s_nop 0
	global_load_lds_dwordx4 v138, vcc
	v_mfma_f32_16x16x32_bf16 v[36:39], v[186:189], v[240:243], v[36:39]
	v_mfma_f32_16x16x32_bf16 v[20:23], v[186:189], v[244:247], v[20:23]
	v_mfma_f32_16x16x32_bf16 v[4:7], v[186:189], v[248:251], v[4:7]
	v_mfma_f32_16x16x32_bf16 v[120:123], v[186:189], v[252:255], v[120:123]
	ds_read_b128 v[186:189], v128 offset:36864
	s_add_i32 m0, s101, 0x2000
	s_nop 0
	global_load_lds_dwordx4 v144, s[98:99]
	v_mfma_f32_16x16x32_bf16 v[32:35], v[190:193], v[240:243], v[32:35]
	v_mfma_f32_16x16x32_bf16 v[16:19], v[190:193], v[244:247], v[16:19]
	v_mfma_f32_16x16x32_bf16 v[0:3], v[190:193], v[248:251], v[0:3]
	v_mfma_f32_16x16x32_bf16 v[124:127], v[190:193], v[252:255], v[124:127]
	ds_read_b128 v[190:193], v128 offset:38912
	s_add_i32 m0, s101, 0xa000
	s_nop 0
	global_load_lds_dwordx4 v136, vcc

.Lex_942:
	s_mov_b32 s101, 0
	s_cmpk_lg_i32 s40, 0x100
	s_cbranch_scc1 .Lnxn_942
	s_add_i32 m0, s39, s40
	s_cmpk_gt_i32 m0, 0x5ff
	s_cbranch_scc1 .Lnxn_942
	s_mul_hi_u32 m0, s39, 0x2aaaaaab
	s_lshr_b32 m0, m0, 5
	s_mul_i32 m0, m0, 0xc0
	s_sub_i32 m0, s39, m0
	s_lshr_b32 m0, m0, 4
	s_cmpk_lg_u32 m0, 0
	s_cbranch_scc1 .Lnxj_942_0
	s_add_u32 vcc_lo, vcc_lo, 0x1ff880
	s_addc_u32 vcc_hi, vcc_hi, 0
	s_add_u32 s98, s98, 0x7ff880
	s_addc_u32 s99, s99, 0
	s_mov_b32 m0, 0xffff
.Lnxj_942_0:
	s_cmpk_lg_u32 m0, 1
	s_cbranch_scc1 .Lnxj_942_1
	s_add_u32 vcc_lo, vcc_lo, 0x1ff880
	s_addc_u32 vcc_hi, vcc_hi, 0
	s_add_u32 s98, s98, 0x7ff880
	s_addc_u32 s99, s99, 0
	s_mov_b32 m0, 0xffff
.Lnxj_942_1:
	s_cmpk_lg_u32 m0, 2
	s_cbranch_scc1 .Lnxj_942_2
	s_add_u32 vcc_lo, vcc_lo, 0x47f880
	s_addc_u32 vcc_hi, vcc_hi, 0
	s_add_u32 s98, s98, 0x7ff880
	s_addc_u32 s99, s99, 0
	s_mov_b32 m0, 0xffff
.Lnxj_942_2:
	s_cmpk_lg_u32 m0, 3
	s_cbranch_scc1 .Lnxj_942_3
	s_add_u32 vcc_lo, vcc_lo, 0x47f880
	s_addc_u32 vcc_hi, vcc_hi, 0
	s_add_u32 s98, s98, 0x7ff880
	s_addc_u32 s99, s99, 0
	s_mov_b32 m0, 0xffff
.Lnxj_942_3:
	s_cmpk_lg_u32 m0, 4
	s_cbranch_scc1 .Lnxj_942_4
	s_add_u32 vcc_lo, vcc_lo, 0x47f880
	s_addc_u32 vcc_hi, vcc_hi, 0
	s_add_u32 s98, s98, 0x7ff880
	s_addc_u32 s99, s99, 0
	s_mov_b32 m0, 0xffff
.Lnxj_942_4:
	s_cmpk_lg_u32 m0, 5
	s_cbranch_scc1 .Lnxj_942_5
	s_add_u32 vcc_lo, vcc_lo, 0x47f880
	s_addc_u32 vcc_hi, vcc_hi, 0
	s_add_u32 s98, s98, 0x7ff880
	s_addc_u32 s99, s99, 0
	s_mov_b32 m0, 0xffff
.Lnxj_942_5:
	s_cmpk_lg_u32 m0, 6
	s_cbranch_scc1 .Lnxj_942_6
	s_add_u32 vcc_lo, vcc_lo, 0x1ff880
	s_addc_u32 vcc_hi, vcc_hi, 0
	s_add_u32 s98, s98, 0x7ff880
	s_addc_u32 s99, s99, 0
	s_mov_b32 m0, 0xffff
.Lnxj_942_6:
	s_cmpk_lg_u32 m0, 7
	s_cbranch_scc1 .Lnxj_942_7
	s_add_u32 vcc_lo, vcc_lo, 0x1ff880
	s_addc_u32 vcc_hi, vcc_hi, 0
	s_add_u32 s98, s98, 0x7ff880
	s_addc_u32 s99, s99, 0
	s_mov_b32 m0, 0xffff
.Lnxj_942_7:
	s_cmpk_lg_u32 m0, 8
	s_cbranch_scc1 .Lnxj_942_8
	s_add_u32 vcc_lo, vcc_lo, 0xff97f880
	s_addc_u32 vcc_hi, vcc_hi, -1
	s_add_u32 s98, s98, 0xfff880
	s_addc_u32 s99, s99, 0
	s_mov_b32 m0, 0xffff
.Lnxj_942_8:
	s_cmpk_lg_u32 m0, 9
	s_cbranch_scc1 .Lnxj_942_9
	s_add_u32 vcc_lo, vcc_lo, 0xff97f880
	s_addc_u32 vcc_hi, vcc_hi, -1
	s_add_u32 s98, s98, 0xfff880
	s_addc_u32 s99, s99, 0
	s_mov_b32 m0, 0xffff
.Lnxj_942_9:
	s_cmpk_lg_u32 m0, 10
	s_cbranch_scc1 .Lnxj_942_10
	s_add_u32 vcc_lo, vcc_lo, 0xff97f880
	s_addc_u32 vcc_hi, vcc_hi, -1
	s_add_u32 s98, s98, 0xfff880
	s_addc_u32 s99, s99, 0
	s_mov_b32 m0, 0xffff
.Lnxj_942_10:
	s_cmpk_lg_u32 m0, 11
	s_cbranch_scc1 .Lnxj_942_11
	s_add_u32 vcc_lo, vcc_lo, 0xff97f880
	s_addc_u32 vcc_hi, vcc_hi, -1
	s_add_u32 s98, s98, 0xfff880
	s_addc_u32 s99, s99, 0
	s_mov_b32 m0, 0xffff
.Lnxj_942_11:
	s_mov_b32 m0, s100
	s_nop 0
	global_load_lds_dwordx4 v146, s[98:99]
	s_add_i32 m0, s100, 0x8000
	s_nop 0
	global_load_lds_dwordx4 v138, vcc
	s_add_i32 m0, s100, 0x2000
	s_nop 0
	global_load_lds_dwordx4 v144, s[98:99]
	s_add_i32 m0, s100, 0xa000
	s_nop 0
	global_load_lds_dwordx4 v136, vcc
	s_add_i32 m0, s100, 0x4000
	s_nop 0
	global_load_lds_dwordx4 v142, s[98:99]
	s_add_i32 m0, s100, 0xc000
	s_nop 0
	global_load_lds_dwordx4 v134, vcc
	s_add_i32 m0, s100, 0x6000
	s_nop 0
	global_load_lds_dwordx4 v140, s[98:99]
	s_add_i32 m0, s100, 0xe000
	s_nop 0
	global_load_lds_dwordx4 v130, vcc
	s_mov_b32 s101, 1
.Lnxn_942:
	s_waitcnt lgkmcnt(0)
	s_waitcnt lgkmcnt(3)
	v_mfma_f32_16x16x32_bf16 v[108:111], v[178:181], v[162:165], v[108:111]
	v_mfma_f32_16x16x32_bf16 v[92:95], v[178:181], v[166:169], v[92:95]
	v_mfma_f32_16x16x32_bf16 v[76:79], v[178:181], v[170:173], v[76:79]
	v_mfma_f32_16x16x32_bf16 v[60:63], v[178:181], v[174:177], v[60:63]
	ds_read_b128 v[240:243], v197
	ds_read_b128 v[244:247], v198
	s_waitcnt lgkmcnt(4)
	v_mfma_f32_16x16x32_bf16 v[104:107], v[182:185], v[162:165], v[104:107]
	v_mfma_f32_16x16x32_bf16 v[88:91], v[182:185], v[166:169], v[88:91]
	v_mfma_f32_16x16x32_bf16 v[72:75], v[182:185], v[170:173], v[72:75]
	v_mfma_f32_16x16x32_bf16 v[56:59], v[182:185], v[174:177], v[56:59]
	ds_read_b128 v[248:251], v199
	ds_read_b128 v[252:255], v200
	s_waitcnt lgkmcnt(5)
	v_mfma_f32_16x16x32_bf16 v[100:103], v[186:189], v[162:165], v[100:103]
	v_mfma_f32_16x16x32_bf16 v[84:87], v[186:189], v[166:169], v[84:87]
	v_mfma_f32_16x16x32_bf16 v[68:71], v[186:189], v[170:173], v[68:71]
	v_mfma_f32_16x16x32_bf16 v[52:55], v[186:189], v[174:177], v[52:55]
	s_waitcnt lgkmcnt(4)
	v_mfma_f32_16x16x32_bf16 v[96:99], v[190:193], v[162:165], v[96:99]
	v_mfma_f32_16x16x32_bf16 v[80:83], v[190:193], v[166:169], v[80:83]
	v_mfma_f32_16x16x32_bf16 v[64:67], v[190:193], v[170:173], v[64:67]
	v_mfma_f32_16x16x32_bf16 v[48:51], v[190:193], v[174:177], v[48:51]
	ds_read_b128 v[162:165], v161 offset:1024
	ds_read_b128 v[166:169], v194 offset:1024
	ds_read_b128 v[170:173], v195 offset:1024
	ds_read_b128 v[174:177], v196 offset:1024
	s_waitcnt lgkmcnt(4)
	v_mfma_f32_16x16x32_bf16 v[44:47], v[178:181], v[240:243], v[44:47]
	v_mfma_f32_16x16x32_bf16 v[28:31], v[178:181], v[244:247], v[28:31]
	v_mfma_f32_16x16x32_bf16 v[12:15], v[178:181], v[248:251], v[12:15]
	v_mfma_f32_16x16x32_bf16 v[112:115], v[178:181], v[252:255], v[112:115]
	ds_read_b128 v[178:181], v128 offset:33792
	v_mfma_f32_16x16x32_bf16 v[40:43], v[182:185], v[240:243], v[40:43]
	v_mfma_f32_16x16x32_bf16 v[24:27], v[182:185], v[244:247], v[24:27]
	v_mfma_f32_16x16x32_bf16 v[8:11], v[182:185], v[248:251], v[8:11]
	v_mfma_f32_16x16x32_bf16 v[116:119], v[182:185], v[252:255], v[116:119]
	ds_read_b128 v[182:185], v128 offset:35840
	v_mfma_f32_16x16x32_bf16 v[36:39], v[186:189], v[240:243], v[36:39]
	v_mfma_f32_16x16x32_bf16 v[20:23], v[186:189], v[244:247], v[20:23]
	v_mfma_f32_16x16x32_bf16 v[4:7], v[186:189], v[248:251], v[4:7]
	v_mfma_f32_16x16x32_bf16 v[120:123], v[186:189], v[252:255], v[120:123]
	ds_read_b128 v[186:189], v128 offset:37888
	v_mfma_f32_16x16x32_bf16 v[32:35], v[190:193], v[240:243], v[32:35]
	v_mfma_f32_16x16x32_bf16 v[16:19], v[190:193], v[244:247], v[16:19]
	v_mfma_f32_16x16x32_bf16 v[0:3], v[190:193], v[248:251], v[0:3]
	v_mfma_f32_16x16x32_bf16 v[124:127], v[190:193], v[252:255], v[124:127]
	ds_read_b128 v[190:193], v128 offset:39936
	s_waitcnt lgkmcnt(3)
	v_mfma_f32_16x16x32_bf16 v[108:111], v[178:181], v[162:165], v[108:111]
	v_mfma_f32_16x16x32_bf16 v[92:95], v[178:181], v[166:169], v[92:95]
	v_mfma_f32_16x16x32_bf16 v[76:79], v[178:181], v[170:173], v[76:79]
	v_mfma_f32_16x16x32_bf16 v[60:63], v[178:181], v[174:177], v[60:63]
	ds_read_b128 v[240:243], v197 offset:1024
	ds_read_b128 v[244:247], v198 offset:1024
	s_waitcnt lgkmcnt(4)
	v_mfma_f32_16x16x32_bf16 v[104:107], v[182:185], v[162:165], v[104:107]
	v_mfma_f32_16x16x32_bf16 v[88:91], v[182:185], v[166:169], v[88:91]
	v_mfma_f32_16x16x32_bf16 v[72:75], v[182:185], v[170:173], v[72:75]
	v_mfma_f32_16x16x32_bf16 v[56:59], v[182:185], v[174:177], v[56:59]
	ds_read_b128 v[248:251], v199 offset:1024
	ds_read_b128 v[252:255], v200 offset:1024
	s_waitcnt lgkmcnt(5)
	v_mfma_f32_16x16x32_bf16 v[100:103], v[186:189], v[162:165], v[100:103]
	v_mfma_f32_16x16x32_bf16 v[84:87], v[186:189], v[166:169], v[84:87]
	v_mfma_f32_16x16x32_bf16 v[68:71], v[186:189], v[170:173], v[68:71]
	v_mfma_f32_16x16x32_bf16 v[52:55], v[186:189], v[174:177], v[52:55]
	s_waitcnt lgkmcnt(4)
	v_mfma_f32_16x16x32_bf16 v[96:99], v[190:193], v[162:165], v[96:99]
	v_mfma_f32_16x16x32_bf16 v[80:83], v[190:193], v[166:169], v[80:83]
	v_mfma_f32_16x16x32_bf16 v[64:67], v[190:193], v[170:173], v[64:67]
	v_mfma_f32_16x16x32_bf16 v[48:51], v[190:193], v[174:177], v[48:51]
	s_waitcnt lgkmcnt(0)
	v_mfma_f32_16x16x32_bf16 v[44:47], v[178:181], v[240:243], v[44:47]
	v_mfma_f32_16x16x32_bf16 v[28:31], v[178:181], v[244:247], v[28:31]
	v_mfma_f32_16x16x32_bf16 v[12:15], v[178:181], v[248:251], v[12:15]
	v_mfma_f32_16x16x32_bf16 v[112:115], v[178:181], v[252:255], v[112:115]
	v_mfma_f32_16x16x32_bf16 v[40:43], v[182:185], v[240:243], v[40:43]
	v_mfma_f32_16x16x32_bf16 v[24:27], v[182:185], v[244:247], v[24:27]
	v_mfma_f32_16x16x32_bf16 v[8:11], v[182:185], v[248:251], v[8:11]
	v_mfma_f32_16x16x32_bf16 v[116:119], v[182:185], v[252:255], v[116:119]
	v_mfma_f32_16x16x32_bf16 v[36:39], v[186:189], v[240:243], v[36:39]
	v_mfma_f32_16x16x32_bf16 v[20:23], v[186:189], v[244:247], v[20:23]
	v_mfma_f32_16x16x32_bf16 v[4:7], v[186:189], v[248:251], v[4:7]
	v_mfma_f32_16x16x32_bf16 v[120:123], v[186:189], v[252:255], v[120:123]
	v_mfma_f32_16x16x32_bf16 v[32:35], v[190:193], v[240:243], v[32:35]
	v_mfma_f32_16x16x32_bf16 v[16:19], v[190:193], v[244:247], v[16:19]
	v_mfma_f32_16x16x32_bf16 v[0:3], v[190:193], v[248:251], v[0:3]
	v_mfma_f32_16x16x32_bf16 v[124:127], v[190:193], v[252:255], v[124:127]
	v_mov_b32_e32 v128, s3
	s_waitcnt vmcnt(8)
	s_barrier
	ds_read_b64 v[130:131], v128
	v_ashrrev_i32_e32 v128, 1, v148
	v_and_b32_e32 v128, 0xffffff80, v128
	v_add_u32_e32 v128, s16, v128
	s_ashr_i32 s15, s14, 31
	s_waitcnt lgkmcnt(0)
	v_mad_i64_i32 v[130:131], s[16:17], v128, s23, v[130:131]
	v_and_b32_e32 v128, 0xc0, v148
	v_lshrrev_b32_e32 v135, 6, v148
	v_lshl_add_u64 v[130:131], s[14:15], 1, v[130:131]
	v_lshlrev_b32_e32 v128, 1, v128
	v_lshl_add_u64 v[130:131], v[130:131], 0, v[128:129]
	v_mul_lo_u32 v128, v135, s27
	v_add_u32_e32 v135, s24, v128
	v_lshrrev_b32_e32 v128, 1, v148
	v_and_b32_e32 v136, 24, v128
	v_lshlrev_b32_e32 v128, 4, v148
	v_bfe_u32 v137, v148, 3, 3
	v_and_b32_e32 v134, 15, v148
	v_and_b32_e32 v128, 0x70, v128
	v_mul_u32_u24_e32 v138, 0x90, v137
	v_lshl_add_u64 v[130:131], v[130:131], 0, v[128:129]
	v_add3_u32 v138, v135, v128, v138
	v_mul_u32_u24_e32 v128, 0x90, v134
	v_add3_u32 v134, v135, v136, v128
	v_cvt_pk_bf16_f32 v108, v108, v109
	v_cvt_pk_bf16_f32 v109, v110, v111
	v_cvt_pk_bf16_f32 v104, v104, v105
	v_cvt_pk_bf16_f32 v105, v106, v107
	v_cvt_pk_bf16_f32 v100, v100, v101
	v_cvt_pk_bf16_f32 v101, v102, v103
	v_cvt_pk_bf16_f32 v96, v96, v97
	v_cvt_pk_bf16_f32 v97, v98, v99
	v_cvt_pk_bf16_f32 v92, v92, v93
	v_cvt_pk_bf16_f32 v93, v94, v95
	v_cvt_pk_bf16_f32 v88, v88, v89
	v_cvt_pk_bf16_f32 v89, v90, v91
	v_cvt_pk_bf16_f32 v84, v84, v85
	v_cvt_pk_bf16_f32 v85, v86, v87
	v_cvt_pk_bf16_f32 v80, v80, v81
	v_cvt_pk_bf16_f32 v81, v82, v83
	v_cvt_pk_bf16_f32 v76, v76, v77
	v_cvt_pk_bf16_f32 v77, v78, v79
	v_cvt_pk_bf16_f32 v72, v72, v73
	v_cvt_pk_bf16_f32 v73, v74, v75
	v_cvt_pk_bf16_f32 v68, v68, v69
	v_cvt_pk_bf16_f32 v69, v70, v71
	v_cvt_pk_bf16_f32 v64, v64, v65
	v_cvt_pk_bf16_f32 v65, v66, v67
	v_cvt_pk_bf16_f32 v60, v60, v61
	v_cvt_pk_bf16_f32 v61, v62, v63
	v_cvt_pk_bf16_f32 v56, v56, v57
	v_cvt_pk_bf16_f32 v57, v58, v59
	v_cvt_pk_bf16_f32 v52, v52, v53
	v_cvt_pk_bf16_f32 v53, v54, v55
	v_cvt_pk_bf16_f32 v48, v48, v49
	v_cvt_pk_bf16_f32 v49, v50, v51
	ds_write_b64 v134, v[108:109]
	ds_write_b64 v134, v[104:105] offset:32
	ds_write_b64 v134, v[100:101] offset:64
	ds_write_b64 v134, v[96:97] offset:96
	ds_write_b64 v134, v[92:93] offset:2304
	ds_write_b64 v134, v[88:89] offset:2336
	ds_write_b64 v134, v[84:85] offset:2368
	ds_write_b64 v134, v[80:81] offset:2400
	ds_write_b64 v134, v[76:77] offset:4608
	ds_write_b64 v134, v[72:73] offset:4640
	ds_write_b64 v134, v[68:69] offset:4672
	ds_write_b64 v134, v[64:65] offset:4704
	ds_write_b64 v134, v[60:61] offset:6912
	ds_write_b64 v134, v[56:57] offset:6944
	ds_write_b64 v134, v[52:53] offset:6976
	ds_write_b64 v134, v[48:49] offset:7008
	ds_read_b128 v[48:51], v138
	v_mul_u32_u24_e32 v54, 0xc00, v137
	v_lshl_add_u64 v[52:53], v[130:131], 0, s[12:13]
	v_lshlrev_b32_e32 v128, 1, v54
	v_lshl_add_u64 v[54:55], v[52:53], 0, v[128:129]
	s_waitcnt lgkmcnt(0)
	global_store_dwordx4 v[54:55], v[48:51], off nt
	ds_read_b128 v[48:51], v138 offset:1152
	v_add_co_u32_e32 v56, vcc, s21, v54
	v_cvt_pk_bf16_f32 v0, v0, v1
	s_nop 0
	v_addc_co_u32_e32 v57, vcc, 0, v55, vcc
	s_waitcnt lgkmcnt(0)
	global_store_dwordx4 v[56:57], v[48:51], off nt
	ds_read_b128 v[48:51], v138 offset:2304
	v_add_co_u32_e32 v56, vcc, s25, v54
	v_cvt_pk_bf16_f32 v1, v2, v3
	s_nop 0
	v_addc_co_u32_e32 v57, vcc, 0, v55, vcc
	s_waitcnt lgkmcnt(0)
	global_store_dwordx4 v[56:57], v[48:51], off nt
	ds_read_b128 v[48:51], v138 offset:3456
	v_add_co_u32_e32 v56, vcc, s28, v54
	v_cvt_pk_bf16_f32 v44, v44, v45
	s_nop 0
	v_addc_co_u32_e32 v57, vcc, 0, v55, vcc
	s_waitcnt lgkmcnt(0)
	global_store_dwordx4 v[56:57], v[48:51], off nt
	ds_read_b128 v[48:51], v138 offset:4608
	v_or_b32_e32 v56, 0x30000, v128
	v_mov_b32_e32 v57, v129
	v_lshl_add_u64 v[56:57], v[52:53], 0, v[56:57]
	v_cvt_pk_bf16_f32 v45, v46, v47
	s_waitcnt lgkmcnt(0)
	global_store_dwordx4 v[56:57], v[48:51], off nt
	ds_read_b128 v[48:51], v138 offset:5760
	v_add_u32_e32 v56, 0x3c000, v128
	v_mov_b32_e32 v57, v129
	v_lshl_add_u64 v[56:57], v[52:53], 0, v[56:57]
	v_cvt_pk_bf16_f32 v40, v40, v41
	s_waitcnt lgkmcnt(0)
	global_store_dwordx4 v[56:57], v[48:51], off nt
	ds_read_b128 v[48:51], v138 offset:6912
	v_add_u32_e32 v56, 0x48000, v128
	v_mov_b32_e32 v57, v129
	v_lshl_add_u64 v[56:57], v[52:53], 0, v[56:57]
	v_add_u32_e32 v128, 0x54000, v128
	s_waitcnt lgkmcnt(0)
	global_store_dwordx4 v[56:57], v[48:51], off nt
	ds_read_b128 v[48:51], v138 offset:8064
	v_lshl_add_u64 v[52:53], v[52:53], 0, v[128:129]
	v_cvt_pk_bf16_f32 v41, v42, v43
	v_cvt_pk_bf16_f32 v36, v36, v37
	v_cvt_pk_bf16_f32 v37, v38, v39
	s_waitcnt lgkmcnt(0)
	global_store_dwordx4 v[52:53], v[48:51], off nt
	ds_write_b64 v134, v[0:1] offset:4704
	v_cvt_pk_bf16_f32 v0, v112, v113
	v_cvt_pk_bf16_f32 v1, v114, v115
	ds_write_b64 v134, v[0:1] offset:6912
	v_cvt_pk_bf16_f32 v0, v116, v117
	v_cvt_pk_bf16_f32 v1, v118, v119
	ds_write_b64 v134, v[0:1] offset:6944
	v_cvt_pk_bf16_f32 v0, v120, v121
	v_cvt_pk_bf16_f32 v1, v122, v123
	v_cvt_pk_bf16_f32 v32, v32, v33
	v_cvt_pk_bf16_f32 v33, v34, v35
	v_cvt_pk_bf16_f32 v28, v28, v29
	v_cvt_pk_bf16_f32 v29, v30, v31
	v_cvt_pk_bf16_f32 v24, v24, v25
	v_cvt_pk_bf16_f32 v25, v26, v27
	v_cvt_pk_bf16_f32 v20, v20, v21
	v_cvt_pk_bf16_f32 v21, v22, v23
	v_cvt_pk_bf16_f32 v16, v16, v17
	v_cvt_pk_bf16_f32 v17, v18, v19
	v_cvt_pk_bf16_f32 v12, v12, v13
	v_cvt_pk_bf16_f32 v13, v14, v15
	v_cvt_pk_bf16_f32 v8, v8, v9
	v_cvt_pk_bf16_f32 v9, v10, v11
	v_cvt_pk_bf16_f32 v4, v4, v5
	v_cvt_pk_bf16_f32 v5, v6, v7
	ds_write_b64 v134, v[0:1] offset:6976
	v_cvt_pk_bf16_f32 v0, v124, v125
	v_cvt_pk_bf16_f32 v1, v126, v127
	ds_write_b64 v134, v[44:45]
	ds_write_b64 v134, v[40:41] offset:32
	ds_write_b64 v134, v[36:37] offset:64
	ds_write_b64 v134, v[32:33] offset:96
	ds_write_b64 v134, v[28:29] offset:2304
	ds_write_b64 v134, v[24:25] offset:2336
	ds_write_b64 v134, v[20:21] offset:2368
	ds_write_b64 v134, v[16:17] offset:2400
	ds_write_b64 v134, v[12:13] offset:4608
	ds_write_b64 v134, v[8:9] offset:4640
	ds_write_b64 v134, v[4:5] offset:4672
	ds_write_b64 v134, v[0:1] offset:7008
	ds_read_b128 v[0:3], v138
	v_add_co_u32_e32 v4, vcc, s29, v54
	s_add_i32 s39, s39, s40
	s_nop 0
	v_addc_co_u32_e32 v5, vcc, 0, v55, vcc
	s_waitcnt lgkmcnt(0)
	global_store_dwordx4 v[4:5], v[0:3], off nt
	ds_read_b128 v[0:3], v138 offset:1152
	v_add_co_u32_e32 v4, vcc, s30, v54
	s_cmpk_gt_i32 s39, 0x5ff
	s_nop 0
	v_addc_co_u32_e32 v5, vcc, 0, v55, vcc
	s_waitcnt lgkmcnt(0)
	global_store_dwordx4 v[4:5], v[0:3], off nt
	ds_read_b128 v[0:3], v138 offset:2304
	v_add_co_u32_e32 v4, vcc, s31, v54
	s_nop 1
	v_addc_co_u32_e32 v5, vcc, 0, v55, vcc
	s_waitcnt lgkmcnt(0)
	global_store_dwordx4 v[4:5], v[0:3], off nt
	ds_read_b128 v[0:3], v138 offset:3456
	v_add_co_u32_e32 v4, vcc, s34, v54
	s_nop 1
	v_addc_co_u32_e32 v5, vcc, 0, v55, vcc
	s_waitcnt lgkmcnt(0)
	global_store_dwordx4 v[4:5], v[0:3], off nt
	ds_read_b128 v[0:3], v138 offset:4608
	v_add_co_u32_e32 v4, vcc, s35, v54
	s_nop 1
	v_addc_co_u32_e32 v5, vcc, 0, v55, vcc
	s_waitcnt lgkmcnt(0)
	global_store_dwordx4 v[4:5], v[0:3], off nt
	ds_read_b128 v[0:3], v138 offset:5760
	v_add_co_u32_e32 v4, vcc, s38, v54
	s_nop 1
	v_addc_co_u32_e32 v5, vcc, 0, v55, vcc
	s_waitcnt lgkmcnt(0)
	global_store_dwordx4 v[4:5], v[0:3], off nt
	ds_read_b128 v[0:3], v138 offset:6912
	v_add_co_u32_e32 v4, vcc, 0xa8000, v54
	s_nop 1
	v_addc_co_u32_e32 v5, vcc, 0, v55, vcc
	s_waitcnt lgkmcnt(0)
	global_store_dwordx4 v[4:5], v[0:3], off nt
	ds_read_b128 v[0:3], v138 offset:8064
	v_add_co_u32_e32 v4, vcc, 0xb4000, v54
	s_nop 1
	v_addc_co_u32_e32 v5, vcc, 0, v55, vcc
	s_waitcnt lgkmcnt(0)
	global_store_dwordx4 v[4:5], v[0:3], off nt
	s_cbranch_scc0 .LBB0_941

.Lnxw_1040:
	s_waitcnt vmcnt(16) lgkmcnt(0)
	s_barrier
	v_readfirstlane_b32 s100, v149
	s_and_b32 s17, s15, 0x10000
	s_xor_b32 s43, s17, 0x10000
	s_add_i32 s17, s17, 0
	v_add3_u32 v128, s17, v150, v151
	v_add3_u32 v161, s17, v150, v152
	v_add3_u32 v194, s17, v154, v153
	v_add3_u32 v195, s17, v154, v155
	v_add3_u32 v196, s17, v154, v156
	v_add3_u32 v197, s17, v154, v157
	v_add3_u32 v198, s17, v154, v158
	v_add3_u32 v199, s17, v154, v159
	v_add3_u32 v200, s17, v154, v160
	ds_read_b128 v[178:181], v128 offset:32768
	ds_read_b128 v[162:165], v161
	ds_read_b128 v[166:169], v194
	ds_read_b128 v[170:173], v195
	ds_read_b128 v[174:177], v196
	ds_read_b128 v[182:185], v128 offset:34816
	ds_read_b128 v[186:189], v128 offset:36864
	ds_read_b128 v[190:193], v128 offset:38912
	s_add_i32 s101, s100, s43
	v_readfirstlane_b32 s98, v146
	v_readfirstlane_b32 s99, v147
	v_readfirstlane_b32 vcc_lo, v138
	v_readfirstlane_b32 vcc_hi, v139
	s_sub_u32 s98, s98, 0x1000000
	s_subb_u32 s99, s99, 0
	s_sub_u32 vcc_lo, vcc_lo, 0x1000000
	s_subb_u32 vcc_hi, vcc_hi, 0
	v_subrev_u32_e32 v146, s98, v146
	v_subrev_u32_e32 v138, vcc_lo, v138
	v_subrev_u32_e32 v144, s98, v144
	v_subrev_u32_e32 v136, vcc_lo, v136
	v_subrev_u32_e32 v142, s98, v142
	v_subrev_u32_e32 v134, vcc_lo, v134
	v_subrev_u32_e32 v140, s98, v140
	v_subrev_u32_e32 v130, vcc_lo, v130
	s_mov_b32 m0, s101
	s_nop 0
	global_load_lds_dwordx4 v146, s[98:99]
	s_add_i32 m0, s101, 0x8000
	s_nop 0
	global_load_lds_dwordx4 v138, vcc
	s_add_i32 m0, s101, 0x2000
	s_nop 0
	global_load_lds_dwordx4 v144, s[98:99]
	s_add_i32 m0, s101, 0xa000
	s_nop 0
	global_load_lds_dwordx4 v136, vcc
	s_add_i32 m0, s101, 0x4000
	s_nop 0
	global_load_lds_dwordx4 v142, s[98:99]
	s_add_i32 m0, s101, 0xc000
	s_nop 0
	global_load_lds_dwordx4 v134, vcc
	s_add_i32 m0, s101, 0x6000
	s_nop 0
	global_load_lds_dwordx4 v140, s[98:99]
	s_add_i32 m0, s101, 0xe000
	s_nop 0
	global_load_lds_dwordx4 v130, vcc
.LBB0_1040:
	s_and_b32 s17, s15, 0x10000
	s_xor_b32 s43, s17, 0x10000
	s_add_i32 s17, s17, 0
	s_add_i32 s101, s100, s43
	s_cmpk_eq_i32 s18, 0
	s_cbranch_scc1 .Lg1n_1040
	s_waitcnt lgkmcnt(3)
	v_mfma_f32_16x16x32_bf16 v[108:111], v[178:181], v[162:165], v[108:111]
	v_mfma_f32_16x16x32_bf16 v[92:95], v[178:181], v[166:169], v[92:95]
	v_mfma_f32_16x16x32_bf16 v[76:79], v[178:181], v[170:173], v[76:79]
	v_mfma_f32_16x16x32_bf16 v[60:63], v[178:181], v[174:177], v[60:63]
	ds_read_b128 v[240:243], v197
	ds_read_b128 v[244:247], v198
	s_add_i32 m0, s101, 0x4000
	s_nop 0
	global_load_lds_dwordx4 v142, s[98:99]
	s_waitcnt lgkmcnt(4)
	v_mfma_f32_16x16x32_bf16 v[104:107], v[182:185], v[162:165], v[104:107]
	v_mfma_f32_16x16x32_bf16 v[88:91], v[182:185], v[166:169], v[88:91]
	v_mfma_f32_16x16x32_bf16 v[72:75], v[182:185], v[170:173], v[72:75]
	v_mfma_f32_16x16x32_bf16 v[56:59], v[182:185], v[174:177], v[56:59]
	ds_read_b128 v[248:251], v199
	ds_read_b128 v[252:255], v200
	s_add_i32 m0, s101, 0xc000
	s_nop 0
	global_load_lds_dwordx4 v134, vcc
	s_waitcnt lgkmcnt(5)
	v_mfma_f32_16x16x32_bf16 v[100:103], v[186:189], v[162:165], v[100:103]
	v_mfma_f32_16x16x32_bf16 v[84:87], v[186:189], v[166:169], v[84:87]
	v_mfma_f32_16x16x32_bf16 v[68:71], v[186:189], v[170:173], v[68:71]
	v_mfma_f32_16x16x32_bf16 v[52:55], v[186:189], v[174:177], v[52:55]
	s_add_i32 m0, s101, 0x6000
	s_nop 0
	global_load_lds_dwordx4 v140, s[98:99]
	s_waitcnt lgkmcnt(4)
	v_mfma_f32_16x16x32_bf16 v[96:99], v[190:193], v[162:165], v[96:99]
	v_mfma_f32_16x16x32_bf16 v[80:83], v[190:193], v[166:169], v[80:83]
	v_mfma_f32_16x16x32_bf16 v[64:67], v[190:193], v[170:173], v[64:67]
	v_mfma_f32_16x16x32_bf16 v[48:51], v[190:193], v[174:177], v[48:51]
	s_add_i32 m0, s101, 0xe000
	s_nop 0
	global_load_lds_dwordx4 v130, vcc
.Lg2_1040:
	ds_read_b128 v[162:165], v161 offset:1024
	ds_read_b128 v[166:169], v194 offset:1024
	ds_read_b128 v[170:173], v195 offset:1024
	ds_read_b128 v[174:177], v196 offset:1024
	s_waitcnt lgkmcnt(4)
	v_mfma_f32_16x16x32_bf16 v[44:47], v[178:181], v[240:243], v[44:47]
	v_mfma_f32_16x16x32_bf16 v[28:31], v[178:181], v[244:247], v[28:31]
	v_mfma_f32_16x16x32_bf16 v[12:15], v[178:181], v[248:251], v[12:15]
	v_mfma_f32_16x16x32_bf16 v[112:115], v[178:181], v[252:255], v[112:115]
	ds_read_b128 v[178:181], v128 offset:33792
	v_mfma_f32_16x16x32_bf16 v[40:43], v[182:185], v[240:243], v[40:43]
	v_mfma_f32_16x16x32_bf16 v[24:27], v[182:185], v[244:247], v[24:27]
	v_mfma_f32_16x16x32_bf16 v[8:11], v[182:185], v[248:251], v[8:11]
	v_mfma_f32_16x16x32_bf16 v[116:119], v[182:185], v[252:255], v[116:119]
	ds_read_b128 v[182:185], v128 offset:35840
	v_mfma_f32_16x16x32_bf16 v[36:39], v[186:189], v[240:243], v[36:39]
	v_mfma_f32_16x16x32_bf16 v[20:23], v[186:189], v[244:247], v[20:23]
	v_mfma_f32_16x16x32_bf16 v[4:7], v[186:189], v[248:251], v[4:7]
	v_mfma_f32_16x16x32_bf16 v[120:123], v[186:189], v[252:255], v[120:123]
	ds_read_b128 v[186:189], v128 offset:37888
	v_mfma_f32_16x16x32_bf16 v[32:35], v[190:193], v[240:243], v[32:35]
	v_mfma_f32_16x16x32_bf16 v[16:19], v[190:193], v[244:247], v[16:19]
	v_mfma_f32_16x16x32_bf16 v[0:3], v[190:193], v[248:251], v[0:3]
	v_mfma_f32_16x16x32_bf16 v[124:127], v[190:193], v[252:255], v[124:127]
	ds_read_b128 v[190:193], v128 offset:39936
	s_waitcnt lgkmcnt(3)
	v_mfma_f32_16x16x32_bf16 v[108:111], v[178:181], v[162:165], v[108:111]
	v_mfma_f32_16x16x32_bf16 v[92:95], v[178:181], v[166:169], v[92:95]
	v_mfma_f32_16x16x32_bf16 v[76:79], v[178:181], v[170:173], v[76:79]
	v_mfma_f32_16x16x32_bf16 v[60:63], v[178:181], v[174:177], v[60:63]
	ds_read_b128 v[240:243], v197 offset:1024
	ds_read_b128 v[244:247], v198 offset:1024
	s_waitcnt lgkmcnt(4)
	v_mfma_f32_16x16x32_bf16 v[104:107], v[182:185], v[162:165], v[104:107]
	v_mfma_f32_16x16x32_bf16 v[88:91], v[182:185], v[166:169], v[88:91]
	v_mfma_f32_16x16x32_bf16 v[72:75], v[182:185], v[170:173], v[72:75]
	v_mfma_f32_16x16x32_bf16 v[56:59], v[182:185], v[174:177], v[56:59]
	ds_read_b128 v[248:251], v199 offset:1024
	ds_read_b128 v[252:255], v200 offset:1024
	s_waitcnt lgkmcnt(5)
	v_mfma_f32_16x16x32_bf16 v[100:103], v[186:189], v[162:165], v[100:103]
	v_mfma_f32_16x16x32_bf16 v[84:87], v[186:189], v[166:169], v[84:87]
	v_mfma_f32_16x16x32_bf16 v[68:71], v[186:189], v[170:173], v[68:71]
	v_mfma_f32_16x16x32_bf16 v[52:55], v[186:189], v[174:177], v[52:55]
	s_waitcnt lgkmcnt(4)
	v_mfma_f32_16x16x32_bf16 v[96:99], v[190:193], v[162:165], v[96:99]
	v_mfma_f32_16x16x32_bf16 v[80:83], v[190:193], v[166:169], v[80:83]
	v_mfma_f32_16x16x32_bf16 v[64:67], v[190:193], v[170:173], v[64:67]
	v_mfma_f32_16x16x32_bf16 v[48:51], v[190:193], v[174:177], v[48:51]
	s_waitcnt vmcnt(0) lgkmcnt(0)
	s_barrier
	s_add_i32 s101, s100, s17
	s_cmpk_eq_i32 s18, 0x700
	s_cbranch_scc1 .Lg4n_1040
	s_add_u32 s98, s98, 0x80
	s_addc_u32 s99, s99, 0
	s_add_u32 vcc_lo, vcc_lo, 0x80
	s_addc_u32 vcc_hi, vcc_hi, 0
	v_mfma_f32_16x16x32_bf16 v[44:47], v[178:181], v[240:243], v[44:47]
	v_mfma_f32_16x16x32_bf16 v[28:31], v[178:181], v[244:247], v[28:31]
	v_mfma_f32_16x16x32_bf16 v[12:15], v[178:181], v[248:251], v[12:15]
	v_mfma_f32_16x16x32_bf16 v[112:115], v[178:181], v[252:255], v[112:115]
	v_add3_u32 v128, s43, v150, v151
	ds_read_b128 v[178:181], v128 offset:32768
	v_add3_u32 v161, s43, v150, v152
	v_add3_u32 v194, s43, v154, v153
	v_add3_u32 v195, s43, v154, v155
	v_add3_u32 v196, s43, v154, v156
	ds_read_b128 v[162:165], v161
	ds_read_b128 v[166:169], v194
	ds_read_b128 v[170:173], v195
	ds_read_b128 v[174:177], v196
	s_mov_b32 m0, s101
	s_nop 0
	global_load_lds_dwordx4 v146, s[98:99]
	v_mfma_f32_16x16x32_bf16 v[40:43], v[182:185], v[240:243], v[40:43]
	v_mfma_f32_16x16x32_bf16 v[24:27], v[182:185], v[244:247], v[24:27]
	v_mfma_f32_16x16x32_bf16 v[8:11], v[182:185], v[248:251], v[8:11]
	v_mfma_f32_16x16x32_bf16 v[116:119], v[182:185], v[252:255], v[116:119]
	ds_read_b128 v[182:185], v128 offset:34816
	v_add3_u32 v197, s43, v154, v157
	v_add3_u32 v198, s43, v154, v158
	v_add3_u32 v199, s43, v154, v159
	v_add3_u32 v200, s43, v154, v160
	s_add_i32 m0, s101, 0x8000
	s_nop 0
	global_load_lds_dwordx4 v138, vcc
	v_mfma_f32_16x16x32_bf16 v[36:39], v[186:189], v[240:243], v[36:39]
	v_mfma_f32_16x16x32_bf16 v[20:23], v[186:189], v[244:247], v[20:23]
	v_mfma_f32_16x16x32_bf16 v[4:7], v[186:189], v[248:251], v[4:7]
	v_mfma_f32_16x16x32_bf16 v[120:123], v[186:189], v[252:255], v[120:123]
	ds_read_b128 v[186:189], v128 offset:36864
	s_add_i32 m0, s101, 0x2000
	s_nop 0
	global_load_lds_dwordx4 v144, s[98:99]
	v_mfma_f32_16x16x32_bf16 v[32:35], v[190:193], v[240:243], v[32:35]
	v_mfma_f32_16x16x32_bf16 v[16:19], v[190:193], v[244:247], v[16:19]
	v_mfma_f32_16x16x32_bf16 v[0:3], v[190:193], v[248:251], v[0:3]
	v_mfma_f32_16x16x32_bf16 v[124:127], v[190:193], v[252:255], v[124:127]
	ds_read_b128 v[190:193], v128 offset:38912
	s_add_i32 m0, s101, 0xa000
	s_nop 0
	global_load_lds_dwordx4 v136, vcc

.Lex_1040:
	s_mov_b32 s101, 0
	s_cmpk_lg_i32 s40, 0x100
	s_cbranch_scc1 .Lnxn_1040
	s_add_i32 m0, s42, s40
	s_cmpk_gt_i32 m0, 0x4ff
	s_cbranch_scc1 .Lnxn_1040
	s_mul_hi_u32 m0, s42, 0x33333334
	s_lshr_b32 m0, m0, 5
	s_mul_i32 m0, m0, 0xa0
	s_sub_i32 m0, s42, m0
	s_lshr_b32 m0, m0, 4
	s_cmpk_lg_u32 m0, 0
	s_cbranch_scc1 .Lnxj_1040_0
	s_add_u32 vcc_lo, vcc_lo, 0x5ff880
	s_addc_u32 vcc_hi, vcc_hi, 0
	s_add_u32 s98, s98, 0x7ff880
	s_addc_u32 s99, s99, 0
	s_mov_b32 m0, 0xffff
.Lnxj_1040_0:
	s_cmpk_lg_u32 m0, 1
	s_cbranch_scc1 .Lnxj_1040_1
	s_add_u32 vcc_lo, vcc_lo, 0x5ff880
	s_addc_u32 vcc_hi, vcc_hi, 0
	s_add_u32 s98, s98, 0x7ff880
	s_addc_u32 s99, s99, 0
	s_mov_b32 m0, 0xffff
.Lnxj_1040_1:
	s_cmpk_lg_u32 m0, 2
	s_cbranch_scc1 .Lnxj_1040_2
	s_add_u32 vcc_lo, vcc_lo, 0x5ff880
	s_addc_u32 vcc_hi, vcc_hi, 0
	s_add_u32 s98, s98, 0x7ff880
	s_addc_u32 s99, s99, 0
	s_mov_b32 m0, 0xffff
.Lnxj_1040_2:
	s_cmpk_lg_u32 m0, 3
	s_cbranch_scc1 .Lnxj_1040_3
	s_add_u32 vcc_lo, vcc_lo, 0x5ff880
	s_addc_u32 vcc_hi, vcc_hi, 0
	s_add_u32 s98, s98, 0x7ff880
	s_addc_u32 s99, s99, 0
	s_mov_b32 m0, 0xffff
.Lnxj_1040_3:
	s_cmpk_lg_u32 m0, 4
	s_cbranch_scc1 .Lnxj_1040_4
	s_add_u32 vcc_lo, vcc_lo, 0xffdff880
	s_addc_u32 vcc_hi, vcc_hi, -1
	s_add_u32 s98, s98, 0xfff880
	s_addc_u32 s99, s99, 0
	s_mov_b32 m0, 0xffff
.Lnxj_1040_4:
	s_cmpk_lg_u32 m0, 5
	s_cbranch_scc1 .Lnxj_1040_5
	s_add_u32 vcc_lo, vcc_lo, 0xffaff880
	s_addc_u32 vcc_hi, vcc_hi, -1
	s_add_u32 s98, s98, 0xfff880
	s_addc_u32 s99, s99, 0
	s_mov_b32 m0, 0xffff
.Lnxj_1040_5:
	s_cmpk_lg_u32 m0, 6
	s_cbranch_scc1 .Lnxj_1040_6
	s_add_u32 vcc_lo, vcc_lo, 0xffaff880
	s_addc_u32 vcc_hi, vcc_hi, -1
	s_add_u32 s98, s98, 0xfff880
	s_addc_u32 s99, s99, 0
	s_mov_b32 m0, 0xffff
.Lnxj_1040_6:
	s_cmpk_lg_u32 m0, 7
	s_cbranch_scc1 .Lnxj_1040_7
	s_add_u32 vcc_lo, vcc_lo, 0xffaff880
	s_addc_u32 vcc_hi, vcc_hi, -1
	s_add_u32 s98, s98, 0xfff880
	s_addc_u32 s99, s99, 0
	s_mov_b32 m0, 0xffff
.Lnxj_1040_7:
	s_cmpk_lg_u32 m0, 8
	s_cbranch_scc1 .Lnxj_1040_8
	s_add_u32 vcc_lo, vcc_lo, 0xffaff880
	s_addc_u32 vcc_hi, vcc_hi, -1
	s_add_u32 s98, s98, 0xfff880
	s_addc_u32 s99, s99, 0
	s_mov_b32 m0, 0xffff
.Lnxj_1040_8:
	s_cmpk_lg_u32 m0, 9
	s_cbranch_scc1 .Lnxj_1040_9
	s_add_u32 vcc_lo, vcc_lo, 0xffdff880
	s_addc_u32 vcc_hi, vcc_hi, -1
	s_add_u32 s98, s98, 0xfff880
	s_addc_u32 s99, s99, 0
	s_mov_b32 m0, 0xffff

.Lnxn_1040:
	s_waitcnt lgkmcnt(0)
	s_waitcnt lgkmcnt(3)
	v_mfma_f32_16x16x32_bf16 v[108:111], v[178:181], v[162:165], v[108:111]
	v_mfma_f32_16x16x32_bf16 v[92:95], v[178:181], v[166:169], v[92:95]
	v_mfma_f32_16x16x32_bf16 v[76:79], v[178:181], v[170:173], v[76:79]
	v_mfma_f32_16x16x32_bf16 v[60:63], v[178:181], v[174:177], v[60:63]
	ds_read_b128 v[240:243], v197
	ds_read_b128 v[244:247], v198
	s_waitcnt lgkmcnt(4)
	v_mfma_f32_16x16x32_bf16 v[104:107], v[182:185], v[162:165], v[104:107]
	v_mfma_f32_16x16x32_bf16 v[88:91], v[182:185], v[166:169], v[88:91]
	v_mfma_f32_16x16x32_bf16 v[72:75], v[182:185], v[170:173], v[72:75]
	v_mfma_f32_16x16x32_bf16 v[56:59], v[182:185], v[174:177], v[56:59]
	ds_read_b128 v[248:251], v199
	ds_read_b128 v[252:255], v200
	s_waitcnt lgkmcnt(5)
	v_mfma_f32_16x16x32_bf16 v[100:103], v[186:189], v[162:165], v[100:103]
	v_mfma_f32_16x16x32_bf16 v[84:87], v[186:189], v[166:169], v[84:87]
	v_mfma_f32_16x16x32_bf16 v[68:71], v[186:189], v[170:173], v[68:71]
	v_mfma_f32_16x16x32_bf16 v[52:55], v[186:189], v[174:177], v[52:55]
	s_waitcnt lgkmcnt(4)
	v_mfma_f32_16x16x32_bf16 v[96:99], v[190:193], v[162:165], v[96:99]
	v_mfma_f32_16x16x32_bf16 v[80:83], v[190:193], v[166:169], v[80:83]
	v_mfma_f32_16x16x32_bf16 v[64:67], v[190:193], v[170:173], v[64:67]
	v_mfma_f32_16x16x32_bf16 v[48:51], v[190:193], v[174:177], v[48:51]
	ds_read_b128 v[162:165], v161 offset:1024
	ds_read_b128 v[166:169], v194 offset:1024
	ds_read_b128 v[170:173], v195 offset:1024
	ds_read_b128 v[174:177], v196 offset:1024
	s_waitcnt lgkmcnt(4)
	v_mfma_f32_16x16x32_bf16 v[44:47], v[178:181], v[240:243], v[44:47]
	v_mfma_f32_16x16x32_bf16 v[28:31], v[178:181], v[244:247], v[28:31]
	v_mfma_f32_16x16x32_bf16 v[12:15], v[178:181], v[248:251], v[12:15]
	v_mfma_f32_16x16x32_bf16 v[112:115], v[178:181], v[252:255], v[112:115]
	ds_read_b128 v[178:181], v128 offset:33792
	v_mfma_f32_16x16x32_bf16 v[40:43], v[182:185], v[240:243], v[40:43]
	v_mfma_f32_16x16x32_bf16 v[24:27], v[182:185], v[244:247], v[24:27]
	v_mfma_f32_16x16x32_bf16 v[8:11], v[182:185], v[248:251], v[8:11]
	v_mfma_f32_16x16x32_bf16 v[116:119], v[182:185], v[252:255], v[116:119]
	ds_read_b128 v[182:185], v128 offset:35840
	v_mfma_f32_16x16x32_bf16 v[36:39], v[186:189], v[240:243], v[36:39]
	v_mfma_f32_16x16x32_bf16 v[20:23], v[186:189], v[244:247], v[20:23]
	v_mfma_f32_16x16x32_bf16 v[4:7], v[186:189], v[248:251], v[4:7]
	v_mfma_f32_16x16x32_bf16 v[120:123], v[186:189], v[252:255], v[120:123]
	ds_read_b128 v[186:189], v128 offset:37888
	v_mfma_f32_16x16x32_bf16 v[32:35], v[190:193], v[240:243], v[32:35]
	v_mfma_f32_16x16x32_bf16 v[16:19], v[190:193], v[244:247], v[16:19]
	v_mfma_f32_16x16x32_bf16 v[0:3], v[190:193], v[248:251], v[0:3]
	v_mfma_f32_16x16x32_bf16 v[124:127], v[190:193], v[252:255], v[124:127]
	ds_read_b128 v[190:193], v128 offset:39936
	s_waitcnt lgkmcnt(3)
	v_mfma_f32_16x16x32_bf16 v[108:111], v[178:181], v[162:165], v[108:111]
	v_mfma_f32_16x16x32_bf16 v[92:95], v[178:181], v[166:169], v[92:95]
	v_mfma_f32_16x16x32_bf16 v[76:79], v[178:181], v[170:173], v[76:79]
	v_mfma_f32_16x16x32_bf16 v[60:63], v[178:181], v[174:177], v[60:63]
	ds_read_b128 v[240:243], v197 offset:1024
	ds_read_b128 v[244:247], v198 offset:1024
	s_waitcnt lgkmcnt(4)
	v_mfma_f32_16x16x32_bf16 v[104:107], v[182:185], v[162:165], v[104:107]
	v_mfma_f32_16x16x32_bf16 v[88:91], v[182:185], v[166:169], v[88:91]
	v_mfma_f32_16x16x32_bf16 v[72:75], v[182:185], v[170:173], v[72:75]
	v_mfma_f32_16x16x32_bf16 v[56:59], v[182:185], v[174:177], v[56:59]
	ds_read_b128 v[248:251], v199 offset:1024
	ds_read_b128 v[252:255], v200 offset:1024
	s_waitcnt lgkmcnt(5)
	v_mfma_f32_16x16x32_bf16 v[100:103], v[186:189], v[162:165], v[100:103]
	v_mfma_f32_16x16x32_bf16 v[84:87], v[186:189], v[166:169], v[84:87]
	v_mfma_f32_16x16x32_bf16 v[68:71], v[186:189], v[170:173], v[68:71]
	v_mfma_f32_16x16x32_bf16 v[52:55], v[186:189], v[174:177], v[52:55]
	s_waitcnt lgkmcnt(4)
	v_mfma_f32_16x16x32_bf16 v[96:99], v[190:193], v[162:165], v[96:99]
	v_mfma_f32_16x16x32_bf16 v[80:83], v[190:193], v[166:169], v[80:83]
	v_mfma_f32_16x16x32_bf16 v[64:67], v[190:193], v[170:173], v[64:67]
	v_mfma_f32_16x16x32_bf16 v[48:51], v[190:193], v[174:177], v[48:51]
	s_waitcnt lgkmcnt(0)
	v_mfma_f32_16x16x32_bf16 v[44:47], v[178:181], v[240:243], v[44:47]
	v_mfma_f32_16x16x32_bf16 v[28:31], v[178:181], v[244:247], v[28:31]
	v_mfma_f32_16x16x32_bf16 v[12:15], v[178:181], v[248:251], v[12:15]
	v_mfma_f32_16x16x32_bf16 v[112:115], v[178:181], v[252:255], v[112:115]
	v_mfma_f32_16x16x32_bf16 v[40:43], v[182:185], v[240:243], v[40:43]
	v_mfma_f32_16x16x32_bf16 v[24:27], v[182:185], v[244:247], v[24:27]
	v_mfma_f32_16x16x32_bf16 v[8:11], v[182:185], v[248:251], v[8:11]
	v_mfma_f32_16x16x32_bf16 v[116:119], v[182:185], v[252:255], v[116:119]
	v_mfma_f32_16x16x32_bf16 v[36:39], v[186:189], v[240:243], v[36:39]
	v_mfma_f32_16x16x32_bf16 v[20:23], v[186:189], v[244:247], v[20:23]
	v_mfma_f32_16x16x32_bf16 v[4:7], v[186:189], v[248:251], v[4:7]
	v_mfma_f32_16x16x32_bf16 v[120:123], v[186:189], v[252:255], v[120:123]
	v_mfma_f32_16x16x32_bf16 v[32:35], v[190:193], v[240:243], v[32:35]
	v_mfma_f32_16x16x32_bf16 v[16:19], v[190:193], v[244:247], v[16:19]
	v_mfma_f32_16x16x32_bf16 v[0:3], v[190:193], v[248:251], v[0:3]
	v_mfma_f32_16x16x32_bf16 v[124:127], v[190:193], v[252:255], v[124:127]
	v_mov_b32_e32 v128, s20
	s_waitcnt vmcnt(8)
	s_barrier
	ds_read_b64 v[130:131], v128
	v_ashrrev_i32_e32 v128, 1, v148
	v_and_b32_e32 v128, 0xffffff80, v128
	v_add_u32_e32 v128, s16, v128
	s_ashr_i32 s15, s14, 31
	s_waitcnt lgkmcnt(0)
	v_mad_i64_i32 v[130:131], s[16:17], v128, s26, v[130:131]
	v_and_b32_e32 v128, 0xc0, v148
	v_lshrrev_b32_e32 v135, 6, v148
	v_lshl_add_u64 v[130:131], s[14:15], 1, v[130:131]
	v_lshlrev_b32_e32 v128, 1, v128
	v_lshl_add_u64 v[130:131], v[130:131], 0, v[128:129]
	v_mul_lo_u32 v128, v135, s27
	v_add_u32_e32 v135, s24, v128
	v_lshrrev_b32_e32 v128, 1, v148
	v_and_b32_e32 v136, 24, v128
	v_lshlrev_b32_e32 v128, 4, v148
	v_bfe_u32 v137, v148, 3, 3
	v_and_b32_e32 v134, 15, v148
	v_and_b32_e32 v128, 0x70, v128
	v_mul_u32_u24_e32 v138, 0x90, v137
	v_lshl_add_u64 v[130:131], v[130:131], 0, v[128:129]
	v_add3_u32 v138, v135, v128, v138
	v_mul_u32_u24_e32 v128, 0x90, v134
	v_add3_u32 v134, v135, v136, v128
	v_cvt_pk_bf16_f32 v108, v108, v109
	v_cvt_pk_bf16_f32 v109, v110, v111
	v_cvt_pk_bf16_f32 v104, v104, v105
	v_cvt_pk_bf16_f32 v105, v106, v107
	v_cvt_pk_bf16_f32 v100, v100, v101
	v_cvt_pk_bf16_f32 v101, v102, v103
	v_cvt_pk_bf16_f32 v96, v96, v97
	v_cvt_pk_bf16_f32 v97, v98, v99
	v_cvt_pk_bf16_f32 v92, v92, v93
	v_cvt_pk_bf16_f32 v93, v94, v95
	v_cvt_pk_bf16_f32 v88, v88, v89
	v_cvt_pk_bf16_f32 v89, v90, v91
	v_cvt_pk_bf16_f32 v84, v84, v85
	v_cvt_pk_bf16_f32 v85, v86, v87
	v_cvt_pk_bf16_f32 v80, v80, v81
	v_cvt_pk_bf16_f32 v81, v82, v83
	v_cvt_pk_bf16_f32 v76, v76, v77
	v_cvt_pk_bf16_f32 v77, v78, v79
	v_cvt_pk_bf16_f32 v72, v72, v73
	v_cvt_pk_bf16_f32 v73, v74, v75
	v_cvt_pk_bf16_f32 v68, v68, v69
	v_cvt_pk_bf16_f32 v69, v70, v71
	v_cvt_pk_bf16_f32 v64, v64, v65
	v_cvt_pk_bf16_f32 v65, v66, v67
	v_cvt_pk_bf16_f32 v60, v60, v61
	v_cvt_pk_bf16_f32 v61, v62, v63
	v_cvt_pk_bf16_f32 v56, v56, v57
	v_cvt_pk_bf16_f32 v57, v58, v59
	v_cvt_pk_bf16_f32 v52, v52, v53
	v_cvt_pk_bf16_f32 v53, v54, v55
	v_cvt_pk_bf16_f32 v48, v48, v49
	v_cvt_pk_bf16_f32 v49, v50, v51
	ds_write_b64 v134, v[108:109]
	ds_write_b64 v134, v[104:105] offset:32
	ds_write_b64 v134, v[100:101] offset:64
	ds_write_b64 v134, v[96:97] offset:96
	ds_write_b64 v134, v[92:93] offset:2304
	ds_write_b64 v134, v[88:89] offset:2336
	ds_write_b64 v134, v[84:85] offset:2368
	ds_write_b64 v134, v[80:81] offset:2400
	ds_write_b64 v134, v[76:77] offset:4608
	ds_write_b64 v134, v[72:73] offset:4640
	ds_write_b64 v134, v[68:69] offset:4672
	ds_write_b64 v134, v[64:65] offset:4704
	ds_write_b64 v134, v[60:61] offset:6912
	ds_write_b64 v134, v[56:57] offset:6944
	ds_write_b64 v134, v[52:53] offset:6976
	ds_write_b64 v134, v[48:49] offset:7008
	ds_read_b128 v[48:51], v138
	v_mul_u32_u24_e32 v54, 0xa00, v137
	v_lshl_add_u64 v[52:53], v[130:131], 0, s[12:13]
	v_lshlrev_b32_e32 v128, 1, v54
	v_lshl_add_u64 v[54:55], v[52:53], 0, v[128:129]
	s_waitcnt lgkmcnt(0)
	global_store_dwordx4 v[54:55], v[48:51], off nt
	ds_read_b128 v[48:51], v138 offset:1152
	v_add_co_u32_e32 v56, vcc, s22, v54
	v_cvt_pk_bf16_f32 v0, v0, v1
	s_nop 0
	v_addc_co_u32_e32 v57, vcc, 0, v55, vcc
	s_waitcnt lgkmcnt(0)
	global_store_dwordx4 v[56:57], v[48:51], off nt
	ds_read_b128 v[48:51], v138 offset:2304
	v_add_co_u32_e32 v56, vcc, s28, v54
	v_cvt_pk_bf16_f32 v1, v2, v3
	s_nop 0
	v_addc_co_u32_e32 v57, vcc, 0, v55, vcc
	s_waitcnt lgkmcnt(0)
	global_store_dwordx4 v[56:57], v[48:51], off nt
	ds_read_b128 v[48:51], v138 offset:3456
	v_add_co_u32_e32 v56, vcc, s29, v54
	v_cvt_pk_bf16_f32 v44, v44, v45
	s_nop 0
	v_addc_co_u32_e32 v57, vcc, 0, v55, vcc
	s_waitcnt lgkmcnt(0)
	global_store_dwordx4 v[56:57], v[48:51], off nt
	ds_read_b128 v[48:51], v138 offset:4608
	v_add_u32_e32 v56, 0x28000, v128
	v_mov_b32_e32 v57, v129
	v_lshl_add_u64 v[56:57], v[52:53], 0, v[56:57]
	v_cvt_pk_bf16_f32 v45, v46, v47
	s_waitcnt lgkmcnt(0)
	global_store_dwordx4 v[56:57], v[48:51], off nt
	ds_read_b128 v[48:51], v138 offset:5760
	v_add_u32_e32 v56, 0x32000, v128
	v_mov_b32_e32 v57, v129
	v_lshl_add_u64 v[56:57], v[52:53], 0, v[56:57]
	v_cvt_pk_bf16_f32 v40, v40, v41
	s_waitcnt lgkmcnt(0)
	global_store_dwordx4 v[56:57], v[48:51], off nt
	ds_read_b128 v[48:51], v138 offset:6912
	v_add_u32_e32 v56, 0x3c000, v128
	v_mov_b32_e32 v57, v129
	v_lshl_add_u64 v[56:57], v[52:53], 0, v[56:57]
	v_add_u32_e32 v128, 0x46000, v128
	s_waitcnt lgkmcnt(0)
	global_store_dwordx4 v[56:57], v[48:51], off nt
	ds_read_b128 v[48:51], v138 offset:8064
	v_lshl_add_u64 v[52:53], v[52:53], 0, v[128:129]
	v_cvt_pk_bf16_f32 v41, v42, v43
	v_cvt_pk_bf16_f32 v36, v36, v37
	v_cvt_pk_bf16_f32 v37, v38, v39
	s_waitcnt lgkmcnt(0)
	global_store_dwordx4 v[52:53], v[48:51], off nt
	ds_write_b64 v134, v[0:1] offset:4704
	v_cvt_pk_bf16_f32 v0, v112, v113
	v_cvt_pk_bf16_f32 v1, v114, v115
	ds_write_b64 v134, v[0:1] offset:6912
	v_cvt_pk_bf16_f32 v0, v116, v117
	v_cvt_pk_bf16_f32 v1, v118, v119
	ds_write_b64 v134, v[0:1] offset:6944
	v_cvt_pk_bf16_f32 v0, v120, v121
	v_cvt_pk_bf16_f32 v1, v122, v123
	v_cvt_pk_bf16_f32 v32, v32, v33
	v_cvt_pk_bf16_f32 v33, v34, v35
	v_cvt_pk_bf16_f32 v28, v28, v29
	v_cvt_pk_bf16_f32 v29, v30, v31
	v_cvt_pk_bf16_f32 v24, v24, v25
	v_cvt_pk_bf16_f32 v25, v26, v27
	v_cvt_pk_bf16_f32 v20, v20, v21
	v_cvt_pk_bf16_f32 v21, v22, v23
	v_cvt_pk_bf16_f32 v16, v16, v17
	v_cvt_pk_bf16_f32 v17, v18, v19
	v_cvt_pk_bf16_f32 v12, v12, v13
	v_cvt_pk_bf16_f32 v13, v14, v15
	v_cvt_pk_bf16_f32 v8, v8, v9
	v_cvt_pk_bf16_f32 v9, v10, v11
	v_cvt_pk_bf16_f32 v4, v4, v5
	v_cvt_pk_bf16_f32 v5, v6, v7
	ds_write_b64 v134, v[0:1] offset:6976
	v_cvt_pk_bf16_f32 v0, v124, v125
	v_cvt_pk_bf16_f32 v1, v126, v127
	ds_write_b64 v134, v[44:45]
	ds_write_b64 v134, v[40:41] offset:32
	ds_write_b64 v134, v[36:37] offset:64
	ds_write_b64 v134, v[32:33] offset:96
	ds_write_b64 v134, v[28:29] offset:2304
	ds_write_b64 v134, v[24:25] offset:2336
	ds_write_b64 v134, v[20:21] offset:2368
	ds_write_b64 v134, v[16:17] offset:2400
	ds_write_b64 v134, v[12:13] offset:4608
	ds_write_b64 v134, v[8:9] offset:4640
	ds_write_b64 v134, v[4:5] offset:4672
	ds_write_b64 v134, v[0:1] offset:7008
	ds_read_b128 v[0:3], v138
	v_add_co_u32_e32 v4, vcc, s30, v54
	s_add_i32 s42, s42, s40
	s_nop 0
	v_addc_co_u32_e32 v5, vcc, 0, v55, vcc
	s_waitcnt lgkmcnt(0)
	global_store_dwordx4 v[4:5], v[0:3], off nt
	ds_read_b128 v[0:3], v138 offset:1152
	v_add_co_u32_e32 v4, vcc, s31, v54
	s_cmpk_gt_i32 s42, 0x4ff
	s_nop 0
	v_addc_co_u32_e32 v5, vcc, 0, v55, vcc
	s_waitcnt lgkmcnt(0)
	global_store_dwordx4 v[4:5], v[0:3], off nt
	ds_read_b128 v[0:3], v138 offset:2304
	v_add_co_u32_e32 v4, vcc, s34, v54
	s_nop 1
	v_addc_co_u32_e32 v5, vcc, 0, v55, vcc
	s_waitcnt lgkmcnt(0)
	global_store_dwordx4 v[4:5], v[0:3], off nt
	ds_read_b128 v[0:3], v138 offset:3456
	v_add_co_u32_e32 v4, vcc, s35, v54
	s_nop 1
	v_addc_co_u32_e32 v5, vcc, 0, v55, vcc
	s_waitcnt lgkmcnt(0)
	global_store_dwordx4 v[4:5], v[0:3], off nt
	ds_read_b128 v[0:3], v138 offset:4608
	v_add_co_u32_e32 v4, vcc, s38, v54
	s_nop 1
	v_addc_co_u32_e32 v5, vcc, 0, v55, vcc
	s_waitcnt lgkmcnt(0)
	global_store_dwordx4 v[4:5], v[0:3], off nt
	ds_read_b128 v[0:3], v138 offset:5760
	v_add_co_u32_e32 v4, vcc, s39, v54
	s_nop 1
	v_addc_co_u32_e32 v5, vcc, 0, v55, vcc
	s_waitcnt lgkmcnt(0)
	global_store_dwordx4 v[4:5], v[0:3], off nt
	ds_read_b128 v[0:3], v138 offset:6912
	v_add_co_u32_e32 v4, vcc, 0x8c000, v54
	s_nop 1
	v_addc_co_u32_e32 v5, vcc, 0, v55, vcc
	s_waitcnt lgkmcnt(0)
	global_store_dwordx4 v[4:5], v[0:3], off nt
	ds_read_b128 v[0:3], v138 offset:8064
	v_add_co_u32_e32 v4, vcc, 0x96000, v54
	s_nop 1
	v_addc_co_u32_e32 v5, vcc, 0, v55, vcc
	s_waitcnt lgkmcnt(0)
	global_store_dwordx4 v[4:5], v[0:3], off nt
	s_cbranch_scc0 .LBB0_1039

.LBB0_1137:
	s_ashr_i32 s10, s23, 31
	s_lshr_b32 s10, s10, 26
	s_add_i32 s10, s23, s10
	s_ashr_i32 s11, s10, 6
	s_and_b32 s10, s10, 0xffc0
	s_sub_i32 s10, s23, s10
	s_bfe_i32 s12, s10, 0x80000
	s_bfe_u32 s12, s12, 0x4000b
	v_mov_b32_e32 v148, v132
	v_mov_b32_e32 v18, v132
	s_add_i32 s12, s10, s12
	ds_read_b64 v[0:1], v133
	s_lshl_b32 s25, s11, 4
	v_lshlrev_b32_e32 v9, 4, v18
	v_and_b32_e32 v8, 32, v18
	s_and_b32 s11, s12, 0xf0
	v_bfe_u32 v19, v18, 2, 4
	v_lshrrev_b32_e32 v10, 1, v18
	v_bitop3_b32 v8, v9, v8, 48 bitop3:0x6c
	v_ashrrev_i32_e32 v22, 3, v18
	s_sub_i32 s10, s10, s11
	v_and_b32_e32 v20, 32, v10
	v_lshrrev_b32_e32 v21, 1, v8
	v_and_or_b32 v8, v22, s14, v19
	s_bfe_i32 s13, s12, 0x80000
	s_sext_i32_i8 s10, s10
	v_or_b32_e32 v12, v21, v20
	v_mul_u32_u24_e32 v8, 0xb00, v8
	s_sext_i32_i16 s13, s13
	s_add_i32 s25, s25, s10
	v_and_b32_e32 v11, 0xfffffc00, v9
	v_or_b32_e32 v128, v12, v8
	v_add_u32_e32 v8, 0x2000, v9
	v_add_u32_e32 v10, 0x4000, v9
	v_add_u32_e32 v9, 0x6000, v9
	s_ashr_i32 s26, s13, 4
	s_lshl_b32 s24, s25, 8
	v_ashrrev_i32_e32 v23, 7, v8
	v_ashrrev_i32_e32 v24, 7, v10
	v_ashrrev_i32_e32 v25, 7, v9
	s_lshl_b32 s10, s26, 8
	s_mul_i32 s12, s25, 0x160000
	s_mul_hi_i32 s13, s24, 0x1600
	v_and_or_b32 v8, v23, s14, v19
	v_and_or_b32 v10, v24, s14, v19
	v_and_or_b32 v9, v25, s14, v19
	s_waitcnt lgkmcnt(0)
	v_lshl_add_u64 v[2:3], v[0:1], 0, s[12:13]
	s_mul_i32 s12, s26, 0x160000
	s_mul_hi_i32 s13, s10, 0x1600
	v_mul_u32_u24_e32 v8, 0xb00, v8
	v_mul_u32_u24_e32 v10, 0xb00, v10
	v_mul_u32_u24_e32 v9, 0xb00, v9
	v_add_u32_e32 v149, 0, v11
	v_lshl_add_u64 v[4:5], v[2:3], 0, s[0:1]
	v_lshl_add_u64 v[0:1], v[0:1], 0, s[12:13]
	v_or_b32_e32 v8, v8, v12
	v_or_b32_e32 v10, v10, v12
	v_or_b32_e32 v12, v9, v12
	v_add_u32_e32 v9, 0x8000, v149
	v_lshlrev_b64 v[14:15], 1, v[128:129]
	v_readfirstlane_b32 s12, v149
	v_lshl_add_u64 v[6:7], v[0:1], 0, s[4:5]
	v_lshl_add_u64 v[16:17], v[4:5], 0, v[14:15]
	s_mov_b32 m0, s12
	v_readfirstlane_b32 s12, v9
	v_mov_b32_e32 v9, v129
	v_add_u32_e32 v11, 0x2000, v149
	global_load_lds_dwordx4 v[16:17], off
	v_lshl_add_u64 v[14:15], v[6:7], 0, v[14:15]
	s_mov_b32 m0, s12
	v_lshlrev_b64 v[8:9], 1, v[8:9]
	v_readfirstlane_b32 s12, v11
	v_add_u32_e32 v11, 0xa000, v149
	global_load_lds_dwordx4 v[14:15], off
	v_lshl_add_u64 v[14:15], v[4:5], 0, v[8:9]
	s_mov_b32 m0, s12
	v_readfirstlane_b32 s12, v11
	global_load_lds_dwordx4 v[14:15], off
	v_lshl_add_u64 v[8:9], v[6:7], 0, v[8:9]
	s_mov_b32 m0, s12
	v_mov_b32_e32 v11, v129
	v_add_u32_e32 v13, 0x4000, v149
	global_load_lds_dwordx4 v[8:9], off
	v_lshlrev_b64 v[8:9], 1, v[10:11]
	v_readfirstlane_b32 s12, v13
	v_lshl_add_u64 v[10:11], v[4:5], 0, v[8:9]
	s_mov_b32 m0, s12
	v_lshl_add_u64 v[8:9], v[6:7], 0, v[8:9]
	global_load_lds_dwordx4 v[10:11], off
	v_add_u32_e32 v10, 0xc000, v149
	v_mov_b32_e32 v13, v129
	v_readfirstlane_b32 s12, v10
	s_mov_b32 m0, s12
	v_add_u32_e32 v10, 0x6000, v149
	global_load_lds_dwordx4 v[8:9], off
	v_lshlrev_b64 v[8:9], 1, v[12:13]
	v_readfirstlane_b32 s12, v10
	v_lshl_add_u64 v[4:5], v[4:5], 0, v[8:9]
	s_mov_b32 m0, s12
	v_and_b32_e32 v26, 15, v18
	global_load_lds_dwordx4 v[4:5], off
	v_lshl_add_u64 v[4:5], v[6:7], 0, v[8:9]
	v_add_u32_e32 v6, 0xe000, v149
	v_lshrrev_b32_e32 v8, 4, v23
	v_readfirstlane_b32 s12, v6
	s_mov_b32 m0, s12
	v_lshlrev_b32_e32 v6, 2, v18
	global_load_lds_dwordx4 v[4:5], off
	v_and_b32_e32 v4, 48, v18
	v_lshlrev_b32_e32 v5, 6, v26
	v_and_b32_e32 v6, 32, v6
	v_bitop3_b32 v150, v5, v6, v4 bitop3:0x36
	v_lshlrev_b32_e32 v5, 7, v18
	v_and_b32_e32 v151, 0x6000, v5
	v_lshlrev_b32_e32 v5, 6, v18
	v_and_b32_e32 v152, 0xffffc000, v5
	v_and_b32_e32 v5, 0x3c0, v5
	v_bitop3_b32 v154, v5, v6, v4 bitop3:0x36
	v_lshrrev_b32_e32 v4, 4, v25
	v_mul_lo_u32 v4, v4, s16
	v_lshrrev_b32_e32 v6, 4, v24
	v_or_b32_e32 v4, v21, v4
	v_mul_lo_u32 v6, v6, s16
	v_mad_u32_u24 v4, v19, s15, v4
	v_or_b32_e32 v6, v21, v6
	v_mul_lo_u32 v8, v8, s16
	v_lshrrev_b32_e32 v10, 4, v22
	v_or_b32_e32 v128, v4, v20
	v_mad_u32_u24 v6, v19, s15, v6
	v_or_b32_e32 v8, v21, v8
	v_mul_lo_u32 v10, v10, s16
	v_lshlrev_b64 v[4:5], 1, v[128:129]
	v_or_b32_e32 v128, v6, v20
	v_mad_u32_u24 v8, v19, s15, v8
	v_or_b32_e32 v10, v21, v10
	v_lshlrev_b64 v[6:7], 1, v[128:129]
	v_or_b32_e32 v128, v8, v20
	v_mad_u32_u24 v10, v19, s15, v10
	v_lshlrev_b64 v[8:9], 1, v[128:129]
	v_or_b32_e32 v128, v10, v20
	s_waitcnt vmcnt(0)
	v_lshl_add_u64 v[0:1], v[0:1], 0, s[6:7]
	v_lshlrev_b64 v[10:11], 1, v[128:129]
	v_lshl_add_u64 v[130:131], v[0:1], 0, v[4:5]
	v_lshl_add_u64 v[134:135], v[0:1], 0, v[6:7]
	v_lshl_add_u64 v[136:137], v[0:1], 0, v[8:9]
	v_lshl_add_u64 v[138:139], v[0:1], 0, v[10:11]
	v_lshl_add_u64 v[0:1], v[2:3], 0, s[8:9]
	s_ashr_i32 s11, s10, 31
	v_or_b32_e32 v153, 0x800, v152
	v_or_b32_e32 v155, 0x1000, v152
	v_or_b32_e32 v156, 0x1800, v152
	v_or_b32_e32 v157, 0x2000, v152
	v_or_b32_e32 v158, 0x2800, v152
	v_or_b32_e32 v159, 0x3000, v152
	v_or_b32_e32 v160, 0x3800, v152
	v_lshl_add_u64 v[140:141], v[0:1], 0, v[4:5]
	v_lshl_add_u64 v[142:143], v[0:1], 0, v[6:7]
	v_lshl_add_u64 v[144:145], v[0:1], 0, v[8:9]
	v_lshl_add_u64 v[146:147], v[0:1], 0, v[10:11]
	s_mov_b64 s[12:13], 0
	s_mov_b32 s26, 0
	v_mov_b32_e32 v12, 0
	v_mov_b32_e32 v14, v129
	v_mov_b32_e32 v15, v129
	v_mov_b32_e32 v20, 0
	v_mov_b32_e32 v21, v129
	v_mov_b32_e32 v22, v129
	v_mov_b32_e32 v23, v129
	v_mov_b32_e32 v28, 0
	v_mov_b32_e32 v29, v129
	v_mov_b32_e32 v30, v129
	v_mov_b32_e32 v31, v129
	v_mov_b32_e32 v36, 0
	v_mov_b32_e32 v37, v129
	v_mov_b32_e32 v38, v129
	v_mov_b32_e32 v39, v129
	v_mov_b32_e32 v0, 0
	v_mov_b32_e32 v1, v129
	v_mov_b32_e32 v2, v129
	v_mov_b32_e32 v3, v129
	v_mov_b32_e32 v4, 0
	v_mov_b32_e32 v5, v129
	v_mov_b32_e32 v6, v129
	v_mov_b32_e32 v7, v129
	v_mov_b32_e32 v8, 0
	v_mov_b32_e32 v9, v129
	v_mov_b32_e32 v10, v129
	v_mov_b32_e32 v11, v129
	v_mov_b32_e32 v16, 0
	v_mov_b32_e32 v17, v129
	v_mov_b32_e32 v18, v129
	v_mov_b32_e32 v19, v129
	v_mov_b32_e32 v24, 0
	v_mov_b32_e32 v25, v129
	v_mov_b32_e32 v26, v129
	v_mov_b32_e32 v27, v129
	v_mov_b32_e32 v32, 0
	v_mov_b32_e32 v33, v129
	v_mov_b32_e32 v34, v129
	v_mov_b32_e32 v35, v129
	v_mov_b32_e32 v40, 0
	v_mov_b32_e32 v41, v129
	v_mov_b32_e32 v42, v129
	v_mov_b32_e32 v43, v129
	v_mov_b32_e32 v44, 0
	v_mov_b32_e32 v45, v129
	v_mov_b32_e32 v46, v129
	v_mov_b32_e32 v47, v129
	v_mov_b32_e32 v48, 0
	v_mov_b32_e32 v49, v129
	v_mov_b32_e32 v50, v129
	v_mov_b32_e32 v51, v129
	v_mov_b32_e32 v52, 0
	v_mov_b32_e32 v53, v129
	v_mov_b32_e32 v54, v129
	v_mov_b32_e32 v55, v129
	v_mov_b32_e32 v56, 0
	v_mov_b32_e32 v57, v129
	v_mov_b32_e32 v58, v129
	v_mov_b32_e32 v59, v129
	v_mov_b32_e32 v60, 0
	v_mov_b32_e32 v61, v129
	v_mov_b32_e32 v62, v129
	v_mov_b32_e32 v63, v129
	v_mov_b32_e32 v64, 0
	v_mov_b32_e32 v65, v129
	v_mov_b32_e32 v66, v129
	v_mov_b32_e32 v67, v129
	v_mov_b32_e32 v68, 0
	v_mov_b32_e32 v69, v129
	v_mov_b32_e32 v70, v129
	v_mov_b32_e32 v71, v129
	v_mov_b32_e32 v72, 0
	v_mov_b32_e32 v73, v129
	v_mov_b32_e32 v74, v129
	v_mov_b32_e32 v75, v129
	v_mov_b32_e32 v76, 0
	v_mov_b32_e32 v77, v129
	v_mov_b32_e32 v78, v129
	v_mov_b32_e32 v79, v129
	v_mov_b32_e32 v80, 0
	v_mov_b32_e32 v81, v129
	v_mov_b32_e32 v82, v129
	v_mov_b32_e32 v83, v129
	v_mov_b32_e32 v84, 0
	v_mov_b32_e32 v85, v129
	v_mov_b32_e32 v86, v129
	v_mov_b32_e32 v87, v129
	v_mov_b32_e32 v88, 0
	v_mov_b32_e32 v89, v129
	v_mov_b32_e32 v90, v129
	v_mov_b32_e32 v91, v129
	v_mov_b32_e32 v92, 0
	v_mov_b32_e32 v93, v129
	v_mov_b32_e32 v94, v129
	v_mov_b32_e32 v95, v129
	v_mov_b32_e32 v96, 0
	v_mov_b32_e32 v97, v129
	v_mov_b32_e32 v98, v129
	v_mov_b32_e32 v99, v129
	v_mov_b32_e32 v100, 0
	v_mov_b32_e32 v101, v129
	v_mov_b32_e32 v102, v129
	v_mov_b32_e32 v103, v129
	v_mov_b32_e32 v104, 0
	v_mov_b32_e32 v105, v129
	v_mov_b32_e32 v106, v129
	v_mov_b32_e32 v107, v129
	v_mov_b32_e32 v108, 0
	v_mov_b32_e32 v109, v129
	v_mov_b32_e32 v110, v129
	v_mov_b32_e32 v111, v129
	v_mov_b32_e32 v112, 0
	v_mov_b32_e32 v113, v129
	v_mov_b32_e32 v114, v129
	v_mov_b32_e32 v115, v129
	v_mov_b32_e32 v116, 0
	v_mov_b32_e32 v117, v129
	v_mov_b32_e32 v118, v129
	v_mov_b32_e32 v119, v129
	v_mov_b32_e32 v120, 0
	v_mov_b32_e32 v121, v129
	v_mov_b32_e32 v122, v129
	v_mov_b32_e32 v123, v129
	v_mov_b32_e32 v124, 0
	v_mov_b32_e32 v125, v129
	v_mov_b32_e32 v126, v129
	v_mov_b32_e32 v127, v129
	s_waitcnt vmcnt(0) lgkmcnt(0)
	s_barrier
	v_readfirstlane_b32 s100, v149
	s_and_b32 s27, s26, 0x10000
	s_xor_b32 s28, s27, 0x10000
	s_add_i32 s27, s27, 0
	v_add3_u32 v128, s27, v150, v151
	v_add3_u32 v161, s27, v150, v152
	v_add3_u32 v194, s27, v154, v153
	v_add3_u32 v195, s27, v154, v155
	v_add3_u32 v196, s27, v154, v156
	v_add3_u32 v197, s27, v154, v157
	v_add3_u32 v198, s27, v154, v158
	v_add3_u32 v199, s27, v154, v159
	v_add3_u32 v200, s27, v154, v160
	ds_read_b128 v[178:181], v128 offset:32768
	ds_read_b128 v[162:165], v161
	ds_read_b128 v[166:169], v194
	ds_read_b128 v[170:173], v195
	ds_read_b128 v[174:177], v196
	ds_read_b128 v[182:185], v128 offset:34816
	ds_read_b128 v[186:189], v128 offset:36864
	ds_read_b128 v[190:193], v128 offset:38912
	s_add_i32 s101, s100, s28
	v_readfirstlane_b32 s98, v146
	v_readfirstlane_b32 s99, v147
	v_readfirstlane_b32 vcc_lo, v138
	v_readfirstlane_b32 vcc_hi, v139
	s_sub_u32 s98, s98, 0x1000000
	s_subb_u32 s99, s99, 0
	s_sub_u32 vcc_lo, vcc_lo, 0x1000000
	s_subb_u32 vcc_hi, vcc_hi, 0
	v_subrev_u32_e32 v146, s98, v146
	v_subrev_u32_e32 v138, vcc_lo, v138
	v_subrev_u32_e32 v144, s98, v144
	v_subrev_u32_e32 v136, vcc_lo, v136
	v_subrev_u32_e32 v142, s98, v142
	v_subrev_u32_e32 v134, vcc_lo, v134
	v_subrev_u32_e32 v140, s98, v140
	v_subrev_u32_e32 v130, vcc_lo, v130
	s_mov_b32 m0, s101
	s_nop 0
	global_load_lds_dwordx4 v146, s[98:99]
	s_add_i32 m0, s101, 0x8000
	s_nop 0
	global_load_lds_dwordx4 v138, vcc
	s_add_i32 m0, s101, 0x2000
	s_nop 0
	global_load_lds_dwordx4 v144, s[98:99]
	s_add_i32 m0, s101, 0xa000
	s_nop 0
	global_load_lds_dwordx4 v136, vcc
	s_add_i32 m0, s101, 0x4000
	s_nop 0
	global_load_lds_dwordx4 v142, s[98:99]
	s_add_i32 m0, s101, 0xc000
	s_nop 0
	global_load_lds_dwordx4 v134, vcc
	s_add_i32 m0, s101, 0x6000
	s_nop 0
	global_load_lds_dwordx4 v140, s[98:99]
	s_add_i32 m0, s101, 0xe000
	s_nop 0
	global_load_lds_dwordx4 v130, vcc
.LBB0_1138:
	s_and_b32 s27, s26, 0x10000
	s_xor_b32 s28, s27, 0x10000
	s_add_i32 s27, s27, 0
	s_add_i32 s101, s100, s28
	s_cmpk_eq_i32 s12, 0
	s_cbranch_scc1 .Lg1n_1138
	s_waitcnt lgkmcnt(3)
	v_mfma_f32_16x16x32_bf16 v[124:127], v[178:181], v[162:165], v[124:127]
	v_mfma_f32_16x16x32_bf16 v[108:111], v[178:181], v[166:169], v[108:111]
	v_mfma_f32_16x16x32_bf16 v[92:95], v[178:181], v[170:173], v[92:95]
	v_mfma_f32_16x16x32_bf16 v[76:79], v[178:181], v[174:177], v[76:79]
	ds_read_b128 v[240:243], v197
	ds_read_b128 v[244:247], v198
	s_add_i32 m0, s101, 0x4000
	s_nop 0
	global_load_lds_dwordx4 v142, s[98:99]
	s_waitcnt lgkmcnt(4)
	v_mfma_f32_16x16x32_bf16 v[120:123], v[182:185], v[162:165], v[120:123]
	v_mfma_f32_16x16x32_bf16 v[104:107], v[182:185], v[166:169], v[104:107]
	v_mfma_f32_16x16x32_bf16 v[88:91], v[182:185], v[170:173], v[88:91]
	v_mfma_f32_16x16x32_bf16 v[72:75], v[182:185], v[174:177], v[72:75]
	ds_read_b128 v[248:251], v199
	ds_read_b128 v[252:255], v200
	s_add_i32 m0, s101, 0xc000
	s_nop 0
	global_load_lds_dwordx4 v134, vcc
	s_waitcnt lgkmcnt(5)
	v_mfma_f32_16x16x32_bf16 v[116:119], v[186:189], v[162:165], v[116:119]
	v_mfma_f32_16x16x32_bf16 v[100:103], v[186:189], v[166:169], v[100:103]
	v_mfma_f32_16x16x32_bf16 v[84:87], v[186:189], v[170:173], v[84:87]
	v_mfma_f32_16x16x32_bf16 v[68:71], v[186:189], v[174:177], v[68:71]
	s_add_i32 m0, s101, 0x6000
	s_nop 0
	global_load_lds_dwordx4 v140, s[98:99]
	s_waitcnt lgkmcnt(4)
	v_mfma_f32_16x16x32_bf16 v[112:115], v[190:193], v[162:165], v[112:115]
	v_mfma_f32_16x16x32_bf16 v[96:99], v[190:193], v[166:169], v[96:99]
	v_mfma_f32_16x16x32_bf16 v[80:83], v[190:193], v[170:173], v[80:83]
	v_mfma_f32_16x16x32_bf16 v[64:67], v[190:193], v[174:177], v[64:67]
	s_add_i32 m0, s101, 0xe000
	s_nop 0
	global_load_lds_dwordx4 v130, vcc
.Lg2_1138:
	ds_read_b128 v[162:165], v161 offset:1024
	ds_read_b128 v[166:169], v194 offset:1024
	ds_read_b128 v[170:173], v195 offset:1024
	ds_read_b128 v[174:177], v196 offset:1024
	s_waitcnt lgkmcnt(4)
	v_mfma_f32_16x16x32_bf16 v[60:63], v[178:181], v[240:243], v[60:63]
	v_mfma_f32_16x16x32_bf16 v[44:47], v[178:181], v[244:247], v[44:47]
	v_mfma_f32_16x16x32_bf16 v[16:19], v[178:181], v[248:251], v[16:19]
	v_mfma_f32_16x16x32_bf16 v[36:39], v[178:181], v[252:255], v[36:39]
	ds_read_b128 v[178:181], v128 offset:33792
	v_mfma_f32_16x16x32_bf16 v[56:59], v[182:185], v[240:243], v[56:59]
	v_mfma_f32_16x16x32_bf16 v[40:43], v[182:185], v[244:247], v[40:43]
	v_mfma_f32_16x16x32_bf16 v[8:11], v[182:185], v[248:251], v[8:11]
	v_mfma_f32_16x16x32_bf16 v[28:31], v[182:185], v[252:255], v[28:31]
	ds_read_b128 v[182:185], v128 offset:35840
	v_mfma_f32_16x16x32_bf16 v[52:55], v[186:189], v[240:243], v[52:55]
	v_mfma_f32_16x16x32_bf16 v[32:35], v[186:189], v[244:247], v[32:35]
	v_mfma_f32_16x16x32_bf16 v[4:7], v[186:189], v[248:251], v[4:7]
	v_mfma_f32_16x16x32_bf16 v[20:23], v[186:189], v[252:255], v[20:23]
	ds_read_b128 v[186:189], v128 offset:37888
	v_mfma_f32_16x16x32_bf16 v[48:51], v[190:193], v[240:243], v[48:51]
	v_mfma_f32_16x16x32_bf16 v[24:27], v[190:193], v[244:247], v[24:27]
	v_mfma_f32_16x16x32_bf16 v[0:3], v[190:193], v[248:251], v[0:3]
	v_mfma_f32_16x16x32_bf16 v[12:15], v[190:193], v[252:255], v[12:15]
	ds_read_b128 v[190:193], v128 offset:39936
	s_waitcnt lgkmcnt(3)
	v_mfma_f32_16x16x32_bf16 v[124:127], v[178:181], v[162:165], v[124:127]
	v_mfma_f32_16x16x32_bf16 v[108:111], v[178:181], v[166:169], v[108:111]
	v_mfma_f32_16x16x32_bf16 v[92:95], v[178:181], v[170:173], v[92:95]
	v_mfma_f32_16x16x32_bf16 v[76:79], v[178:181], v[174:177], v[76:79]
	ds_read_b128 v[240:243], v197 offset:1024
	ds_read_b128 v[244:247], v198 offset:1024
	s_waitcnt lgkmcnt(4)
	v_mfma_f32_16x16x32_bf16 v[120:123], v[182:185], v[162:165], v[120:123]
	v_mfma_f32_16x16x32_bf16 v[104:107], v[182:185], v[166:169], v[104:107]
	v_mfma_f32_16x16x32_bf16 v[88:91], v[182:185], v[170:173], v[88:91]
	v_mfma_f32_16x16x32_bf16 v[72:75], v[182:185], v[174:177], v[72:75]
	ds_read_b128 v[248:251], v199 offset:1024
	ds_read_b128 v[252:255], v200 offset:1024
	s_waitcnt lgkmcnt(5)
	v_mfma_f32_16x16x32_bf16 v[116:119], v[186:189], v[162:165], v[116:119]
	v_mfma_f32_16x16x32_bf16 v[100:103], v[186:189], v[166:169], v[100:103]
	v_mfma_f32_16x16x32_bf16 v[84:87], v[186:189], v[170:173], v[84:87]
	v_mfma_f32_16x16x32_bf16 v[68:71], v[186:189], v[174:177], v[68:71]
	s_waitcnt lgkmcnt(4)
	v_mfma_f32_16x16x32_bf16 v[112:115], v[190:193], v[162:165], v[112:115]
	v_mfma_f32_16x16x32_bf16 v[96:99], v[190:193], v[166:169], v[96:99]
	v_mfma_f32_16x16x32_bf16 v[80:83], v[190:193], v[170:173], v[80:83]
	v_mfma_f32_16x16x32_bf16 v[64:67], v[190:193], v[174:177], v[64:67]
	s_waitcnt vmcnt(0) lgkmcnt(0)
	s_barrier
	s_add_i32 s101, s100, s27
	s_cmpk_eq_i32 s12, 0x1500
	s_cbranch_scc1 .Lg4n_1138
	s_add_u32 s98, s98, 0x80
	s_addc_u32 s99, s99, 0
	s_add_u32 vcc_lo, vcc_lo, 0x80
	s_addc_u32 vcc_hi, vcc_hi, 0
	v_mfma_f32_16x16x32_bf16 v[60:63], v[178:181], v[240:243], v[60:63]
	v_mfma_f32_16x16x32_bf16 v[44:47], v[178:181], v[244:247], v[44:47]
	v_mfma_f32_16x16x32_bf16 v[16:19], v[178:181], v[248:251], v[16:19]
	v_mfma_f32_16x16x32_bf16 v[36:39], v[178:181], v[252:255], v[36:39]
	v_add3_u32 v128, s28, v150, v151
	ds_read_b128 v[178:181], v128 offset:32768
	v_add3_u32 v161, s28, v150, v152
	v_add3_u32 v194, s28, v154, v153
	v_add3_u32 v195, s28, v154, v155
	v_add3_u32 v196, s28, v154, v156
	ds_read_b128 v[162:165], v161
	ds_read_b128 v[166:169], v194
	ds_read_b128 v[170:173], v195
	ds_read_b128 v[174:177], v196
	s_mov_b32 m0, s101
	s_nop 0
	global_load_lds_dwordx4 v146, s[98:99]
	v_mfma_f32_16x16x32_bf16 v[56:59], v[182:185], v[240:243], v[56:59]
	v_mfma_f32_16x16x32_bf16 v[40:43], v[182:185], v[244:247], v[40:43]
	v_mfma_f32_16x16x32_bf16 v[8:11], v[182:185], v[248:251], v[8:11]
	v_mfma_f32_16x16x32_bf16 v[28:31], v[182:185], v[252:255], v[28:31]
	ds_read_b128 v[182:185], v128 offset:34816
	v_add3_u32 v197, s28, v154, v157
	v_add3_u32 v198, s28, v154, v158
	v_add3_u32 v199, s28, v154, v159
	v_add3_u32 v200, s28, v154, v160
	s_add_i32 m0, s101, 0x8000
	s_nop 0
	global_load_lds_dwordx4 v138, vcc
	v_mfma_f32_16x16x32_bf16 v[52:55], v[186:189], v[240:243], v[52:55]
	v_mfma_f32_16x16x32_bf16 v[32:35], v[186:189], v[244:247], v[32:35]
	v_mfma_f32_16x16x32_bf16 v[4:7], v[186:189], v[248:251], v[4:7]
	v_mfma_f32_16x16x32_bf16 v[20:23], v[186:189], v[252:255], v[20:23]
	ds_read_b128 v[186:189], v128 offset:36864
	s_add_i32 m0, s101, 0x2000
	s_nop 0
	global_load_lds_dwordx4 v144, s[98:99]
	v_mfma_f32_16x16x32_bf16 v[48:51], v[190:193], v[240:243], v[48:51]
	v_mfma_f32_16x16x32_bf16 v[24:27], v[190:193], v[244:247], v[24:27]
	v_mfma_f32_16x16x32_bf16 v[0:3], v[190:193], v[248:251], v[0:3]
	v_mfma_f32_16x16x32_bf16 v[12:15], v[190:193], v[252:255], v[12:15]
	ds_read_b128 v[190:193], v128 offset:38912
	s_add_i32 m0, s101, 0xa000
	s_nop 0
	global_load_lds_dwordx4 v136, vcc
